# 4 barriers per 2 K-tiles (H0 runs [M L], H1 runs [L M] between barriers), duplicated loop bodies
# baseline (speedup 1.0000x reference)
.LBB0_485:
	s_lshl_b32 s7, s5, 5
	s_and_b32 s12, s7, 0x60
	s_add_i32 m0, s39, 0x18000
	v_lshl_add_u64 v[8:9], v[8:9], 0, s[2:3]
	s_lshl_b32 s9, s8, 13
	s_lshr_b32 s13, s12, 3
	s_waitcnt vmcnt(2)
	s_barrier
	global_load_lds_dwordx4 v[8:9], off
	v_lshl_add_u64 v[6:7], v[6:7], 0, s[2:3]
	s_add_i32 m0, s39, 0x1a000
	s_add_i32 s45, s39, 0x8000
	s_add_i32 s46, s39, 0xa000
	global_load_lds_dwordx4 v[6:7], off
	v_lshl_add_u64 v[2:3], v[2:3], 0, s[2:3]
	s_mov_b32 m0, s45
	s_add_u32 s10, s18, 0x80080
	global_load_lds_dwordx4 v[2:3], off
	v_lshl_add_u64 v[2:3], v[4:5], 0, s[2:3]
	s_mov_b32 m0, s46
	s_addc_u32 s11, s19, 0
	global_load_lds_dwordx4 v[2:3], off
	s_add_i32 m0, s39, 0x1c000
	v_lshl_add_u64 v[2:3], s[10:11], 0, v[0:1]
	global_load_lds_dwordx4 v[2:3], off
	v_lshl_add_u64 v[2:3], s[10:11], 0, v[130:131]
	s_add_i32 m0, s39, 0x1e000
	v_and_b32_e32 v5, 48, v11
	global_load_lds_dwordx4 v[2:3], off
	v_and_b32_e32 v2, 15, v11
	v_lshl_or_b32 v140, s8, 6, v2
	v_ashrrev_i32_e32 v4, 6, v11
	v_lshl_or_b32 v2, v2, 6, v5
	v_lshlrev_b32_e32 v5, 2, v11
	v_lshl_add_u32 v6, v4, 10, s9
	v_and_b32_e32 v5, 32, v5
	v_add_lshl_u32 v4, s13, v4, 10
	v_ashrrev_i32_e32 v3, 1, v11
	v_bitop3_b32 v6, v2, v6, v5 bitop3:0xde
	v_bitop3_b32 v141, v2, v4, v5 bitop3:0xde
	v_lshlrev_b32_e32 v2, 15, v14
	v_and_b32_e32 v3, -8, v3
	v_and_b32_e32 v2, 0xffff0000, v2
	v_add_u32_e32 v142, s12, v3
	v_lshl_add_u32 v2, v15, 12, v2
	v_and_b32_e32 v3, 1, v14
	v_lshl_or_b32 v2, v3, 6, v2
	v_lshl_add_u32 v136, v16, 1, v2
	v_lshlrev_b32_e32 v2, 15, v10
	v_and_b32_e32 v2, 0xffff0000, v2
	s_waitcnt vmcnt(6)
	v_lshl_add_u32 v2, v12, 12, v2
	v_and_b32_e32 v3, 1, v10
	s_cmp_lt_u32 s5, 4
	v_lshl_or_b32 v2, v3, 6, v2
	s_sext_i32_i16 s7, s4
	s_cselect_b64 s[4:5], -1, 0
	s_ashr_i32 s47, s23, 31
	v_mov_b32_e32 v137, v1
	v_lshl_add_u32 v138, v13, 1, v2
	v_mov_b32_e32 v139, v1
	s_mov_b32 s48, 0
	v_add_u32_e32 v143, 0, v6
	s_waitcnt vmcnt(0)
	s_branch .LBB0_488

.LBB0_491:
	s_and_b64 vcc, exec, s[4:5]
	s_cbranch_vccz .Lh1_0
.Lh0_0:
	s_add_u32 s18, s16, 0xfff80080
	s_addc_u32 s19, s17, -1
	s_add_i32 s54, 0, 0x10000
	s_cmp_eq_u32 s53, 28
	s_cselect_b32 s21, s11, s19
	s_cselect_b32 s20, s49, s18
	s_cselect_b32 s19, s9, s52
	s_cselect_b32 s18, s50, s51
	s_add_i32 s56, 0, 0x14000
	v_add_u32_e32 v156, s54, v141
	v_add_u32_e32 v172, s56, v141
	ds_read_b128 v[144:147], v156
	ds_read_b128 v[148:151], v156 offset:1024
	ds_read_b128 v[152:155], v156 offset:2048
	ds_read_b128 v[156:159], v156 offset:3072
	ds_read_b128 v[160:163], v172
	ds_read_b128 v[164:167], v172 offset:1024
	ds_read_b128 v[168:171], v172 offset:2048
	ds_read_b128 v[172:175], v172 offset:3072
	v_lshl_add_u64 v[208:209], s[16:17], 0, v[136:137]
	s_add_i32 m0, s39, 0xc000
	ds_read_b128 v[176:179], v143
	ds_read_b128 v[180:183], v143 offset:1024
	ds_read_b128 v[184:187], v143 offset:2048
	ds_read_b128 v[188:191], v143 offset:3072
	ds_read_b128 v[192:195], v143 offset:4096
	ds_read_b128 v[196:199], v143 offset:5120
	ds_read_b128 v[200:203], v143 offset:6144
	ds_read_b128 v[204:207], v143 offset:7168
	global_load_lds_dwordx4 v[208:209], off
	v_lshl_add_u64 v[208:209], s[16:17], 0, v[138:139]
	s_add_i32 m0, s39, 0xe000
	s_nop 0
	global_load_lds_dwordx4 v[208:209], off
	s_waitcnt vmcnt(8)
	s_waitcnt lgkmcnt(0)
	s_barrier
	s_setprio 1
	s_waitcnt lgkmcnt(0)
	v_mfma_f32_16x16x32_bf16 v[126:129], v[144:147], v[176:179], v[126:129]
	v_mfma_f32_16x16x32_bf16 v[122:125], v[152:155], v[176:179], v[122:125]
	v_mfma_f32_16x16x32_bf16 v[118:121], v[144:147], v[184:187], v[118:121]
	v_mfma_f32_16x16x32_bf16 v[114:117], v[152:155], v[184:187], v[114:117]
	v_mfma_f32_16x16x32_bf16 v[102:105], v[144:147], v[192:195], v[102:105]
	v_mfma_f32_16x16x32_bf16 v[98:101], v[152:155], v[192:195], v[98:101]
	v_mfma_f32_16x16x32_bf16 v[86:89], v[144:147], v[200:203], v[86:89]
	v_mfma_f32_16x16x32_bf16 v[82:85], v[152:155], v[200:203], v[82:85]
	v_mfma_f32_16x16x32_bf16 v[126:129], v[148:151], v[180:183], v[126:129]
	v_mfma_f32_16x16x32_bf16 v[122:125], v[156:159], v[180:183], v[122:125]
	v_mfma_f32_16x16x32_bf16 v[118:121], v[148:151], v[188:191], v[118:121]
	v_mfma_f32_16x16x32_bf16 v[114:117], v[156:159], v[188:191], v[114:117]
	v_mfma_f32_16x16x32_bf16 v[102:105], v[148:151], v[196:199], v[102:105]
	v_mfma_f32_16x16x32_bf16 v[98:101], v[156:159], v[196:199], v[98:101]
	v_mfma_f32_16x16x32_bf16 v[86:89], v[148:151], v[204:207], v[86:89]
	v_mfma_f32_16x16x32_bf16 v[82:85], v[156:159], v[204:207], v[82:85]
	s_setprio 0
	s_setprio 1
	v_mfma_f32_16x16x32_bf16 v[110:113], v[160:163], v[176:179], v[110:113]
	v_mfma_f32_16x16x32_bf16 v[106:109], v[168:171], v[176:179], v[106:109]
	v_mfma_f32_16x16x32_bf16 v[94:97], v[160:163], v[184:187], v[94:97]
	v_mfma_f32_16x16x32_bf16 v[90:93], v[168:171], v[184:187], v[90:93]
	v_mfma_f32_16x16x32_bf16 v[78:81], v[160:163], v[192:195], v[78:81]
	v_mfma_f32_16x16x32_bf16 v[74:77], v[168:171], v[192:195], v[74:77]
	v_mfma_f32_16x16x32_bf16 v[70:73], v[160:163], v[200:203], v[70:73]
	v_mfma_f32_16x16x32_bf16 v[66:69], v[168:171], v[200:203], v[66:69]
	v_mfma_f32_16x16x32_bf16 v[110:113], v[164:167], v[180:183], v[110:113]
	v_mfma_f32_16x16x32_bf16 v[106:109], v[172:175], v[180:183], v[106:109]
	v_mfma_f32_16x16x32_bf16 v[94:97], v[164:167], v[188:191], v[94:97]
	v_mfma_f32_16x16x32_bf16 v[90:93], v[172:175], v[188:191], v[90:93]
	v_mfma_f32_16x16x32_bf16 v[78:81], v[164:167], v[196:199], v[78:81]
	v_mfma_f32_16x16x32_bf16 v[74:77], v[172:175], v[196:199], v[74:77]
	v_mfma_f32_16x16x32_bf16 v[70:73], v[164:167], v[204:207], v[70:73]
	v_mfma_f32_16x16x32_bf16 v[66:69], v[172:175], v[204:207], v[66:69]
	s_setprio 0
	s_add_i32 s54, s54, s37
	v_lshl_add_u64 v[208:209], s[18:19], 0, v[0:1]
	s_mov_b32 m0, s54
	ds_read_b128 v[176:179], v143 offset:16384
	ds_read_b128 v[180:183], v143 offset:17408
	ds_read_b128 v[184:187], v143 offset:18432
	ds_read_b128 v[188:191], v143 offset:19456
	ds_read_b128 v[192:195], v143 offset:20480
	ds_read_b128 v[196:199], v143 offset:21504
	ds_read_b128 v[200:203], v143 offset:22528
	ds_read_b128 v[204:207], v143 offset:23552
	global_load_lds_dwordx4 v[208:209], off
	s_add_i32 m0, s54, 0x2000
	s_add_u32 s54, s18, 0x80000
	v_lshl_add_u64 v[220:221], s[18:19], 0, v[130:131]
	s_addc_u32 s55, s19, 0
	s_add_i32 s56, s56, s37
	global_load_lds_dwordx4 v[220:221], off
	v_lshl_add_u64 v[222:223], s[54:55], 0, v[0:1]
	s_mov_b32 m0, s56
	v_lshl_add_u64 v[224:225], s[20:21], 0, v[132:133]
	global_load_lds_dwordx4 v[222:223], off
	v_lshl_add_u64 v[222:223], s[54:55], 0, v[130:131]
	s_add_i32 m0, s56, 0x2000
	s_nop 0
	global_load_lds_dwordx4 v[222:223], off
	v_lshl_add_u64 v[222:223], s[20:21], 0, v[134:135]
	s_mov_b32 m0, s39
	s_nop 0
	global_load_lds_dwordx4 v[222:223], off
	s_mov_b32 m0, s40
	s_nop 0
	global_load_lds_dwordx4 v[224:225], off
	s_waitcnt vmcnt(8)
	s_waitcnt lgkmcnt(0)
	s_barrier
	s_setprio 1
	s_waitcnt lgkmcnt(0)
	v_mfma_f32_16x16x32_bf16 v[62:65], v[144:147], v[176:179], v[62:65]
	v_mfma_f32_16x16x32_bf16 v[58:61], v[152:155], v[176:179], v[58:61]
	v_mfma_f32_16x16x32_bf16 v[54:57], v[144:147], v[184:187], v[54:57]
	v_mfma_f32_16x16x32_bf16 v[50:53], v[152:155], v[184:187], v[50:53]
	v_mfma_f32_16x16x32_bf16 v[38:41], v[144:147], v[192:195], v[38:41]
	v_mfma_f32_16x16x32_bf16 v[34:37], v[152:155], v[192:195], v[34:37]
	v_mfma_f32_16x16x32_bf16 v[22:25], v[144:147], v[200:203], v[22:25]
	v_mfma_f32_16x16x32_bf16 v[18:21], v[152:155], v[200:203], v[18:21]
	v_mfma_f32_16x16x32_bf16 v[62:65], v[148:151], v[180:183], v[62:65]
	v_mfma_f32_16x16x32_bf16 v[58:61], v[156:159], v[180:183], v[58:61]
	v_mfma_f32_16x16x32_bf16 v[54:57], v[148:151], v[188:191], v[54:57]
	v_mfma_f32_16x16x32_bf16 v[50:53], v[156:159], v[188:191], v[50:53]
	v_mfma_f32_16x16x32_bf16 v[38:41], v[148:151], v[196:199], v[38:41]
	v_mfma_f32_16x16x32_bf16 v[34:37], v[156:159], v[196:199], v[34:37]
	v_mfma_f32_16x16x32_bf16 v[22:25], v[148:151], v[204:207], v[22:25]
	v_mfma_f32_16x16x32_bf16 v[18:21], v[156:159], v[204:207], v[18:21]
	s_setprio 0
	s_setprio 1
	v_mfma_f32_16x16x32_bf16 v[46:49], v[160:163], v[176:179], v[46:49]
	v_mfma_f32_16x16x32_bf16 v[42:45], v[168:171], v[176:179], v[42:45]
	v_mfma_f32_16x16x32_bf16 v[30:33], v[160:163], v[184:187], v[30:33]
	v_mfma_f32_16x16x32_bf16 v[26:29], v[168:171], v[184:187], v[26:29]
	v_mfma_f32_16x16x32_bf16 v[14:17], v[160:163], v[192:195], v[14:17]
	v_mfma_f32_16x16x32_bf16 v[10:13], v[168:171], v[192:195], v[10:13]
	v_mfma_f32_16x16x32_bf16 v[6:9], v[160:163], v[200:203], v[6:9]
	v_mfma_f32_16x16x32_bf16 v[2:5], v[168:171], v[200:203], v[2:5]
	v_mfma_f32_16x16x32_bf16 v[46:49], v[164:167], v[180:183], v[46:49]
	v_mfma_f32_16x16x32_bf16 v[42:45], v[172:175], v[180:183], v[42:45]
	v_mfma_f32_16x16x32_bf16 v[30:33], v[164:167], v[188:191], v[30:33]
	v_mfma_f32_16x16x32_bf16 v[26:29], v[172:175], v[188:191], v[26:29]
	v_mfma_f32_16x16x32_bf16 v[14:17], v[164:167], v[196:199], v[14:17]
	v_mfma_f32_16x16x32_bf16 v[10:13], v[172:175], v[196:199], v[10:13]
	v_mfma_f32_16x16x32_bf16 v[6:9], v[164:167], v[204:207], v[6:9]
	v_mfma_f32_16x16x32_bf16 v[2:5], v[172:175], v[204:207], v[2:5]
	s_setprio 0
	s_add_i32 s54, 0, 0x18000
	s_add_i32 s55, 0, 0x1c000
	v_add_u32_e32 v156, s54, v141
	v_add_u32_e32 v172, s55, v141
	ds_read_b128 v[144:147], v156
	ds_read_b128 v[148:151], v156 offset:1024
	ds_read_b128 v[152:155], v156 offset:2048
	ds_read_b128 v[156:159], v156 offset:3072
	ds_read_b128 v[160:163], v172
	ds_read_b128 v[164:167], v172 offset:1024
	ds_read_b128 v[168:171], v172 offset:2048
	ds_read_b128 v[172:175], v172 offset:3072
	s_add_u32 s20, s20, 0x80000
	s_addc_u32 s21, s21, 0
	s_mov_b32 m0, s41
	v_lshl_add_u64 v[226:227], s[20:21], 0, v[134:135]
	ds_read_b128 v[176:179], v143 offset:32768
	ds_read_b128 v[180:183], v143 offset:33792
	ds_read_b128 v[184:187], v143 offset:34816
	ds_read_b128 v[188:191], v143 offset:35840
	ds_read_b128 v[192:195], v143 offset:36864
	ds_read_b128 v[196:199], v143 offset:37888
	ds_read_b128 v[200:203], v143 offset:38912
	ds_read_b128 v[204:207], v143 offset:39936
	global_load_lds_dwordx4 v[226:227], off
	v_lshl_add_u64 v[226:227], s[20:21], 0, v[132:133]
	s_mov_b32 m0, s44
	s_nop 0
	global_load_lds_dwordx4 v[226:227], off
	s_waitcnt vmcnt(8)
	s_waitcnt lgkmcnt(0)
	s_barrier
	s_setprio 1
	s_waitcnt lgkmcnt(0)
	v_mfma_f32_16x16x32_bf16 v[126:129], v[144:147], v[176:179], v[126:129]
	v_mfma_f32_16x16x32_bf16 v[122:125], v[152:155], v[176:179], v[122:125]
	v_mfma_f32_16x16x32_bf16 v[118:121], v[144:147], v[184:187], v[118:121]
	v_mfma_f32_16x16x32_bf16 v[114:117], v[152:155], v[184:187], v[114:117]
	v_mfma_f32_16x16x32_bf16 v[102:105], v[144:147], v[192:195], v[102:105]
	v_mfma_f32_16x16x32_bf16 v[98:101], v[152:155], v[192:195], v[98:101]
	v_mfma_f32_16x16x32_bf16 v[86:89], v[144:147], v[200:203], v[86:89]
	v_mfma_f32_16x16x32_bf16 v[82:85], v[152:155], v[200:203], v[82:85]
	v_mfma_f32_16x16x32_bf16 v[126:129], v[148:151], v[180:183], v[126:129]
	v_mfma_f32_16x16x32_bf16 v[122:125], v[156:159], v[180:183], v[122:125]
	v_mfma_f32_16x16x32_bf16 v[118:121], v[148:151], v[188:191], v[118:121]
	v_mfma_f32_16x16x32_bf16 v[114:117], v[156:159], v[188:191], v[114:117]
	v_mfma_f32_16x16x32_bf16 v[102:105], v[148:151], v[196:199], v[102:105]
	v_mfma_f32_16x16x32_bf16 v[98:101], v[156:159], v[196:199], v[98:101]
	v_mfma_f32_16x16x32_bf16 v[86:89], v[148:151], v[204:207], v[86:89]
	v_mfma_f32_16x16x32_bf16 v[82:85], v[156:159], v[204:207], v[82:85]
	s_setprio 0
	s_setprio 1
	v_mfma_f32_16x16x32_bf16 v[110:113], v[160:163], v[176:179], v[110:113]
	v_mfma_f32_16x16x32_bf16 v[106:109], v[168:171], v[176:179], v[106:109]
	v_mfma_f32_16x16x32_bf16 v[94:97], v[160:163], v[184:187], v[94:97]
	v_mfma_f32_16x16x32_bf16 v[90:93], v[168:171], v[184:187], v[90:93]
	v_mfma_f32_16x16x32_bf16 v[78:81], v[160:163], v[192:195], v[78:81]
	v_mfma_f32_16x16x32_bf16 v[74:77], v[168:171], v[192:195], v[74:77]
	v_mfma_f32_16x16x32_bf16 v[70:73], v[160:163], v[200:203], v[70:73]
	v_mfma_f32_16x16x32_bf16 v[66:69], v[168:171], v[200:203], v[66:69]
	v_mfma_f32_16x16x32_bf16 v[110:113], v[164:167], v[180:183], v[110:113]
	v_mfma_f32_16x16x32_bf16 v[106:109], v[172:175], v[180:183], v[106:109]
	v_mfma_f32_16x16x32_bf16 v[94:97], v[164:167], v[188:191], v[94:97]
	v_mfma_f32_16x16x32_bf16 v[90:93], v[172:175], v[188:191], v[90:93]
	v_mfma_f32_16x16x32_bf16 v[78:81], v[164:167], v[196:199], v[78:81]
	v_mfma_f32_16x16x32_bf16 v[74:77], v[172:175], v[196:199], v[74:77]
	v_mfma_f32_16x16x32_bf16 v[70:73], v[164:167], v[204:207], v[70:73]
	v_mfma_f32_16x16x32_bf16 v[66:69], v[172:175], v[204:207], v[66:69]
	s_setprio 0
	s_add_i32 s20, s54, s37
	v_lshl_add_u64 v[208:209], v[208:209], 0, s[2:3]
	s_mov_b32 m0, s20
	ds_read_b128 v[176:179], v143 offset:49152
	ds_read_b128 v[180:183], v143 offset:50176
	ds_read_b128 v[184:187], v143 offset:51200
	ds_read_b128 v[188:191], v143 offset:52224
	ds_read_b128 v[192:195], v143 offset:53248
	ds_read_b128 v[196:199], v143 offset:54272
	ds_read_b128 v[200:203], v143 offset:55296
	ds_read_b128 v[204:207], v143 offset:56320
	global_load_lds_dwordx4 v[208:209], off
	s_add_i32 m0, s20, 0x2000
	s_add_u32 s18, s18, 0x80080
	v_lshl_add_u64 v[208:209], v[220:221], 0, s[2:3]
	s_addc_u32 s19, s19, 0
	s_add_i32 s20, s55, s37
	global_load_lds_dwordx4 v[208:209], off
	v_lshl_add_u64 v[208:209], s[18:19], 0, v[0:1]
	s_mov_b32 m0, s20
	s_nop 0
	global_load_lds_dwordx4 v[208:209], off
	v_lshl_add_u64 v[208:209], s[18:19], 0, v[130:131]
	s_add_i32 m0, s20, 0x2000
	s_nop 0
	global_load_lds_dwordx4 v[208:209], off
	v_lshl_add_u64 v[208:209], v[222:223], 0, s[2:3]
	s_mov_b32 m0, s45
	s_nop 0
	global_load_lds_dwordx4 v[208:209], off
	v_lshl_add_u64 v[208:209], v[224:225], 0, s[2:3]
	s_mov_b32 m0, s46
	s_nop 0
	global_load_lds_dwordx4 v[208:209], off
	s_waitcnt vmcnt(8)
	s_waitcnt lgkmcnt(0)
	s_barrier
	s_setprio 1
	s_waitcnt lgkmcnt(0)
	v_mfma_f32_16x16x32_bf16 v[62:65], v[144:147], v[176:179], v[62:65]
	v_mfma_f32_16x16x32_bf16 v[58:61], v[152:155], v[176:179], v[58:61]
	v_mfma_f32_16x16x32_bf16 v[54:57], v[144:147], v[184:187], v[54:57]
	v_mfma_f32_16x16x32_bf16 v[50:53], v[152:155], v[184:187], v[50:53]
	v_mfma_f32_16x16x32_bf16 v[38:41], v[144:147], v[192:195], v[38:41]
	v_mfma_f32_16x16x32_bf16 v[34:37], v[152:155], v[192:195], v[34:37]
	v_mfma_f32_16x16x32_bf16 v[22:25], v[144:147], v[200:203], v[22:25]
	v_mfma_f32_16x16x32_bf16 v[18:21], v[152:155], v[200:203], v[18:21]
	v_mfma_f32_16x16x32_bf16 v[62:65], v[148:151], v[180:183], v[62:65]
	v_mfma_f32_16x16x32_bf16 v[58:61], v[156:159], v[180:183], v[58:61]
	v_mfma_f32_16x16x32_bf16 v[54:57], v[148:151], v[188:191], v[54:57]
	v_mfma_f32_16x16x32_bf16 v[50:53], v[156:159], v[188:191], v[50:53]
	v_mfma_f32_16x16x32_bf16 v[38:41], v[148:151], v[196:199], v[38:41]
	v_mfma_f32_16x16x32_bf16 v[34:37], v[156:159], v[196:199], v[34:37]
	v_mfma_f32_16x16x32_bf16 v[22:25], v[148:151], v[204:207], v[22:25]
	v_mfma_f32_16x16x32_bf16 v[18:21], v[156:159], v[204:207], v[18:21]
	s_setprio 0
	s_setprio 1
	v_mfma_f32_16x16x32_bf16 v[46:49], v[160:163], v[176:179], v[46:49]
	v_mfma_f32_16x16x32_bf16 v[42:45], v[168:171], v[176:179], v[42:45]
	v_mfma_f32_16x16x32_bf16 v[30:33], v[160:163], v[184:187], v[30:33]
	v_mfma_f32_16x16x32_bf16 v[26:29], v[168:171], v[184:187], v[26:29]
	v_mfma_f32_16x16x32_bf16 v[14:17], v[160:163], v[192:195], v[14:17]
	v_mfma_f32_16x16x32_bf16 v[10:13], v[168:171], v[192:195], v[10:13]
	v_mfma_f32_16x16x32_bf16 v[6:9], v[160:163], v[200:203], v[6:9]
	v_mfma_f32_16x16x32_bf16 v[2:5], v[168:171], v[200:203], v[2:5]
	v_mfma_f32_16x16x32_bf16 v[46:49], v[164:167], v[180:183], v[46:49]
	v_mfma_f32_16x16x32_bf16 v[42:45], v[172:175], v[180:183], v[42:45]
	v_mfma_f32_16x16x32_bf16 v[30:33], v[164:167], v[188:191], v[30:33]
	v_mfma_f32_16x16x32_bf16 v[26:29], v[172:175], v[188:191], v[26:29]
	v_mfma_f32_16x16x32_bf16 v[14:17], v[164:167], v[196:199], v[14:17]
	v_mfma_f32_16x16x32_bf16 v[10:13], v[172:175], v[196:199], v[10:13]
	v_mfma_f32_16x16x32_bf16 v[6:9], v[164:167], v[204:207], v[6:9]
	v_mfma_f32_16x16x32_bf16 v[2:5], v[172:175], v[204:207], v[2:5]
	s_setprio 0
	s_add_i32 s53, s53, 2
	s_add_u32 s16, s16, 0x100
	s_addc_u32 s17, s17, 0
	s_add_u32 s51, s51, 0x100
	s_addc_u32 s52, s52, 0
	s_cmp_gt_u32 s53, 29
	s_cbranch_scc0 .Lh0_0
	s_branch .Ldone_0
.Lh1_0:
	s_add_u32 s18, s16, 0xfff80080
	s_addc_u32 s19, s17, -1
	s_add_i32 s54, 0, 0x10000
	s_cmp_eq_u32 s53, 28
	s_cselect_b32 s21, s11, s19
	s_cselect_b32 s20, s49, s18
	s_cselect_b32 s19, s9, s52
	s_cselect_b32 s18, s50, s51
	s_add_i32 s56, 0, 0x14000
	v_add_u32_e32 v156, s54, v141
	v_add_u32_e32 v172, s56, v141
	ds_read_b128 v[144:147], v156
	ds_read_b128 v[148:151], v156 offset:1024
	ds_read_b128 v[152:155], v156 offset:2048
	ds_read_b128 v[156:159], v156 offset:3072
	ds_read_b128 v[160:163], v172
	ds_read_b128 v[164:167], v172 offset:1024
	ds_read_b128 v[168:171], v172 offset:2048
	ds_read_b128 v[172:175], v172 offset:3072
	v_lshl_add_u64 v[208:209], s[16:17], 0, v[136:137]
	s_add_i32 m0, s39, 0xc000
	ds_read_b128 v[176:179], v143
	ds_read_b128 v[180:183], v143 offset:1024
	ds_read_b128 v[184:187], v143 offset:2048
	ds_read_b128 v[188:191], v143 offset:3072
	ds_read_b128 v[192:195], v143 offset:4096
	ds_read_b128 v[196:199], v143 offset:5120
	ds_read_b128 v[200:203], v143 offset:6144
	ds_read_b128 v[204:207], v143 offset:7168
	global_load_lds_dwordx4 v[208:209], off
	v_lshl_add_u64 v[208:209], s[16:17], 0, v[138:139]
	s_add_i32 m0, s39, 0xe000
	s_nop 0
	global_load_lds_dwordx4 v[208:209], off
	s_waitcnt vmcnt(8)
	s_waitcnt lgkmcnt(0)
	s_setprio 1
	s_waitcnt lgkmcnt(0)
	v_mfma_f32_16x16x32_bf16 v[126:129], v[144:147], v[176:179], v[126:129]
	v_mfma_f32_16x16x32_bf16 v[122:125], v[152:155], v[176:179], v[122:125]
	v_mfma_f32_16x16x32_bf16 v[118:121], v[144:147], v[184:187], v[118:121]
	v_mfma_f32_16x16x32_bf16 v[114:117], v[152:155], v[184:187], v[114:117]
	v_mfma_f32_16x16x32_bf16 v[102:105], v[144:147], v[192:195], v[102:105]
	v_mfma_f32_16x16x32_bf16 v[98:101], v[152:155], v[192:195], v[98:101]
	v_mfma_f32_16x16x32_bf16 v[86:89], v[144:147], v[200:203], v[86:89]
	v_mfma_f32_16x16x32_bf16 v[82:85], v[152:155], v[200:203], v[82:85]
	v_mfma_f32_16x16x32_bf16 v[126:129], v[148:151], v[180:183], v[126:129]
	v_mfma_f32_16x16x32_bf16 v[122:125], v[156:159], v[180:183], v[122:125]
	v_mfma_f32_16x16x32_bf16 v[118:121], v[148:151], v[188:191], v[118:121]
	v_mfma_f32_16x16x32_bf16 v[114:117], v[156:159], v[188:191], v[114:117]
	v_mfma_f32_16x16x32_bf16 v[102:105], v[148:151], v[196:199], v[102:105]
	v_mfma_f32_16x16x32_bf16 v[98:101], v[156:159], v[196:199], v[98:101]
	v_mfma_f32_16x16x32_bf16 v[86:89], v[148:151], v[204:207], v[86:89]
	v_mfma_f32_16x16x32_bf16 v[82:85], v[156:159], v[204:207], v[82:85]
	s_setprio 0
	s_setprio 1
	v_mfma_f32_16x16x32_bf16 v[110:113], v[160:163], v[176:179], v[110:113]
	v_mfma_f32_16x16x32_bf16 v[106:109], v[168:171], v[176:179], v[106:109]
	v_mfma_f32_16x16x32_bf16 v[94:97], v[160:163], v[184:187], v[94:97]
	v_mfma_f32_16x16x32_bf16 v[90:93], v[168:171], v[184:187], v[90:93]
	v_mfma_f32_16x16x32_bf16 v[78:81], v[160:163], v[192:195], v[78:81]
	v_mfma_f32_16x16x32_bf16 v[74:77], v[168:171], v[192:195], v[74:77]
	v_mfma_f32_16x16x32_bf16 v[70:73], v[160:163], v[200:203], v[70:73]
	v_mfma_f32_16x16x32_bf16 v[66:69], v[168:171], v[200:203], v[66:69]
	v_mfma_f32_16x16x32_bf16 v[110:113], v[164:167], v[180:183], v[110:113]
	v_mfma_f32_16x16x32_bf16 v[106:109], v[172:175], v[180:183], v[106:109]
	v_mfma_f32_16x16x32_bf16 v[94:97], v[164:167], v[188:191], v[94:97]
	v_mfma_f32_16x16x32_bf16 v[90:93], v[172:175], v[188:191], v[90:93]
	v_mfma_f32_16x16x32_bf16 v[78:81], v[164:167], v[196:199], v[78:81]
	v_mfma_f32_16x16x32_bf16 v[74:77], v[172:175], v[196:199], v[74:77]
	v_mfma_f32_16x16x32_bf16 v[70:73], v[164:167], v[204:207], v[70:73]
	v_mfma_f32_16x16x32_bf16 v[66:69], v[172:175], v[204:207], v[66:69]
	s_setprio 0
	s_barrier
	s_add_i32 s54, s54, s37
	v_lshl_add_u64 v[208:209], s[18:19], 0, v[0:1]
	s_mov_b32 m0, s54
	ds_read_b128 v[176:179], v143 offset:16384
	ds_read_b128 v[180:183], v143 offset:17408
	ds_read_b128 v[184:187], v143 offset:18432
	ds_read_b128 v[188:191], v143 offset:19456
	ds_read_b128 v[192:195], v143 offset:20480
	ds_read_b128 v[196:199], v143 offset:21504
	ds_read_b128 v[200:203], v143 offset:22528
	ds_read_b128 v[204:207], v143 offset:23552
	global_load_lds_dwordx4 v[208:209], off
	s_add_i32 m0, s54, 0x2000
	s_add_u32 s54, s18, 0x80000
	v_lshl_add_u64 v[220:221], s[18:19], 0, v[130:131]
	s_addc_u32 s55, s19, 0
	s_add_i32 s56, s56, s37
	global_load_lds_dwordx4 v[220:221], off
	v_lshl_add_u64 v[222:223], s[54:55], 0, v[0:1]
	s_mov_b32 m0, s56
	v_lshl_add_u64 v[224:225], s[20:21], 0, v[132:133]
	global_load_lds_dwordx4 v[222:223], off
	v_lshl_add_u64 v[222:223], s[54:55], 0, v[130:131]
	s_add_i32 m0, s56, 0x2000
	s_nop 0
	global_load_lds_dwordx4 v[222:223], off
	v_lshl_add_u64 v[222:223], s[20:21], 0, v[134:135]
	s_mov_b32 m0, s39
	s_nop 0
	global_load_lds_dwordx4 v[222:223], off
	s_mov_b32 m0, s40
	s_nop 0
	global_load_lds_dwordx4 v[224:225], off
	s_waitcnt vmcnt(8)
	s_waitcnt lgkmcnt(0)
	s_setprio 1
	s_waitcnt lgkmcnt(0)
	v_mfma_f32_16x16x32_bf16 v[62:65], v[144:147], v[176:179], v[62:65]
	v_mfma_f32_16x16x32_bf16 v[58:61], v[152:155], v[176:179], v[58:61]
	v_mfma_f32_16x16x32_bf16 v[54:57], v[144:147], v[184:187], v[54:57]
	v_mfma_f32_16x16x32_bf16 v[50:53], v[152:155], v[184:187], v[50:53]
	v_mfma_f32_16x16x32_bf16 v[38:41], v[144:147], v[192:195], v[38:41]
	v_mfma_f32_16x16x32_bf16 v[34:37], v[152:155], v[192:195], v[34:37]
	v_mfma_f32_16x16x32_bf16 v[22:25], v[144:147], v[200:203], v[22:25]
	v_mfma_f32_16x16x32_bf16 v[18:21], v[152:155], v[200:203], v[18:21]
	v_mfma_f32_16x16x32_bf16 v[62:65], v[148:151], v[180:183], v[62:65]
	v_mfma_f32_16x16x32_bf16 v[58:61], v[156:159], v[180:183], v[58:61]
	v_mfma_f32_16x16x32_bf16 v[54:57], v[148:151], v[188:191], v[54:57]
	v_mfma_f32_16x16x32_bf16 v[50:53], v[156:159], v[188:191], v[50:53]
	v_mfma_f32_16x16x32_bf16 v[38:41], v[148:151], v[196:199], v[38:41]
	v_mfma_f32_16x16x32_bf16 v[34:37], v[156:159], v[196:199], v[34:37]
	v_mfma_f32_16x16x32_bf16 v[22:25], v[148:151], v[204:207], v[22:25]
	v_mfma_f32_16x16x32_bf16 v[18:21], v[156:159], v[204:207], v[18:21]
	s_setprio 0
	s_setprio 1
	v_mfma_f32_16x16x32_bf16 v[46:49], v[160:163], v[176:179], v[46:49]
	v_mfma_f32_16x16x32_bf16 v[42:45], v[168:171], v[176:179], v[42:45]
	v_mfma_f32_16x16x32_bf16 v[30:33], v[160:163], v[184:187], v[30:33]
	v_mfma_f32_16x16x32_bf16 v[26:29], v[168:171], v[184:187], v[26:29]
	v_mfma_f32_16x16x32_bf16 v[14:17], v[160:163], v[192:195], v[14:17]
	v_mfma_f32_16x16x32_bf16 v[10:13], v[168:171], v[192:195], v[10:13]
	v_mfma_f32_16x16x32_bf16 v[6:9], v[160:163], v[200:203], v[6:9]
	v_mfma_f32_16x16x32_bf16 v[2:5], v[168:171], v[200:203], v[2:5]
	v_mfma_f32_16x16x32_bf16 v[46:49], v[164:167], v[180:183], v[46:49]
	v_mfma_f32_16x16x32_bf16 v[42:45], v[172:175], v[180:183], v[42:45]
	v_mfma_f32_16x16x32_bf16 v[30:33], v[164:167], v[188:191], v[30:33]
	v_mfma_f32_16x16x32_bf16 v[26:29], v[172:175], v[188:191], v[26:29]
	v_mfma_f32_16x16x32_bf16 v[14:17], v[164:167], v[196:199], v[14:17]
	v_mfma_f32_16x16x32_bf16 v[10:13], v[172:175], v[196:199], v[10:13]
	v_mfma_f32_16x16x32_bf16 v[6:9], v[164:167], v[204:207], v[6:9]
	v_mfma_f32_16x16x32_bf16 v[2:5], v[172:175], v[204:207], v[2:5]
	s_setprio 0
	s_barrier
	s_add_i32 s54, 0, 0x18000
	s_add_i32 s55, 0, 0x1c000
	v_add_u32_e32 v156, s54, v141
	v_add_u32_e32 v172, s55, v141
	ds_read_b128 v[144:147], v156
	ds_read_b128 v[148:151], v156 offset:1024
	ds_read_b128 v[152:155], v156 offset:2048
	ds_read_b128 v[156:159], v156 offset:3072
	ds_read_b128 v[160:163], v172
	ds_read_b128 v[164:167], v172 offset:1024
	ds_read_b128 v[168:171], v172 offset:2048
	ds_read_b128 v[172:175], v172 offset:3072
	s_add_u32 s20, s20, 0x80000
	s_addc_u32 s21, s21, 0
	s_mov_b32 m0, s41
	v_lshl_add_u64 v[226:227], s[20:21], 0, v[134:135]
	ds_read_b128 v[176:179], v143 offset:32768
	ds_read_b128 v[180:183], v143 offset:33792
	ds_read_b128 v[184:187], v143 offset:34816
	ds_read_b128 v[188:191], v143 offset:35840
	ds_read_b128 v[192:195], v143 offset:36864
	ds_read_b128 v[196:199], v143 offset:37888
	ds_read_b128 v[200:203], v143 offset:38912
	ds_read_b128 v[204:207], v143 offset:39936
	global_load_lds_dwordx4 v[226:227], off
	v_lshl_add_u64 v[226:227], s[20:21], 0, v[132:133]
	s_mov_b32 m0, s44
	s_nop 0
	global_load_lds_dwordx4 v[226:227], off
	s_waitcnt vmcnt(8)
	s_waitcnt lgkmcnt(0)
	s_setprio 1
	s_waitcnt lgkmcnt(0)
	v_mfma_f32_16x16x32_bf16 v[126:129], v[144:147], v[176:179], v[126:129]
	v_mfma_f32_16x16x32_bf16 v[122:125], v[152:155], v[176:179], v[122:125]
	v_mfma_f32_16x16x32_bf16 v[118:121], v[144:147], v[184:187], v[118:121]
	v_mfma_f32_16x16x32_bf16 v[114:117], v[152:155], v[184:187], v[114:117]
	v_mfma_f32_16x16x32_bf16 v[102:105], v[144:147], v[192:195], v[102:105]
	v_mfma_f32_16x16x32_bf16 v[98:101], v[152:155], v[192:195], v[98:101]
	v_mfma_f32_16x16x32_bf16 v[86:89], v[144:147], v[200:203], v[86:89]
	v_mfma_f32_16x16x32_bf16 v[82:85], v[152:155], v[200:203], v[82:85]
	v_mfma_f32_16x16x32_bf16 v[126:129], v[148:151], v[180:183], v[126:129]
	v_mfma_f32_16x16x32_bf16 v[122:125], v[156:159], v[180:183], v[122:125]
	v_mfma_f32_16x16x32_bf16 v[118:121], v[148:151], v[188:191], v[118:121]
	v_mfma_f32_16x16x32_bf16 v[114:117], v[156:159], v[188:191], v[114:117]
	v_mfma_f32_16x16x32_bf16 v[102:105], v[148:151], v[196:199], v[102:105]
	v_mfma_f32_16x16x32_bf16 v[98:101], v[156:159], v[196:199], v[98:101]
	v_mfma_f32_16x16x32_bf16 v[86:89], v[148:151], v[204:207], v[86:89]
	v_mfma_f32_16x16x32_bf16 v[82:85], v[156:159], v[204:207], v[82:85]
	s_setprio 0
	s_setprio 1
	v_mfma_f32_16x16x32_bf16 v[110:113], v[160:163], v[176:179], v[110:113]
	v_mfma_f32_16x16x32_bf16 v[106:109], v[168:171], v[176:179], v[106:109]
	v_mfma_f32_16x16x32_bf16 v[94:97], v[160:163], v[184:187], v[94:97]
	v_mfma_f32_16x16x32_bf16 v[90:93], v[168:171], v[184:187], v[90:93]
	v_mfma_f32_16x16x32_bf16 v[78:81], v[160:163], v[192:195], v[78:81]
	v_mfma_f32_16x16x32_bf16 v[74:77], v[168:171], v[192:195], v[74:77]
	v_mfma_f32_16x16x32_bf16 v[70:73], v[160:163], v[200:203], v[70:73]
	v_mfma_f32_16x16x32_bf16 v[66:69], v[168:171], v[200:203], v[66:69]
	v_mfma_f32_16x16x32_bf16 v[110:113], v[164:167], v[180:183], v[110:113]
	v_mfma_f32_16x16x32_bf16 v[106:109], v[172:175], v[180:183], v[106:109]
	v_mfma_f32_16x16x32_bf16 v[94:97], v[164:167], v[188:191], v[94:97]
	v_mfma_f32_16x16x32_bf16 v[90:93], v[172:175], v[188:191], v[90:93]
	v_mfma_f32_16x16x32_bf16 v[78:81], v[164:167], v[196:199], v[78:81]
	v_mfma_f32_16x16x32_bf16 v[74:77], v[172:175], v[196:199], v[74:77]
	v_mfma_f32_16x16x32_bf16 v[70:73], v[164:167], v[204:207], v[70:73]
	v_mfma_f32_16x16x32_bf16 v[66:69], v[172:175], v[204:207], v[66:69]
	s_setprio 0
	s_barrier
	s_add_i32 s20, s54, s37
	v_lshl_add_u64 v[208:209], v[208:209], 0, s[2:3]
	s_mov_b32 m0, s20
	ds_read_b128 v[176:179], v143 offset:49152
	ds_read_b128 v[180:183], v143 offset:50176
	ds_read_b128 v[184:187], v143 offset:51200
	ds_read_b128 v[188:191], v143 offset:52224
	ds_read_b128 v[192:195], v143 offset:53248
	ds_read_b128 v[196:199], v143 offset:54272
	ds_read_b128 v[200:203], v143 offset:55296
	ds_read_b128 v[204:207], v143 offset:56320
	global_load_lds_dwordx4 v[208:209], off
	s_add_i32 m0, s20, 0x2000
	s_add_u32 s18, s18, 0x80080
	v_lshl_add_u64 v[208:209], v[220:221], 0, s[2:3]
	s_addc_u32 s19, s19, 0
	s_add_i32 s20, s55, s37
	global_load_lds_dwordx4 v[208:209], off
	v_lshl_add_u64 v[208:209], s[18:19], 0, v[0:1]
	s_mov_b32 m0, s20
	s_nop 0
	global_load_lds_dwordx4 v[208:209], off
	v_lshl_add_u64 v[208:209], s[18:19], 0, v[130:131]
	s_add_i32 m0, s20, 0x2000
	s_nop 0
	global_load_lds_dwordx4 v[208:209], off
	v_lshl_add_u64 v[208:209], v[222:223], 0, s[2:3]
	s_mov_b32 m0, s45
	s_nop 0
	global_load_lds_dwordx4 v[208:209], off
	v_lshl_add_u64 v[208:209], v[224:225], 0, s[2:3]
	s_mov_b32 m0, s46
	s_nop 0
	global_load_lds_dwordx4 v[208:209], off
	s_waitcnt vmcnt(8)
	s_waitcnt lgkmcnt(0)
	s_setprio 1
	s_waitcnt lgkmcnt(0)
	v_mfma_f32_16x16x32_bf16 v[62:65], v[144:147], v[176:179], v[62:65]
	v_mfma_f32_16x16x32_bf16 v[58:61], v[152:155], v[176:179], v[58:61]
	v_mfma_f32_16x16x32_bf16 v[54:57], v[144:147], v[184:187], v[54:57]
	v_mfma_f32_16x16x32_bf16 v[50:53], v[152:155], v[184:187], v[50:53]
	v_mfma_f32_16x16x32_bf16 v[38:41], v[144:147], v[192:195], v[38:41]
	v_mfma_f32_16x16x32_bf16 v[34:37], v[152:155], v[192:195], v[34:37]
	v_mfma_f32_16x16x32_bf16 v[22:25], v[144:147], v[200:203], v[22:25]
	v_mfma_f32_16x16x32_bf16 v[18:21], v[152:155], v[200:203], v[18:21]
	v_mfma_f32_16x16x32_bf16 v[62:65], v[148:151], v[180:183], v[62:65]
	v_mfma_f32_16x16x32_bf16 v[58:61], v[156:159], v[180:183], v[58:61]
	v_mfma_f32_16x16x32_bf16 v[54:57], v[148:151], v[188:191], v[54:57]
	v_mfma_f32_16x16x32_bf16 v[50:53], v[156:159], v[188:191], v[50:53]
	v_mfma_f32_16x16x32_bf16 v[38:41], v[148:151], v[196:199], v[38:41]
	v_mfma_f32_16x16x32_bf16 v[34:37], v[156:159], v[196:199], v[34:37]
	v_mfma_f32_16x16x32_bf16 v[22:25], v[148:151], v[204:207], v[22:25]
	v_mfma_f32_16x16x32_bf16 v[18:21], v[156:159], v[204:207], v[18:21]
	s_setprio 0
	s_setprio 1
	v_mfma_f32_16x16x32_bf16 v[46:49], v[160:163], v[176:179], v[46:49]
	v_mfma_f32_16x16x32_bf16 v[42:45], v[168:171], v[176:179], v[42:45]
	v_mfma_f32_16x16x32_bf16 v[30:33], v[160:163], v[184:187], v[30:33]
	v_mfma_f32_16x16x32_bf16 v[26:29], v[168:171], v[184:187], v[26:29]
	v_mfma_f32_16x16x32_bf16 v[14:17], v[160:163], v[192:195], v[14:17]
	v_mfma_f32_16x16x32_bf16 v[10:13], v[168:171], v[192:195], v[10:13]
	v_mfma_f32_16x16x32_bf16 v[6:9], v[160:163], v[200:203], v[6:9]
	v_mfma_f32_16x16x32_bf16 v[2:5], v[168:171], v[200:203], v[2:5]
	v_mfma_f32_16x16x32_bf16 v[46:49], v[164:167], v[180:183], v[46:49]
	v_mfma_f32_16x16x32_bf16 v[42:45], v[172:175], v[180:183], v[42:45]
	v_mfma_f32_16x16x32_bf16 v[30:33], v[164:167], v[188:191], v[30:33]
	v_mfma_f32_16x16x32_bf16 v[26:29], v[172:175], v[188:191], v[26:29]
	v_mfma_f32_16x16x32_bf16 v[14:17], v[164:167], v[196:199], v[14:17]
	v_mfma_f32_16x16x32_bf16 v[10:13], v[172:175], v[196:199], v[10:13]
	v_mfma_f32_16x16x32_bf16 v[6:9], v[164:167], v[204:207], v[6:9]
	v_mfma_f32_16x16x32_bf16 v[2:5], v[172:175], v[204:207], v[2:5]
	s_setprio 0
	s_barrier
	s_add_i32 s53, s53, 2
	s_add_u32 s16, s16, 0x100
	s_addc_u32 s17, s17, 0
	s_add_u32 s51, s51, 0x100
	s_addc_u32 s52, s52, 0
	s_cmp_gt_u32 s53, 29
	s_cbranch_scc0 .Lh1_0

.LBB0_494:
	v_lshl_add_u32 v150, s6, 8, v140
	v_lshl_add_u32 v144, s7, 8, v142
	v_ashrrev_i32_e32 v145, 31, v144
	v_mov_b64_e32 v[146:147], s[96:97]
	s_movk_i32 s9, 0x3000
	v_cvt_pk_bf16_f32 v70, v70, v71
	v_cvt_pk_bf16_f32 v71, v72, v73
	v_cvt_pk_bf16_f32 v72, v66, v67
	v_add_u32_e32 v66, 0x80, v150
	v_mad_i64_i32 v[148:149], s[6:7], v150, s9, v[146:147]
	v_lshlrev_b64 v[144:145], 1, v[144:145]
	v_cvt_pk_bf16_f32 v110, v110, v111
	v_cvt_pk_bf16_f32 v111, v112, v113
	v_cvt_pk_bf16_f32 v112, v106, v107
	v_or_b32_e32 v106, 16, v150
	v_mad_i64_i32 v[66:67], s[6:7], v66, s9, v[146:147]
	v_cvt_pk_bf16_f32 v46, v46, v47
	v_cvt_pk_bf16_f32 v47, v48, v49
	v_cvt_pk_bf16_f32 v48, v42, v43
	v_add_u32_e32 v42, 0x90, v150
	v_lshl_add_u64 v[148:149], v[148:149], 0, v[144:145]
	v_cvt_pk_bf16_f32 v113, v108, v109
	v_mad_i64_i32 v[106:107], s[6:7], v106, s9, v[146:147]
	v_cvt_pk_bf16_f32 v94, v94, v95
	v_cvt_pk_bf16_f32 v95, v96, v97
	v_cvt_pk_bf16_f32 v96, v90, v91
	v_or_b32_e32 v90, 32, v150
	v_lshl_add_u64 v[66:67], v[66:67], 0, v[144:145]
	v_cvt_pk_bf16_f32 v49, v44, v45
	v_mad_i64_i32 v[42:43], s[6:7], v42, s9, v[146:147]
	v_cvt_pk_bf16_f32 v30, v30, v31
	v_cvt_pk_bf16_f32 v31, v32, v33
	v_cvt_pk_bf16_f32 v32, v26, v27
	v_add_u32_e32 v26, 0xa0, v150
	global_store_dwordx4 v[148:149], v[110:113], off offset:256
	v_cvt_pk_bf16_f32 v97, v92, v93
	v_mad_i64_i32 v[90:91], s[6:7], v90, s9, v[146:147]
	v_lshl_add_u64 v[110:111], v[106:107], 0, v[144:145]
	v_cvt_pk_bf16_f32 v78, v78, v79
	v_cvt_pk_bf16_f32 v79, v80, v81
	v_cvt_pk_bf16_f32 v80, v74, v75
	v_or_b32_e32 v74, 48, v150
	global_store_dwordx4 v[66:67], v[46:49], off offset:256
	v_cvt_pk_bf16_f32 v33, v28, v29
	v_mad_i64_i32 v[26:27], s[6:7], v26, s9, v[146:147]
	v_lshl_add_u64 v[46:47], v[42:43], 0, v[144:145]
	v_cvt_pk_bf16_f32 v14, v14, v15
	v_cvt_pk_bf16_f32 v15, v16, v17
	v_cvt_pk_bf16_f32 v16, v10, v11
	v_add_u32_e32 v10, 0xb0, v150
	global_store_dwordx4 v[110:111], v[94:97], off offset:256
	v_cvt_pk_bf16_f32 v81, v76, v77
	v_mad_i64_i32 v[74:75], s[6:7], v74, s9, v[146:147]
	v_lshl_add_u64 v[94:95], v[90:91], 0, v[144:145]
	global_store_dwordx4 v[46:47], v[30:33], off offset:256
	v_cvt_pk_bf16_f32 v17, v12, v13
	v_mad_i64_i32 v[10:11], s[6:7], v10, s9, v[146:147]
	v_lshl_add_u64 v[30:31], v[26:27], 0, v[144:145]
	v_cvt_pk_bf16_f32 v126, v126, v127
	v_cvt_pk_bf16_f32 v127, v128, v129
	v_cvt_pk_bf16_f32 v128, v122, v123
	v_cvt_pk_bf16_f32 v129, v124, v125
	v_cvt_pk_bf16_f32 v106, v118, v119
	v_cvt_pk_bf16_f32 v107, v120, v121
	v_cvt_pk_bf16_f32 v108, v114, v115
	v_cvt_pk_bf16_f32 v109, v116, v117
	v_cvt_pk_bf16_f32 v90, v102, v103
	v_cvt_pk_bf16_f32 v91, v104, v105
	v_cvt_pk_bf16_f32 v92, v98, v99
	v_cvt_pk_bf16_f32 v93, v100, v101
	global_store_dwordx4 v[94:95], v[78:81], off offset:256
	v_cvt_pk_bf16_f32 v76, v82, v83
	v_cvt_pk_bf16_f32 v77, v84, v85
	v_lshl_add_u64 v[78:79], v[74:75], 0, v[144:145]
	v_cvt_pk_bf16_f32 v74, v86, v87
	v_cvt_pk_bf16_f32 v75, v88, v89
	v_cvt_pk_bf16_f32 v73, v68, v69
	v_cvt_pk_bf16_f32 v62, v62, v63
	v_cvt_pk_bf16_f32 v63, v64, v65
	v_cvt_pk_bf16_f32 v64, v58, v59
	v_cvt_pk_bf16_f32 v65, v60, v61
	v_cvt_pk_bf16_f32 v42, v54, v55
	v_cvt_pk_bf16_f32 v43, v56, v57
	v_cvt_pk_bf16_f32 v44, v50, v51
	v_cvt_pk_bf16_f32 v45, v52, v53
	v_cvt_pk_bf16_f32 v26, v38, v39
	v_cvt_pk_bf16_f32 v27, v40, v41
	v_cvt_pk_bf16_f32 v28, v34, v35
	v_cvt_pk_bf16_f32 v29, v36, v37
	global_store_dwordx4 v[30:31], v[14:17], off offset:256
	v_cvt_pk_bf16_f32 v12, v18, v19
	v_cvt_pk_bf16_f32 v13, v20, v21
	v_lshl_add_u64 v[14:15], v[10:11], 0, v[144:145]
	v_cvt_pk_bf16_f32 v10, v22, v23
	v_cvt_pk_bf16_f32 v11, v24, v25
	v_cvt_pk_bf16_f32 v6, v6, v7
	v_cvt_pk_bf16_f32 v7, v8, v9
	v_cvt_pk_bf16_f32 v8, v2, v3
	v_cvt_pk_bf16_f32 v9, v4, v5
	s_andn2_b64 vcc, exec, s[34:35]
	s_mov_b64 s[6:7], -1
	global_store_dwordx4 v[148:149], v[126:129], off
	global_store_dwordx4 v[110:111], v[106:109], off
	global_store_dwordx4 v[94:95], v[90:93], off
	global_store_dwordx4 v[78:79], v[74:77], off
	global_store_dwordx4 v[78:79], v[70:73], off offset:256
	global_store_dwordx4 v[66:67], v[62:65], off
	global_store_dwordx4 v[46:47], v[42:45], off
	global_store_dwordx4 v[30:31], v[26:29], off
	global_store_dwordx4 v[14:15], v[10:13], off
	global_store_dwordx4 v[14:15], v[6:9], off offset:256
	s_cbranch_vccnz .LBB0_487
	s_andn2_b64 vcc, exec, s[0:1]
	s_cbranch_vccnz .LBB0_486
	s_branch .LBB0_486

.LBB0_867:
	v_readlane_b32 s80, v254, 53
	s_and_b32 s16, s10, 3
	v_readlane_b32 s92, v255, 1
	v_readlane_b32 s93, v255, 2
	s_lshr_b32 s56, s8, 6
	s_lshl_b32 s57, s15, 6
	s_lshl_b32 s58, s16, 5
	s_lshl_b64 s[12:13], s[6:7], 13
	v_readlane_b32 s94, v255, 3
	v_readlane_b32 s95, v255, 4
	s_mov_b64 s[72:73], s[92:93]
	s_add_u32 s8, s72, s12
	s_mov_b64 s[74:75], s[94:95]
	s_addc_u32 s9, s73, s13
	s_add_u32 s34, s74, s12
	s_addc_u32 s35, s75, s13
	s_lshl_b32 s68, s6, 13
	s_lshl_b64 s[12:13], s[68:69], 2
	v_readlane_b32 s6, v254, 44
	s_add_u32 s59, s6, s12
	v_readlane_b32 s6, v254, 45
	s_addc_u32 s60, s6, s13
	s_add_i32 m0, s52, 0x18000
	v_lshl_add_u64 v[2:3], v[2:3], 0, s[2:3]
	s_waitcnt vmcnt(2)
	s_barrier
	global_load_lds_dwordx4 v[2:3], off
	v_lshl_add_u64 v[2:3], v[4:5], 0, s[2:3]
	s_add_i32 m0, s52, 0x1a000
	s_add_i32 s61, s52, 0x8000
	global_load_lds_dwordx4 v[2:3], off
	v_lshl_add_u64 v[2:3], v[10:11], 0, s[2:3]
	s_mov_b32 m0, s61
	s_add_i32 s62, s52, 0xa000
	global_load_lds_dwordx4 v[2:3], off
	v_lshl_add_u64 v[2:3], v[12:13], 0, s[2:3]
	s_mov_b32 m0, s62
	s_add_i32 s63, s56, -2
	global_load_lds_dwordx4 v[2:3], off
	s_add_i32 m0, s52, 0x1c000
	v_lshl_add_u64 v[2:3], v[6:7], 0, s[2:3]
	global_load_lds_dwordx4 v[2:3], off
	v_lshl_add_u64 v[2:3], v[8:9], 0, s[2:3]
	s_add_i32 m0, s52, 0x1e000
	s_cmp_lt_u32 s10, 4
	global_load_lds_dwordx4 v[2:3], off
	s_cselect_b64 s[6:7], -1, 0
	s_lshl_b32 s17, s15, 11
	s_lshl_b32 s68, s10, 5
	s_cmp_eq_u32 s10, 0
	v_mul_f32_e32 v0, 0x4f7ffffe, v0
	s_cselect_b64 s[10:11], -1, 0
	s_ashr_i32 s73, s24, 31
	s_ashr_i32 s64, s25, 31
	v_cvt_u32_f32_e32 v0, v0
	v_and_b32_e32 v21, 0xfffffc00, v21
	s_cmp_lg_u64 s[28:29], 0
	v_lshl_add_u32 v23, s15, 13, v21
	v_lshl_add_u32 v21, s16, 12, v21
	s_cselect_b64 s[12:13], -1, 0
	s_lshl_b32 s16, s16, 3
	s_add_i32 s16, s16, 0
	s_add_i32 s65, s16, s17
	v_readfirstlane_b32 s16, v0
	v_lshlrev_b32_e32 v0, 15, v14
	v_and_b32_e32 v0, 0xffff0000, v0
	v_lshl_add_u32 v0, v15, 12, v0
	v_and_b32_e32 v2, 1, v14
	v_lshl_or_b32 v0, v2, 6, v0
	s_lshl_b32 s15, s15, 9
	v_lshl_add_u32 v202, v16, 1, v0
	v_lshlrev_b32_e32 v0, 15, v18
	v_ashrrev_i32_e32 v222, 4, v17
	v_and_b32_e32 v223, 15, v17
	v_and_b32_e32 v22, 48, v17
	v_lshlrev_b32_e32 v17, 2, v17
	s_add_i32 s76, s15, 0
	s_sub_i32 s15, 0, s48
	v_and_b32_e32 v0, 0xffff0000, v0
	v_lshl_or_b32 v22, v223, 6, v22
	v_and_b32_e32 v17, 32, v17
	s_waitcnt vmcnt(6)
	s_mul_i32 s15, s15, s16
	v_lshl_add_u32 v0, v19, 12, v0
	v_and_b32_e32 v2, 1, v18
	v_bitop3_b32 v23, v22, v23, v17 bitop3:0xde
	s_mul_hi_u32 s15, s16, s15
	v_lshl_or_b32 v0, v2, 6, v0
	v_bitop3_b32 v224, v22, v21, v17 bitop3:0xde
	s_mov_b32 s72, 0
	s_add_i32 s65, s65, 0x20400
	s_add_i32 s76, s76, 0x22400
	s_add_i32 s77, s16, s15
	v_mov_b32_e32 v203, v1
	v_lshl_add_u32 v204, v20, 1, v0
	v_mov_b32_e32 v205, v1
	v_add_u32_e32 v225, 0, v23
	v_readlane_b32 s81, v254, 54
	v_readlane_b32 s82, v254, 55
	v_readlane_b32 s83, v254, 56
	v_readlane_b32 s84, v254, 57
	v_readlane_b32 s85, v254, 58
	v_readlane_b32 s86, v254, 59
	v_readlane_b32 s87, v254, 60
	v_readlane_b32 s88, v254, 61
	v_readlane_b32 s89, v254, 62
	v_readlane_b32 s90, v254, 63
	v_readlane_b32 s91, v255, 0
	s_branch .LBB0_870

.LBB0_883:
	s_and_b64 vcc, exec, s[6:7]
	s_cbranch_vccz .Lh1_1
.Lh0_1:
	s_add_i32 s41, s22, 2
	s_add_u32 s42, s38, 0xfff80080
	s_addc_u32 s23, s39, -1
	s_add_i32 s44, 0, 0x10000
	s_cmp_eq_u32 s63, s22
	s_cselect_b32 s23, s17, s23
	s_cselect_b32 s22, s16, s42
	v_add_u32_e32 v0, s44, v224
	s_cselect_b32 s43, s19, s21
	s_cselect_b32 s42, s18, s15
	s_add_i32 s45, 0, 0x14000
	ds_read_b128 v[30:33], v0
	ds_read_b128 v[134:137], v0 offset:1024
	ds_read_b128 v[138:141], v0 offset:2048
	ds_read_b128 v[142:145], v0 offset:3072
	v_add_u32_e32 v0, s45, v224
	ds_read_b128 v[146:149], v0
	ds_read_b128 v[150:153], v0 offset:1024
	ds_read_b128 v[154:157], v0 offset:2048
	ds_read_b128 v[158:161], v0 offset:3072
	v_lshl_add_u64 v[206:207], s[38:39], 0, v[202:203]
	s_add_i32 m0, s52, 0xc000
	ds_read_b128 v[162:165], v225
	ds_read_b128 v[166:169], v225 offset:1024
	ds_read_b128 v[170:173], v225 offset:2048
	ds_read_b128 v[174:177], v225 offset:3072
	ds_read_b128 v[178:181], v225 offset:4096
	ds_read_b128 v[182:185], v225 offset:5120
	ds_read_b128 v[186:189], v225 offset:6144
	ds_read_b128 v[190:193], v225 offset:7168
	global_load_lds_dwordx4 v[206:207], off
	v_lshl_add_u64 v[206:207], s[38:39], 0, v[204:205]
	s_add_i32 m0, s52, 0xe000
	s_nop 0
	global_load_lds_dwordx4 v[206:207], off
	s_waitcnt vmcnt(8)
	s_waitcnt lgkmcnt(0)
	s_barrier
	s_setprio 1
	s_waitcnt lgkmcnt(0)
	v_mfma_f32_16x16x32_bf16 v[26:29], v[30:33], v[162:165], v[26:29]
	v_mfma_f32_16x16x32_bf16 v[22:25], v[138:141], v[162:165], v[22:25]
	v_mfma_f32_16x16x32_bf16 v[62:65], v[30:33], v[170:173], v[62:65]
	v_mfma_f32_16x16x32_bf16 v[14:17], v[138:141], v[170:173], v[14:17]
	v_mfma_f32_16x16x32_bf16 v[58:61], v[30:33], v[178:181], v[58:61]
	v_mfma_f32_16x16x32_bf16 v[54:57], v[138:141], v[178:181], v[54:57]
	v_mfma_f32_16x16x32_bf16 v[94:97], v[30:33], v[186:189], v[94:97]
	v_mfma_f32_16x16x32_bf16 v[46:49], v[138:141], v[186:189], v[46:49]
	v_mfma_f32_16x16x32_bf16 v[26:29], v[134:137], v[166:169], v[26:29]
	v_mfma_f32_16x16x32_bf16 v[22:25], v[142:145], v[166:169], v[22:25]
	v_mfma_f32_16x16x32_bf16 v[62:65], v[134:137], v[174:177], v[62:65]
	v_mfma_f32_16x16x32_bf16 v[14:17], v[142:145], v[174:177], v[14:17]
	v_mfma_f32_16x16x32_bf16 v[58:61], v[134:137], v[182:185], v[58:61]
	v_mfma_f32_16x16x32_bf16 v[54:57], v[142:145], v[182:185], v[54:57]
	v_mfma_f32_16x16x32_bf16 v[94:97], v[134:137], v[190:193], v[94:97]
	v_mfma_f32_16x16x32_bf16 v[46:49], v[142:145], v[190:193], v[46:49]
	s_setprio 0
	s_setprio 1
	v_mfma_f32_16x16x32_bf16 v[18:21], v[146:149], v[162:165], v[18:21]
	v_mfma_f32_16x16x32_bf16 v[10:13], v[154:157], v[162:165], v[10:13]
	v_mfma_f32_16x16x32_bf16 v[2:5], v[146:149], v[170:173], v[2:5]
	v_mfma_f32_16x16x32_bf16 v[6:9], v[154:157], v[170:173], v[6:9]
	v_mfma_f32_16x16x32_bf16 v[50:53], v[146:149], v[178:181], v[50:53]
	v_mfma_f32_16x16x32_bf16 v[42:45], v[154:157], v[178:181], v[42:45]
	v_mfma_f32_16x16x32_bf16 v[34:37], v[146:149], v[186:189], v[34:37]
	v_mfma_f32_16x16x32_bf16 v[38:41], v[154:157], v[186:189], v[38:41]
	v_mfma_f32_16x16x32_bf16 v[18:21], v[150:153], v[166:169], v[18:21]
	v_mfma_f32_16x16x32_bf16 v[10:13], v[158:161], v[166:169], v[10:13]
	v_mfma_f32_16x16x32_bf16 v[2:5], v[150:153], v[174:177], v[2:5]
	v_mfma_f32_16x16x32_bf16 v[6:9], v[158:161], v[174:177], v[6:9]
	v_mfma_f32_16x16x32_bf16 v[50:53], v[150:153], v[182:185], v[50:53]
	v_mfma_f32_16x16x32_bf16 v[42:45], v[158:161], v[182:185], v[42:45]
	v_mfma_f32_16x16x32_bf16 v[34:37], v[150:153], v[190:193], v[34:37]
	v_mfma_f32_16x16x32_bf16 v[38:41], v[158:161], v[190:193], v[38:41]
	s_setprio 0
	s_add_i32 s44, s44, s49
	v_lshl_add_u64 v[206:207], s[42:43], 0, v[196:197]
	s_mov_b32 m0, s44
	ds_read_b128 v[162:165], v225 offset:16384
	ds_read_b128 v[166:169], v225 offset:17408
	ds_read_b128 v[170:173], v225 offset:18432
	ds_read_b128 v[174:177], v225 offset:19456
	ds_read_b128 v[178:181], v225 offset:20480
	ds_read_b128 v[182:185], v225 offset:21504
	ds_read_b128 v[186:189], v225 offset:22528
	ds_read_b128 v[190:193], v225 offset:23552
	global_load_lds_dwordx4 v[206:207], off
	s_add_i32 m0, s44, 0x2000
	v_lshl_add_u64 v[208:209], s[42:43], 0, v[200:201]
	s_add_u32 s42, s42, s50
	s_addc_u32 s43, s43, 0
	s_add_i32 s44, s45, s49
	global_load_lds_dwordx4 v[208:209], off
	v_lshl_add_u64 v[220:221], s[42:43], 0, v[196:197]
	s_mov_b32 m0, s44
	v_lshl_add_u64 v[226:227], s[42:43], 0, v[200:201]
	global_load_lds_dwordx4 v[220:221], off
	s_add_i32 m0, s44, 0x2000
	v_lshl_add_u64 v[228:229], s[22:23], 0, v[194:195]
	global_load_lds_dwordx4 v[226:227], off
	s_mov_b32 m0, s52
	v_lshl_add_u64 v[230:231], s[22:23], 0, v[198:199]
	global_load_lds_dwordx4 v[228:229], off
	s_mov_b32 m0, s53
	s_nop 0
	global_load_lds_dwordx4 v[230:231], off
	s_waitcnt vmcnt(8)
	s_waitcnt lgkmcnt(0)
	s_barrier
	s_setprio 1
	s_waitcnt lgkmcnt(0)
	v_mfma_f32_16x16x32_bf16 v[90:93], v[30:33], v[162:165], v[90:93]
	v_mfma_f32_16x16x32_bf16 v[86:89], v[138:141], v[162:165], v[86:89]
	v_mfma_f32_16x16x32_bf16 v[130:133], v[30:33], v[170:173], v[130:133]
	v_mfma_f32_16x16x32_bf16 v[78:81], v[138:141], v[170:173], v[78:81]
	v_mfma_f32_16x16x32_bf16 v[126:129], v[30:33], v[178:181], v[126:129]
	v_mfma_f32_16x16x32_bf16 v[118:121], v[138:141], v[178:181], v[118:121]
	v_mfma_f32_16x16x32_bf16 v[110:113], v[138:141], v[186:189], v[110:113]
	v_mfma_f32_16x16x32_bf16 v[90:93], v[134:137], v[166:169], v[90:93]
	v_mfma_f32_16x16x32_bf16 v[86:89], v[142:145], v[166:169], v[86:89]
	v_mfma_f32_16x16x32_bf16 v[130:133], v[134:137], v[174:177], v[130:133]
	v_mfma_f32_16x16x32_bf16 v[78:81], v[142:145], v[174:177], v[78:81]
	v_mfma_f32_16x16x32_bf16 v[126:129], v[134:137], v[182:185], v[126:129]
	v_mfma_f32_16x16x32_bf16 v[118:121], v[142:145], v[182:185], v[118:121]
	v_mfma_f32_16x16x32_bf16 v[30:33], v[30:33], v[186:189], v[122:125]
	v_mfma_f32_16x16x32_bf16 v[110:113], v[142:145], v[190:193], v[110:113]
	v_mfma_f32_16x16x32_bf16 v[30:33], v[134:137], v[190:193], v[30:33]
	s_setprio 0
	s_setprio 1
	v_mfma_f32_16x16x32_bf16 v[82:85], v[146:149], v[162:165], v[82:85]
	v_mfma_f32_16x16x32_bf16 v[74:77], v[154:157], v[162:165], v[74:77]
	v_mfma_f32_16x16x32_bf16 v[66:69], v[146:149], v[170:173], v[66:69]
	v_mfma_f32_16x16x32_bf16 v[70:73], v[154:157], v[170:173], v[70:73]
	v_mfma_f32_16x16x32_bf16 v[114:117], v[146:149], v[178:181], v[114:117]
	v_mfma_f32_16x16x32_bf16 v[106:109], v[154:157], v[178:181], v[106:109]
	v_mfma_f32_16x16x32_bf16 v[98:101], v[146:149], v[186:189], v[98:101]
	v_mfma_f32_16x16x32_bf16 v[102:105], v[154:157], v[186:189], v[102:105]
	v_mfma_f32_16x16x32_bf16 v[82:85], v[150:153], v[166:169], v[82:85]
	v_mfma_f32_16x16x32_bf16 v[74:77], v[158:161], v[166:169], v[74:77]
	v_mfma_f32_16x16x32_bf16 v[66:69], v[150:153], v[174:177], v[66:69]
	v_mfma_f32_16x16x32_bf16 v[70:73], v[158:161], v[174:177], v[70:73]
	v_mfma_f32_16x16x32_bf16 v[114:117], v[150:153], v[182:185], v[114:117]
	v_mfma_f32_16x16x32_bf16 v[106:109], v[158:161], v[182:185], v[106:109]
	v_mfma_f32_16x16x32_bf16 v[98:101], v[150:153], v[190:193], v[98:101]
	v_mfma_f32_16x16x32_bf16 v[102:105], v[158:161], v[190:193], v[102:105]
	s_setprio 0
	s_add_i32 s42, 0, 0x18000
	v_add_u32_e32 v0, s42, v224
	s_add_i32 s43, 0, 0x1c000
	ds_read_b128 v[122:125], v0
	ds_read_b128 v[134:137], v0 offset:1024
	ds_read_b128 v[138:141], v0 offset:2048
	ds_read_b128 v[142:145], v0 offset:3072
	v_add_u32_e32 v0, s43, v224
	ds_read_b128 v[146:149], v0
	ds_read_b128 v[150:153], v0 offset:1024
	ds_read_b128 v[154:157], v0 offset:2048
	ds_read_b128 v[158:161], v0 offset:3072
	s_add_u32 s22, s22, 0x80000
	s_addc_u32 s23, s23, 0
	s_mov_b32 m0, s54
	v_lshl_add_u64 v[232:233], s[22:23], 0, v[194:195]
	ds_read_b128 v[162:165], v225 offset:32768
	ds_read_b128 v[166:169], v225 offset:33792
	ds_read_b128 v[170:173], v225 offset:34816
	ds_read_b128 v[174:177], v225 offset:35840
	ds_read_b128 v[178:181], v225 offset:36864
	ds_read_b128 v[182:185], v225 offset:37888
	ds_read_b128 v[186:189], v225 offset:38912
	ds_read_b128 v[190:193], v225 offset:39936
	global_load_lds_dwordx4 v[232:233], off
	v_lshl_add_u64 v[232:233], s[22:23], 0, v[198:199]
	s_mov_b32 m0, s55
	s_nop 0
	global_load_lds_dwordx4 v[232:233], off
	s_waitcnt vmcnt(8)
	s_waitcnt lgkmcnt(0)
	s_barrier
	s_setprio 1
	s_waitcnt lgkmcnt(0)
	v_mfma_f32_16x16x32_bf16 v[26:29], v[122:125], v[162:165], v[26:29]
	v_mfma_f32_16x16x32_bf16 v[22:25], v[138:141], v[162:165], v[22:25]
	v_mfma_f32_16x16x32_bf16 v[62:65], v[122:125], v[170:173], v[62:65]
	v_mfma_f32_16x16x32_bf16 v[14:17], v[138:141], v[170:173], v[14:17]
	v_mfma_f32_16x16x32_bf16 v[58:61], v[122:125], v[178:181], v[58:61]
	v_mfma_f32_16x16x32_bf16 v[54:57], v[138:141], v[178:181], v[54:57]
	v_mfma_f32_16x16x32_bf16 v[94:97], v[122:125], v[186:189], v[94:97]
	v_mfma_f32_16x16x32_bf16 v[46:49], v[138:141], v[186:189], v[46:49]
	v_mfma_f32_16x16x32_bf16 v[26:29], v[134:137], v[166:169], v[26:29]
	v_mfma_f32_16x16x32_bf16 v[22:25], v[142:145], v[166:169], v[22:25]
	v_mfma_f32_16x16x32_bf16 v[62:65], v[134:137], v[174:177], v[62:65]
	v_mfma_f32_16x16x32_bf16 v[14:17], v[142:145], v[174:177], v[14:17]
	v_mfma_f32_16x16x32_bf16 v[58:61], v[134:137], v[182:185], v[58:61]
	v_mfma_f32_16x16x32_bf16 v[54:57], v[142:145], v[182:185], v[54:57]
	v_mfma_f32_16x16x32_bf16 v[94:97], v[134:137], v[190:193], v[94:97]
	v_mfma_f32_16x16x32_bf16 v[46:49], v[142:145], v[190:193], v[46:49]
	s_setprio 0
	s_setprio 1
	v_mfma_f32_16x16x32_bf16 v[18:21], v[146:149], v[162:165], v[18:21]
	v_mfma_f32_16x16x32_bf16 v[10:13], v[154:157], v[162:165], v[10:13]
	v_mfma_f32_16x16x32_bf16 v[2:5], v[146:149], v[170:173], v[2:5]
	v_mfma_f32_16x16x32_bf16 v[6:9], v[154:157], v[170:173], v[6:9]
	v_mfma_f32_16x16x32_bf16 v[50:53], v[146:149], v[178:181], v[50:53]
	v_mfma_f32_16x16x32_bf16 v[42:45], v[154:157], v[178:181], v[42:45]
	v_mfma_f32_16x16x32_bf16 v[34:37], v[146:149], v[186:189], v[34:37]
	v_mfma_f32_16x16x32_bf16 v[38:41], v[154:157], v[186:189], v[38:41]
	v_mfma_f32_16x16x32_bf16 v[18:21], v[150:153], v[166:169], v[18:21]
	v_mfma_f32_16x16x32_bf16 v[10:13], v[158:161], v[166:169], v[10:13]
	v_mfma_f32_16x16x32_bf16 v[2:5], v[150:153], v[174:177], v[2:5]
	v_mfma_f32_16x16x32_bf16 v[6:9], v[158:161], v[174:177], v[6:9]
	v_mfma_f32_16x16x32_bf16 v[50:53], v[150:153], v[182:185], v[50:53]
	v_mfma_f32_16x16x32_bf16 v[42:45], v[158:161], v[182:185], v[42:45]
	v_mfma_f32_16x16x32_bf16 v[34:37], v[150:153], v[190:193], v[34:37]
	v_mfma_f32_16x16x32_bf16 v[38:41], v[158:161], v[190:193], v[38:41]
	s_setprio 0
	s_add_i32 s22, s42, s49
	v_lshl_add_u64 v[206:207], v[206:207], 0, s[2:3]
	s_mov_b32 m0, s22
	ds_read_b128 v[162:165], v225 offset:49152
	ds_read_b128 v[166:169], v225 offset:50176
	ds_read_b128 v[170:173], v225 offset:51200
	ds_read_b128 v[174:177], v225 offset:52224
	ds_read_b128 v[178:181], v225 offset:53248
	ds_read_b128 v[182:185], v225 offset:54272
	ds_read_b128 v[186:189], v225 offset:55296
	ds_read_b128 v[190:193], v225 offset:56320
	global_load_lds_dwordx4 v[206:207], off
	v_lshl_add_u64 v[206:207], v[208:209], 0, s[2:3]
	s_add_i32 m0, s22, 0x2000
	s_add_i32 s22, s43, s49
	global_load_lds_dwordx4 v[206:207], off
	v_lshl_add_u64 v[206:207], v[220:221], 0, s[2:3]
	s_mov_b32 m0, s22
	s_nop 0
	global_load_lds_dwordx4 v[206:207], off
	v_lshl_add_u64 v[206:207], v[226:227], 0, s[2:3]
	s_add_i32 m0, s22, 0x2000
	s_nop 0
	global_load_lds_dwordx4 v[206:207], off
	v_lshl_add_u64 v[206:207], v[228:229], 0, s[2:3]
	s_mov_b32 m0, s61
	s_nop 0
	global_load_lds_dwordx4 v[206:207], off
	v_lshl_add_u64 v[206:207], v[230:231], 0, s[2:3]
	s_mov_b32 m0, s62
	s_nop 0
	global_load_lds_dwordx4 v[206:207], off
	s_waitcnt vmcnt(8)
	s_waitcnt lgkmcnt(0)
	s_barrier
	s_setprio 1
	s_waitcnt lgkmcnt(0)
	v_mfma_f32_16x16x32_bf16 v[30:33], v[122:125], v[186:189], v[30:33]
	v_mfma_f32_16x16x32_bf16 v[90:93], v[122:125], v[162:165], v[90:93]
	v_mfma_f32_16x16x32_bf16 v[86:89], v[138:141], v[162:165], v[86:89]
	v_mfma_f32_16x16x32_bf16 v[130:133], v[122:125], v[170:173], v[130:133]
	v_mfma_f32_16x16x32_bf16 v[78:81], v[138:141], v[170:173], v[78:81]
	v_mfma_f32_16x16x32_bf16 v[126:129], v[122:125], v[178:181], v[126:129]
	v_mfma_f32_16x16x32_bf16 v[118:121], v[138:141], v[178:181], v[118:121]
	v_mfma_f32_16x16x32_bf16 v[122:125], v[134:137], v[190:193], v[30:33]
	v_mfma_f32_16x16x32_bf16 v[30:33], v[138:141], v[186:189], v[110:113]
	v_mfma_f32_16x16x32_bf16 v[90:93], v[134:137], v[166:169], v[90:93]
	v_mfma_f32_16x16x32_bf16 v[86:89], v[142:145], v[166:169], v[86:89]
	v_mfma_f32_16x16x32_bf16 v[130:133], v[134:137], v[174:177], v[130:133]
	v_mfma_f32_16x16x32_bf16 v[78:81], v[142:145], v[174:177], v[78:81]
	v_mfma_f32_16x16x32_bf16 v[126:129], v[134:137], v[182:185], v[126:129]
	v_mfma_f32_16x16x32_bf16 v[118:121], v[142:145], v[182:185], v[118:121]
	v_mfma_f32_16x16x32_bf16 v[110:113], v[142:145], v[190:193], v[30:33]
	s_setprio 0
	s_setprio 1
	v_mfma_f32_16x16x32_bf16 v[30:33], v[146:149], v[162:165], v[82:85]
	v_mfma_f32_16x16x32_bf16 v[82:85], v[150:153], v[166:169], v[30:33]
	v_mfma_f32_16x16x32_bf16 v[30:33], v[154:157], v[162:165], v[74:77]
	v_mfma_f32_16x16x32_bf16 v[74:77], v[158:161], v[166:169], v[30:33]
	v_mfma_f32_16x16x32_bf16 v[30:33], v[146:149], v[170:173], v[66:69]
	v_mfma_f32_16x16x32_bf16 v[66:69], v[150:153], v[174:177], v[30:33]
	v_mfma_f32_16x16x32_bf16 v[30:33], v[154:157], v[170:173], v[70:73]
	v_mfma_f32_16x16x32_bf16 v[70:73], v[158:161], v[174:177], v[30:33]
	v_mfma_f32_16x16x32_bf16 v[30:33], v[146:149], v[178:181], v[114:117]
	v_mfma_f32_16x16x32_bf16 v[114:117], v[150:153], v[182:185], v[30:33]
	v_mfma_f32_16x16x32_bf16 v[30:33], v[154:157], v[178:181], v[106:109]
	v_mfma_f32_16x16x32_bf16 v[106:109], v[158:161], v[182:185], v[30:33]
	v_mfma_f32_16x16x32_bf16 v[30:33], v[146:149], v[186:189], v[98:101]
	v_mfma_f32_16x16x32_bf16 v[98:101], v[150:153], v[190:193], v[30:33]
	v_mfma_f32_16x16x32_bf16 v[30:33], v[154:157], v[186:189], v[102:105]
	v_mfma_f32_16x16x32_bf16 v[102:105], v[158:161], v[190:193], v[30:33]
	s_setprio 0
	s_add_u32 s38, s38, 0x100
	s_addc_u32 s39, s39, 0
	s_add_u32 s15, s15, 0x100
	s_addc_u32 s21, s21, 0
	s_cmp_ge_u32 s41, s56
	s_mov_b32 s22, s41
	s_cbranch_scc0 .Lh0_1
	s_branch .Ldone_1
.Lh1_1:
	s_add_i32 s41, s22, 2
	s_add_u32 s42, s38, 0xfff80080
	s_addc_u32 s23, s39, -1
	s_add_i32 s44, 0, 0x10000
	s_cmp_eq_u32 s63, s22
	s_cselect_b32 s23, s17, s23
	s_cselect_b32 s22, s16, s42
	v_add_u32_e32 v0, s44, v224
	s_cselect_b32 s43, s19, s21
	s_cselect_b32 s42, s18, s15
	s_add_i32 s45, 0, 0x14000
	ds_read_b128 v[30:33], v0
	ds_read_b128 v[134:137], v0 offset:1024
	ds_read_b128 v[138:141], v0 offset:2048
	ds_read_b128 v[142:145], v0 offset:3072
	v_add_u32_e32 v0, s45, v224
	ds_read_b128 v[146:149], v0
	ds_read_b128 v[150:153], v0 offset:1024
	ds_read_b128 v[154:157], v0 offset:2048
	ds_read_b128 v[158:161], v0 offset:3072
	v_lshl_add_u64 v[206:207], s[38:39], 0, v[202:203]
	s_add_i32 m0, s52, 0xc000
	ds_read_b128 v[162:165], v225
	ds_read_b128 v[166:169], v225 offset:1024
	ds_read_b128 v[170:173], v225 offset:2048
	ds_read_b128 v[174:177], v225 offset:3072
	ds_read_b128 v[178:181], v225 offset:4096
	ds_read_b128 v[182:185], v225 offset:5120
	ds_read_b128 v[186:189], v225 offset:6144
	ds_read_b128 v[190:193], v225 offset:7168
	global_load_lds_dwordx4 v[206:207], off
	v_lshl_add_u64 v[206:207], s[38:39], 0, v[204:205]
	s_add_i32 m0, s52, 0xe000
	s_nop 0
	global_load_lds_dwordx4 v[206:207], off
	s_waitcnt vmcnt(8)
	s_waitcnt lgkmcnt(0)
	s_setprio 1
	s_waitcnt lgkmcnt(0)
	v_mfma_f32_16x16x32_bf16 v[26:29], v[30:33], v[162:165], v[26:29]
	v_mfma_f32_16x16x32_bf16 v[22:25], v[138:141], v[162:165], v[22:25]
	v_mfma_f32_16x16x32_bf16 v[62:65], v[30:33], v[170:173], v[62:65]
	v_mfma_f32_16x16x32_bf16 v[14:17], v[138:141], v[170:173], v[14:17]
	v_mfma_f32_16x16x32_bf16 v[58:61], v[30:33], v[178:181], v[58:61]
	v_mfma_f32_16x16x32_bf16 v[54:57], v[138:141], v[178:181], v[54:57]
	v_mfma_f32_16x16x32_bf16 v[94:97], v[30:33], v[186:189], v[94:97]
	v_mfma_f32_16x16x32_bf16 v[46:49], v[138:141], v[186:189], v[46:49]
	v_mfma_f32_16x16x32_bf16 v[26:29], v[134:137], v[166:169], v[26:29]
	v_mfma_f32_16x16x32_bf16 v[22:25], v[142:145], v[166:169], v[22:25]
	v_mfma_f32_16x16x32_bf16 v[62:65], v[134:137], v[174:177], v[62:65]
	v_mfma_f32_16x16x32_bf16 v[14:17], v[142:145], v[174:177], v[14:17]
	v_mfma_f32_16x16x32_bf16 v[58:61], v[134:137], v[182:185], v[58:61]
	v_mfma_f32_16x16x32_bf16 v[54:57], v[142:145], v[182:185], v[54:57]
	v_mfma_f32_16x16x32_bf16 v[94:97], v[134:137], v[190:193], v[94:97]
	v_mfma_f32_16x16x32_bf16 v[46:49], v[142:145], v[190:193], v[46:49]
	s_setprio 0
	s_setprio 1
	v_mfma_f32_16x16x32_bf16 v[18:21], v[146:149], v[162:165], v[18:21]
	v_mfma_f32_16x16x32_bf16 v[10:13], v[154:157], v[162:165], v[10:13]
	v_mfma_f32_16x16x32_bf16 v[2:5], v[146:149], v[170:173], v[2:5]
	v_mfma_f32_16x16x32_bf16 v[6:9], v[154:157], v[170:173], v[6:9]
	v_mfma_f32_16x16x32_bf16 v[50:53], v[146:149], v[178:181], v[50:53]
	v_mfma_f32_16x16x32_bf16 v[42:45], v[154:157], v[178:181], v[42:45]
	v_mfma_f32_16x16x32_bf16 v[34:37], v[146:149], v[186:189], v[34:37]
	v_mfma_f32_16x16x32_bf16 v[38:41], v[154:157], v[186:189], v[38:41]
	v_mfma_f32_16x16x32_bf16 v[18:21], v[150:153], v[166:169], v[18:21]
	v_mfma_f32_16x16x32_bf16 v[10:13], v[158:161], v[166:169], v[10:13]
	v_mfma_f32_16x16x32_bf16 v[2:5], v[150:153], v[174:177], v[2:5]
	v_mfma_f32_16x16x32_bf16 v[6:9], v[158:161], v[174:177], v[6:9]
	v_mfma_f32_16x16x32_bf16 v[50:53], v[150:153], v[182:185], v[50:53]
	v_mfma_f32_16x16x32_bf16 v[42:45], v[158:161], v[182:185], v[42:45]
	v_mfma_f32_16x16x32_bf16 v[34:37], v[150:153], v[190:193], v[34:37]
	v_mfma_f32_16x16x32_bf16 v[38:41], v[158:161], v[190:193], v[38:41]
	s_setprio 0
	s_barrier
	s_add_i32 s44, s44, s49
	v_lshl_add_u64 v[206:207], s[42:43], 0, v[196:197]
	s_mov_b32 m0, s44
	ds_read_b128 v[162:165], v225 offset:16384
	ds_read_b128 v[166:169], v225 offset:17408
	ds_read_b128 v[170:173], v225 offset:18432
	ds_read_b128 v[174:177], v225 offset:19456
	ds_read_b128 v[178:181], v225 offset:20480
	ds_read_b128 v[182:185], v225 offset:21504
	ds_read_b128 v[186:189], v225 offset:22528
	ds_read_b128 v[190:193], v225 offset:23552
	global_load_lds_dwordx4 v[206:207], off
	s_add_i32 m0, s44, 0x2000
	v_lshl_add_u64 v[208:209], s[42:43], 0, v[200:201]
	s_add_u32 s42, s42, s50
	s_addc_u32 s43, s43, 0
	s_add_i32 s44, s45, s49
	global_load_lds_dwordx4 v[208:209], off
	v_lshl_add_u64 v[220:221], s[42:43], 0, v[196:197]
	s_mov_b32 m0, s44
	v_lshl_add_u64 v[226:227], s[42:43], 0, v[200:201]
	global_load_lds_dwordx4 v[220:221], off
	s_add_i32 m0, s44, 0x2000
	v_lshl_add_u64 v[228:229], s[22:23], 0, v[194:195]
	global_load_lds_dwordx4 v[226:227], off
	s_mov_b32 m0, s52
	v_lshl_add_u64 v[230:231], s[22:23], 0, v[198:199]
	global_load_lds_dwordx4 v[228:229], off
	s_mov_b32 m0, s53
	s_nop 0
	global_load_lds_dwordx4 v[230:231], off
	s_waitcnt vmcnt(8)
	s_waitcnt lgkmcnt(0)
	s_setprio 1
	s_waitcnt lgkmcnt(0)
	v_mfma_f32_16x16x32_bf16 v[90:93], v[30:33], v[162:165], v[90:93]
	v_mfma_f32_16x16x32_bf16 v[86:89], v[138:141], v[162:165], v[86:89]
	v_mfma_f32_16x16x32_bf16 v[130:133], v[30:33], v[170:173], v[130:133]
	v_mfma_f32_16x16x32_bf16 v[78:81], v[138:141], v[170:173], v[78:81]
	v_mfma_f32_16x16x32_bf16 v[126:129], v[30:33], v[178:181], v[126:129]
	v_mfma_f32_16x16x32_bf16 v[118:121], v[138:141], v[178:181], v[118:121]
	v_mfma_f32_16x16x32_bf16 v[110:113], v[138:141], v[186:189], v[110:113]
	v_mfma_f32_16x16x32_bf16 v[90:93], v[134:137], v[166:169], v[90:93]
	v_mfma_f32_16x16x32_bf16 v[86:89], v[142:145], v[166:169], v[86:89]
	v_mfma_f32_16x16x32_bf16 v[130:133], v[134:137], v[174:177], v[130:133]
	v_mfma_f32_16x16x32_bf16 v[78:81], v[142:145], v[174:177], v[78:81]
	v_mfma_f32_16x16x32_bf16 v[126:129], v[134:137], v[182:185], v[126:129]
	v_mfma_f32_16x16x32_bf16 v[118:121], v[142:145], v[182:185], v[118:121]
	v_mfma_f32_16x16x32_bf16 v[30:33], v[30:33], v[186:189], v[122:125]
	v_mfma_f32_16x16x32_bf16 v[110:113], v[142:145], v[190:193], v[110:113]
	v_mfma_f32_16x16x32_bf16 v[30:33], v[134:137], v[190:193], v[30:33]
	s_setprio 0
	s_setprio 1
	v_mfma_f32_16x16x32_bf16 v[82:85], v[146:149], v[162:165], v[82:85]
	v_mfma_f32_16x16x32_bf16 v[74:77], v[154:157], v[162:165], v[74:77]
	v_mfma_f32_16x16x32_bf16 v[66:69], v[146:149], v[170:173], v[66:69]
	v_mfma_f32_16x16x32_bf16 v[70:73], v[154:157], v[170:173], v[70:73]
	v_mfma_f32_16x16x32_bf16 v[114:117], v[146:149], v[178:181], v[114:117]
	v_mfma_f32_16x16x32_bf16 v[106:109], v[154:157], v[178:181], v[106:109]
	v_mfma_f32_16x16x32_bf16 v[98:101], v[146:149], v[186:189], v[98:101]
	v_mfma_f32_16x16x32_bf16 v[102:105], v[154:157], v[186:189], v[102:105]
	v_mfma_f32_16x16x32_bf16 v[82:85], v[150:153], v[166:169], v[82:85]
	v_mfma_f32_16x16x32_bf16 v[74:77], v[158:161], v[166:169], v[74:77]
	v_mfma_f32_16x16x32_bf16 v[66:69], v[150:153], v[174:177], v[66:69]
	v_mfma_f32_16x16x32_bf16 v[70:73], v[158:161], v[174:177], v[70:73]
	v_mfma_f32_16x16x32_bf16 v[114:117], v[150:153], v[182:185], v[114:117]
	v_mfma_f32_16x16x32_bf16 v[106:109], v[158:161], v[182:185], v[106:109]
	v_mfma_f32_16x16x32_bf16 v[98:101], v[150:153], v[190:193], v[98:101]
	v_mfma_f32_16x16x32_bf16 v[102:105], v[158:161], v[190:193], v[102:105]
	s_setprio 0
	s_barrier
	s_add_i32 s42, 0, 0x18000
	v_add_u32_e32 v0, s42, v224
	s_add_i32 s43, 0, 0x1c000
	ds_read_b128 v[122:125], v0
	ds_read_b128 v[134:137], v0 offset:1024
	ds_read_b128 v[138:141], v0 offset:2048
	ds_read_b128 v[142:145], v0 offset:3072
	v_add_u32_e32 v0, s43, v224
	ds_read_b128 v[146:149], v0
	ds_read_b128 v[150:153], v0 offset:1024
	ds_read_b128 v[154:157], v0 offset:2048
	ds_read_b128 v[158:161], v0 offset:3072
	s_add_u32 s22, s22, 0x80000
	s_addc_u32 s23, s23, 0
	s_mov_b32 m0, s54
	v_lshl_add_u64 v[232:233], s[22:23], 0, v[194:195]
	ds_read_b128 v[162:165], v225 offset:32768
	ds_read_b128 v[166:169], v225 offset:33792
	ds_read_b128 v[170:173], v225 offset:34816
	ds_read_b128 v[174:177], v225 offset:35840
	ds_read_b128 v[178:181], v225 offset:36864
	ds_read_b128 v[182:185], v225 offset:37888
	ds_read_b128 v[186:189], v225 offset:38912
	ds_read_b128 v[190:193], v225 offset:39936
	global_load_lds_dwordx4 v[232:233], off
	v_lshl_add_u64 v[232:233], s[22:23], 0, v[198:199]
	s_mov_b32 m0, s55
	s_nop 0
	global_load_lds_dwordx4 v[232:233], off
	s_waitcnt vmcnt(8)
	s_waitcnt lgkmcnt(0)
	s_setprio 1
	s_waitcnt lgkmcnt(0)
	v_mfma_f32_16x16x32_bf16 v[26:29], v[122:125], v[162:165], v[26:29]
	v_mfma_f32_16x16x32_bf16 v[22:25], v[138:141], v[162:165], v[22:25]
	v_mfma_f32_16x16x32_bf16 v[62:65], v[122:125], v[170:173], v[62:65]
	v_mfma_f32_16x16x32_bf16 v[14:17], v[138:141], v[170:173], v[14:17]
	v_mfma_f32_16x16x32_bf16 v[58:61], v[122:125], v[178:181], v[58:61]
	v_mfma_f32_16x16x32_bf16 v[54:57], v[138:141], v[178:181], v[54:57]
	v_mfma_f32_16x16x32_bf16 v[94:97], v[122:125], v[186:189], v[94:97]
	v_mfma_f32_16x16x32_bf16 v[46:49], v[138:141], v[186:189], v[46:49]
	v_mfma_f32_16x16x32_bf16 v[26:29], v[134:137], v[166:169], v[26:29]
	v_mfma_f32_16x16x32_bf16 v[22:25], v[142:145], v[166:169], v[22:25]
	v_mfma_f32_16x16x32_bf16 v[62:65], v[134:137], v[174:177], v[62:65]
	v_mfma_f32_16x16x32_bf16 v[14:17], v[142:145], v[174:177], v[14:17]
	v_mfma_f32_16x16x32_bf16 v[58:61], v[134:137], v[182:185], v[58:61]
	v_mfma_f32_16x16x32_bf16 v[54:57], v[142:145], v[182:185], v[54:57]
	v_mfma_f32_16x16x32_bf16 v[94:97], v[134:137], v[190:193], v[94:97]
	v_mfma_f32_16x16x32_bf16 v[46:49], v[142:145], v[190:193], v[46:49]
	s_setprio 0
	s_setprio 1
	v_mfma_f32_16x16x32_bf16 v[18:21], v[146:149], v[162:165], v[18:21]
	v_mfma_f32_16x16x32_bf16 v[10:13], v[154:157], v[162:165], v[10:13]
	v_mfma_f32_16x16x32_bf16 v[2:5], v[146:149], v[170:173], v[2:5]
	v_mfma_f32_16x16x32_bf16 v[6:9], v[154:157], v[170:173], v[6:9]
	v_mfma_f32_16x16x32_bf16 v[50:53], v[146:149], v[178:181], v[50:53]
	v_mfma_f32_16x16x32_bf16 v[42:45], v[154:157], v[178:181], v[42:45]
	v_mfma_f32_16x16x32_bf16 v[34:37], v[146:149], v[186:189], v[34:37]
	v_mfma_f32_16x16x32_bf16 v[38:41], v[154:157], v[186:189], v[38:41]
	v_mfma_f32_16x16x32_bf16 v[18:21], v[150:153], v[166:169], v[18:21]
	v_mfma_f32_16x16x32_bf16 v[10:13], v[158:161], v[166:169], v[10:13]
	v_mfma_f32_16x16x32_bf16 v[2:5], v[150:153], v[174:177], v[2:5]
	v_mfma_f32_16x16x32_bf16 v[6:9], v[158:161], v[174:177], v[6:9]
	v_mfma_f32_16x16x32_bf16 v[50:53], v[150:153], v[182:185], v[50:53]
	v_mfma_f32_16x16x32_bf16 v[42:45], v[158:161], v[182:185], v[42:45]
	v_mfma_f32_16x16x32_bf16 v[34:37], v[150:153], v[190:193], v[34:37]
	v_mfma_f32_16x16x32_bf16 v[38:41], v[158:161], v[190:193], v[38:41]
	s_setprio 0
	s_barrier
	s_add_i32 s22, s42, s49
	v_lshl_add_u64 v[206:207], v[206:207], 0, s[2:3]
	s_mov_b32 m0, s22
	ds_read_b128 v[162:165], v225 offset:49152
	ds_read_b128 v[166:169], v225 offset:50176
	ds_read_b128 v[170:173], v225 offset:51200
	ds_read_b128 v[174:177], v225 offset:52224
	ds_read_b128 v[178:181], v225 offset:53248
	ds_read_b128 v[182:185], v225 offset:54272
	ds_read_b128 v[186:189], v225 offset:55296
	ds_read_b128 v[190:193], v225 offset:56320
	global_load_lds_dwordx4 v[206:207], off
	v_lshl_add_u64 v[206:207], v[208:209], 0, s[2:3]
	s_add_i32 m0, s22, 0x2000
	s_add_i32 s22, s43, s49
	global_load_lds_dwordx4 v[206:207], off
	v_lshl_add_u64 v[206:207], v[220:221], 0, s[2:3]
	s_mov_b32 m0, s22
	s_nop 0
	global_load_lds_dwordx4 v[206:207], off
	v_lshl_add_u64 v[206:207], v[226:227], 0, s[2:3]
	s_add_i32 m0, s22, 0x2000
	s_nop 0
	global_load_lds_dwordx4 v[206:207], off
	v_lshl_add_u64 v[206:207], v[228:229], 0, s[2:3]
	s_mov_b32 m0, s61
	s_nop 0
	global_load_lds_dwordx4 v[206:207], off
	v_lshl_add_u64 v[206:207], v[230:231], 0, s[2:3]
	s_mov_b32 m0, s62
	s_nop 0
	global_load_lds_dwordx4 v[206:207], off
	s_waitcnt vmcnt(8)
	s_waitcnt lgkmcnt(0)
	s_setprio 1
	s_waitcnt lgkmcnt(0)
	v_mfma_f32_16x16x32_bf16 v[30:33], v[122:125], v[186:189], v[30:33]
	v_mfma_f32_16x16x32_bf16 v[90:93], v[122:125], v[162:165], v[90:93]
	v_mfma_f32_16x16x32_bf16 v[86:89], v[138:141], v[162:165], v[86:89]
	v_mfma_f32_16x16x32_bf16 v[130:133], v[122:125], v[170:173], v[130:133]
	v_mfma_f32_16x16x32_bf16 v[78:81], v[138:141], v[170:173], v[78:81]
	v_mfma_f32_16x16x32_bf16 v[126:129], v[122:125], v[178:181], v[126:129]
	v_mfma_f32_16x16x32_bf16 v[118:121], v[138:141], v[178:181], v[118:121]
	v_mfma_f32_16x16x32_bf16 v[122:125], v[134:137], v[190:193], v[30:33]
	v_mfma_f32_16x16x32_bf16 v[30:33], v[138:141], v[186:189], v[110:113]
	v_mfma_f32_16x16x32_bf16 v[90:93], v[134:137], v[166:169], v[90:93]
	v_mfma_f32_16x16x32_bf16 v[86:89], v[142:145], v[166:169], v[86:89]
	v_mfma_f32_16x16x32_bf16 v[130:133], v[134:137], v[174:177], v[130:133]
	v_mfma_f32_16x16x32_bf16 v[78:81], v[142:145], v[174:177], v[78:81]
	v_mfma_f32_16x16x32_bf16 v[126:129], v[134:137], v[182:185], v[126:129]
	v_mfma_f32_16x16x32_bf16 v[118:121], v[142:145], v[182:185], v[118:121]
	v_mfma_f32_16x16x32_bf16 v[110:113], v[142:145], v[190:193], v[30:33]
	s_setprio 0
	s_setprio 1
	v_mfma_f32_16x16x32_bf16 v[30:33], v[146:149], v[162:165], v[82:85]
	v_mfma_f32_16x16x32_bf16 v[82:85], v[150:153], v[166:169], v[30:33]
	v_mfma_f32_16x16x32_bf16 v[30:33], v[154:157], v[162:165], v[74:77]
	v_mfma_f32_16x16x32_bf16 v[74:77], v[158:161], v[166:169], v[30:33]
	v_mfma_f32_16x16x32_bf16 v[30:33], v[146:149], v[170:173], v[66:69]
	v_mfma_f32_16x16x32_bf16 v[66:69], v[150:153], v[174:177], v[30:33]
	v_mfma_f32_16x16x32_bf16 v[30:33], v[154:157], v[170:173], v[70:73]
	v_mfma_f32_16x16x32_bf16 v[70:73], v[158:161], v[174:177], v[30:33]
	v_mfma_f32_16x16x32_bf16 v[30:33], v[146:149], v[178:181], v[114:117]
	v_mfma_f32_16x16x32_bf16 v[114:117], v[150:153], v[182:185], v[30:33]
	v_mfma_f32_16x16x32_bf16 v[30:33], v[154:157], v[178:181], v[106:109]
	v_mfma_f32_16x16x32_bf16 v[106:109], v[158:161], v[182:185], v[30:33]
	v_mfma_f32_16x16x32_bf16 v[30:33], v[146:149], v[186:189], v[98:101]
	v_mfma_f32_16x16x32_bf16 v[98:101], v[150:153], v[190:193], v[30:33]
	v_mfma_f32_16x16x32_bf16 v[30:33], v[154:157], v[186:189], v[102:105]
	v_mfma_f32_16x16x32_bf16 v[102:105], v[158:161], v[190:193], v[30:33]
	s_setprio 0
	s_barrier
	s_add_u32 s38, s38, 0x100
	s_addc_u32 s39, s39, 0
	s_add_u32 s15, s15, 0x100
	s_addc_u32 s21, s21, 0
	s_cmp_ge_u32 s41, s56
	s_mov_b32 s22, s41
	s_cbranch_scc0 .Lh1_1

.LBB0_972:
	s_or_b64 exec, exec, s[14:15]
	s_waitcnt lgkmcnt(0)
	v_cmp_eq_u32_e32 vcc, 0, v0
	v_lshl_add_u32 v0, v208, 11, v206
	s_waitcnt vmcnt(5)
	v_pk_add_f32 v[208:209], v[190:191], 1.0 op_sel_hi:[1,0]
	v_pk_add_f32 v[206:207], v[192:193], 1.0 op_sel_hi:[1,0]
	v_pk_mul_f32 v[192:193], v[154:155], v[208:209]
	s_waitcnt vmcnt(3)
	v_pk_fma_f32 v[186:187], v[158:159], v[208:209], v[186:187]
	v_pk_add_f32 v[208:209], v[184:185], 1.0 op_sel_hi:[1,0]
	v_pk_add_f32 v[178:179], v[178:179], 1.0 op_sel_hi:[1,0]
	v_pk_mul_f32 v[184:185], v[148:149], v[208:209]
	v_pk_fma_f32 v[208:209], v[152:153], v[208:209], v[176:177]
	v_pk_mul_f32 v[176:177], v[130:131], v[178:179]
	s_waitcnt vmcnt(2)
	v_pk_fma_f32 v[170:171], v[134:135], v[178:179], v[170:171]
	s_waitcnt vmcnt(1)
	v_pk_add_f32 v[178:179], v[168:169], 1.0 op_sel_hi:[1,0]
	s_waitcnt lgkmcnt(0)
	s_barrier
	v_pk_mul_f32 v[168:169], v[124:125], v[178:179]
	s_waitcnt vmcnt(0)
	v_pk_fma_f32 v[164:165], v[128:129], v[178:179], v[164:165]
	v_lshl_add_u32 v178, v226, 3, s76
	ds_read2_b64 v[226:229], v178 offset1:16
	v_pk_mul_f32 v[190:191], v[156:157], v[206:207]
	v_pk_fma_f32 v[188:189], v[160:161], v[206:207], v[188:189]
	v_pk_add_f32 v[206:207], v[182:183], 1.0 op_sel_hi:[1,0]
	v_pk_add_f32 v[180:181], v[180:181], 1.0 op_sel_hi:[1,0]
	v_pk_mul_f32 v[182:183], v[146:147], v[206:207]
	v_pk_fma_f32 v[206:207], v[150:151], v[206:207], v[174:175]
	v_pk_mul_f32 v[174:175], v[132:133], v[180:181]
	v_pk_fma_f32 v[172:173], v[136:137], v[180:181], v[172:173]
	v_pk_add_f32 v[180:181], v[166:167], 1.0 op_sel_hi:[1,0]
	s_waitcnt lgkmcnt(0)
	v_pk_fma_f32 v[216:217], v[28:29], v[226:227], v[226:227] op_sel:[0,1,0] op_sel_hi:[1,1,0]
	v_pk_mul_f32 v[166:167], v[122:123], v[180:181]
	v_pk_fma_f32 v[162:163], v[126:127], v[180:181], v[162:163]
	v_pk_fma_f32 v[180:181], v[26:27], v[226:227], v[226:227] op_sel:[0,1,0] op_sel_hi:[1,1,0]
	v_pk_fma_f32 v[30:31], v[30:31], v[226:227], v[226:227] op_sel:[0,1,0] op_sel_hi:[1,1,0]
	v_pk_fma_f32 v[32:33], v[32:33], v[226:227], v[226:227] op_sel:[0,1,0] op_sel_hi:[1,1,0]
	v_pk_fma_f32 v[26:27], v[156:157], v[216:217], v[160:161]
	v_pk_fma_f32 v[28:29], v[154:155], v[180:181], v[158:159]
	v_pk_fma_f32 v[220:221], v[148:149], v[32:33], v[152:153]
	v_pk_fma_f32 v[230:231], v[146:147], v[30:31], v[150:151]
	v_cvt_pk_f16_f32 v28, v28, v29
	v_cvt_pk_f16_f32 v26, v26, v27
	v_cndmask_b32_e32 v27, v248, v26, vcc
	v_cndmask_b32_e32 v26, v248, v28, vcc
	v_cvt_pk_f16_f32 v28, v230, v231
	v_cvt_pk_f16_f32 v29, v220, v221
	v_lshlrev_b64 v[220:221], 1, v[0:1]
	v_cndmask_b32_e32 v29, v248, v29, vcc
	v_cndmask_b32_e32 v28, v248, v28, vcc
	v_lshl_add_u64 v[230:231], s[70:71], 0, v[220:221]
	global_store_dwordx4 v[230:231], v[26:29], off
	v_pk_fma_f32 v[32:33], v[184:185], v[32:33], v[208:209]
	v_pk_fma_f32 v[30:31], v[182:183], v[30:31], v[206:207]
	v_pk_fma_f32 v[26:27], v[190:191], v[216:217], v[188:189]
	v_pk_fma_f32 v[28:29], v[192:193], v[180:181], v[186:187]
	v_readlane_b32 s14, v253, 25
	v_cvt_pk_bf16_f32 v179, v28, v29
	v_cvt_pk_bf16_f32 v26, v26, v27
	v_cvt_pk_bf16_f32 v27, v30, v31
	v_cvt_pk_bf16_f32 v28, v32, v33
	v_readlane_b32 s15, v253, 26
	v_cndmask_b32_e32 v29, v249, v28, vcc
	v_cndmask_b32_e32 v28, v249, v27, vcc
	v_cndmask_b32_e32 v27, v249, v26, vcc
	v_cndmask_b32_e32 v26, v249, v179, vcc
	v_lshl_add_u64 v[30:31], s[14:15], 0, v[220:221]
	global_store_dwordx4 v[30:31], v[26:29], off
	v_pk_fma_f32 v[30:31], v[20:21], v[226:227], v[226:227] op_sel:[0,1,0] op_sel_hi:[1,1,0]
	v_pk_fma_f32 v[22:23], v[22:23], v[226:227], v[226:227] op_sel:[0,1,0] op_sel_hi:[1,1,0]
	v_pk_fma_f32 v[28:29], v[18:19], v[226:227], v[226:227] op_sel:[0,1,0] op_sel_hi:[1,1,0]
	v_pk_fma_f32 v[24:25], v[24:25], v[226:227], v[226:227] op_sel:[0,1,0] op_sel_hi:[1,1,0]
	v_pk_fma_f32 v[18:19], v[132:133], v[30:31], v[136:137]
	v_pk_fma_f32 v[20:21], v[130:131], v[28:29], v[134:135]
	v_add_u32_e32 v26, 0x80, v0
	v_pk_fma_f32 v[32:33], v[124:125], v[24:25], v[128:129]
	v_pk_fma_f32 v[180:181], v[122:123], v[22:23], v[126:127]
	v_cvt_pk_f16_f32 v20, v20, v21
	v_cvt_pk_f16_f32 v18, v18, v19
	v_mov_b32_e32 v27, v1
	v_cndmask_b32_e32 v19, v248, v18, vcc
	v_cndmask_b32_e32 v18, v248, v20, vcc
	v_cvt_pk_f16_f32 v20, v180, v181
	v_cvt_pk_f16_f32 v21, v32, v33
	v_lshlrev_b64 v[26:27], 1, v[26:27]
	v_cndmask_b32_e32 v21, v248, v21, vcc
	v_cndmask_b32_e32 v20, v248, v20, vcc
	v_lshl_add_u64 v[32:33], s[70:71], 0, v[26:27]
	global_store_dwordx4 v[32:33], v[18:21], off
	v_pk_fma_f32 v[24:25], v[168:169], v[24:25], v[164:165]
	v_pk_fma_f32 v[22:23], v[166:167], v[22:23], v[162:163]
	v_pk_fma_f32 v[18:19], v[174:175], v[30:31], v[172:173]
	v_pk_fma_f32 v[20:21], v[176:177], v[28:29], v[170:171]
	v_cvt_pk_bf16_f32 v18, v18, v19
	v_cvt_pk_bf16_f32 v28, v20, v21
	v_cvt_pk_bf16_f32 v19, v22, v23
	v_cvt_pk_bf16_f32 v20, v24, v25
	v_cndmask_b32_e32 v21, v249, v20, vcc
	v_cndmask_b32_e32 v20, v249, v19, vcc
	v_cndmask_b32_e32 v19, v249, v18, vcc
	v_cndmask_b32_e32 v18, v249, v28, vcc
	v_lshl_add_u64 v[22:23], s[14:15], 0, v[26:27]
	global_store_dwordx4 v[22:23], v[18:21], off
	v_pk_fma_f32 v[22:23], v[12:13], v[228:229], v[228:229] op_sel:[0,1,0] op_sel_hi:[1,1,0]
	v_pk_fma_f32 v[14:15], v[14:15], v[228:229], v[228:229] op_sel:[0,1,0] op_sel_hi:[1,1,0]
	v_pk_fma_f32 v[20:21], v[10:11], v[228:229], v[228:229] op_sel:[0,1,0] op_sel_hi:[1,1,0]
	v_pk_fma_f32 v[16:17], v[16:17], v[228:229], v[228:229] op_sel:[0,1,0] op_sel_hi:[1,1,0]
	v_pk_fma_f32 v[10:11], v[156:157], v[22:23], v[160:161]
	v_pk_fma_f32 v[12:13], v[154:155], v[20:21], v[158:159]
	v_add_u32_e32 v18, 0x8000, v0
	v_pk_fma_f32 v[24:25], v[148:149], v[16:17], v[152:153]
	v_pk_fma_f32 v[26:27], v[146:147], v[14:15], v[150:151]
	v_cvt_pk_f16_f32 v12, v12, v13
	v_cvt_pk_f16_f32 v10, v10, v11
	v_mov_b32_e32 v19, v1
	v_cndmask_b32_e32 v11, v248, v10, vcc
	v_cndmask_b32_e32 v10, v248, v12, vcc
	v_cvt_pk_f16_f32 v12, v26, v27
	v_cvt_pk_f16_f32 v13, v24, v25
	v_lshlrev_b64 v[18:19], 1, v[18:19]
	v_cndmask_b32_e32 v13, v248, v13, vcc
	v_cndmask_b32_e32 v12, v248, v12, vcc
	v_lshl_add_u64 v[24:25], s[70:71], 0, v[18:19]
	global_store_dwordx4 v[24:25], v[10:13], off
	v_pk_fma_f32 v[16:17], v[184:185], v[16:17], v[208:209]
	v_pk_fma_f32 v[14:15], v[182:183], v[14:15], v[206:207]
	v_pk_fma_f32 v[10:11], v[190:191], v[22:23], v[188:189]
	v_pk_fma_f32 v[12:13], v[192:193], v[20:21], v[186:187]
	v_cvt_pk_bf16_f32 v10, v10, v11
	v_cvt_pk_bf16_f32 v20, v12, v13
	v_cvt_pk_bf16_f32 v11, v14, v15
	v_cvt_pk_bf16_f32 v12, v16, v17
	v_cndmask_b32_e32 v13, v249, v12, vcc
	v_cndmask_b32_e32 v12, v249, v11, vcc
	v_cndmask_b32_e32 v11, v249, v10, vcc
	v_cndmask_b32_e32 v10, v249, v20, vcc
	v_lshl_add_u64 v[14:15], s[14:15], 0, v[18:19]
	global_store_dwordx4 v[14:15], v[10:13], off
	v_pk_fma_f32 v[14:15], v[4:5], v[228:229], v[228:229] op_sel:[0,1,0] op_sel_hi:[1,1,0]
	v_pk_fma_f32 v[6:7], v[6:7], v[228:229], v[228:229] op_sel:[0,1,0] op_sel_hi:[1,1,0]
	v_pk_fma_f32 v[12:13], v[2:3], v[228:229], v[228:229] op_sel:[0,1,0] op_sel_hi:[1,1,0]
	v_pk_fma_f32 v[8:9], v[8:9], v[228:229], v[228:229] op_sel:[0,1,0] op_sel_hi:[1,1,0]
	v_pk_fma_f32 v[2:3], v[132:133], v[14:15], v[136:137]
	v_pk_fma_f32 v[4:5], v[130:131], v[12:13], v[134:135]
	v_add_u32_e32 v10, 0x8080, v0
	v_pk_fma_f32 v[16:17], v[124:125], v[8:9], v[128:129]
	v_pk_fma_f32 v[18:19], v[122:123], v[6:7], v[126:127]
	v_cvt_pk_f16_f32 v4, v4, v5
	v_cvt_pk_f16_f32 v2, v2, v3
	v_mov_b32_e32 v11, v1
	v_cndmask_b32_e32 v3, v248, v2, vcc
	v_cndmask_b32_e32 v2, v248, v4, vcc
	v_cvt_pk_f16_f32 v4, v18, v19
	v_cvt_pk_f16_f32 v5, v16, v17
	v_lshlrev_b64 v[10:11], 1, v[10:11]
	v_cndmask_b32_e32 v5, v248, v5, vcc
	v_cndmask_b32_e32 v4, v248, v4, vcc
	v_lshl_add_u64 v[16:17], s[70:71], 0, v[10:11]
	global_store_dwordx4 v[16:17], v[2:5], off
	v_pk_fma_f32 v[8:9], v[168:169], v[8:9], v[164:165]
	v_pk_fma_f32 v[6:7], v[166:167], v[6:7], v[162:163]
	v_pk_fma_f32 v[2:3], v[174:175], v[14:15], v[172:173]
	v_pk_fma_f32 v[4:5], v[176:177], v[12:13], v[170:171]
	v_cvt_pk_bf16_f32 v2, v2, v3
	v_cvt_pk_bf16_f32 v12, v4, v5
	v_cvt_pk_bf16_f32 v3, v6, v7
	v_cvt_pk_bf16_f32 v4, v8, v9
	v_cndmask_b32_e32 v5, v249, v4, vcc
	v_cndmask_b32_e32 v4, v249, v3, vcc
	v_cndmask_b32_e32 v3, v249, v2, vcc
	v_cndmask_b32_e32 v2, v249, v12, vcc
	v_lshl_add_u64 v[6:7], s[14:15], 0, v[10:11]
	global_store_dwordx4 v[6:7], v[2:5], off
	ds_read2_b64 v[2:5], v178 offset0:32 offset1:48
	v_add_u32_e32 v10, 0x10000, v0
	v_mov_b32_e32 v11, v1
	v_lshlrev_b64 v[10:11], 1, v[10:11]
	s_waitcnt lgkmcnt(0)
	v_pk_fma_f32 v[12:13], v[58:59], v[2:3], v[2:3] op_sel:[0,1,0] op_sel_hi:[1,1,0]
	v_pk_fma_f32 v[14:15], v[60:61], v[2:3], v[2:3] op_sel:[0,1,0] op_sel_hi:[1,1,0]
	v_pk_fma_f32 v[16:17], v[62:63], v[2:3], v[2:3] op_sel:[0,1,0] op_sel_hi:[1,1,0]
	v_pk_fma_f32 v[18:19], v[64:65], v[2:3], v[2:3] op_sel:[0,1,0] op_sel_hi:[1,1,0]
	v_pk_fma_f32 v[6:7], v[156:157], v[14:15], v[160:161]
	v_pk_fma_f32 v[8:9], v[154:155], v[12:13], v[158:159]
	v_pk_fma_f32 v[20:21], v[148:149], v[18:19], v[152:153]
	v_pk_fma_f32 v[22:23], v[146:147], v[16:17], v[150:151]
	v_cvt_pk_f16_f32 v8, v8, v9
	v_cvt_pk_f16_f32 v6, v6, v7
	v_cndmask_b32_e32 v7, v248, v6, vcc
	v_cndmask_b32_e32 v6, v248, v8, vcc
	v_cvt_pk_f16_f32 v8, v22, v23
	v_cvt_pk_f16_f32 v9, v20, v21
	v_cndmask_b32_e32 v9, v248, v9, vcc
	v_cndmask_b32_e32 v8, v248, v8, vcc
	v_lshl_add_u64 v[20:21], s[70:71], 0, v[10:11]
	global_store_dwordx4 v[20:21], v[6:9], off
	v_lshl_add_u64 v[10:11], s[14:15], 0, v[10:11]
	s_nop 0
	v_pk_fma_f32 v[6:7], v[190:191], v[14:15], v[188:189]
	v_pk_fma_f32 v[8:9], v[192:193], v[12:13], v[186:187]
	v_pk_fma_f32 v[12:13], v[184:185], v[18:19], v[208:209]
	v_pk_fma_f32 v[14:15], v[182:183], v[16:17], v[206:207]
	v_cvt_pk_bf16_f32 v16, v8, v9
	v_cvt_pk_bf16_f32 v6, v6, v7
	v_cvt_pk_bf16_f32 v7, v14, v15
	v_cvt_pk_bf16_f32 v8, v12, v13
	v_cndmask_b32_e32 v9, v249, v8, vcc
	v_cndmask_b32_e32 v8, v249, v7, vcc
	v_cndmask_b32_e32 v7, v249, v6, vcc
	v_cndmask_b32_e32 v6, v249, v16, vcc
	v_pk_fma_f32 v[12:13], v[50:51], v[2:3], v[2:3] op_sel:[0,1,0] op_sel_hi:[1,1,0]
	v_pk_fma_f32 v[14:15], v[52:53], v[2:3], v[2:3] op_sel:[0,1,0] op_sel_hi:[1,1,0]
	global_store_dwordx4 v[10:11], v[6:9], off
	v_pk_fma_f32 v[16:17], v[54:55], v[2:3], v[2:3] op_sel:[0,1,0] op_sel_hi:[1,1,0]
	v_pk_fma_f32 v[2:3], v[56:57], v[2:3], v[2:3] op_sel:[0,1,0] op_sel_hi:[1,1,0]
	v_pk_fma_f32 v[6:7], v[132:133], v[14:15], v[136:137]
	v_pk_fma_f32 v[8:9], v[130:131], v[12:13], v[134:135]
	v_add_u32_e32 v10, 0x10080, v0
	v_pk_fma_f32 v[18:19], v[124:125], v[2:3], v[128:129]
	v_pk_fma_f32 v[20:21], v[122:123], v[16:17], v[126:127]
	v_cvt_pk_f16_f32 v8, v8, v9
	v_cvt_pk_f16_f32 v6, v6, v7
	v_mov_b32_e32 v11, v1
	v_cndmask_b32_e32 v7, v248, v6, vcc
	v_cndmask_b32_e32 v6, v248, v8, vcc
	v_cvt_pk_f16_f32 v8, v20, v21
	v_cvt_pk_f16_f32 v9, v18, v19
	v_lshlrev_b64 v[10:11], 1, v[10:11]
	v_cndmask_b32_e32 v9, v248, v9, vcc
	v_cndmask_b32_e32 v8, v248, v8, vcc
	v_lshl_add_u64 v[18:19], s[70:71], 0, v[10:11]
	global_store_dwordx4 v[18:19], v[6:9], off
	v_pk_fma_f32 v[2:3], v[168:169], v[2:3], v[164:165]
	s_nop 0
	v_pk_fma_f32 v[6:7], v[174:175], v[14:15], v[172:173]
	v_pk_fma_f32 v[8:9], v[176:177], v[12:13], v[170:171]
	v_pk_fma_f32 v[12:13], v[166:167], v[16:17], v[162:163]
	v_cvt_pk_bf16_f32 v14, v8, v9
	v_cvt_pk_bf16_f32 v6, v6, v7
	v_cvt_pk_bf16_f32 v7, v12, v13
	v_cvt_pk_bf16_f32 v2, v2, v3
	v_cndmask_b32_e32 v9, v249, v2, vcc
	v_cndmask_b32_e32 v8, v249, v7, vcc
	v_cndmask_b32_e32 v7, v249, v6, vcc
	v_cndmask_b32_e32 v6, v249, v14, vcc
	v_lshl_add_u64 v[2:3], s[14:15], 0, v[10:11]
	v_pk_fma_f32 v[10:11], v[42:43], v[4:5], v[4:5] op_sel:[0,1,0] op_sel_hi:[1,1,0]
	v_pk_fma_f32 v[12:13], v[44:45], v[4:5], v[4:5] op_sel:[0,1,0] op_sel_hi:[1,1,0]
	global_store_dwordx4 v[2:3], v[6:9], off
	v_pk_fma_f32 v[14:15], v[46:47], v[4:5], v[4:5] op_sel:[0,1,0] op_sel_hi:[1,1,0]
	v_pk_fma_f32 v[16:17], v[48:49], v[4:5], v[4:5] op_sel:[0,1,0] op_sel_hi:[1,1,0]
	v_pk_fma_f32 v[6:7], v[156:157], v[12:13], v[160:161]
	v_pk_fma_f32 v[8:9], v[154:155], v[10:11], v[158:159]
	v_pk_fma_f32 v[18:19], v[148:149], v[16:17], v[152:153]
	v_pk_fma_f32 v[20:21], v[146:147], v[14:15], v[150:151]
	v_cvt_pk_f16_f32 v3, v8, v9
	v_cvt_pk_f16_f32 v6, v6, v7
	v_cndmask_b32_e32 v7, v248, v6, vcc
	v_cndmask_b32_e32 v6, v248, v3, vcc
	v_cvt_pk_f16_f32 v3, v20, v21
	v_cvt_pk_f16_f32 v8, v18, v19
	v_add_u32_e32 v2, 0x18000, v0
	v_cndmask_b32_e32 v9, v248, v8, vcc
	v_cndmask_b32_e32 v8, v248, v3, vcc
	v_mov_b32_e32 v3, v1
	v_lshlrev_b64 v[2:3], 1, v[2:3]
	v_lshl_add_u64 v[18:19], s[70:71], 0, v[2:3]
	global_store_dwordx4 v[18:19], v[6:9], off
	v_lshl_add_u64 v[2:3], s[14:15], 0, v[2:3]
	s_nop 0
	v_pk_fma_f32 v[6:7], v[190:191], v[12:13], v[188:189]
	v_pk_fma_f32 v[8:9], v[192:193], v[10:11], v[186:187]
	v_pk_fma_f32 v[10:11], v[184:185], v[16:17], v[208:209]
	v_pk_fma_f32 v[12:13], v[182:183], v[14:15], v[206:207]
	v_cvt_pk_bf16_f32 v14, v8, v9
	v_cvt_pk_bf16_f32 v6, v6, v7
	v_cvt_pk_bf16_f32 v7, v12, v13
	v_cvt_pk_bf16_f32 v8, v10, v11
	v_cndmask_b32_e32 v9, v249, v8, vcc
	v_cndmask_b32_e32 v8, v249, v7, vcc
	v_cndmask_b32_e32 v7, v249, v6, vcc
	v_cndmask_b32_e32 v6, v249, v14, vcc
	global_store_dwordx4 v[2:3], v[6:9], off
	v_pk_fma_f32 v[10:11], v[36:37], v[4:5], v[4:5] op_sel:[0,1,0] op_sel_hi:[1,1,0]
	v_pk_fma_f32 v[12:13], v[38:39], v[4:5], v[4:5] op_sel:[0,1,0] op_sel_hi:[1,1,0]
	v_pk_fma_f32 v[8:9], v[34:35], v[4:5], v[4:5] op_sel:[0,1,0] op_sel_hi:[1,1,0]
	v_pk_fma_f32 v[14:15], v[40:41], v[4:5], v[4:5] op_sel:[0,1,0] op_sel_hi:[1,1,0]
	v_pk_fma_f32 v[2:3], v[132:133], v[10:11], v[136:137]
	v_pk_fma_f32 v[4:5], v[130:131], v[8:9], v[134:135]
	v_add_u32_e32 v6, 0x18080, v0
	v_pk_fma_f32 v[16:17], v[124:125], v[14:15], v[128:129]
	v_pk_fma_f32 v[18:19], v[122:123], v[12:13], v[126:127]
	v_cvt_pk_f16_f32 v4, v4, v5
	v_cvt_pk_f16_f32 v2, v2, v3
	v_mov_b32_e32 v7, v1
	v_cndmask_b32_e32 v3, v248, v2, vcc
	v_cndmask_b32_e32 v2, v248, v4, vcc
	v_cvt_pk_f16_f32 v4, v18, v19
	v_cvt_pk_f16_f32 v5, v16, v17
	v_lshlrev_b64 v[6:7], 1, v[6:7]
	v_cndmask_b32_e32 v5, v248, v5, vcc
	v_cndmask_b32_e32 v4, v248, v4, vcc
	v_lshl_add_u64 v[16:17], s[70:71], 0, v[6:7]
	global_store_dwordx4 v[16:17], v[2:5], off
	v_lshl_add_u64 v[6:7], s[14:15], 0, v[6:7]
	s_nop 0
	v_pk_fma_f32 v[2:3], v[174:175], v[10:11], v[172:173]
	v_pk_fma_f32 v[4:5], v[176:177], v[8:9], v[170:171]
	v_pk_fma_f32 v[8:9], v[168:169], v[14:15], v[164:165]
	v_pk_fma_f32 v[10:11], v[166:167], v[12:13], v[162:163]
	v_cvt_pk_bf16_f32 v12, v4, v5
	v_cvt_pk_bf16_f32 v2, v2, v3
	v_cvt_pk_bf16_f32 v3, v10, v11
	v_cvt_pk_bf16_f32 v4, v8, v9
	v_cndmask_b32_e32 v5, v249, v4, vcc
	v_cndmask_b32_e32 v4, v249, v3, vcc
	v_cndmask_b32_e32 v3, v249, v2, vcc
	v_cndmask_b32_e32 v2, v249, v12, vcc
	global_store_dwordx4 v[6:7], v[2:5], off
	ds_read2_b64 v[2:5], v178 offset0:128 offset1:144
	v_add_u32_e32 v10, 0x40000, v0
	v_mov_b32_e32 v11, v1
	v_lshlrev_b64 v[10:11], 1, v[10:11]
	s_waitcnt lgkmcnt(0)
	v_pk_fma_f32 v[12:13], v[90:91], v[2:3], v[2:3] op_sel:[0,1,0] op_sel_hi:[1,1,0]
	v_pk_fma_f32 v[14:15], v[92:93], v[2:3], v[2:3] op_sel:[0,1,0] op_sel_hi:[1,1,0]
	v_pk_fma_f32 v[16:17], v[94:95], v[2:3], v[2:3] op_sel:[0,1,0] op_sel_hi:[1,1,0]
	v_pk_fma_f32 v[18:19], v[96:97], v[2:3], v[2:3] op_sel:[0,1,0] op_sel_hi:[1,1,0]
	v_pk_fma_f32 v[6:7], v[156:157], v[14:15], v[160:161]
	v_pk_fma_f32 v[8:9], v[154:155], v[12:13], v[158:159]
	v_pk_fma_f32 v[20:21], v[148:149], v[18:19], v[152:153]
	v_pk_fma_f32 v[22:23], v[146:147], v[16:17], v[150:151]
	v_cvt_pk_f16_f32 v8, v8, v9
	v_cvt_pk_f16_f32 v6, v6, v7
	v_cndmask_b32_e32 v7, v248, v6, vcc
	v_cndmask_b32_e32 v6, v248, v8, vcc
	v_cvt_pk_f16_f32 v8, v22, v23
	v_cvt_pk_f16_f32 v9, v20, v21
	v_cndmask_b32_e32 v9, v248, v9, vcc
	v_cndmask_b32_e32 v8, v248, v8, vcc
	v_lshl_add_u64 v[20:21], s[70:71], 0, v[10:11]
	global_store_dwordx4 v[20:21], v[6:9], off
	v_lshl_add_u64 v[10:11], s[14:15], 0, v[10:11]
	s_nop 0
	v_pk_fma_f32 v[6:7], v[190:191], v[14:15], v[188:189]
	v_pk_fma_f32 v[8:9], v[192:193], v[12:13], v[186:187]
	v_pk_fma_f32 v[12:13], v[184:185], v[18:19], v[208:209]
	v_pk_fma_f32 v[14:15], v[182:183], v[16:17], v[206:207]
	v_cvt_pk_bf16_f32 v16, v8, v9
	v_cvt_pk_bf16_f32 v6, v6, v7
	v_cvt_pk_bf16_f32 v7, v14, v15
	v_cvt_pk_bf16_f32 v8, v12, v13
	v_cndmask_b32_e32 v9, v249, v8, vcc
	v_cndmask_b32_e32 v8, v249, v7, vcc
	v_cndmask_b32_e32 v7, v249, v6, vcc
	v_cndmask_b32_e32 v6, v249, v16, vcc
	v_pk_fma_f32 v[12:13], v[82:83], v[2:3], v[2:3] op_sel:[0,1,0] op_sel_hi:[1,1,0]
	v_pk_fma_f32 v[14:15], v[84:85], v[2:3], v[2:3] op_sel:[0,1,0] op_sel_hi:[1,1,0]
	global_store_dwordx4 v[10:11], v[6:9], off
	v_pk_fma_f32 v[16:17], v[86:87], v[2:3], v[2:3] op_sel:[0,1,0] op_sel_hi:[1,1,0]
	v_pk_fma_f32 v[2:3], v[88:89], v[2:3], v[2:3] op_sel:[0,1,0] op_sel_hi:[1,1,0]
	v_pk_fma_f32 v[6:7], v[132:133], v[14:15], v[136:137]
	v_pk_fma_f32 v[8:9], v[130:131], v[12:13], v[134:135]
	v_add_u32_e32 v10, 0x40080, v0
	v_pk_fma_f32 v[18:19], v[124:125], v[2:3], v[128:129]
	v_pk_fma_f32 v[20:21], v[122:123], v[16:17], v[126:127]
	v_cvt_pk_f16_f32 v8, v8, v9
	v_cvt_pk_f16_f32 v6, v6, v7
	v_mov_b32_e32 v11, v1
	v_cndmask_b32_e32 v7, v248, v6, vcc
	v_cndmask_b32_e32 v6, v248, v8, vcc
	v_cvt_pk_f16_f32 v8, v20, v21
	v_cvt_pk_f16_f32 v9, v18, v19
	v_lshlrev_b64 v[10:11], 1, v[10:11]
	v_cndmask_b32_e32 v9, v248, v9, vcc
	v_cndmask_b32_e32 v8, v248, v8, vcc
	v_lshl_add_u64 v[18:19], s[70:71], 0, v[10:11]
	global_store_dwordx4 v[18:19], v[6:9], off
	v_pk_fma_f32 v[2:3], v[168:169], v[2:3], v[164:165]
	s_nop 0
	v_pk_fma_f32 v[6:7], v[174:175], v[14:15], v[172:173]
	v_pk_fma_f32 v[8:9], v[176:177], v[12:13], v[170:171]
	v_pk_fma_f32 v[12:13], v[166:167], v[16:17], v[162:163]
	v_cvt_pk_bf16_f32 v14, v8, v9
	v_cvt_pk_bf16_f32 v6, v6, v7
	v_cvt_pk_bf16_f32 v7, v12, v13
	v_cvt_pk_bf16_f32 v2, v2, v3
	v_cndmask_b32_e32 v9, v249, v2, vcc
	v_cndmask_b32_e32 v8, v249, v7, vcc
	v_cndmask_b32_e32 v7, v249, v6, vcc
	v_cndmask_b32_e32 v6, v249, v14, vcc
	v_lshl_add_u64 v[2:3], s[14:15], 0, v[10:11]
	v_pk_fma_f32 v[10:11], v[74:75], v[4:5], v[4:5] op_sel:[0,1,0] op_sel_hi:[1,1,0]
	v_pk_fma_f32 v[12:13], v[76:77], v[4:5], v[4:5] op_sel:[0,1,0] op_sel_hi:[1,1,0]
	global_store_dwordx4 v[2:3], v[6:9], off
	v_pk_fma_f32 v[14:15], v[78:79], v[4:5], v[4:5] op_sel:[0,1,0] op_sel_hi:[1,1,0]
	v_pk_fma_f32 v[16:17], v[80:81], v[4:5], v[4:5] op_sel:[0,1,0] op_sel_hi:[1,1,0]
	v_pk_fma_f32 v[6:7], v[156:157], v[12:13], v[160:161]
	v_pk_fma_f32 v[8:9], v[154:155], v[10:11], v[158:159]
	v_pk_fma_f32 v[18:19], v[148:149], v[16:17], v[152:153]
	v_pk_fma_f32 v[20:21], v[146:147], v[14:15], v[150:151]
	v_cvt_pk_f16_f32 v3, v8, v9
	v_cvt_pk_f16_f32 v6, v6, v7
	v_cndmask_b32_e32 v7, v248, v6, vcc
	v_cndmask_b32_e32 v6, v248, v3, vcc
	v_cvt_pk_f16_f32 v3, v20, v21
	v_cvt_pk_f16_f32 v8, v18, v19
	v_add_u32_e32 v2, 0x48000, v0
	v_cndmask_b32_e32 v9, v248, v8, vcc
	v_cndmask_b32_e32 v8, v248, v3, vcc
	v_mov_b32_e32 v3, v1
	v_lshlrev_b64 v[2:3], 1, v[2:3]
	v_lshl_add_u64 v[18:19], s[70:71], 0, v[2:3]
	global_store_dwordx4 v[18:19], v[6:9], off
	v_lshl_add_u64 v[2:3], s[14:15], 0, v[2:3]
	s_nop 0
	v_pk_fma_f32 v[6:7], v[190:191], v[12:13], v[188:189]
	v_pk_fma_f32 v[8:9], v[192:193], v[10:11], v[186:187]
	v_pk_fma_f32 v[10:11], v[184:185], v[16:17], v[208:209]
	v_pk_fma_f32 v[12:13], v[182:183], v[14:15], v[206:207]
	v_cvt_pk_bf16_f32 v14, v8, v9
	v_cvt_pk_bf16_f32 v6, v6, v7
	v_cvt_pk_bf16_f32 v7, v12, v13
	v_cvt_pk_bf16_f32 v8, v10, v11
	v_cndmask_b32_e32 v9, v249, v8, vcc
	v_cndmask_b32_e32 v8, v249, v7, vcc
	v_cndmask_b32_e32 v7, v249, v6, vcc
	v_cndmask_b32_e32 v6, v249, v14, vcc
	global_store_dwordx4 v[2:3], v[6:9], off
	v_pk_fma_f32 v[10:11], v[68:69], v[4:5], v[4:5] op_sel:[0,1,0] op_sel_hi:[1,1,0]
	v_pk_fma_f32 v[12:13], v[70:71], v[4:5], v[4:5] op_sel:[0,1,0] op_sel_hi:[1,1,0]
	v_pk_fma_f32 v[8:9], v[66:67], v[4:5], v[4:5] op_sel:[0,1,0] op_sel_hi:[1,1,0]
	v_pk_fma_f32 v[14:15], v[72:73], v[4:5], v[4:5] op_sel:[0,1,0] op_sel_hi:[1,1,0]
	v_pk_fma_f32 v[2:3], v[132:133], v[10:11], v[136:137]
	v_pk_fma_f32 v[4:5], v[130:131], v[8:9], v[134:135]
	v_add_u32_e32 v6, 0x48080, v0
	v_pk_fma_f32 v[16:17], v[124:125], v[14:15], v[128:129]
	v_pk_fma_f32 v[18:19], v[122:123], v[12:13], v[126:127]
	v_cvt_pk_f16_f32 v4, v4, v5
	v_cvt_pk_f16_f32 v2, v2, v3
	v_mov_b32_e32 v7, v1
	v_cndmask_b32_e32 v3, v248, v2, vcc
	v_cndmask_b32_e32 v2, v248, v4, vcc
	v_cvt_pk_f16_f32 v4, v18, v19
	v_cvt_pk_f16_f32 v5, v16, v17
	v_lshlrev_b64 v[6:7], 1, v[6:7]
	v_cndmask_b32_e32 v5, v248, v5, vcc
	v_cndmask_b32_e32 v4, v248, v4, vcc
	v_lshl_add_u64 v[16:17], s[70:71], 0, v[6:7]
	global_store_dwordx4 v[16:17], v[2:5], off
	v_lshl_add_u64 v[6:7], s[14:15], 0, v[6:7]
	s_nop 0
	v_pk_fma_f32 v[2:3], v[174:175], v[10:11], v[172:173]
	v_pk_fma_f32 v[4:5], v[176:177], v[8:9], v[170:171]
	v_pk_fma_f32 v[8:9], v[168:169], v[14:15], v[164:165]
	v_pk_fma_f32 v[10:11], v[166:167], v[12:13], v[162:163]
	v_cvt_pk_bf16_f32 v12, v4, v5
	v_cvt_pk_bf16_f32 v2, v2, v3
	v_cvt_pk_bf16_f32 v3, v10, v11
	v_cvt_pk_bf16_f32 v4, v8, v9
	v_cndmask_b32_e32 v5, v249, v4, vcc
	v_cndmask_b32_e32 v4, v249, v3, vcc
	v_cndmask_b32_e32 v3, v249, v2, vcc
	v_cndmask_b32_e32 v2, v249, v12, vcc
	global_store_dwordx4 v[6:7], v[2:5], off
	ds_read2_b64 v[2:5], v178 offset0:160 offset1:176
	v_add_u32_e32 v10, 0x50000, v0
	v_mov_b32_e32 v11, v1
	v_lshlrev_b64 v[10:11], 1, v[10:11]
	s_waitcnt lgkmcnt(0)
	v_pk_fma_f32 v[12:13], v[138:139], v[2:3], v[2:3] op_sel:[0,1,0] op_sel_hi:[1,1,0]
	v_pk_fma_f32 v[14:15], v[140:141], v[2:3], v[2:3] op_sel:[0,1,0] op_sel_hi:[1,1,0]
	v_pk_fma_f32 v[16:17], v[142:143], v[2:3], v[2:3] op_sel:[0,1,0] op_sel_hi:[1,1,0]
	v_pk_fma_f32 v[18:19], v[144:145], v[2:3], v[2:3] op_sel:[0,1,0] op_sel_hi:[1,1,0]
	v_pk_fma_f32 v[6:7], v[156:157], v[14:15], v[160:161]
	v_pk_fma_f32 v[8:9], v[154:155], v[12:13], v[158:159]
	v_pk_fma_f32 v[20:21], v[148:149], v[18:19], v[152:153]
	v_pk_fma_f32 v[22:23], v[146:147], v[16:17], v[150:151]
	v_cvt_pk_f16_f32 v8, v8, v9
	v_cvt_pk_f16_f32 v6, v6, v7
	v_cndmask_b32_e32 v7, v248, v6, vcc
	v_cndmask_b32_e32 v6, v248, v8, vcc
	v_cvt_pk_f16_f32 v8, v22, v23
	v_cvt_pk_f16_f32 v9, v20, v21
	v_cndmask_b32_e32 v9, v248, v9, vcc
	v_cndmask_b32_e32 v8, v248, v8, vcc
	v_lshl_add_u64 v[20:21], s[70:71], 0, v[10:11]
	global_store_dwordx4 v[20:21], v[6:9], off
	v_lshl_add_u64 v[10:11], s[14:15], 0, v[10:11]
	s_nop 0
	v_pk_fma_f32 v[6:7], v[190:191], v[14:15], v[188:189]
	v_pk_fma_f32 v[8:9], v[192:193], v[12:13], v[186:187]
	v_pk_fma_f32 v[12:13], v[184:185], v[18:19], v[208:209]
	v_pk_fma_f32 v[14:15], v[182:183], v[16:17], v[206:207]
	v_cvt_pk_bf16_f32 v16, v8, v9
	v_cvt_pk_bf16_f32 v6, v6, v7
	v_cvt_pk_bf16_f32 v7, v14, v15
	v_cvt_pk_bf16_f32 v8, v12, v13
	v_cndmask_b32_e32 v9, v249, v8, vcc
	v_cndmask_b32_e32 v8, v249, v7, vcc
	v_cndmask_b32_e32 v7, v249, v6, vcc
	v_cndmask_b32_e32 v6, v249, v16, vcc
	v_pk_fma_f32 v[12:13], v[114:115], v[2:3], v[2:3] op_sel:[0,1,0] op_sel_hi:[1,1,0]
	v_pk_fma_f32 v[14:15], v[116:117], v[2:3], v[2:3] op_sel:[0,1,0] op_sel_hi:[1,1,0]
	global_store_dwordx4 v[10:11], v[6:9], off
	v_pk_fma_f32 v[16:17], v[118:119], v[2:3], v[2:3] op_sel:[0,1,0] op_sel_hi:[1,1,0]
	v_pk_fma_f32 v[2:3], v[120:121], v[2:3], v[2:3] op_sel:[0,1,0] op_sel_hi:[1,1,0]
	v_pk_fma_f32 v[6:7], v[132:133], v[14:15], v[136:137]
	v_pk_fma_f32 v[8:9], v[130:131], v[12:13], v[134:135]
	v_add_u32_e32 v10, 0x50080, v0
	v_pk_fma_f32 v[18:19], v[124:125], v[2:3], v[128:129]
	v_pk_fma_f32 v[20:21], v[122:123], v[16:17], v[126:127]
	v_cvt_pk_f16_f32 v8, v8, v9
	v_cvt_pk_f16_f32 v6, v6, v7
	v_mov_b32_e32 v11, v1
	v_cndmask_b32_e32 v7, v248, v6, vcc
	v_cndmask_b32_e32 v6, v248, v8, vcc
	v_cvt_pk_f16_f32 v8, v20, v21
	v_cvt_pk_f16_f32 v9, v18, v19
	v_lshlrev_b64 v[10:11], 1, v[10:11]
	v_cndmask_b32_e32 v9, v248, v9, vcc
	v_cndmask_b32_e32 v8, v248, v8, vcc
	v_lshl_add_u64 v[18:19], s[70:71], 0, v[10:11]
	global_store_dwordx4 v[18:19], v[6:9], off
	v_pk_fma_f32 v[2:3], v[168:169], v[2:3], v[164:165]
	s_nop 0
	v_pk_fma_f32 v[6:7], v[174:175], v[14:15], v[172:173]
	v_pk_fma_f32 v[8:9], v[176:177], v[12:13], v[170:171]
	v_pk_fma_f32 v[12:13], v[166:167], v[16:17], v[162:163]
	v_cvt_pk_bf16_f32 v14, v8, v9
	v_cvt_pk_bf16_f32 v6, v6, v7
	v_cvt_pk_bf16_f32 v7, v12, v13
	v_cvt_pk_bf16_f32 v2, v2, v3
	v_cndmask_b32_e32 v9, v249, v2, vcc
	v_cndmask_b32_e32 v8, v249, v7, vcc
	v_cndmask_b32_e32 v7, v249, v6, vcc
	v_cndmask_b32_e32 v6, v249, v14, vcc
	v_lshl_add_u64 v[2:3], s[14:15], 0, v[10:11]
	v_pk_fma_f32 v[10:11], v[106:107], v[4:5], v[4:5] op_sel:[0,1,0] op_sel_hi:[1,1,0]
	v_pk_fma_f32 v[12:13], v[108:109], v[4:5], v[4:5] op_sel:[0,1,0] op_sel_hi:[1,1,0]
	global_store_dwordx4 v[2:3], v[6:9], off
	v_pk_fma_f32 v[14:15], v[110:111], v[4:5], v[4:5] op_sel:[0,1,0] op_sel_hi:[1,1,0]
	v_pk_fma_f32 v[16:17], v[112:113], v[4:5], v[4:5] op_sel:[0,1,0] op_sel_hi:[1,1,0]
	v_pk_fma_f32 v[6:7], v[156:157], v[12:13], v[160:161]
	v_pk_fma_f32 v[8:9], v[154:155], v[10:11], v[158:159]
	v_pk_fma_f32 v[18:19], v[148:149], v[16:17], v[152:153]
	v_pk_fma_f32 v[20:21], v[146:147], v[14:15], v[150:151]
	v_cvt_pk_f16_f32 v3, v8, v9
	v_cvt_pk_f16_f32 v6, v6, v7
	v_cndmask_b32_e32 v7, v248, v6, vcc
	v_cndmask_b32_e32 v6, v248, v3, vcc
	v_cvt_pk_f16_f32 v3, v20, v21
	v_cvt_pk_f16_f32 v8, v18, v19
	v_add_u32_e32 v2, 0x58000, v0
	v_cndmask_b32_e32 v9, v248, v8, vcc
	v_cndmask_b32_e32 v8, v248, v3, vcc
	v_mov_b32_e32 v3, v1
	v_lshlrev_b64 v[2:3], 1, v[2:3]
	v_lshl_add_u64 v[18:19], s[70:71], 0, v[2:3]
	global_store_dwordx4 v[18:19], v[6:9], off
	v_lshl_add_u64 v[2:3], s[14:15], 0, v[2:3]
	v_add_u32_e32 v0, 0x58080, v0
	v_pk_fma_f32 v[6:7], v[190:191], v[12:13], v[188:189]
	v_pk_fma_f32 v[8:9], v[192:193], v[10:11], v[186:187]
	v_pk_fma_f32 v[10:11], v[184:185], v[16:17], v[208:209]
	v_pk_fma_f32 v[12:13], v[182:183], v[14:15], v[206:207]
	v_cvt_pk_bf16_f32 v14, v8, v9
	v_cvt_pk_bf16_f32 v6, v6, v7
	v_cvt_pk_bf16_f32 v7, v12, v13
	v_cvt_pk_bf16_f32 v8, v10, v11
	v_cndmask_b32_e32 v9, v249, v8, vcc
	v_cndmask_b32_e32 v8, v249, v7, vcc
	v_cndmask_b32_e32 v7, v249, v6, vcc
	v_cndmask_b32_e32 v6, v249, v14, vcc
	global_store_dwordx4 v[2:3], v[6:9], off
	v_pk_fma_f32 v[10:11], v[102:103], v[4:5], v[4:5] op_sel:[0,1,0] op_sel_hi:[1,1,0]
	v_pk_fma_f32 v[12:13], v[104:105], v[4:5], v[4:5] op_sel:[0,1,0] op_sel_hi:[1,1,0]
	v_pk_fma_f32 v[6:7], v[98:99], v[4:5], v[4:5] op_sel:[0,1,0] op_sel_hi:[1,1,0]
	v_pk_fma_f32 v[8:9], v[100:101], v[4:5], v[4:5] op_sel:[0,1,0] op_sel_hi:[1,1,0]
	v_pk_fma_f32 v[4:5], v[130:131], v[6:7], v[134:135]
	v_pk_fma_f32 v[2:3], v[132:133], v[8:9], v[136:137]
	v_pk_fma_f32 v[14:15], v[124:125], v[12:13], v[128:129]
	v_pk_fma_f32 v[16:17], v[122:123], v[10:11], v[126:127]
	v_cvt_pk_f16_f32 v4, v4, v5
	v_cvt_pk_f16_f32 v2, v2, v3
	v_cndmask_b32_e32 v3, v248, v2, vcc
	v_cndmask_b32_e32 v2, v248, v4, vcc
	v_cvt_pk_f16_f32 v4, v16, v17
	v_cvt_pk_f16_f32 v5, v14, v15
	v_lshlrev_b64 v[14:15], 1, v[0:1]
	v_cndmask_b32_e32 v5, v248, v5, vcc
	v_cndmask_b32_e32 v4, v248, v4, vcc
	v_lshl_add_u64 v[16:17], s[70:71], 0, v[14:15]
	global_store_dwordx4 v[16:17], v[2:5], off
	s_nop 1
	v_pk_fma_f32 v[2:3], v[174:175], v[8:9], v[172:173]
	v_pk_fma_f32 v[4:5], v[176:177], v[6:7], v[170:171]
	v_pk_fma_f32 v[6:7], v[168:169], v[12:13], v[164:165]
	v_pk_fma_f32 v[8:9], v[166:167], v[10:11], v[162:163]
	v_cvt_pk_bf16_f32 v0, v4, v5
	v_cvt_pk_bf16_f32 v2, v2, v3
	v_cvt_pk_bf16_f32 v3, v8, v9
	v_cvt_pk_bf16_f32 v4, v6, v7
	v_cndmask_b32_e32 v5, v249, v4, vcc
	v_cndmask_b32_e32 v4, v249, v3, vcc
	v_cndmask_b32_e32 v3, v249, v2, vcc
	v_cndmask_b32_e32 v2, v249, v0, vcc
	v_lshl_add_u64 v[6:7], s[14:15], 0, v[14:15]
	s_mov_b64 s[14:15], -1
	s_and_b64 vcc, exec, s[36:37]
	global_store_dwordx4 v[6:7], v[2:5], off
	s_cbranch_vccnz .LBB0_869
	v_readlane_b32 s14, v255, 43
	v_readlane_b32 s15, v255, 44
	s_andn2_b64 vcc, exec, s[14:15]
	s_cbranch_vccnz .LBB0_868
	s_branch .LBB0_868

.LBB0_980:
	v_ashrrev_i32_e32 v20, 6, v16
	s_lshl_b32 s5, s11, 13
	v_lshl_add_u32 v22, v20, 10, s5
	s_lshl_b32 s5, s10, 5
	v_and_b32_e32 v17, 15, v16
	s_and_b32 s5, s5, 0x60
	s_add_i32 m0, s7, 0x18000
	v_lshl_add_u64 v[8:9], v[8:9], 0, s[2:3]
	v_lshl_or_b32 v18, s11, 6, v17
	s_lshr_b32 s11, s5, 3
	s_waitcnt vmcnt(2)
	s_barrier
	global_load_lds_dwordx4 v[8:9], off
	v_lshl_add_u64 v[6:7], v[6:7], 0, s[2:3]
	s_add_i32 m0, s7, 0x1a000
	s_add_i32 s44, s7, 0x8000
	s_add_i32 s45, s7, 0xa000
	global_load_lds_dwordx4 v[6:7], off
	v_lshl_add_u64 v[2:3], v[2:3], 0, s[2:3]
	s_mov_b32 m0, s44
	s_add_u32 s12, s22, 0x80080
	global_load_lds_dwordx4 v[2:3], off
	v_lshl_add_u64 v[2:3], v[4:5], 0, s[2:3]
	s_mov_b32 m0, s45
	s_addc_u32 s13, s23, 0
	global_load_lds_dwordx4 v[2:3], off
	s_add_i32 m0, s7, 0x1c000
	v_lshl_add_u64 v[2:3], s[12:13], 0, v[0:1]
	global_load_lds_dwordx4 v[2:3], off
	v_lshl_add_u64 v[2:3], s[12:13], 0, v[130:131]
	s_add_i32 m0, s7, 0x1e000
	v_ashrrev_i32_e32 v19, 1, v16
	global_load_lds_dwordx4 v[2:3], off
	v_lshlrev_b32_e32 v2, 15, v13
	v_and_b32_e32 v2, 0xffff0000, v2
	v_lshl_add_u32 v2, v14, 12, v2
	v_and_b32_e32 v3, 1, v13
	v_lshl_or_b32 v2, v3, 6, v2
	v_lshl_add_u32 v136, v15, 1, v2
	v_lshlrev_b32_e32 v2, 15, v10
	v_and_b32_e32 v21, 48, v16
	v_lshlrev_b32_e32 v16, 2, v16
	v_and_b32_e32 v2, 0xffff0000, v2
	v_lshl_or_b32 v17, v17, 6, v21
	v_and_b32_e32 v16, 32, v16
	s_waitcnt vmcnt(6)
	v_lshl_add_u32 v2, v11, 12, v2
	v_and_b32_e32 v3, 1, v10
	v_and_b32_e32 v19, -8, v19
	v_bitop3_b32 v21, v17, v22, v16 bitop3:0xde
	v_add_lshl_u32 v20, s11, v20, 10
	s_cmp_lt_u32 s10, 4
	v_lshl_or_b32 v2, v3, 6, v2
	v_bitop3_b32 v140, v17, v20, v16 bitop3:0xde
	s_cselect_b64 s[10:11], -1, 0
	v_add_u32_e32 v141, s5, v19
	s_ashr_i32 s46, s24, 31
	v_add_u32_e32 v142, 0xffffc000, v18
	v_mov_b32_e32 v137, v1
	v_lshl_add_u32 v138, v12, 1, v2
	v_mov_b32_e32 v139, v1
	s_mov_b32 s47, 0
	v_add_u32_e32 v143, 0, v21
	s_branch .LBB0_983

.LBB0_990:
	s_and_b64 vcc, exec, s[10:11]
	s_cbranch_vccz .Lh1_2
.Lh0_2:
	s_add_u32 s17, s36, 0xfff80080
	s_addc_u32 s22, s37, -1
	s_add_i32 s48, 0, 0x10000
	s_cmp_eq_u32 s15, 4
	s_cselect_b32 s39, s19, s22
	s_cselect_b32 s38, s18, s17
	s_cselect_b32 s23, s21, s13
	s_cselect_b32 s22, s20, s5
	s_add_i32 s17, 0, 0x14000
	v_add_u32_e32 v156, s48, v140
	v_add_u32_e32 v172, s17, v140
	ds_read_b128 v[144:147], v156
	ds_read_b128 v[148:151], v156 offset:1024
	ds_read_b128 v[152:155], v156 offset:2048
	ds_read_b128 v[156:159], v156 offset:3072
	ds_read_b128 v[160:163], v172
	ds_read_b128 v[164:167], v172 offset:1024
	ds_read_b128 v[168:171], v172 offset:2048
	ds_read_b128 v[172:175], v172 offset:3072
	v_lshl_add_u64 v[208:209], s[36:37], 0, v[136:137]
	s_add_i32 m0, s7, 0xc000
	ds_read_b128 v[176:179], v143
	ds_read_b128 v[180:183], v143 offset:1024
	ds_read_b128 v[184:187], v143 offset:2048
	ds_read_b128 v[188:191], v143 offset:3072
	ds_read_b128 v[192:195], v143 offset:4096
	ds_read_b128 v[196:199], v143 offset:5120
	ds_read_b128 v[200:203], v143 offset:6144
	ds_read_b128 v[204:207], v143 offset:7168
	global_load_lds_dwordx4 v[208:209], off
	v_lshl_add_u64 v[208:209], s[36:37], 0, v[138:139]
	s_add_i32 m0, s7, 0xe000
	s_nop 0
	global_load_lds_dwordx4 v[208:209], off
	s_waitcnt vmcnt(8)
	s_waitcnt lgkmcnt(0)
	s_barrier
	s_setprio 1
	s_waitcnt lgkmcnt(0)
	v_mfma_f32_16x16x32_bf16 v[126:129], v[144:147], v[176:179], v[126:129]
	v_mfma_f32_16x16x32_bf16 v[122:125], v[152:155], v[176:179], v[122:125]
	v_mfma_f32_16x16x32_bf16 v[118:121], v[144:147], v[184:187], v[118:121]
	v_mfma_f32_16x16x32_bf16 v[114:117], v[152:155], v[184:187], v[114:117]
	v_mfma_f32_16x16x32_bf16 v[102:105], v[144:147], v[192:195], v[102:105]
	v_mfma_f32_16x16x32_bf16 v[98:101], v[152:155], v[192:195], v[98:101]
	v_mfma_f32_16x16x32_bf16 v[86:89], v[144:147], v[200:203], v[86:89]
	v_mfma_f32_16x16x32_bf16 v[82:85], v[152:155], v[200:203], v[82:85]
	v_mfma_f32_16x16x32_bf16 v[126:129], v[148:151], v[180:183], v[126:129]
	v_mfma_f32_16x16x32_bf16 v[122:125], v[156:159], v[180:183], v[122:125]
	v_mfma_f32_16x16x32_bf16 v[118:121], v[148:151], v[188:191], v[118:121]
	v_mfma_f32_16x16x32_bf16 v[114:117], v[156:159], v[188:191], v[114:117]
	v_mfma_f32_16x16x32_bf16 v[102:105], v[148:151], v[196:199], v[102:105]
	v_mfma_f32_16x16x32_bf16 v[98:101], v[156:159], v[196:199], v[98:101]
	v_mfma_f32_16x16x32_bf16 v[86:89], v[148:151], v[204:207], v[86:89]
	v_mfma_f32_16x16x32_bf16 v[82:85], v[156:159], v[204:207], v[82:85]
	s_setprio 0
	s_setprio 1
	v_mfma_f32_16x16x32_bf16 v[110:113], v[160:163], v[176:179], v[110:113]
	v_mfma_f32_16x16x32_bf16 v[106:109], v[168:171], v[176:179], v[106:109]
	v_mfma_f32_16x16x32_bf16 v[94:97], v[160:163], v[184:187], v[94:97]
	v_mfma_f32_16x16x32_bf16 v[90:93], v[168:171], v[184:187], v[90:93]
	v_mfma_f32_16x16x32_bf16 v[78:81], v[160:163], v[192:195], v[78:81]
	v_mfma_f32_16x16x32_bf16 v[74:77], v[168:171], v[192:195], v[74:77]
	v_mfma_f32_16x16x32_bf16 v[70:73], v[160:163], v[200:203], v[70:73]
	v_mfma_f32_16x16x32_bf16 v[66:69], v[168:171], v[200:203], v[66:69]
	v_mfma_f32_16x16x32_bf16 v[110:113], v[164:167], v[180:183], v[110:113]
	v_mfma_f32_16x16x32_bf16 v[106:109], v[172:175], v[180:183], v[106:109]
	v_mfma_f32_16x16x32_bf16 v[94:97], v[164:167], v[188:191], v[94:97]
	v_mfma_f32_16x16x32_bf16 v[90:93], v[172:175], v[188:191], v[90:93]
	v_mfma_f32_16x16x32_bf16 v[78:81], v[164:167], v[196:199], v[78:81]
	v_mfma_f32_16x16x32_bf16 v[74:77], v[172:175], v[196:199], v[74:77]
	v_mfma_f32_16x16x32_bf16 v[70:73], v[164:167], v[204:207], v[70:73]
	v_mfma_f32_16x16x32_bf16 v[66:69], v[172:175], v[204:207], v[66:69]
	s_setprio 0
	s_add_i32 s48, s48, s40
	v_lshl_add_u64 v[208:209], s[22:23], 0, v[0:1]
	s_mov_b32 m0, s48
	ds_read_b128 v[176:179], v143 offset:16384
	ds_read_b128 v[180:183], v143 offset:17408
	ds_read_b128 v[184:187], v143 offset:18432
	ds_read_b128 v[188:191], v143 offset:19456
	ds_read_b128 v[192:195], v143 offset:20480
	ds_read_b128 v[196:199], v143 offset:21504
	ds_read_b128 v[200:203], v143 offset:22528
	ds_read_b128 v[204:207], v143 offset:23552
	global_load_lds_dwordx4 v[208:209], off
	s_add_i32 m0, s48, 0x2000
	s_add_u32 s48, s22, 0x80000
	v_lshl_add_u64 v[216:217], s[22:23], 0, v[130:131]
	s_addc_u32 s49, s23, 0
	s_add_i32 s17, s17, s40
	global_load_lds_dwordx4 v[216:217], off
	v_lshl_add_u64 v[220:221], s[48:49], 0, v[0:1]
	s_mov_b32 m0, s17
	v_lshl_add_u64 v[222:223], s[38:39], 0, v[132:133]
	global_load_lds_dwordx4 v[220:221], off
	v_lshl_add_u64 v[220:221], s[48:49], 0, v[130:131]
	s_add_i32 m0, s17, 0x2000
	s_nop 0
	global_load_lds_dwordx4 v[220:221], off
	v_lshl_add_u64 v[220:221], s[38:39], 0, v[134:135]
	s_mov_b32 m0, s7
	s_nop 0
	global_load_lds_dwordx4 v[220:221], off
	s_mov_b32 m0, s9
	s_nop 0
	global_load_lds_dwordx4 v[222:223], off
	s_waitcnt vmcnt(8)
	s_waitcnt lgkmcnt(0)
	s_barrier
	s_setprio 1
	s_waitcnt lgkmcnt(0)
	v_mfma_f32_16x16x32_bf16 v[62:65], v[144:147], v[176:179], v[62:65]
	v_mfma_f32_16x16x32_bf16 v[58:61], v[152:155], v[176:179], v[58:61]
	v_mfma_f32_16x16x32_bf16 v[54:57], v[144:147], v[184:187], v[54:57]
	v_mfma_f32_16x16x32_bf16 v[50:53], v[152:155], v[184:187], v[50:53]
	v_mfma_f32_16x16x32_bf16 v[38:41], v[144:147], v[192:195], v[38:41]
	v_mfma_f32_16x16x32_bf16 v[34:37], v[152:155], v[192:195], v[34:37]
	v_mfma_f32_16x16x32_bf16 v[22:25], v[144:147], v[200:203], v[22:25]
	v_mfma_f32_16x16x32_bf16 v[18:21], v[152:155], v[200:203], v[18:21]
	v_mfma_f32_16x16x32_bf16 v[62:65], v[148:151], v[180:183], v[62:65]
	v_mfma_f32_16x16x32_bf16 v[58:61], v[156:159], v[180:183], v[58:61]
	v_mfma_f32_16x16x32_bf16 v[54:57], v[148:151], v[188:191], v[54:57]
	v_mfma_f32_16x16x32_bf16 v[50:53], v[156:159], v[188:191], v[50:53]
	v_mfma_f32_16x16x32_bf16 v[38:41], v[148:151], v[196:199], v[38:41]
	v_mfma_f32_16x16x32_bf16 v[34:37], v[156:159], v[196:199], v[34:37]
	v_mfma_f32_16x16x32_bf16 v[22:25], v[148:151], v[204:207], v[22:25]
	v_mfma_f32_16x16x32_bf16 v[18:21], v[156:159], v[204:207], v[18:21]
	s_setprio 0
	s_setprio 1
	v_mfma_f32_16x16x32_bf16 v[46:49], v[160:163], v[176:179], v[46:49]
	v_mfma_f32_16x16x32_bf16 v[42:45], v[168:171], v[176:179], v[42:45]
	v_mfma_f32_16x16x32_bf16 v[30:33], v[160:163], v[184:187], v[30:33]
	v_mfma_f32_16x16x32_bf16 v[26:29], v[168:171], v[184:187], v[26:29]
	v_mfma_f32_16x16x32_bf16 v[14:17], v[160:163], v[192:195], v[14:17]
	v_mfma_f32_16x16x32_bf16 v[10:13], v[168:171], v[192:195], v[10:13]
	v_mfma_f32_16x16x32_bf16 v[6:9], v[160:163], v[200:203], v[6:9]
	v_mfma_f32_16x16x32_bf16 v[2:5], v[168:171], v[200:203], v[2:5]
	v_mfma_f32_16x16x32_bf16 v[46:49], v[164:167], v[180:183], v[46:49]
	v_mfma_f32_16x16x32_bf16 v[42:45], v[172:175], v[180:183], v[42:45]
	v_mfma_f32_16x16x32_bf16 v[30:33], v[164:167], v[188:191], v[30:33]
	v_mfma_f32_16x16x32_bf16 v[26:29], v[172:175], v[188:191], v[26:29]
	v_mfma_f32_16x16x32_bf16 v[14:17], v[164:167], v[196:199], v[14:17]
	v_mfma_f32_16x16x32_bf16 v[10:13], v[172:175], v[196:199], v[10:13]
	v_mfma_f32_16x16x32_bf16 v[6:9], v[164:167], v[204:207], v[6:9]
	v_mfma_f32_16x16x32_bf16 v[2:5], v[172:175], v[204:207], v[2:5]
	s_setprio 0
	s_add_i32 s17, 0, 0x18000
	s_add_i32 s48, 0, 0x1c000
	v_add_u32_e32 v156, s17, v140
	v_add_u32_e32 v172, s48, v140
	ds_read_b128 v[144:147], v156
	ds_read_b128 v[148:151], v156 offset:1024
	ds_read_b128 v[152:155], v156 offset:2048
	ds_read_b128 v[156:159], v156 offset:3072
	ds_read_b128 v[160:163], v172
	ds_read_b128 v[164:167], v172 offset:1024
	ds_read_b128 v[168:171], v172 offset:2048
	ds_read_b128 v[172:175], v172 offset:3072
	s_add_u32 s38, s38, 0x80000
	s_addc_u32 s39, s39, 0
	s_mov_b32 m0, s42
	v_lshl_add_u64 v[224:225], s[38:39], 0, v[134:135]
	ds_read_b128 v[176:179], v143 offset:32768
	ds_read_b128 v[180:183], v143 offset:33792
	ds_read_b128 v[184:187], v143 offset:34816
	ds_read_b128 v[188:191], v143 offset:35840
	ds_read_b128 v[192:195], v143 offset:36864
	ds_read_b128 v[196:199], v143 offset:37888
	ds_read_b128 v[200:203], v143 offset:38912
	ds_read_b128 v[204:207], v143 offset:39936
	global_load_lds_dwordx4 v[224:225], off
	v_lshl_add_u64 v[224:225], s[38:39], 0, v[132:133]
	s_mov_b32 m0, s43
	s_nop 0
	global_load_lds_dwordx4 v[224:225], off
	s_waitcnt vmcnt(8)
	s_waitcnt lgkmcnt(0)
	s_barrier
	s_setprio 1
	s_waitcnt lgkmcnt(0)
	v_mfma_f32_16x16x32_bf16 v[126:129], v[144:147], v[176:179], v[126:129]
	v_mfma_f32_16x16x32_bf16 v[122:125], v[152:155], v[176:179], v[122:125]
	v_mfma_f32_16x16x32_bf16 v[118:121], v[144:147], v[184:187], v[118:121]
	v_mfma_f32_16x16x32_bf16 v[114:117], v[152:155], v[184:187], v[114:117]
	v_mfma_f32_16x16x32_bf16 v[102:105], v[144:147], v[192:195], v[102:105]
	v_mfma_f32_16x16x32_bf16 v[98:101], v[152:155], v[192:195], v[98:101]
	v_mfma_f32_16x16x32_bf16 v[86:89], v[144:147], v[200:203], v[86:89]
	v_mfma_f32_16x16x32_bf16 v[82:85], v[152:155], v[200:203], v[82:85]
	v_mfma_f32_16x16x32_bf16 v[126:129], v[148:151], v[180:183], v[126:129]
	v_mfma_f32_16x16x32_bf16 v[122:125], v[156:159], v[180:183], v[122:125]
	v_mfma_f32_16x16x32_bf16 v[118:121], v[148:151], v[188:191], v[118:121]
	v_mfma_f32_16x16x32_bf16 v[114:117], v[156:159], v[188:191], v[114:117]
	v_mfma_f32_16x16x32_bf16 v[102:105], v[148:151], v[196:199], v[102:105]
	v_mfma_f32_16x16x32_bf16 v[98:101], v[156:159], v[196:199], v[98:101]
	v_mfma_f32_16x16x32_bf16 v[86:89], v[148:151], v[204:207], v[86:89]
	v_mfma_f32_16x16x32_bf16 v[82:85], v[156:159], v[204:207], v[82:85]
	s_setprio 0
	s_setprio 1
	v_mfma_f32_16x16x32_bf16 v[110:113], v[160:163], v[176:179], v[110:113]
	v_mfma_f32_16x16x32_bf16 v[106:109], v[168:171], v[176:179], v[106:109]
	v_mfma_f32_16x16x32_bf16 v[94:97], v[160:163], v[184:187], v[94:97]
	v_mfma_f32_16x16x32_bf16 v[90:93], v[168:171], v[184:187], v[90:93]
	v_mfma_f32_16x16x32_bf16 v[78:81], v[160:163], v[192:195], v[78:81]
	v_mfma_f32_16x16x32_bf16 v[74:77], v[168:171], v[192:195], v[74:77]
	v_mfma_f32_16x16x32_bf16 v[70:73], v[160:163], v[200:203], v[70:73]
	v_mfma_f32_16x16x32_bf16 v[66:69], v[168:171], v[200:203], v[66:69]
	v_mfma_f32_16x16x32_bf16 v[110:113], v[164:167], v[180:183], v[110:113]
	v_mfma_f32_16x16x32_bf16 v[106:109], v[172:175], v[180:183], v[106:109]
	v_mfma_f32_16x16x32_bf16 v[94:97], v[164:167], v[188:191], v[94:97]
	v_mfma_f32_16x16x32_bf16 v[90:93], v[172:175], v[188:191], v[90:93]
	v_mfma_f32_16x16x32_bf16 v[78:81], v[164:167], v[196:199], v[78:81]
	v_mfma_f32_16x16x32_bf16 v[74:77], v[172:175], v[196:199], v[74:77]
	v_mfma_f32_16x16x32_bf16 v[70:73], v[164:167], v[204:207], v[70:73]
	v_mfma_f32_16x16x32_bf16 v[66:69], v[172:175], v[204:207], v[66:69]
	s_setprio 0
	s_add_i32 s17, s17, s40
	v_lshl_add_u64 v[208:209], v[208:209], 0, s[2:3]
	s_mov_b32 m0, s17
	ds_read_b128 v[176:179], v143 offset:49152
	ds_read_b128 v[180:183], v143 offset:50176
	ds_read_b128 v[184:187], v143 offset:51200
	ds_read_b128 v[188:191], v143 offset:52224
	ds_read_b128 v[192:195], v143 offset:53248
	ds_read_b128 v[196:199], v143 offset:54272
	ds_read_b128 v[200:203], v143 offset:55296
	ds_read_b128 v[204:207], v143 offset:56320
	global_load_lds_dwordx4 v[208:209], off
	s_add_i32 m0, s17, 0x2000
	s_add_u32 s22, s22, 0x80080
	v_lshl_add_u64 v[208:209], v[216:217], 0, s[2:3]
	s_addc_u32 s23, s23, 0
	s_add_i32 s17, s48, s40
	global_load_lds_dwordx4 v[208:209], off
	v_lshl_add_u64 v[208:209], s[22:23], 0, v[0:1]
	s_mov_b32 m0, s17
	s_nop 0
	global_load_lds_dwordx4 v[208:209], off
	v_lshl_add_u64 v[208:209], s[22:23], 0, v[130:131]
	s_add_i32 m0, s17, 0x2000
	s_nop 0
	global_load_lds_dwordx4 v[208:209], off
	v_lshl_add_u64 v[208:209], v[220:221], 0, s[2:3]
	s_mov_b32 m0, s44
	s_nop 0
	global_load_lds_dwordx4 v[208:209], off
	v_lshl_add_u64 v[208:209], v[222:223], 0, s[2:3]
	s_mov_b32 m0, s45
	s_nop 0
	global_load_lds_dwordx4 v[208:209], off
	s_waitcnt vmcnt(8)
	s_waitcnt lgkmcnt(0)
	s_barrier
	s_setprio 1
	s_waitcnt lgkmcnt(0)
	v_mfma_f32_16x16x32_bf16 v[62:65], v[144:147], v[176:179], v[62:65]
	v_mfma_f32_16x16x32_bf16 v[58:61], v[152:155], v[176:179], v[58:61]
	v_mfma_f32_16x16x32_bf16 v[54:57], v[144:147], v[184:187], v[54:57]
	v_mfma_f32_16x16x32_bf16 v[50:53], v[152:155], v[184:187], v[50:53]
	v_mfma_f32_16x16x32_bf16 v[38:41], v[144:147], v[192:195], v[38:41]
	v_mfma_f32_16x16x32_bf16 v[34:37], v[152:155], v[192:195], v[34:37]
	v_mfma_f32_16x16x32_bf16 v[22:25], v[144:147], v[200:203], v[22:25]
	v_mfma_f32_16x16x32_bf16 v[18:21], v[152:155], v[200:203], v[18:21]
	v_mfma_f32_16x16x32_bf16 v[62:65], v[148:151], v[180:183], v[62:65]
	v_mfma_f32_16x16x32_bf16 v[58:61], v[156:159], v[180:183], v[58:61]
	v_mfma_f32_16x16x32_bf16 v[54:57], v[148:151], v[188:191], v[54:57]
	v_mfma_f32_16x16x32_bf16 v[50:53], v[156:159], v[188:191], v[50:53]
	v_mfma_f32_16x16x32_bf16 v[38:41], v[148:151], v[196:199], v[38:41]
	v_mfma_f32_16x16x32_bf16 v[34:37], v[156:159], v[196:199], v[34:37]
	v_mfma_f32_16x16x32_bf16 v[22:25], v[148:151], v[204:207], v[22:25]
	v_mfma_f32_16x16x32_bf16 v[18:21], v[156:159], v[204:207], v[18:21]
	s_setprio 0
	s_setprio 1
	v_mfma_f32_16x16x32_bf16 v[46:49], v[160:163], v[176:179], v[46:49]
	v_mfma_f32_16x16x32_bf16 v[42:45], v[168:171], v[176:179], v[42:45]
	v_mfma_f32_16x16x32_bf16 v[30:33], v[160:163], v[184:187], v[30:33]
	v_mfma_f32_16x16x32_bf16 v[26:29], v[168:171], v[184:187], v[26:29]
	v_mfma_f32_16x16x32_bf16 v[14:17], v[160:163], v[192:195], v[14:17]
	v_mfma_f32_16x16x32_bf16 v[10:13], v[168:171], v[192:195], v[10:13]
	v_mfma_f32_16x16x32_bf16 v[6:9], v[160:163], v[200:203], v[6:9]
	v_mfma_f32_16x16x32_bf16 v[2:5], v[168:171], v[200:203], v[2:5]
	v_mfma_f32_16x16x32_bf16 v[46:49], v[164:167], v[180:183], v[46:49]
	v_mfma_f32_16x16x32_bf16 v[42:45], v[172:175], v[180:183], v[42:45]
	v_mfma_f32_16x16x32_bf16 v[30:33], v[164:167], v[188:191], v[30:33]
	v_mfma_f32_16x16x32_bf16 v[26:29], v[172:175], v[188:191], v[26:29]
	v_mfma_f32_16x16x32_bf16 v[14:17], v[164:167], v[196:199], v[14:17]
	v_mfma_f32_16x16x32_bf16 v[10:13], v[172:175], v[196:199], v[10:13]
	v_mfma_f32_16x16x32_bf16 v[6:9], v[164:167], v[204:207], v[6:9]
	v_mfma_f32_16x16x32_bf16 v[2:5], v[172:175], v[204:207], v[2:5]
	s_setprio 0
	s_add_i32 s15, s15, 2
	s_add_u32 s36, s36, 0x100
	s_addc_u32 s37, s37, 0
	s_add_u32 s5, s5, 0x100
	s_addc_u32 s13, s13, 0
	s_cmp_gt_u32 s15, 5
	s_cbranch_scc0 .Lh0_2
	s_branch .Ldone_2
.Lh1_2:
	s_add_u32 s17, s36, 0xfff80080
	s_addc_u32 s22, s37, -1
	s_add_i32 s48, 0, 0x10000
	s_cmp_eq_u32 s15, 4
	s_cselect_b32 s39, s19, s22
	s_cselect_b32 s38, s18, s17
	s_cselect_b32 s23, s21, s13
	s_cselect_b32 s22, s20, s5
	s_add_i32 s17, 0, 0x14000
	v_add_u32_e32 v156, s48, v140
	v_add_u32_e32 v172, s17, v140
	ds_read_b128 v[144:147], v156
	ds_read_b128 v[148:151], v156 offset:1024
	ds_read_b128 v[152:155], v156 offset:2048
	ds_read_b128 v[156:159], v156 offset:3072
	ds_read_b128 v[160:163], v172
	ds_read_b128 v[164:167], v172 offset:1024
	ds_read_b128 v[168:171], v172 offset:2048
	ds_read_b128 v[172:175], v172 offset:3072
	v_lshl_add_u64 v[208:209], s[36:37], 0, v[136:137]
	s_add_i32 m0, s7, 0xc000
	ds_read_b128 v[176:179], v143
	ds_read_b128 v[180:183], v143 offset:1024
	ds_read_b128 v[184:187], v143 offset:2048
	ds_read_b128 v[188:191], v143 offset:3072
	ds_read_b128 v[192:195], v143 offset:4096
	ds_read_b128 v[196:199], v143 offset:5120
	ds_read_b128 v[200:203], v143 offset:6144
	ds_read_b128 v[204:207], v143 offset:7168
	global_load_lds_dwordx4 v[208:209], off
	v_lshl_add_u64 v[208:209], s[36:37], 0, v[138:139]
	s_add_i32 m0, s7, 0xe000
	s_nop 0
	global_load_lds_dwordx4 v[208:209], off
	s_waitcnt vmcnt(8)
	s_waitcnt lgkmcnt(0)
	s_setprio 1
	s_waitcnt lgkmcnt(0)
	v_mfma_f32_16x16x32_bf16 v[126:129], v[144:147], v[176:179], v[126:129]
	v_mfma_f32_16x16x32_bf16 v[122:125], v[152:155], v[176:179], v[122:125]
	v_mfma_f32_16x16x32_bf16 v[118:121], v[144:147], v[184:187], v[118:121]
	v_mfma_f32_16x16x32_bf16 v[114:117], v[152:155], v[184:187], v[114:117]
	v_mfma_f32_16x16x32_bf16 v[102:105], v[144:147], v[192:195], v[102:105]
	v_mfma_f32_16x16x32_bf16 v[98:101], v[152:155], v[192:195], v[98:101]
	v_mfma_f32_16x16x32_bf16 v[86:89], v[144:147], v[200:203], v[86:89]
	v_mfma_f32_16x16x32_bf16 v[82:85], v[152:155], v[200:203], v[82:85]
	v_mfma_f32_16x16x32_bf16 v[126:129], v[148:151], v[180:183], v[126:129]
	v_mfma_f32_16x16x32_bf16 v[122:125], v[156:159], v[180:183], v[122:125]
	v_mfma_f32_16x16x32_bf16 v[118:121], v[148:151], v[188:191], v[118:121]
	v_mfma_f32_16x16x32_bf16 v[114:117], v[156:159], v[188:191], v[114:117]
	v_mfma_f32_16x16x32_bf16 v[102:105], v[148:151], v[196:199], v[102:105]
	v_mfma_f32_16x16x32_bf16 v[98:101], v[156:159], v[196:199], v[98:101]
	v_mfma_f32_16x16x32_bf16 v[86:89], v[148:151], v[204:207], v[86:89]
	v_mfma_f32_16x16x32_bf16 v[82:85], v[156:159], v[204:207], v[82:85]
	s_setprio 0
	s_setprio 1
	v_mfma_f32_16x16x32_bf16 v[110:113], v[160:163], v[176:179], v[110:113]
	v_mfma_f32_16x16x32_bf16 v[106:109], v[168:171], v[176:179], v[106:109]
	v_mfma_f32_16x16x32_bf16 v[94:97], v[160:163], v[184:187], v[94:97]
	v_mfma_f32_16x16x32_bf16 v[90:93], v[168:171], v[184:187], v[90:93]
	v_mfma_f32_16x16x32_bf16 v[78:81], v[160:163], v[192:195], v[78:81]
	v_mfma_f32_16x16x32_bf16 v[74:77], v[168:171], v[192:195], v[74:77]
	v_mfma_f32_16x16x32_bf16 v[70:73], v[160:163], v[200:203], v[70:73]
	v_mfma_f32_16x16x32_bf16 v[66:69], v[168:171], v[200:203], v[66:69]
	v_mfma_f32_16x16x32_bf16 v[110:113], v[164:167], v[180:183], v[110:113]
	v_mfma_f32_16x16x32_bf16 v[106:109], v[172:175], v[180:183], v[106:109]
	v_mfma_f32_16x16x32_bf16 v[94:97], v[164:167], v[188:191], v[94:97]
	v_mfma_f32_16x16x32_bf16 v[90:93], v[172:175], v[188:191], v[90:93]
	v_mfma_f32_16x16x32_bf16 v[78:81], v[164:167], v[196:199], v[78:81]
	v_mfma_f32_16x16x32_bf16 v[74:77], v[172:175], v[196:199], v[74:77]
	v_mfma_f32_16x16x32_bf16 v[70:73], v[164:167], v[204:207], v[70:73]
	v_mfma_f32_16x16x32_bf16 v[66:69], v[172:175], v[204:207], v[66:69]
	s_setprio 0
	s_barrier
	s_add_i32 s48, s48, s40
	v_lshl_add_u64 v[208:209], s[22:23], 0, v[0:1]
	s_mov_b32 m0, s48
	ds_read_b128 v[176:179], v143 offset:16384
	ds_read_b128 v[180:183], v143 offset:17408
	ds_read_b128 v[184:187], v143 offset:18432
	ds_read_b128 v[188:191], v143 offset:19456
	ds_read_b128 v[192:195], v143 offset:20480
	ds_read_b128 v[196:199], v143 offset:21504
	ds_read_b128 v[200:203], v143 offset:22528
	ds_read_b128 v[204:207], v143 offset:23552
	global_load_lds_dwordx4 v[208:209], off
	s_add_i32 m0, s48, 0x2000
	s_add_u32 s48, s22, 0x80000
	v_lshl_add_u64 v[216:217], s[22:23], 0, v[130:131]
	s_addc_u32 s49, s23, 0
	s_add_i32 s17, s17, s40
	global_load_lds_dwordx4 v[216:217], off
	v_lshl_add_u64 v[220:221], s[48:49], 0, v[0:1]
	s_mov_b32 m0, s17
	v_lshl_add_u64 v[222:223], s[38:39], 0, v[132:133]
	global_load_lds_dwordx4 v[220:221], off
	v_lshl_add_u64 v[220:221], s[48:49], 0, v[130:131]
	s_add_i32 m0, s17, 0x2000
	s_nop 0
	global_load_lds_dwordx4 v[220:221], off
	v_lshl_add_u64 v[220:221], s[38:39], 0, v[134:135]
	s_mov_b32 m0, s7
	s_nop 0
	global_load_lds_dwordx4 v[220:221], off
	s_mov_b32 m0, s9
	s_nop 0
	global_load_lds_dwordx4 v[222:223], off
	s_waitcnt vmcnt(8)
	s_waitcnt lgkmcnt(0)
	s_setprio 1
	s_waitcnt lgkmcnt(0)
	v_mfma_f32_16x16x32_bf16 v[62:65], v[144:147], v[176:179], v[62:65]
	v_mfma_f32_16x16x32_bf16 v[58:61], v[152:155], v[176:179], v[58:61]
	v_mfma_f32_16x16x32_bf16 v[54:57], v[144:147], v[184:187], v[54:57]
	v_mfma_f32_16x16x32_bf16 v[50:53], v[152:155], v[184:187], v[50:53]
	v_mfma_f32_16x16x32_bf16 v[38:41], v[144:147], v[192:195], v[38:41]
	v_mfma_f32_16x16x32_bf16 v[34:37], v[152:155], v[192:195], v[34:37]
	v_mfma_f32_16x16x32_bf16 v[22:25], v[144:147], v[200:203], v[22:25]
	v_mfma_f32_16x16x32_bf16 v[18:21], v[152:155], v[200:203], v[18:21]
	v_mfma_f32_16x16x32_bf16 v[62:65], v[148:151], v[180:183], v[62:65]
	v_mfma_f32_16x16x32_bf16 v[58:61], v[156:159], v[180:183], v[58:61]
	v_mfma_f32_16x16x32_bf16 v[54:57], v[148:151], v[188:191], v[54:57]
	v_mfma_f32_16x16x32_bf16 v[50:53], v[156:159], v[188:191], v[50:53]
	v_mfma_f32_16x16x32_bf16 v[38:41], v[148:151], v[196:199], v[38:41]
	v_mfma_f32_16x16x32_bf16 v[34:37], v[156:159], v[196:199], v[34:37]
	v_mfma_f32_16x16x32_bf16 v[22:25], v[148:151], v[204:207], v[22:25]
	v_mfma_f32_16x16x32_bf16 v[18:21], v[156:159], v[204:207], v[18:21]
	s_setprio 0
	s_setprio 1
	v_mfma_f32_16x16x32_bf16 v[46:49], v[160:163], v[176:179], v[46:49]
	v_mfma_f32_16x16x32_bf16 v[42:45], v[168:171], v[176:179], v[42:45]
	v_mfma_f32_16x16x32_bf16 v[30:33], v[160:163], v[184:187], v[30:33]
	v_mfma_f32_16x16x32_bf16 v[26:29], v[168:171], v[184:187], v[26:29]
	v_mfma_f32_16x16x32_bf16 v[14:17], v[160:163], v[192:195], v[14:17]
	v_mfma_f32_16x16x32_bf16 v[10:13], v[168:171], v[192:195], v[10:13]
	v_mfma_f32_16x16x32_bf16 v[6:9], v[160:163], v[200:203], v[6:9]
	v_mfma_f32_16x16x32_bf16 v[2:5], v[168:171], v[200:203], v[2:5]
	v_mfma_f32_16x16x32_bf16 v[46:49], v[164:167], v[180:183], v[46:49]
	v_mfma_f32_16x16x32_bf16 v[42:45], v[172:175], v[180:183], v[42:45]
	v_mfma_f32_16x16x32_bf16 v[30:33], v[164:167], v[188:191], v[30:33]
	v_mfma_f32_16x16x32_bf16 v[26:29], v[172:175], v[188:191], v[26:29]
	v_mfma_f32_16x16x32_bf16 v[14:17], v[164:167], v[196:199], v[14:17]
	v_mfma_f32_16x16x32_bf16 v[10:13], v[172:175], v[196:199], v[10:13]
	v_mfma_f32_16x16x32_bf16 v[6:9], v[164:167], v[204:207], v[6:9]
	v_mfma_f32_16x16x32_bf16 v[2:5], v[172:175], v[204:207], v[2:5]
	s_setprio 0
	s_barrier
	s_add_i32 s17, 0, 0x18000
	s_add_i32 s48, 0, 0x1c000
	v_add_u32_e32 v156, s17, v140
	v_add_u32_e32 v172, s48, v140
	ds_read_b128 v[144:147], v156
	ds_read_b128 v[148:151], v156 offset:1024
	ds_read_b128 v[152:155], v156 offset:2048
	ds_read_b128 v[156:159], v156 offset:3072
	ds_read_b128 v[160:163], v172
	ds_read_b128 v[164:167], v172 offset:1024
	ds_read_b128 v[168:171], v172 offset:2048
	ds_read_b128 v[172:175], v172 offset:3072
	s_add_u32 s38, s38, 0x80000
	s_addc_u32 s39, s39, 0
	s_mov_b32 m0, s42
	v_lshl_add_u64 v[224:225], s[38:39], 0, v[134:135]
	ds_read_b128 v[176:179], v143 offset:32768
	ds_read_b128 v[180:183], v143 offset:33792
	ds_read_b128 v[184:187], v143 offset:34816
	ds_read_b128 v[188:191], v143 offset:35840
	ds_read_b128 v[192:195], v143 offset:36864
	ds_read_b128 v[196:199], v143 offset:37888
	ds_read_b128 v[200:203], v143 offset:38912
	ds_read_b128 v[204:207], v143 offset:39936
	global_load_lds_dwordx4 v[224:225], off
	v_lshl_add_u64 v[224:225], s[38:39], 0, v[132:133]
	s_mov_b32 m0, s43
	s_nop 0
	global_load_lds_dwordx4 v[224:225], off
	s_waitcnt vmcnt(8)
	s_waitcnt lgkmcnt(0)
	s_setprio 1
	s_waitcnt lgkmcnt(0)
	v_mfma_f32_16x16x32_bf16 v[126:129], v[144:147], v[176:179], v[126:129]
	v_mfma_f32_16x16x32_bf16 v[122:125], v[152:155], v[176:179], v[122:125]
	v_mfma_f32_16x16x32_bf16 v[118:121], v[144:147], v[184:187], v[118:121]
	v_mfma_f32_16x16x32_bf16 v[114:117], v[152:155], v[184:187], v[114:117]
	v_mfma_f32_16x16x32_bf16 v[102:105], v[144:147], v[192:195], v[102:105]
	v_mfma_f32_16x16x32_bf16 v[98:101], v[152:155], v[192:195], v[98:101]
	v_mfma_f32_16x16x32_bf16 v[86:89], v[144:147], v[200:203], v[86:89]
	v_mfma_f32_16x16x32_bf16 v[82:85], v[152:155], v[200:203], v[82:85]
	v_mfma_f32_16x16x32_bf16 v[126:129], v[148:151], v[180:183], v[126:129]
	v_mfma_f32_16x16x32_bf16 v[122:125], v[156:159], v[180:183], v[122:125]
	v_mfma_f32_16x16x32_bf16 v[118:121], v[148:151], v[188:191], v[118:121]
	v_mfma_f32_16x16x32_bf16 v[114:117], v[156:159], v[188:191], v[114:117]
	v_mfma_f32_16x16x32_bf16 v[102:105], v[148:151], v[196:199], v[102:105]
	v_mfma_f32_16x16x32_bf16 v[98:101], v[156:159], v[196:199], v[98:101]
	v_mfma_f32_16x16x32_bf16 v[86:89], v[148:151], v[204:207], v[86:89]
	v_mfma_f32_16x16x32_bf16 v[82:85], v[156:159], v[204:207], v[82:85]
	s_setprio 0
	s_setprio 1
	v_mfma_f32_16x16x32_bf16 v[110:113], v[160:163], v[176:179], v[110:113]
	v_mfma_f32_16x16x32_bf16 v[106:109], v[168:171], v[176:179], v[106:109]
	v_mfma_f32_16x16x32_bf16 v[94:97], v[160:163], v[184:187], v[94:97]
	v_mfma_f32_16x16x32_bf16 v[90:93], v[168:171], v[184:187], v[90:93]
	v_mfma_f32_16x16x32_bf16 v[78:81], v[160:163], v[192:195], v[78:81]
	v_mfma_f32_16x16x32_bf16 v[74:77], v[168:171], v[192:195], v[74:77]
	v_mfma_f32_16x16x32_bf16 v[70:73], v[160:163], v[200:203], v[70:73]
	v_mfma_f32_16x16x32_bf16 v[66:69], v[168:171], v[200:203], v[66:69]
	v_mfma_f32_16x16x32_bf16 v[110:113], v[164:167], v[180:183], v[110:113]
	v_mfma_f32_16x16x32_bf16 v[106:109], v[172:175], v[180:183], v[106:109]
	v_mfma_f32_16x16x32_bf16 v[94:97], v[164:167], v[188:191], v[94:97]
	v_mfma_f32_16x16x32_bf16 v[90:93], v[172:175], v[188:191], v[90:93]
	v_mfma_f32_16x16x32_bf16 v[78:81], v[164:167], v[196:199], v[78:81]
	v_mfma_f32_16x16x32_bf16 v[74:77], v[172:175], v[196:199], v[74:77]
	v_mfma_f32_16x16x32_bf16 v[70:73], v[164:167], v[204:207], v[70:73]
	v_mfma_f32_16x16x32_bf16 v[66:69], v[172:175], v[204:207], v[66:69]
	s_setprio 0
	s_barrier
	s_add_i32 s17, s17, s40
	v_lshl_add_u64 v[208:209], v[208:209], 0, s[2:3]
	s_mov_b32 m0, s17
	ds_read_b128 v[176:179], v143 offset:49152
	ds_read_b128 v[180:183], v143 offset:50176
	ds_read_b128 v[184:187], v143 offset:51200
	ds_read_b128 v[188:191], v143 offset:52224
	ds_read_b128 v[192:195], v143 offset:53248
	ds_read_b128 v[196:199], v143 offset:54272
	ds_read_b128 v[200:203], v143 offset:55296
	ds_read_b128 v[204:207], v143 offset:56320
	global_load_lds_dwordx4 v[208:209], off
	s_add_i32 m0, s17, 0x2000
	s_add_u32 s22, s22, 0x80080
	v_lshl_add_u64 v[208:209], v[216:217], 0, s[2:3]
	s_addc_u32 s23, s23, 0
	s_add_i32 s17, s48, s40
	global_load_lds_dwordx4 v[208:209], off
	v_lshl_add_u64 v[208:209], s[22:23], 0, v[0:1]
	s_mov_b32 m0, s17
	s_nop 0
	global_load_lds_dwordx4 v[208:209], off
	v_lshl_add_u64 v[208:209], s[22:23], 0, v[130:131]
	s_add_i32 m0, s17, 0x2000
	s_nop 0
	global_load_lds_dwordx4 v[208:209], off
	v_lshl_add_u64 v[208:209], v[220:221], 0, s[2:3]
	s_mov_b32 m0, s44
	s_nop 0
	global_load_lds_dwordx4 v[208:209], off
	v_lshl_add_u64 v[208:209], v[222:223], 0, s[2:3]
	s_mov_b32 m0, s45
	s_nop 0
	global_load_lds_dwordx4 v[208:209], off
	s_waitcnt vmcnt(8)
	s_waitcnt lgkmcnt(0)
	s_setprio 1
	s_waitcnt lgkmcnt(0)
	v_mfma_f32_16x16x32_bf16 v[62:65], v[144:147], v[176:179], v[62:65]
	v_mfma_f32_16x16x32_bf16 v[58:61], v[152:155], v[176:179], v[58:61]
	v_mfma_f32_16x16x32_bf16 v[54:57], v[144:147], v[184:187], v[54:57]
	v_mfma_f32_16x16x32_bf16 v[50:53], v[152:155], v[184:187], v[50:53]
	v_mfma_f32_16x16x32_bf16 v[38:41], v[144:147], v[192:195], v[38:41]
	v_mfma_f32_16x16x32_bf16 v[34:37], v[152:155], v[192:195], v[34:37]
	v_mfma_f32_16x16x32_bf16 v[22:25], v[144:147], v[200:203], v[22:25]
	v_mfma_f32_16x16x32_bf16 v[18:21], v[152:155], v[200:203], v[18:21]
	v_mfma_f32_16x16x32_bf16 v[62:65], v[148:151], v[180:183], v[62:65]
	v_mfma_f32_16x16x32_bf16 v[58:61], v[156:159], v[180:183], v[58:61]
	v_mfma_f32_16x16x32_bf16 v[54:57], v[148:151], v[188:191], v[54:57]
	v_mfma_f32_16x16x32_bf16 v[50:53], v[156:159], v[188:191], v[50:53]
	v_mfma_f32_16x16x32_bf16 v[38:41], v[148:151], v[196:199], v[38:41]
	v_mfma_f32_16x16x32_bf16 v[34:37], v[156:159], v[196:199], v[34:37]
	v_mfma_f32_16x16x32_bf16 v[22:25], v[148:151], v[204:207], v[22:25]
	v_mfma_f32_16x16x32_bf16 v[18:21], v[156:159], v[204:207], v[18:21]
	s_setprio 0
	s_setprio 1
	v_mfma_f32_16x16x32_bf16 v[46:49], v[160:163], v[176:179], v[46:49]
	v_mfma_f32_16x16x32_bf16 v[42:45], v[168:171], v[176:179], v[42:45]
	v_mfma_f32_16x16x32_bf16 v[30:33], v[160:163], v[184:187], v[30:33]
	v_mfma_f32_16x16x32_bf16 v[26:29], v[168:171], v[184:187], v[26:29]
	v_mfma_f32_16x16x32_bf16 v[14:17], v[160:163], v[192:195], v[14:17]
	v_mfma_f32_16x16x32_bf16 v[10:13], v[168:171], v[192:195], v[10:13]
	v_mfma_f32_16x16x32_bf16 v[6:9], v[160:163], v[200:203], v[6:9]
	v_mfma_f32_16x16x32_bf16 v[2:5], v[168:171], v[200:203], v[2:5]
	v_mfma_f32_16x16x32_bf16 v[46:49], v[164:167], v[180:183], v[46:49]
	v_mfma_f32_16x16x32_bf16 v[42:45], v[172:175], v[180:183], v[42:45]
	v_mfma_f32_16x16x32_bf16 v[30:33], v[164:167], v[188:191], v[30:33]
	v_mfma_f32_16x16x32_bf16 v[26:29], v[172:175], v[188:191], v[26:29]
	v_mfma_f32_16x16x32_bf16 v[14:17], v[164:167], v[196:199], v[14:17]
	v_mfma_f32_16x16x32_bf16 v[10:13], v[172:175], v[196:199], v[10:13]
	v_mfma_f32_16x16x32_bf16 v[6:9], v[164:167], v[204:207], v[6:9]
	v_mfma_f32_16x16x32_bf16 v[2:5], v[172:175], v[204:207], v[2:5]
	s_setprio 0
	s_barrier
	s_add_i32 s15, s15, 2
	s_add_u32 s36, s36, 0x100
	s_addc_u32 s37, s37, 0
	s_add_u32 s5, s5, 0x100
	s_addc_u32 s13, s13, 0
	s_cmp_gt_u32 s15, 5
	s_cbranch_scc0 .Lh1_2

.LBB0_993:
	s_ashr_i32 s5, s4, 31
	v_lshl_add_u32 v144, s8, 8, v141
	s_lshl_b64 s[4:5], s[4:5], 22
	v_readlane_b32 s8, v254, 40
	s_add_u32 s4, s8, s4
	v_readlane_b32 s8, v254, 41
	v_lshl_add_u32 v146, s6, 8, v142
	s_addc_u32 s5, s8, s5
	v_ashrrev_i32_e32 v145, 31, v144
	v_ashrrev_i32_e32 v147, 31, v146
	v_lshl_add_u64 v[144:145], v[144:145], 1, s[4:5]
	v_lshlrev_b64 v[148:149], 12, v[146:147]
	v_lshl_add_u64 v[148:149], v[144:145], 0, v[148:149]
	v_cvt_pk_f16_f32 v109, v108, v109
	v_cvt_pk_f16_f32 v108, v106, v107
	v_cvt_pk_f16_f32 v107, v112, v113
	v_cvt_pk_f16_f32 v106, v110, v111
	global_store_dwordx4 v[148:149], v[106:109], off offset:256
	v_cvt_pk_f16_f32 v93, v92, v93
	v_cvt_pk_f16_f32 v92, v90, v91
	v_or_b32_e32 v106, 16, v146
	v_ashrrev_i32_e32 v107, 31, v106
	v_lshlrev_b64 v[106:107], 12, v[106:107]
	v_lshl_add_u64 v[110:111], v[144:145], 0, v[106:107]
	v_cvt_pk_f16_f32 v91, v96, v97
	v_cvt_pk_f16_f32 v90, v94, v95
	global_store_dwordx4 v[110:111], v[90:93], off offset:256
	v_cvt_pk_f16_f32 v77, v76, v77
	v_cvt_pk_f16_f32 v76, v74, v75
	v_or_b32_e32 v90, 32, v146
	v_ashrrev_i32_e32 v91, 31, v90
	v_lshlrev_b64 v[90:91], 12, v[90:91]
	v_lshl_add_u64 v[94:95], v[144:145], 0, v[90:91]
	v_cvt_pk_f16_f32 v75, v80, v81
	v_cvt_pk_f16_f32 v74, v78, v79
	global_store_dwordx4 v[94:95], v[74:77], off offset:256
	v_cvt_pk_f16_f32 v69, v68, v69
	v_cvt_pk_f16_f32 v68, v66, v67
	v_or_b32_e32 v74, 48, v146
	v_ashrrev_i32_e32 v75, 31, v74
	v_lshlrev_b64 v[74:75], 12, v[74:75]
	v_lshl_add_u64 v[78:79], v[144:145], 0, v[74:75]
	v_cvt_pk_f16_f32 v67, v72, v73
	v_cvt_pk_f16_f32 v66, v70, v71
	s_mov_b64 s[4:5], 0x80000
	global_store_dwordx4 v[78:79], v[66:69], off offset:256
	v_cvt_pk_f16_f32 v61, v60, v61
	v_cvt_pk_f16_f32 v60, v58, v59
	v_lshl_add_u64 v[66:67], v[148:149], 0, s[4:5]
	v_cvt_pk_f16_f32 v58, v62, v63
	v_add_co_u32_e32 v62, vcc, s79, v148
	s_mov_b64 s[4:5], 0x90000
	s_nop 0
	v_addc_co_u32_e32 v63, vcc, 0, v149, vcc
	v_cvt_pk_f16_f32 v45, v44, v45
	v_cvt_pk_f16_f32 v44, v42, v43
	v_cvt_pk_f16_f32 v42, v46, v47
	v_lshl_add_u64 v[46:47], v[148:149], 0, s[4:5]
	s_mov_b32 s4, 0x90000
	v_cvt_pk_f16_f32 v43, v48, v49
	v_add_co_u32_e32 v48, vcc, s4, v148
	s_mov_b64 s[4:5], 0xa0000
	s_nop 0
	v_addc_co_u32_e32 v49, vcc, 0, v149, vcc
	v_cvt_pk_f16_f32 v29, v28, v29
	v_cvt_pk_f16_f32 v28, v26, v27
	v_cvt_pk_f16_f32 v26, v30, v31
	v_lshl_add_u64 v[30:31], v[148:149], 0, s[4:5]
	s_mov_b32 s4, 0xa0000
	v_cvt_pk_f16_f32 v27, v32, v33
	v_add_co_u32_e32 v32, vcc, s4, v148
	s_mov_b64 s[4:5], 0xb0000
	s_nop 0
	v_addc_co_u32_e32 v33, vcc, 0, v149, vcc
	v_cvt_pk_f16_f32 v13, v12, v13
	v_cvt_pk_f16_f32 v12, v10, v11
	v_cvt_pk_f16_f32 v10, v14, v15
	v_lshl_add_u64 v[14:15], v[148:149], 0, s[4:5]
	s_mov_b32 s4, 0xb0000
	v_cvt_pk_f16_f32 v11, v16, v17
	v_add_co_u32_e32 v16, vcc, s4, v148
	v_cvt_pk_f16_f32 v125, v124, v125
	s_nop 0
	v_addc_co_u32_e32 v17, vcc, 0, v149, vcc
	v_cvt_pk_f16_f32 v124, v122, v123
	v_cvt_pk_f16_f32 v123, v128, v129
	v_cvt_pk_f16_f32 v122, v126, v127
	v_cvt_pk_f16_f32 v109, v116, v117
	v_cvt_pk_f16_f32 v108, v114, v115
	v_cvt_pk_f16_f32 v107, v120, v121
	v_cvt_pk_f16_f32 v106, v118, v119
	v_cvt_pk_f16_f32 v93, v100, v101
	v_cvt_pk_f16_f32 v92, v98, v99
	v_cvt_pk_f16_f32 v91, v104, v105
	v_cvt_pk_f16_f32 v90, v102, v103
	v_cvt_pk_f16_f32 v77, v84, v85
	v_cvt_pk_f16_f32 v76, v82, v83
	v_cvt_pk_f16_f32 v75, v88, v89
	v_cvt_pk_f16_f32 v74, v86, v87
	v_cvt_pk_f16_f32 v59, v64, v65
	global_store_dwordx4 v[66:67], v[42:45], off offset:256
	global_store_dwordx4 v[46:47], v[26:29], off offset:256
	global_store_dwordx4 v[30:31], v[10:13], off offset:256
	v_cvt_pk_f16_f32 v45, v52, v53
	v_cvt_pk_f16_f32 v44, v50, v51
	v_cvt_pk_f16_f32 v43, v56, v57
	v_cvt_pk_f16_f32 v42, v54, v55
	v_cvt_pk_f16_f32 v29, v36, v37
	v_cvt_pk_f16_f32 v28, v34, v35
	v_cvt_pk_f16_f32 v27, v40, v41
	v_cvt_pk_f16_f32 v26, v38, v39
	v_cvt_pk_f16_f32 v13, v20, v21
	v_cvt_pk_f16_f32 v12, v18, v19
	v_cvt_pk_f16_f32 v11, v24, v25
	v_cvt_pk_f16_f32 v10, v22, v23
	v_cvt_pk_f16_f32 v5, v4, v5
	v_cvt_pk_f16_f32 v4, v2, v3
	v_cvt_pk_f16_f32 v3, v8, v9
	v_cvt_pk_f16_f32 v2, v6, v7
	s_and_b64 vcc, exec, s[34:35]
	s_mov_b64 s[4:5], -1
	global_store_dwordx4 v[148:149], v[122:125], off
	global_store_dwordx4 v[110:111], v[106:109], off
	global_store_dwordx4 v[94:95], v[90:93], off
	global_store_dwordx4 v[78:79], v[74:77], off
	global_store_dwordx4 v[62:63], v[58:61], off
	global_store_dwordx4 v[48:49], v[42:45], off
	global_store_dwordx4 v[32:33], v[26:29], off
	global_store_dwordx4 v[16:17], v[10:13], off
	global_store_dwordx4 v[14:15], v[2:5], off offset:256
	s_cbranch_vccnz .LBB0_982
	s_andn2_b64 vcc, exec, s[0:1]
	s_cbranch_vccnz .LBB0_981
	s_branch .LBB0_981

.LBB0_1193:
	v_and_b32_e32 v17, 15, v11
	v_lshl_or_b32 v170, s5, 6, v17
	v_ashrrev_i32_e32 v18, 6, v11
	s_lshl_b32 s5, s5, 13
	v_lshl_add_u32 v20, v18, 10, s5
	s_lshl_b32 s5, s4, 5
	s_and_b32 s8, s5, 0x60
	s_add_i32 m0, s17, 0x18000
	v_lshl_add_u64 v[8:9], v[8:9], 0, s[2:3]
	s_lshr_b32 s5, s8, 3
	s_waitcnt vmcnt(2)
	s_barrier
	global_load_lds_dwordx4 v[8:9], off
	v_lshl_add_u64 v[6:7], v[6:7], 0, s[2:3]
	s_add_i32 m0, s17, 0x1a000
	s_add_i32 s43, s17, 0x8000
	s_add_i32 s44, s17, 0xa000
	global_load_lds_dwordx4 v[6:7], off
	v_lshl_add_u64 v[2:3], v[2:3], 0, s[2:3]
	s_mov_b32 m0, s43
	s_add_u32 s6, s20, 0x20080
	global_load_lds_dwordx4 v[2:3], off
	v_lshl_add_u64 v[2:3], v[4:5], 0, s[2:3]
	s_mov_b32 m0, s44
	s_addc_u32 s7, s21, 0
	global_load_lds_dwordx4 v[2:3], off
	s_add_i32 m0, s17, 0x1c000
	v_lshl_add_u64 v[2:3], s[6:7], 0, v[0:1]
	global_load_lds_dwordx4 v[2:3], off
	v_lshl_add_u64 v[2:3], s[6:7], 0, v[146:147]
	s_add_i32 m0, s17, 0x1e000
	v_and_b32_e32 v19, 48, v11
	global_load_lds_dwordx4 v[2:3], off
	v_ashrrev_i32_e32 v2, 2, v11
	v_and_b32_e32 v2, -4, v2
	v_add_u32_e32 v172, s8, v2
	v_lshlrev_b32_e32 v2, 15, v14
	v_and_b32_e32 v2, 0xffff0000, v2
	v_lshl_add_u32 v2, v15, 12, v2
	v_and_b32_e32 v3, 1, v14
	v_lshl_or_b32 v2, v3, 6, v2
	v_lshl_add_u32 v152, v16, 1, v2
	v_lshlrev_b32_e32 v2, 15, v10
	v_lshl_or_b32 v17, v17, 6, v19
	v_lshlrev_b32_e32 v19, 2, v11
	v_and_b32_e32 v2, 0xffff0000, v2
	v_and_b32_e32 v19, 32, v19
	s_waitcnt vmcnt(6)
	v_lshl_add_u32 v2, v12, 12, v2
	v_and_b32_e32 v3, 1, v10
	v_bitop3_b32 v20, v17, v20, v19 bitop3:0xde
	v_add_lshl_u32 v18, s5, v18, 10
	s_cmp_lt_u32 s4, 4
	v_lshl_or_b32 v2, v3, 6, v2
	v_bitop3_b32 v171, v17, v18, v19 bitop3:0xde
	s_cselect_b64 s[4:5], -1, 0
	s_ashr_i32 s45, s24, 31
	v_mov_b32_e32 v153, v1
	v_lshl_add_u32 v154, v13, 1, v2
	v_mov_b32_e32 v155, v1
	s_mov_b32 s46, 0
	v_add_u32_e32 v173, 0, v20
	s_branch .LBB0_1196

.Lh0_3:
	s_add_u32 s20, s18, 0xfff80080
	s_addc_u32 s21, s19, -1
	s_add_i32 s47, 0, 0x10000
	s_cmp_eq_u32 s37, 4
	s_cselect_b32 s23, s11, s21
	s_cselect_b32 s22, s10, s20
	s_cselect_b32 s21, s7, s36
	s_cselect_b32 s20, s9, s15
	s_add_i32 s50, 0, 0x14000
	v_add_u32_e32 v142, s47, v171
	v_add_u32_e32 v168, s50, v171
	ds_read_b128 v[130:133], v142
	ds_read_b128 v[134:137], v142 offset:1024
	ds_read_b128 v[138:141], v142 offset:2048
	ds_read_b128 v[142:145], v142 offset:3072
	ds_read_b128 v[156:159], v168
	ds_read_b128 v[160:163], v168 offset:1024
	ds_read_b128 v[164:167], v168 offset:2048
	ds_read_b128 v[174:177], v168 offset:3072
	v_lshl_add_u64 v[168:169], s[18:19], 0, v[152:153]
	s_add_i32 m0, s17, 0xc000
	ds_read_b128 v[178:181], v173
	ds_read_b128 v[182:185], v173 offset:1024
	ds_read_b128 v[186:189], v173 offset:2048
	ds_read_b128 v[190:193], v173 offset:3072
	ds_read_b128 v[194:197], v173 offset:4096
	ds_read_b128 v[198:201], v173 offset:5120
	ds_read_b128 v[202:205], v173 offset:6144
	ds_read_b128 v[206:209], v173 offset:7168
	global_load_lds_dwordx4 v[168:169], off
	v_lshl_add_u64 v[168:169], s[18:19], 0, v[154:155]
	s_add_i32 m0, s17, 0xe000
	s_nop 0
	global_load_lds_dwordx4 v[168:169], off
	s_waitcnt vmcnt(8)
	s_waitcnt lgkmcnt(0)
	s_barrier
	s_setprio 1
	s_waitcnt lgkmcnt(0)
	v_mfma_f32_16x16x32_bf16 v[126:129], v[130:133], v[178:181], v[126:129]
	v_mfma_f32_16x16x32_bf16 v[122:125], v[138:141], v[178:181], v[122:125]
	v_mfma_f32_16x16x32_bf16 v[118:121], v[130:133], v[186:189], v[118:121]
	v_mfma_f32_16x16x32_bf16 v[106:109], v[138:141], v[186:189], v[106:109]
	v_mfma_f32_16x16x32_bf16 v[98:101], v[130:133], v[194:197], v[98:101]
	v_mfma_f32_16x16x32_bf16 v[90:93], v[138:141], v[194:197], v[90:93]
	v_mfma_f32_16x16x32_bf16 v[82:85], v[130:133], v[202:205], v[82:85]
	v_mfma_f32_16x16x32_bf16 v[74:77], v[138:141], v[202:205], v[74:77]
	v_mfma_f32_16x16x32_bf16 v[126:129], v[134:137], v[182:185], v[126:129]
	v_mfma_f32_16x16x32_bf16 v[122:125], v[142:145], v[182:185], v[122:125]
	v_mfma_f32_16x16x32_bf16 v[118:121], v[134:137], v[190:193], v[118:121]
	v_mfma_f32_16x16x32_bf16 v[106:109], v[142:145], v[190:193], v[106:109]
	v_mfma_f32_16x16x32_bf16 v[98:101], v[134:137], v[198:201], v[98:101]
	v_mfma_f32_16x16x32_bf16 v[90:93], v[142:145], v[198:201], v[90:93]
	v_mfma_f32_16x16x32_bf16 v[82:85], v[134:137], v[206:209], v[82:85]
	v_mfma_f32_16x16x32_bf16 v[74:77], v[142:145], v[206:209], v[74:77]
	s_setprio 0
	s_setprio 1
	v_mfma_f32_16x16x32_bf16 v[114:117], v[156:159], v[178:181], v[114:117]
	v_mfma_f32_16x16x32_bf16 v[110:113], v[164:167], v[178:181], v[110:113]
	v_mfma_f32_16x16x32_bf16 v[102:105], v[156:159], v[186:189], v[102:105]
	v_mfma_f32_16x16x32_bf16 v[94:97], v[164:167], v[186:189], v[94:97]
	v_mfma_f32_16x16x32_bf16 v[86:89], v[156:159], v[194:197], v[86:89]
	v_mfma_f32_16x16x32_bf16 v[78:81], v[164:167], v[194:197], v[78:81]
	v_mfma_f32_16x16x32_bf16 v[70:73], v[156:159], v[202:205], v[70:73]
	v_mfma_f32_16x16x32_bf16 v[66:69], v[164:167], v[202:205], v[66:69]
	v_mfma_f32_16x16x32_bf16 v[114:117], v[160:163], v[182:185], v[114:117]
	v_mfma_f32_16x16x32_bf16 v[110:113], v[174:177], v[182:185], v[110:113]
	v_mfma_f32_16x16x32_bf16 v[102:105], v[160:163], v[190:193], v[102:105]
	v_mfma_f32_16x16x32_bf16 v[94:97], v[174:177], v[190:193], v[94:97]
	v_mfma_f32_16x16x32_bf16 v[86:89], v[160:163], v[198:201], v[86:89]
	v_mfma_f32_16x16x32_bf16 v[78:81], v[174:177], v[198:201], v[78:81]
	v_mfma_f32_16x16x32_bf16 v[70:73], v[160:163], v[206:209], v[70:73]
	v_mfma_f32_16x16x32_bf16 v[66:69], v[174:177], v[206:209], v[66:69]
	s_setprio 0
	s_add_i32 s47, s47, s38
	v_lshl_add_u64 v[168:169], s[20:21], 0, v[0:1]
	s_mov_b32 m0, s47
	ds_read_b128 v[178:181], v173 offset:16384
	ds_read_b128 v[182:185], v173 offset:17408
	ds_read_b128 v[186:189], v173 offset:18432
	ds_read_b128 v[190:193], v173 offset:19456
	ds_read_b128 v[194:197], v173 offset:20480
	ds_read_b128 v[198:201], v173 offset:21504
	ds_read_b128 v[202:205], v173 offset:22528
	ds_read_b128 v[206:209], v173 offset:23552
	global_load_lds_dwordx4 v[168:169], off
	s_add_i32 m0, s47, 0x2000
	s_add_u32 s48, s20, 0x20000
	v_lshl_add_u64 v[216:217], s[20:21], 0, v[146:147]
	s_addc_u32 s49, s21, 0
	s_add_i32 s47, s50, s38
	global_load_lds_dwordx4 v[216:217], off
	v_lshl_add_u64 v[220:221], s[48:49], 0, v[0:1]
	s_mov_b32 m0, s47
	v_lshl_add_u64 v[222:223], s[22:23], 0, v[148:149]
	global_load_lds_dwordx4 v[220:221], off
	v_lshl_add_u64 v[220:221], s[48:49], 0, v[146:147]
	s_add_i32 m0, s47, 0x2000
	s_nop 0
	global_load_lds_dwordx4 v[220:221], off
	v_lshl_add_u64 v[220:221], s[22:23], 0, v[150:151]
	s_mov_b32 m0, s17
	s_nop 0
	global_load_lds_dwordx4 v[220:221], off
	s_mov_b32 m0, s40
	s_nop 0
	global_load_lds_dwordx4 v[222:223], off
	s_waitcnt vmcnt(8)
	s_waitcnt lgkmcnt(0)
	s_barrier
	s_setprio 1
	s_waitcnt lgkmcnt(0)
	v_mfma_f32_16x16x32_bf16 v[62:65], v[130:133], v[178:181], v[62:65]
	v_mfma_f32_16x16x32_bf16 v[58:61], v[138:141], v[178:181], v[58:61]
	v_mfma_f32_16x16x32_bf16 v[50:53], v[130:133], v[186:189], v[50:53]
	v_mfma_f32_16x16x32_bf16 v[42:45], v[138:141], v[186:189], v[42:45]
	v_mfma_f32_16x16x32_bf16 v[34:37], v[130:133], v[194:197], v[34:37]
	v_mfma_f32_16x16x32_bf16 v[26:29], v[138:141], v[194:197], v[26:29]
	v_mfma_f32_16x16x32_bf16 v[18:21], v[130:133], v[202:205], v[18:21]
	v_mfma_f32_16x16x32_bf16 v[10:13], v[138:141], v[202:205], v[10:13]
	v_mfma_f32_16x16x32_bf16 v[62:65], v[134:137], v[182:185], v[62:65]
	v_mfma_f32_16x16x32_bf16 v[58:61], v[142:145], v[182:185], v[58:61]
	v_mfma_f32_16x16x32_bf16 v[50:53], v[134:137], v[190:193], v[50:53]
	v_mfma_f32_16x16x32_bf16 v[42:45], v[142:145], v[190:193], v[42:45]
	v_mfma_f32_16x16x32_bf16 v[34:37], v[134:137], v[198:201], v[34:37]
	v_mfma_f32_16x16x32_bf16 v[26:29], v[142:145], v[198:201], v[26:29]
	v_mfma_f32_16x16x32_bf16 v[18:21], v[134:137], v[206:209], v[18:21]
	v_mfma_f32_16x16x32_bf16 v[10:13], v[142:145], v[206:209], v[10:13]
	s_setprio 0
	s_setprio 1
	v_mfma_f32_16x16x32_bf16 v[54:57], v[156:159], v[178:181], v[54:57]
	v_mfma_f32_16x16x32_bf16 v[46:49], v[164:167], v[178:181], v[46:49]
	v_mfma_f32_16x16x32_bf16 v[38:41], v[156:159], v[186:189], v[38:41]
	v_mfma_f32_16x16x32_bf16 v[30:33], v[164:167], v[186:189], v[30:33]
	v_mfma_f32_16x16x32_bf16 v[22:25], v[156:159], v[194:197], v[22:25]
	v_mfma_f32_16x16x32_bf16 v[14:17], v[164:167], v[194:197], v[14:17]
	v_mfma_f32_16x16x32_bf16 v[6:9], v[156:159], v[202:205], v[6:9]
	v_mfma_f32_16x16x32_bf16 v[2:5], v[164:167], v[202:205], v[2:5]
	v_mfma_f32_16x16x32_bf16 v[54:57], v[160:163], v[182:185], v[54:57]
	v_mfma_f32_16x16x32_bf16 v[46:49], v[174:177], v[182:185], v[46:49]
	v_mfma_f32_16x16x32_bf16 v[38:41], v[160:163], v[190:193], v[38:41]
	v_mfma_f32_16x16x32_bf16 v[30:33], v[174:177], v[190:193], v[30:33]
	v_mfma_f32_16x16x32_bf16 v[22:25], v[160:163], v[198:201], v[22:25]
	v_mfma_f32_16x16x32_bf16 v[14:17], v[174:177], v[198:201], v[14:17]
	v_mfma_f32_16x16x32_bf16 v[6:9], v[160:163], v[206:209], v[6:9]
	v_mfma_f32_16x16x32_bf16 v[2:5], v[174:177], v[206:209], v[2:5]
	s_setprio 0
	s_add_i32 s47, 0, 0x18000
	s_add_i32 s48, 0, 0x1c000
	v_add_u32_e32 v142, s47, v171
	v_add_u32_e32 v174, s48, v171
	ds_read_b128 v[130:133], v142
	ds_read_b128 v[134:137], v142 offset:1024
	ds_read_b128 v[138:141], v142 offset:2048
	ds_read_b128 v[142:145], v142 offset:3072
	ds_read_b128 v[156:159], v174
	ds_read_b128 v[160:163], v174 offset:1024
	ds_read_b128 v[164:167], v174 offset:2048
	ds_read_b128 v[174:177], v174 offset:3072
	s_add_u32 s22, s22, 0x80000
	s_addc_u32 s23, s23, 0
	s_mov_b32 m0, s41
	v_lshl_add_u64 v[224:225], s[22:23], 0, v[150:151]
	ds_read_b128 v[178:181], v173 offset:32768
	ds_read_b128 v[182:185], v173 offset:33792
	ds_read_b128 v[186:189], v173 offset:34816
	ds_read_b128 v[190:193], v173 offset:35840
	ds_read_b128 v[194:197], v173 offset:36864
	ds_read_b128 v[198:201], v173 offset:37888
	ds_read_b128 v[202:205], v173 offset:38912
	ds_read_b128 v[206:209], v173 offset:39936
	global_load_lds_dwordx4 v[224:225], off
	v_lshl_add_u64 v[224:225], s[22:23], 0, v[148:149]
	s_mov_b32 m0, s42
	s_nop 0
	global_load_lds_dwordx4 v[224:225], off
	s_waitcnt vmcnt(8)
	s_waitcnt lgkmcnt(0)
	s_barrier
	s_setprio 1
	s_waitcnt lgkmcnt(0)
	v_mfma_f32_16x16x32_bf16 v[126:129], v[130:133], v[178:181], v[126:129]
	v_mfma_f32_16x16x32_bf16 v[122:125], v[138:141], v[178:181], v[122:125]
	v_mfma_f32_16x16x32_bf16 v[118:121], v[130:133], v[186:189], v[118:121]
	v_mfma_f32_16x16x32_bf16 v[106:109], v[138:141], v[186:189], v[106:109]
	v_mfma_f32_16x16x32_bf16 v[98:101], v[130:133], v[194:197], v[98:101]
	v_mfma_f32_16x16x32_bf16 v[90:93], v[138:141], v[194:197], v[90:93]
	v_mfma_f32_16x16x32_bf16 v[82:85], v[130:133], v[202:205], v[82:85]
	v_mfma_f32_16x16x32_bf16 v[74:77], v[138:141], v[202:205], v[74:77]
	v_mfma_f32_16x16x32_bf16 v[126:129], v[134:137], v[182:185], v[126:129]
	v_mfma_f32_16x16x32_bf16 v[122:125], v[142:145], v[182:185], v[122:125]
	v_mfma_f32_16x16x32_bf16 v[118:121], v[134:137], v[190:193], v[118:121]
	v_mfma_f32_16x16x32_bf16 v[106:109], v[142:145], v[190:193], v[106:109]
	v_mfma_f32_16x16x32_bf16 v[98:101], v[134:137], v[198:201], v[98:101]
	v_mfma_f32_16x16x32_bf16 v[90:93], v[142:145], v[198:201], v[90:93]
	v_mfma_f32_16x16x32_bf16 v[82:85], v[134:137], v[206:209], v[82:85]
	v_mfma_f32_16x16x32_bf16 v[74:77], v[142:145], v[206:209], v[74:77]
	s_setprio 0
	s_setprio 1
	v_mfma_f32_16x16x32_bf16 v[114:117], v[156:159], v[178:181], v[114:117]
	v_mfma_f32_16x16x32_bf16 v[110:113], v[164:167], v[178:181], v[110:113]
	v_mfma_f32_16x16x32_bf16 v[102:105], v[156:159], v[186:189], v[102:105]
	v_mfma_f32_16x16x32_bf16 v[94:97], v[164:167], v[186:189], v[94:97]
	v_mfma_f32_16x16x32_bf16 v[86:89], v[156:159], v[194:197], v[86:89]
	v_mfma_f32_16x16x32_bf16 v[78:81], v[164:167], v[194:197], v[78:81]
	v_mfma_f32_16x16x32_bf16 v[70:73], v[156:159], v[202:205], v[70:73]
	v_mfma_f32_16x16x32_bf16 v[66:69], v[164:167], v[202:205], v[66:69]
	v_mfma_f32_16x16x32_bf16 v[114:117], v[160:163], v[182:185], v[114:117]
	v_mfma_f32_16x16x32_bf16 v[110:113], v[174:177], v[182:185], v[110:113]
	v_mfma_f32_16x16x32_bf16 v[102:105], v[160:163], v[190:193], v[102:105]
	v_mfma_f32_16x16x32_bf16 v[94:97], v[174:177], v[190:193], v[94:97]
	v_mfma_f32_16x16x32_bf16 v[86:89], v[160:163], v[198:201], v[86:89]
	v_mfma_f32_16x16x32_bf16 v[78:81], v[174:177], v[198:201], v[78:81]
	v_mfma_f32_16x16x32_bf16 v[70:73], v[160:163], v[206:209], v[70:73]
	v_mfma_f32_16x16x32_bf16 v[66:69], v[174:177], v[206:209], v[66:69]
	s_setprio 0
	s_add_i32 s22, s47, s38
	v_lshl_add_u64 v[168:169], v[168:169], 0, s[2:3]
	s_mov_b32 m0, s22
	ds_read_b128 v[178:181], v173 offset:49152
	ds_read_b128 v[182:185], v173 offset:50176
	ds_read_b128 v[186:189], v173 offset:51200
	ds_read_b128 v[190:193], v173 offset:52224
	ds_read_b128 v[194:197], v173 offset:53248
	ds_read_b128 v[198:201], v173 offset:54272
	ds_read_b128 v[202:205], v173 offset:55296
	ds_read_b128 v[206:209], v173 offset:56320
	global_load_lds_dwordx4 v[168:169], off
	s_add_i32 m0, s22, 0x2000
	s_add_u32 s20, s20, 0x20080
	v_lshl_add_u64 v[168:169], v[216:217], 0, s[2:3]
	s_addc_u32 s21, s21, 0
	s_add_i32 s22, s48, s38
	global_load_lds_dwordx4 v[168:169], off
	v_lshl_add_u64 v[168:169], s[20:21], 0, v[0:1]
	s_mov_b32 m0, s22
	s_nop 0
	global_load_lds_dwordx4 v[168:169], off
	v_lshl_add_u64 v[168:169], s[20:21], 0, v[146:147]
	s_add_i32 m0, s22, 0x2000
	s_nop 0
	global_load_lds_dwordx4 v[168:169], off
	v_lshl_add_u64 v[168:169], v[220:221], 0, s[2:3]
	s_mov_b32 m0, s43
	s_nop 0
	global_load_lds_dwordx4 v[168:169], off
	v_lshl_add_u64 v[168:169], v[222:223], 0, s[2:3]
	s_mov_b32 m0, s44
	s_nop 0
	global_load_lds_dwordx4 v[168:169], off
	s_waitcnt vmcnt(8)
	s_waitcnt lgkmcnt(0)
	s_barrier
	s_setprio 1
	s_waitcnt lgkmcnt(0)
	v_mfma_f32_16x16x32_bf16 v[62:65], v[130:133], v[178:181], v[62:65]
	v_mfma_f32_16x16x32_bf16 v[58:61], v[138:141], v[178:181], v[58:61]
	v_mfma_f32_16x16x32_bf16 v[50:53], v[130:133], v[186:189], v[50:53]
	v_mfma_f32_16x16x32_bf16 v[42:45], v[138:141], v[186:189], v[42:45]
	v_mfma_f32_16x16x32_bf16 v[34:37], v[130:133], v[194:197], v[34:37]
	v_mfma_f32_16x16x32_bf16 v[26:29], v[138:141], v[194:197], v[26:29]
	v_mfma_f32_16x16x32_bf16 v[18:21], v[130:133], v[202:205], v[18:21]
	v_mfma_f32_16x16x32_bf16 v[10:13], v[138:141], v[202:205], v[10:13]
	v_mfma_f32_16x16x32_bf16 v[62:65], v[134:137], v[182:185], v[62:65]
	v_mfma_f32_16x16x32_bf16 v[58:61], v[142:145], v[182:185], v[58:61]
	v_mfma_f32_16x16x32_bf16 v[50:53], v[134:137], v[190:193], v[50:53]
	v_mfma_f32_16x16x32_bf16 v[42:45], v[142:145], v[190:193], v[42:45]
	v_mfma_f32_16x16x32_bf16 v[34:37], v[134:137], v[198:201], v[34:37]
	v_mfma_f32_16x16x32_bf16 v[26:29], v[142:145], v[198:201], v[26:29]
	v_mfma_f32_16x16x32_bf16 v[18:21], v[134:137], v[206:209], v[18:21]
	v_mfma_f32_16x16x32_bf16 v[10:13], v[142:145], v[206:209], v[10:13]
	s_setprio 0
	s_setprio 1
	v_mfma_f32_16x16x32_bf16 v[54:57], v[156:159], v[178:181], v[54:57]
	v_mfma_f32_16x16x32_bf16 v[46:49], v[164:167], v[178:181], v[46:49]
	v_mfma_f32_16x16x32_bf16 v[38:41], v[156:159], v[186:189], v[38:41]
	v_mfma_f32_16x16x32_bf16 v[30:33], v[164:167], v[186:189], v[30:33]
	v_mfma_f32_16x16x32_bf16 v[22:25], v[156:159], v[194:197], v[22:25]
	v_mfma_f32_16x16x32_bf16 v[14:17], v[164:167], v[194:197], v[14:17]
	v_mfma_f32_16x16x32_bf16 v[6:9], v[156:159], v[202:205], v[6:9]
	v_mfma_f32_16x16x32_bf16 v[2:5], v[164:167], v[202:205], v[2:5]
	v_mfma_f32_16x16x32_bf16 v[54:57], v[160:163], v[182:185], v[54:57]
	v_mfma_f32_16x16x32_bf16 v[46:49], v[174:177], v[182:185], v[46:49]
	v_mfma_f32_16x16x32_bf16 v[38:41], v[160:163], v[190:193], v[38:41]
	v_mfma_f32_16x16x32_bf16 v[30:33], v[174:177], v[190:193], v[30:33]
	v_mfma_f32_16x16x32_bf16 v[22:25], v[160:163], v[198:201], v[22:25]
	v_mfma_f32_16x16x32_bf16 v[14:17], v[174:177], v[198:201], v[14:17]
	v_mfma_f32_16x16x32_bf16 v[6:9], v[160:163], v[206:209], v[6:9]
	v_mfma_f32_16x16x32_bf16 v[2:5], v[174:177], v[206:209], v[2:5]
	s_setprio 0
	s_add_i32 s37, s37, 2
	s_add_u32 s18, s18, 0x100
	s_addc_u32 s19, s19, 0
	s_add_u32 s15, s15, 0x100
	s_addc_u32 s36, s36, 0
	s_cmp_gt_u32 s37, 5
	s_cbranch_scc0 .Lh0_3
	s_branch .Ldone_3
.Lh1_3:
	s_add_u32 s20, s18, 0xfff80080
	s_addc_u32 s21, s19, -1
	s_add_i32 s47, 0, 0x10000
	s_cmp_eq_u32 s37, 4
	s_cselect_b32 s23, s11, s21
	s_cselect_b32 s22, s10, s20
	s_cselect_b32 s21, s7, s36
	s_cselect_b32 s20, s9, s15
	s_add_i32 s50, 0, 0x14000
	v_add_u32_e32 v142, s47, v171
	v_add_u32_e32 v168, s50, v171
	ds_read_b128 v[130:133], v142
	ds_read_b128 v[134:137], v142 offset:1024
	ds_read_b128 v[138:141], v142 offset:2048
	ds_read_b128 v[142:145], v142 offset:3072
	ds_read_b128 v[156:159], v168
	ds_read_b128 v[160:163], v168 offset:1024
	ds_read_b128 v[164:167], v168 offset:2048
	ds_read_b128 v[174:177], v168 offset:3072
	v_lshl_add_u64 v[168:169], s[18:19], 0, v[152:153]
	s_add_i32 m0, s17, 0xc000
	ds_read_b128 v[178:181], v173
	ds_read_b128 v[182:185], v173 offset:1024
	ds_read_b128 v[186:189], v173 offset:2048
	ds_read_b128 v[190:193], v173 offset:3072
	ds_read_b128 v[194:197], v173 offset:4096
	ds_read_b128 v[198:201], v173 offset:5120
	ds_read_b128 v[202:205], v173 offset:6144
	ds_read_b128 v[206:209], v173 offset:7168
	global_load_lds_dwordx4 v[168:169], off
	v_lshl_add_u64 v[168:169], s[18:19], 0, v[154:155]
	s_add_i32 m0, s17, 0xe000
	s_nop 0
	global_load_lds_dwordx4 v[168:169], off
	s_waitcnt vmcnt(8)
	s_waitcnt lgkmcnt(0)
	s_setprio 1
	s_waitcnt lgkmcnt(0)
	v_mfma_f32_16x16x32_bf16 v[126:129], v[130:133], v[178:181], v[126:129]
	v_mfma_f32_16x16x32_bf16 v[122:125], v[138:141], v[178:181], v[122:125]
	v_mfma_f32_16x16x32_bf16 v[118:121], v[130:133], v[186:189], v[118:121]
	v_mfma_f32_16x16x32_bf16 v[106:109], v[138:141], v[186:189], v[106:109]
	v_mfma_f32_16x16x32_bf16 v[98:101], v[130:133], v[194:197], v[98:101]
	v_mfma_f32_16x16x32_bf16 v[90:93], v[138:141], v[194:197], v[90:93]
	v_mfma_f32_16x16x32_bf16 v[82:85], v[130:133], v[202:205], v[82:85]
	v_mfma_f32_16x16x32_bf16 v[74:77], v[138:141], v[202:205], v[74:77]
	v_mfma_f32_16x16x32_bf16 v[126:129], v[134:137], v[182:185], v[126:129]
	v_mfma_f32_16x16x32_bf16 v[122:125], v[142:145], v[182:185], v[122:125]
	v_mfma_f32_16x16x32_bf16 v[118:121], v[134:137], v[190:193], v[118:121]
	v_mfma_f32_16x16x32_bf16 v[106:109], v[142:145], v[190:193], v[106:109]
	v_mfma_f32_16x16x32_bf16 v[98:101], v[134:137], v[198:201], v[98:101]
	v_mfma_f32_16x16x32_bf16 v[90:93], v[142:145], v[198:201], v[90:93]
	v_mfma_f32_16x16x32_bf16 v[82:85], v[134:137], v[206:209], v[82:85]
	v_mfma_f32_16x16x32_bf16 v[74:77], v[142:145], v[206:209], v[74:77]
	s_setprio 0
	s_setprio 1
	v_mfma_f32_16x16x32_bf16 v[114:117], v[156:159], v[178:181], v[114:117]
	v_mfma_f32_16x16x32_bf16 v[110:113], v[164:167], v[178:181], v[110:113]
	v_mfma_f32_16x16x32_bf16 v[102:105], v[156:159], v[186:189], v[102:105]
	v_mfma_f32_16x16x32_bf16 v[94:97], v[164:167], v[186:189], v[94:97]
	v_mfma_f32_16x16x32_bf16 v[86:89], v[156:159], v[194:197], v[86:89]
	v_mfma_f32_16x16x32_bf16 v[78:81], v[164:167], v[194:197], v[78:81]
	v_mfma_f32_16x16x32_bf16 v[70:73], v[156:159], v[202:205], v[70:73]
	v_mfma_f32_16x16x32_bf16 v[66:69], v[164:167], v[202:205], v[66:69]
	v_mfma_f32_16x16x32_bf16 v[114:117], v[160:163], v[182:185], v[114:117]
	v_mfma_f32_16x16x32_bf16 v[110:113], v[174:177], v[182:185], v[110:113]
	v_mfma_f32_16x16x32_bf16 v[102:105], v[160:163], v[190:193], v[102:105]
	v_mfma_f32_16x16x32_bf16 v[94:97], v[174:177], v[190:193], v[94:97]
	v_mfma_f32_16x16x32_bf16 v[86:89], v[160:163], v[198:201], v[86:89]
	v_mfma_f32_16x16x32_bf16 v[78:81], v[174:177], v[198:201], v[78:81]
	v_mfma_f32_16x16x32_bf16 v[70:73], v[160:163], v[206:209], v[70:73]
	v_mfma_f32_16x16x32_bf16 v[66:69], v[174:177], v[206:209], v[66:69]
	s_setprio 0
	s_barrier
	s_add_i32 s47, s47, s38
	v_lshl_add_u64 v[168:169], s[20:21], 0, v[0:1]
	s_mov_b32 m0, s47
	ds_read_b128 v[178:181], v173 offset:16384
	ds_read_b128 v[182:185], v173 offset:17408
	ds_read_b128 v[186:189], v173 offset:18432
	ds_read_b128 v[190:193], v173 offset:19456
	ds_read_b128 v[194:197], v173 offset:20480
	ds_read_b128 v[198:201], v173 offset:21504
	ds_read_b128 v[202:205], v173 offset:22528
	ds_read_b128 v[206:209], v173 offset:23552
	global_load_lds_dwordx4 v[168:169], off
	s_add_i32 m0, s47, 0x2000
	s_add_u32 s48, s20, 0x20000
	v_lshl_add_u64 v[216:217], s[20:21], 0, v[146:147]
	s_addc_u32 s49, s21, 0
	s_add_i32 s47, s50, s38
	global_load_lds_dwordx4 v[216:217], off
	v_lshl_add_u64 v[220:221], s[48:49], 0, v[0:1]
	s_mov_b32 m0, s47
	v_lshl_add_u64 v[222:223], s[22:23], 0, v[148:149]
	global_load_lds_dwordx4 v[220:221], off
	v_lshl_add_u64 v[220:221], s[48:49], 0, v[146:147]
	s_add_i32 m0, s47, 0x2000
	s_nop 0
	global_load_lds_dwordx4 v[220:221], off
	v_lshl_add_u64 v[220:221], s[22:23], 0, v[150:151]
	s_mov_b32 m0, s17
	s_nop 0
	global_load_lds_dwordx4 v[220:221], off
	s_mov_b32 m0, s40
	s_nop 0
	global_load_lds_dwordx4 v[222:223], off
	s_waitcnt vmcnt(8)
	s_waitcnt lgkmcnt(0)
	s_setprio 1
	s_waitcnt lgkmcnt(0)
	v_mfma_f32_16x16x32_bf16 v[62:65], v[130:133], v[178:181], v[62:65]
	v_mfma_f32_16x16x32_bf16 v[58:61], v[138:141], v[178:181], v[58:61]
	v_mfma_f32_16x16x32_bf16 v[50:53], v[130:133], v[186:189], v[50:53]
	v_mfma_f32_16x16x32_bf16 v[42:45], v[138:141], v[186:189], v[42:45]
	v_mfma_f32_16x16x32_bf16 v[34:37], v[130:133], v[194:197], v[34:37]
	v_mfma_f32_16x16x32_bf16 v[26:29], v[138:141], v[194:197], v[26:29]
	v_mfma_f32_16x16x32_bf16 v[18:21], v[130:133], v[202:205], v[18:21]
	v_mfma_f32_16x16x32_bf16 v[10:13], v[138:141], v[202:205], v[10:13]
	v_mfma_f32_16x16x32_bf16 v[62:65], v[134:137], v[182:185], v[62:65]
	v_mfma_f32_16x16x32_bf16 v[58:61], v[142:145], v[182:185], v[58:61]
	v_mfma_f32_16x16x32_bf16 v[50:53], v[134:137], v[190:193], v[50:53]
	v_mfma_f32_16x16x32_bf16 v[42:45], v[142:145], v[190:193], v[42:45]
	v_mfma_f32_16x16x32_bf16 v[34:37], v[134:137], v[198:201], v[34:37]
	v_mfma_f32_16x16x32_bf16 v[26:29], v[142:145], v[198:201], v[26:29]
	v_mfma_f32_16x16x32_bf16 v[18:21], v[134:137], v[206:209], v[18:21]
	v_mfma_f32_16x16x32_bf16 v[10:13], v[142:145], v[206:209], v[10:13]
	s_setprio 0
	s_setprio 1
	v_mfma_f32_16x16x32_bf16 v[54:57], v[156:159], v[178:181], v[54:57]
	v_mfma_f32_16x16x32_bf16 v[46:49], v[164:167], v[178:181], v[46:49]
	v_mfma_f32_16x16x32_bf16 v[38:41], v[156:159], v[186:189], v[38:41]
	v_mfma_f32_16x16x32_bf16 v[30:33], v[164:167], v[186:189], v[30:33]
	v_mfma_f32_16x16x32_bf16 v[22:25], v[156:159], v[194:197], v[22:25]
	v_mfma_f32_16x16x32_bf16 v[14:17], v[164:167], v[194:197], v[14:17]
	v_mfma_f32_16x16x32_bf16 v[6:9], v[156:159], v[202:205], v[6:9]
	v_mfma_f32_16x16x32_bf16 v[2:5], v[164:167], v[202:205], v[2:5]
	v_mfma_f32_16x16x32_bf16 v[54:57], v[160:163], v[182:185], v[54:57]
	v_mfma_f32_16x16x32_bf16 v[46:49], v[174:177], v[182:185], v[46:49]
	v_mfma_f32_16x16x32_bf16 v[38:41], v[160:163], v[190:193], v[38:41]
	v_mfma_f32_16x16x32_bf16 v[30:33], v[174:177], v[190:193], v[30:33]
	v_mfma_f32_16x16x32_bf16 v[22:25], v[160:163], v[198:201], v[22:25]
	v_mfma_f32_16x16x32_bf16 v[14:17], v[174:177], v[198:201], v[14:17]
	v_mfma_f32_16x16x32_bf16 v[6:9], v[160:163], v[206:209], v[6:9]
	v_mfma_f32_16x16x32_bf16 v[2:5], v[174:177], v[206:209], v[2:5]
	s_setprio 0
	s_barrier
	s_add_i32 s47, 0, 0x18000
	s_add_i32 s48, 0, 0x1c000
	v_add_u32_e32 v142, s47, v171
	v_add_u32_e32 v174, s48, v171
	ds_read_b128 v[130:133], v142
	ds_read_b128 v[134:137], v142 offset:1024
	ds_read_b128 v[138:141], v142 offset:2048
	ds_read_b128 v[142:145], v142 offset:3072
	ds_read_b128 v[156:159], v174
	ds_read_b128 v[160:163], v174 offset:1024
	ds_read_b128 v[164:167], v174 offset:2048
	ds_read_b128 v[174:177], v174 offset:3072
	s_add_u32 s22, s22, 0x80000
	s_addc_u32 s23, s23, 0
	s_mov_b32 m0, s41
	v_lshl_add_u64 v[224:225], s[22:23], 0, v[150:151]
	ds_read_b128 v[178:181], v173 offset:32768
	ds_read_b128 v[182:185], v173 offset:33792
	ds_read_b128 v[186:189], v173 offset:34816
	ds_read_b128 v[190:193], v173 offset:35840
	ds_read_b128 v[194:197], v173 offset:36864
	ds_read_b128 v[198:201], v173 offset:37888
	ds_read_b128 v[202:205], v173 offset:38912
	ds_read_b128 v[206:209], v173 offset:39936
	global_load_lds_dwordx4 v[224:225], off
	v_lshl_add_u64 v[224:225], s[22:23], 0, v[148:149]
	s_mov_b32 m0, s42
	s_nop 0
	global_load_lds_dwordx4 v[224:225], off
	s_waitcnt vmcnt(8)
	s_waitcnt lgkmcnt(0)
	s_setprio 1
	s_waitcnt lgkmcnt(0)
	v_mfma_f32_16x16x32_bf16 v[126:129], v[130:133], v[178:181], v[126:129]
	v_mfma_f32_16x16x32_bf16 v[122:125], v[138:141], v[178:181], v[122:125]
	v_mfma_f32_16x16x32_bf16 v[118:121], v[130:133], v[186:189], v[118:121]
	v_mfma_f32_16x16x32_bf16 v[106:109], v[138:141], v[186:189], v[106:109]
	v_mfma_f32_16x16x32_bf16 v[98:101], v[130:133], v[194:197], v[98:101]
	v_mfma_f32_16x16x32_bf16 v[90:93], v[138:141], v[194:197], v[90:93]
	v_mfma_f32_16x16x32_bf16 v[82:85], v[130:133], v[202:205], v[82:85]
	v_mfma_f32_16x16x32_bf16 v[74:77], v[138:141], v[202:205], v[74:77]
	v_mfma_f32_16x16x32_bf16 v[126:129], v[134:137], v[182:185], v[126:129]
	v_mfma_f32_16x16x32_bf16 v[122:125], v[142:145], v[182:185], v[122:125]
	v_mfma_f32_16x16x32_bf16 v[118:121], v[134:137], v[190:193], v[118:121]
	v_mfma_f32_16x16x32_bf16 v[106:109], v[142:145], v[190:193], v[106:109]
	v_mfma_f32_16x16x32_bf16 v[98:101], v[134:137], v[198:201], v[98:101]
	v_mfma_f32_16x16x32_bf16 v[90:93], v[142:145], v[198:201], v[90:93]
	v_mfma_f32_16x16x32_bf16 v[82:85], v[134:137], v[206:209], v[82:85]
	v_mfma_f32_16x16x32_bf16 v[74:77], v[142:145], v[206:209], v[74:77]
	s_setprio 0
	s_setprio 1
	v_mfma_f32_16x16x32_bf16 v[114:117], v[156:159], v[178:181], v[114:117]
	v_mfma_f32_16x16x32_bf16 v[110:113], v[164:167], v[178:181], v[110:113]
	v_mfma_f32_16x16x32_bf16 v[102:105], v[156:159], v[186:189], v[102:105]
	v_mfma_f32_16x16x32_bf16 v[94:97], v[164:167], v[186:189], v[94:97]
	v_mfma_f32_16x16x32_bf16 v[86:89], v[156:159], v[194:197], v[86:89]
	v_mfma_f32_16x16x32_bf16 v[78:81], v[164:167], v[194:197], v[78:81]
	v_mfma_f32_16x16x32_bf16 v[70:73], v[156:159], v[202:205], v[70:73]
	v_mfma_f32_16x16x32_bf16 v[66:69], v[164:167], v[202:205], v[66:69]
	v_mfma_f32_16x16x32_bf16 v[114:117], v[160:163], v[182:185], v[114:117]
	v_mfma_f32_16x16x32_bf16 v[110:113], v[174:177], v[182:185], v[110:113]
	v_mfma_f32_16x16x32_bf16 v[102:105], v[160:163], v[190:193], v[102:105]
	v_mfma_f32_16x16x32_bf16 v[94:97], v[174:177], v[190:193], v[94:97]
	v_mfma_f32_16x16x32_bf16 v[86:89], v[160:163], v[198:201], v[86:89]
	v_mfma_f32_16x16x32_bf16 v[78:81], v[174:177], v[198:201], v[78:81]
	v_mfma_f32_16x16x32_bf16 v[70:73], v[160:163], v[206:209], v[70:73]
	v_mfma_f32_16x16x32_bf16 v[66:69], v[174:177], v[206:209], v[66:69]
	s_setprio 0
	s_barrier
	s_add_i32 s22, s47, s38
	v_lshl_add_u64 v[168:169], v[168:169], 0, s[2:3]
	s_mov_b32 m0, s22
	ds_read_b128 v[178:181], v173 offset:49152
	ds_read_b128 v[182:185], v173 offset:50176
	ds_read_b128 v[186:189], v173 offset:51200
	ds_read_b128 v[190:193], v173 offset:52224
	ds_read_b128 v[194:197], v173 offset:53248
	ds_read_b128 v[198:201], v173 offset:54272
	ds_read_b128 v[202:205], v173 offset:55296
	ds_read_b128 v[206:209], v173 offset:56320
	global_load_lds_dwordx4 v[168:169], off
	s_add_i32 m0, s22, 0x2000
	s_add_u32 s20, s20, 0x20080
	v_lshl_add_u64 v[168:169], v[216:217], 0, s[2:3]
	s_addc_u32 s21, s21, 0
	s_add_i32 s22, s48, s38
	global_load_lds_dwordx4 v[168:169], off
	v_lshl_add_u64 v[168:169], s[20:21], 0, v[0:1]
	s_mov_b32 m0, s22
	s_nop 0
	global_load_lds_dwordx4 v[168:169], off
	v_lshl_add_u64 v[168:169], s[20:21], 0, v[146:147]
	s_add_i32 m0, s22, 0x2000
	s_nop 0
	global_load_lds_dwordx4 v[168:169], off
	v_lshl_add_u64 v[168:169], v[220:221], 0, s[2:3]
	s_mov_b32 m0, s43
	s_nop 0
	global_load_lds_dwordx4 v[168:169], off
	v_lshl_add_u64 v[168:169], v[222:223], 0, s[2:3]
	s_mov_b32 m0, s44
	s_nop 0
	global_load_lds_dwordx4 v[168:169], off
	s_waitcnt vmcnt(8)
	s_waitcnt lgkmcnt(0)
	s_setprio 1
	s_waitcnt lgkmcnt(0)
	v_mfma_f32_16x16x32_bf16 v[62:65], v[130:133], v[178:181], v[62:65]
	v_mfma_f32_16x16x32_bf16 v[58:61], v[138:141], v[178:181], v[58:61]
	v_mfma_f32_16x16x32_bf16 v[50:53], v[130:133], v[186:189], v[50:53]
	v_mfma_f32_16x16x32_bf16 v[42:45], v[138:141], v[186:189], v[42:45]
	v_mfma_f32_16x16x32_bf16 v[34:37], v[130:133], v[194:197], v[34:37]
	v_mfma_f32_16x16x32_bf16 v[26:29], v[138:141], v[194:197], v[26:29]
	v_mfma_f32_16x16x32_bf16 v[18:21], v[130:133], v[202:205], v[18:21]
	v_mfma_f32_16x16x32_bf16 v[10:13], v[138:141], v[202:205], v[10:13]
	v_mfma_f32_16x16x32_bf16 v[62:65], v[134:137], v[182:185], v[62:65]
	v_mfma_f32_16x16x32_bf16 v[58:61], v[142:145], v[182:185], v[58:61]
	v_mfma_f32_16x16x32_bf16 v[50:53], v[134:137], v[190:193], v[50:53]
	v_mfma_f32_16x16x32_bf16 v[42:45], v[142:145], v[190:193], v[42:45]
	v_mfma_f32_16x16x32_bf16 v[34:37], v[134:137], v[198:201], v[34:37]
	v_mfma_f32_16x16x32_bf16 v[26:29], v[142:145], v[198:201], v[26:29]
	v_mfma_f32_16x16x32_bf16 v[18:21], v[134:137], v[206:209], v[18:21]
	v_mfma_f32_16x16x32_bf16 v[10:13], v[142:145], v[206:209], v[10:13]
	s_setprio 0
	s_setprio 1
	v_mfma_f32_16x16x32_bf16 v[54:57], v[156:159], v[178:181], v[54:57]
	v_mfma_f32_16x16x32_bf16 v[46:49], v[164:167], v[178:181], v[46:49]
	v_mfma_f32_16x16x32_bf16 v[38:41], v[156:159], v[186:189], v[38:41]
	v_mfma_f32_16x16x32_bf16 v[30:33], v[164:167], v[186:189], v[30:33]
	v_mfma_f32_16x16x32_bf16 v[22:25], v[156:159], v[194:197], v[22:25]
	v_mfma_f32_16x16x32_bf16 v[14:17], v[164:167], v[194:197], v[14:17]
	v_mfma_f32_16x16x32_bf16 v[6:9], v[156:159], v[202:205], v[6:9]
	v_mfma_f32_16x16x32_bf16 v[2:5], v[164:167], v[202:205], v[2:5]
	v_mfma_f32_16x16x32_bf16 v[54:57], v[160:163], v[182:185], v[54:57]
	v_mfma_f32_16x16x32_bf16 v[46:49], v[174:177], v[182:185], v[46:49]
	v_mfma_f32_16x16x32_bf16 v[38:41], v[160:163], v[190:193], v[38:41]
	v_mfma_f32_16x16x32_bf16 v[30:33], v[174:177], v[190:193], v[30:33]
	v_mfma_f32_16x16x32_bf16 v[22:25], v[160:163], v[198:201], v[22:25]
	v_mfma_f32_16x16x32_bf16 v[14:17], v[174:177], v[198:201], v[14:17]
	v_mfma_f32_16x16x32_bf16 v[6:9], v[160:163], v[206:209], v[6:9]
	v_mfma_f32_16x16x32_bf16 v[2:5], v[174:177], v[206:209], v[2:5]
	s_setprio 0
	s_barrier
	s_add_i32 s37, s37, 2
	s_add_u32 s18, s18, 0x100
	s_addc_u32 s19, s19, 0
	s_add_u32 s15, s15, 0x100
	s_addc_u32 s36, s36, 0
	s_cmp_gt_u32 s37, 5
	s_cbranch_scc0 .Lh1_3

.LBB0_1212:
	v_lshl_add_u32 v162, s14, 8, v170
	v_lshlrev_b64 v[156:157], 1, v[156:157]
	v_ashrrev_i32_e32 v163, 31, v162
	v_lshl_add_u64 v[158:159], s[70:71], 0, v[156:157]
	v_lshlrev_b64 v[160:161], 12, v[162:163]
	v_or_b32_e32 v166, 16, v162
	v_lshl_add_u64 v[164:165], v[158:159], 0, v[160:161]
	v_ashrrev_i32_e32 v167, 31, v166
	global_load_dwordx2 v[174:175], v[164:165], off
	global_load_dwordx2 v[176:177], v[164:165], off offset:32
	global_load_dwordx2 v[178:179], v[164:165], off offset:256
	global_load_dwordx2 v[180:181], v[164:165], off offset:288
	v_lshlrev_b64 v[164:165], 12, v[166:167]
	v_lshl_add_u64 v[166:167], v[158:159], 0, v[164:165]
	global_load_dwordx2 v[182:183], v[166:167], off
	global_load_dwordx2 v[184:185], v[166:167], off offset:32
	global_load_dwordx2 v[188:189], v[166:167], off offset:256
	v_or_b32_e32 v168, 32, v162
	v_or_b32_e32 v162, 48, v162
	v_ashrrev_i32_e32 v169, 31, v168
	v_ashrrev_i32_e32 v163, 31, v162
	v_lshlrev_b64 v[186:187], 12, v[168:169]
	v_lshlrev_b64 v[162:163], 12, v[162:163]
	v_lshl_add_u64 v[168:169], s[70:71], 0, v[160:161]
	v_lshl_add_u64 v[190:191], v[158:159], 0, v[186:187]
	v_lshl_add_u64 v[192:193], v[158:159], 0, v[162:163]
	v_lshl_add_u64 v[194:195], v[168:169], 0, v[156:157]
	v_lshl_add_u64 v[196:197], s[70:71], 0, v[164:165]
	global_load_dwordx2 v[198:199], v[166:167], off offset:288
	global_load_dwordx2 v[200:201], v[190:191], off
	global_load_dwordx2 v[202:203], v[190:191], off offset:32
	global_load_dwordx2 v[204:205], v[190:191], off offset:256
	s_nop 0
	global_load_dwordx2 v[190:191], v[190:191], off offset:288
	s_nop 0
	global_load_dwordx2 v[206:207], v[192:193], off
	global_load_dwordx2 v[168:169], v[192:193], off offset:32
	global_load_dwordx2 v[166:167], v[192:193], off offset:256
	global_load_dwordx2 v[164:165], v[192:193], off offset:288
	v_lshl_add_u64 v[192:193], v[196:197], 0, v[156:157]
	s_mov_b64 s[14:15], 0x80000
	s_and_b64 vcc, exec, s[34:35]
	s_waitcnt vmcnt(0)
	v_cvt_f32_f16_e32 v196, v174
	v_cvt_f32_f16_sdwa v197, v174 dst_sel:DWORD dst_unused:UNUSED_PAD src0_sel:WORD_1
	v_cvt_f32_f16_e32 v174, v175
	v_cvt_f32_f16_sdwa v175, v175 dst_sel:DWORD dst_unused:UNUSED_PAD src0_sel:WORD_1
	v_cvt_f32_f16_e32 v216, v178
	v_cvt_f32_f16_sdwa v217, v178 dst_sel:DWORD dst_unused:UNUSED_PAD src0_sel:WORD_1
	v_cvt_f32_f16_e32 v178, v179
	v_cvt_f32_f16_sdwa v179, v179 dst_sel:DWORD dst_unused:UNUSED_PAD src0_sel:WORD_1
	v_cvt_f32_f16_e32 v220, v180
	v_cvt_f32_f16_sdwa v221, v180 dst_sel:DWORD dst_unused:UNUSED_PAD src0_sel:WORD_1
	v_cvt_f32_f16_e32 v180, v181
	v_cvt_f32_f16_sdwa v181, v181 dst_sel:DWORD dst_unused:UNUSED_PAD src0_sel:WORD_1
	v_cvt_f32_f16_e32 v208, v176
	v_cvt_f32_f16_sdwa v209, v176 dst_sel:DWORD dst_unused:UNUSED_PAD src0_sel:WORD_1
	v_cvt_f32_f16_e32 v176, v177
	v_cvt_f32_f16_sdwa v177, v177 dst_sel:DWORD dst_unused:UNUSED_PAD src0_sel:WORD_1
	v_cvt_f32_f16_e32 v222, v182
	v_cvt_f32_f16_sdwa v223, v182 dst_sel:DWORD dst_unused:UNUSED_PAD src0_sel:WORD_1
	v_cvt_f32_f16_e32 v182, v183
	v_cvt_f32_f16_sdwa v183, v183 dst_sel:DWORD dst_unused:UNUSED_PAD src0_sel:WORD_1
	v_pk_mul_f32 v[174:175], v[174:175], s[66:67] op_sel_hi:[1,0]
	v_pk_mul_f32 v[196:197], v[196:197], s[66:67] op_sel_hi:[1,0]
	v_pk_mul_f32 v[178:179], v[178:179], s[66:67] op_sel_hi:[1,0]
	v_pk_mul_f32 v[216:217], v[216:217], s[66:67] op_sel_hi:[1,0]
	v_pk_mul_f32 v[180:181], v[180:181], s[66:67] op_sel_hi:[1,0]
	v_pk_mul_f32 v[176:177], v[176:177], s[66:67] op_sel_hi:[1,0]
	v_pk_mul_f32 v[208:209], v[208:209], s[66:67] op_sel_hi:[1,0]
	v_pk_mul_f32 v[220:221], v[220:221], s[66:67] op_sel_hi:[1,0]
	v_pk_fma_f32 v[126:127], v[126:127], v[130:131], v[196:197]
	v_pk_fma_f32 v[128:129], v[128:129], v[132:133], v[174:175]
	v_pk_fma_f32 v[114:115], v[114:115], v[138:139], v[216:217]
	v_pk_fma_f32 v[116:117], v[116:117], v[140:141], v[178:179]
	v_pk_fma_f32 v[112:113], v[112:113], v[144:145], v[180:181]
	v_pk_mul_f32 v[174:175], v[182:183], s[66:67] op_sel_hi:[1,0]
	v_pk_fma_f32 v[122:123], v[122:123], v[134:135], v[208:209]
	v_pk_fma_f32 v[124:125], v[124:125], v[136:137], v[176:177]
	v_pk_fma_f32 v[110:111], v[110:111], v[142:143], v[220:221]
	v_cvt_pk_f16_f32 v129, v128, v129
	v_cvt_pk_f16_f32 v128, v126, v127
	v_cvt_pk_f16_f32 v117, v116, v117
	v_cvt_pk_f16_f32 v116, v114, v115
	v_cvt_pk_f16_f32 v113, v112, v113
	v_pk_fma_f32 v[114:115], v[120:121], v[132:133], v[174:175]
	v_cvt_f32_f16_e32 v224, v184
	v_cvt_pk_f16_f32 v125, v124, v125
	v_cvt_pk_f16_f32 v124, v122, v123
	v_cvt_pk_f16_f32 v112, v110, v111
	global_store_dwordx2 v[194:195], v[128:129], off
	global_store_dwordx2 v[194:195], v[124:125], off offset:32
	global_store_dwordx2 v[194:195], v[116:117], off offset:256
	global_store_dwordx2 v[194:195], v[112:113], off offset:288
	v_cvt_pk_f16_f32 v113, v114, v115
	v_cvt_f32_f16_e32 v114, v185
	v_cvt_f32_f16_sdwa v115, v185 dst_sel:DWORD dst_unused:UNUSED_PAD src0_sel:WORD_1
	v_cvt_f32_f16_sdwa v225, v184 dst_sel:DWORD dst_unused:UNUSED_PAD src0_sel:WORD_1
	v_pk_mul_f32 v[176:177], v[222:223], s[66:67] op_sel_hi:[1,0]
	s_nop 0
	v_pk_fma_f32 v[110:111], v[118:119], v[130:131], v[176:177]
	s_nop 0
	v_cvt_pk_f16_f32 v112, v110, v111
	global_store_dwordx2 v[192:193], v[112:113], off
	v_pk_mul_f32 v[110:111], v[114:115], s[66:67] op_sel_hi:[1,0]
	v_pk_mul_f32 v[112:113], v[224:225], s[66:67] op_sel_hi:[1,0]
	v_pk_fma_f32 v[108:109], v[108:109], v[136:137], v[110:111]
	v_pk_fma_f32 v[106:107], v[106:107], v[134:135], v[112:113]
	v_cvt_f32_f16_e32 v110, v188
	v_cvt_f32_f16_e32 v112, v189
	v_cvt_f32_f16_sdwa v113, v189 dst_sel:DWORD dst_unused:UNUSED_PAD src0_sel:WORD_1
	v_cvt_f32_f16_sdwa v111, v188 dst_sel:DWORD dst_unused:UNUSED_PAD src0_sel:WORD_1
	v_cvt_pk_f16_f32 v109, v108, v109
	v_cvt_pk_f16_f32 v108, v106, v107
	global_store_dwordx2 v[192:193], v[108:109], off offset:32
	v_pk_mul_f32 v[106:107], v[112:113], s[66:67] op_sel_hi:[1,0]
	v_pk_mul_f32 v[108:109], v[110:111], s[66:67] op_sel_hi:[1,0]
	v_pk_fma_f32 v[104:105], v[104:105], v[140:141], v[106:107]
	v_pk_fma_f32 v[102:103], v[102:103], v[138:139], v[108:109]
	v_cvt_f32_f16_e32 v106, v198
	v_cvt_f32_f16_e32 v108, v199
	v_cvt_f32_f16_sdwa v109, v199 dst_sel:DWORD dst_unused:UNUSED_PAD src0_sel:WORD_1
	v_cvt_f32_f16_sdwa v107, v198 dst_sel:DWORD dst_unused:UNUSED_PAD src0_sel:WORD_1
	v_cvt_pk_f16_f32 v105, v104, v105
	v_cvt_pk_f16_f32 v104, v102, v103
	global_store_dwordx2 v[192:193], v[104:105], off offset:256
	v_pk_mul_f32 v[102:103], v[108:109], s[66:67] op_sel_hi:[1,0]
	v_pk_mul_f32 v[104:105], v[106:107], s[66:67] op_sel_hi:[1,0]
	v_pk_fma_f32 v[96:97], v[96:97], v[144:145], v[102:103]
	v_pk_fma_f32 v[94:95], v[94:95], v[142:143], v[104:105]
	v_cvt_pk_f16_f32 v97, v96, v97
	v_cvt_pk_f16_f32 v96, v94, v95
	global_store_dwordx2 v[192:193], v[96:97], off offset:288
	v_cvt_f32_f16_e32 v94, v200
	v_cvt_f32_f16_e32 v96, v201
	v_cvt_f32_f16_sdwa v97, v201 dst_sel:DWORD dst_unused:UNUSED_PAD src0_sel:WORD_1
	v_cvt_f32_f16_sdwa v95, v200 dst_sel:DWORD dst_unused:UNUSED_PAD src0_sel:WORD_1
	v_lshl_add_u64 v[102:103], s[70:71], 0, v[186:187]
	v_lshl_add_u64 v[102:103], v[102:103], 0, v[156:157]
	v_pk_mul_f32 v[96:97], v[96:97], s[66:67] op_sel_hi:[1,0]
	v_pk_mul_f32 v[94:95], v[94:95], s[66:67] op_sel_hi:[1,0]
	v_pk_fma_f32 v[96:97], v[100:101], v[132:133], v[96:97]
	v_pk_fma_f32 v[94:95], v[98:99], v[130:131], v[94:95]
	v_cvt_f32_f16_e32 v98, v202
	v_cvt_f32_f16_e32 v100, v203
	v_cvt_f32_f16_sdwa v101, v203 dst_sel:DWORD dst_unused:UNUSED_PAD src0_sel:WORD_1
	v_cvt_f32_f16_sdwa v99, v202 dst_sel:DWORD dst_unused:UNUSED_PAD src0_sel:WORD_1
	v_cvt_pk_f16_f32 v97, v96, v97
	v_cvt_pk_f16_f32 v96, v94, v95
	global_store_dwordx2 v[102:103], v[96:97], off
	v_pk_mul_f32 v[94:95], v[100:101], s[66:67] op_sel_hi:[1,0]
	v_pk_mul_f32 v[96:97], v[98:99], s[66:67] op_sel_hi:[1,0]
	v_pk_fma_f32 v[92:93], v[92:93], v[136:137], v[94:95]
	v_pk_fma_f32 v[90:91], v[90:91], v[134:135], v[96:97]
	v_cvt_f32_f16_e32 v94, v204
	v_cvt_f32_f16_e32 v96, v205
	v_cvt_f32_f16_sdwa v97, v205 dst_sel:DWORD dst_unused:UNUSED_PAD src0_sel:WORD_1
	v_cvt_f32_f16_sdwa v95, v204 dst_sel:DWORD dst_unused:UNUSED_PAD src0_sel:WORD_1
	v_cvt_pk_f16_f32 v93, v92, v93
	v_cvt_pk_f16_f32 v92, v90, v91
	global_store_dwordx2 v[102:103], v[92:93], off offset:32
	v_pk_mul_f32 v[90:91], v[96:97], s[66:67] op_sel_hi:[1,0]
	v_pk_mul_f32 v[92:93], v[94:95], s[66:67] op_sel_hi:[1,0]
	v_pk_fma_f32 v[88:89], v[88:89], v[140:141], v[90:91]
	v_pk_fma_f32 v[86:87], v[86:87], v[138:139], v[92:93]
	v_cvt_f32_f16_e32 v90, v190
	v_cvt_f32_f16_e32 v92, v191
	v_cvt_f32_f16_sdwa v93, v191 dst_sel:DWORD dst_unused:UNUSED_PAD src0_sel:WORD_1
	v_cvt_f32_f16_sdwa v91, v190 dst_sel:DWORD dst_unused:UNUSED_PAD src0_sel:WORD_1
	v_cvt_pk_f16_f32 v89, v88, v89
	v_cvt_pk_f16_f32 v88, v86, v87
	global_store_dwordx2 v[102:103], v[88:89], off offset:256
	v_pk_mul_f32 v[86:87], v[92:93], s[66:67] op_sel_hi:[1,0]
	v_pk_mul_f32 v[88:89], v[90:91], s[66:67] op_sel_hi:[1,0]
	v_pk_fma_f32 v[80:81], v[80:81], v[144:145], v[86:87]
	v_pk_fma_f32 v[78:79], v[78:79], v[142:143], v[88:89]
	v_cvt_pk_f16_f32 v81, v80, v81
	v_cvt_pk_f16_f32 v80, v78, v79
	global_store_dwordx2 v[102:103], v[80:81], off offset:288
	v_cvt_f32_f16_e32 v78, v206
	v_cvt_f32_f16_e32 v80, v207
	v_cvt_f32_f16_sdwa v81, v207 dst_sel:DWORD dst_unused:UNUSED_PAD src0_sel:WORD_1
	v_cvt_f32_f16_sdwa v79, v206 dst_sel:DWORD dst_unused:UNUSED_PAD src0_sel:WORD_1
	v_lshl_add_u64 v[86:87], s[70:71], 0, v[162:163]
	v_lshl_add_u64 v[86:87], v[86:87], 0, v[156:157]
	v_pk_mul_f32 v[80:81], v[80:81], s[66:67] op_sel_hi:[1,0]
	v_pk_mul_f32 v[78:79], v[78:79], s[66:67] op_sel_hi:[1,0]
	v_pk_fma_f32 v[80:81], v[84:85], v[132:133], v[80:81]
	v_pk_fma_f32 v[78:79], v[82:83], v[130:131], v[78:79]
	v_cvt_f32_f16_e32 v82, v168
	v_cvt_f32_f16_e32 v84, v169
	v_cvt_f32_f16_sdwa v85, v169 dst_sel:DWORD dst_unused:UNUSED_PAD src0_sel:WORD_1
	v_cvt_f32_f16_sdwa v83, v168 dst_sel:DWORD dst_unused:UNUSED_PAD src0_sel:WORD_1
	v_cvt_pk_f16_f32 v81, v80, v81
	v_cvt_pk_f16_f32 v80, v78, v79
	global_store_dwordx2 v[86:87], v[80:81], off
	v_pk_mul_f32 v[78:79], v[84:85], s[66:67] op_sel_hi:[1,0]
	v_pk_mul_f32 v[80:81], v[82:83], s[66:67] op_sel_hi:[1,0]
	v_pk_fma_f32 v[76:77], v[76:77], v[136:137], v[78:79]
	v_pk_fma_f32 v[74:75], v[74:75], v[134:135], v[80:81]
	v_cvt_f32_f16_e32 v78, v166
	v_cvt_f32_f16_e32 v80, v167
	v_cvt_f32_f16_sdwa v81, v167 dst_sel:DWORD dst_unused:UNUSED_PAD src0_sel:WORD_1
	v_cvt_f32_f16_sdwa v79, v166 dst_sel:DWORD dst_unused:UNUSED_PAD src0_sel:WORD_1
	v_cvt_pk_f16_f32 v77, v76, v77
	v_cvt_pk_f16_f32 v76, v74, v75
	global_store_dwordx2 v[86:87], v[76:77], off offset:32
	v_pk_mul_f32 v[74:75], v[80:81], s[66:67] op_sel_hi:[1,0]
	v_pk_mul_f32 v[76:77], v[78:79], s[66:67] op_sel_hi:[1,0]
	v_pk_fma_f32 v[72:73], v[72:73], v[140:141], v[74:75]
	v_pk_fma_f32 v[70:71], v[70:71], v[138:139], v[76:77]
	v_cvt_f32_f16_e32 v74, v164
	v_cvt_f32_f16_e32 v76, v165
	v_cvt_f32_f16_sdwa v77, v165 dst_sel:DWORD dst_unused:UNUSED_PAD src0_sel:WORD_1
	v_cvt_f32_f16_sdwa v75, v164 dst_sel:DWORD dst_unused:UNUSED_PAD src0_sel:WORD_1
	v_cvt_pk_f16_f32 v73, v72, v73
	v_cvt_pk_f16_f32 v72, v70, v71
	global_store_dwordx2 v[86:87], v[72:73], off offset:256
	v_pk_mul_f32 v[70:71], v[76:77], s[66:67] op_sel_hi:[1,0]
	v_pk_mul_f32 v[72:73], v[74:75], s[66:67] op_sel_hi:[1,0]
	v_pk_fma_f32 v[68:69], v[68:69], v[144:145], v[70:71]
	v_pk_fma_f32 v[66:67], v[66:67], v[142:143], v[72:73]
	v_cvt_pk_f16_f32 v69, v68, v69
	v_cvt_pk_f16_f32 v68, v66, v67
	global_store_dwordx2 v[86:87], v[68:69], off offset:288
	v_lshl_add_u64 v[78:79], v[160:161], 0, s[14:15]
	v_lshl_add_u64 v[66:67], v[158:159], 0, v[78:79]
	global_load_dwordx2 v[80:81], v[66:67], off
	global_load_dwordx2 v[82:83], v[66:67], off offset:32
	global_load_dwordx2 v[84:85], v[66:67], off offset:256
	global_load_dwordx2 v[86:87], v[66:67], off offset:288
	s_mov_b64 s[14:15], 0x90000
	v_lshl_add_u64 v[88:89], v[160:161], 0, s[14:15]
	v_lshl_add_u64 v[66:67], v[158:159], 0, v[88:89]
	global_load_dwordx2 v[90:91], v[66:67], off
	global_load_dwordx2 v[92:93], v[66:67], off offset:32
	global_load_dwordx2 v[94:95], v[66:67], off offset:256
	global_load_dwordx2 v[96:97], v[66:67], off offset:288
	s_mov_b64 s[14:15], 0xa0000
	v_lshl_add_u64 v[98:99], v[160:161], 0, s[14:15]
	v_lshl_add_u64 v[66:67], v[158:159], 0, v[98:99]
	global_load_dwordx2 v[100:101], v[66:67], off
	global_load_dwordx2 v[102:103], v[66:67], off offset:32
	global_load_dwordx2 v[104:105], v[66:67], off offset:256
	global_load_dwordx2 v[76:77], v[66:67], off offset:288
	s_mov_b64 s[14:15], 0xb0000
	v_lshl_add_u64 v[72:73], v[160:161], 0, s[14:15]
	v_lshl_add_u64 v[66:67], v[158:159], 0, v[72:73]
	global_load_dwordx2 v[74:75], v[66:67], off
	global_load_dwordx2 v[70:71], v[66:67], off offset:32
	global_load_dwordx2 v[68:69], v[66:67], off offset:256
	s_nop 0
	global_load_dwordx2 v[66:67], v[66:67], off offset:288
	v_lshl_add_u64 v[78:79], s[70:71], 0, v[78:79]
	v_lshl_add_u64 v[78:79], v[78:79], 0, v[156:157]
	s_mov_b64 s[14:15], -1
	s_waitcnt vmcnt(15)
	v_cvt_f32_f16_e32 v106, v80
	v_cvt_f32_f16_e32 v108, v81
	v_cvt_f32_f16_sdwa v109, v81 dst_sel:DWORD dst_unused:UNUSED_PAD src0_sel:WORD_1
	v_cvt_f32_f16_sdwa v107, v80 dst_sel:DWORD dst_unused:UNUSED_PAD src0_sel:WORD_1
	v_pk_mul_f32 v[80:81], v[108:109], s[66:67] op_sel_hi:[1,0]
	v_pk_mul_f32 v[106:107], v[106:107], s[66:67] op_sel_hi:[1,0]
	v_pk_fma_f32 v[64:65], v[64:65], v[132:133], v[80:81]
	v_pk_fma_f32 v[62:63], v[62:63], v[130:131], v[106:107]
	s_waitcnt vmcnt(14)
	v_cvt_f32_f16_e32 v80, v82
	v_cvt_f32_f16_e32 v106, v83
	v_cvt_f32_f16_sdwa v107, v83 dst_sel:DWORD dst_unused:UNUSED_PAD src0_sel:WORD_1
	v_cvt_f32_f16_sdwa v81, v82 dst_sel:DWORD dst_unused:UNUSED_PAD src0_sel:WORD_1
	v_cvt_pk_f16_f32 v65, v64, v65
	v_cvt_pk_f16_f32 v64, v62, v63
	global_store_dwordx2 v[78:79], v[64:65], off
	v_pk_mul_f32 v[62:63], v[106:107], s[66:67] op_sel_hi:[1,0]
	v_pk_mul_f32 v[64:65], v[80:81], s[66:67] op_sel_hi:[1,0]
	v_pk_fma_f32 v[60:61], v[60:61], v[136:137], v[62:63]
	v_pk_fma_f32 v[58:59], v[58:59], v[134:135], v[64:65]
	s_waitcnt vmcnt(14)
	v_cvt_f32_f16_e32 v62, v84
	v_cvt_f32_f16_e32 v64, v85
	v_cvt_f32_f16_sdwa v65, v85 dst_sel:DWORD dst_unused:UNUSED_PAD src0_sel:WORD_1
	v_cvt_f32_f16_sdwa v63, v84 dst_sel:DWORD dst_unused:UNUSED_PAD src0_sel:WORD_1
	v_cvt_pk_f16_f32 v61, v60, v61
	v_cvt_pk_f16_f32 v60, v58, v59
	global_store_dwordx2 v[78:79], v[60:61], off offset:32
	v_pk_mul_f32 v[58:59], v[64:65], s[66:67] op_sel_hi:[1,0]
	v_pk_mul_f32 v[60:61], v[62:63], s[66:67] op_sel_hi:[1,0]
	v_pk_fma_f32 v[56:57], v[56:57], v[140:141], v[58:59]
	v_pk_fma_f32 v[54:55], v[54:55], v[138:139], v[60:61]
	s_waitcnt vmcnt(14)
	v_cvt_f32_f16_e32 v58, v86
	v_cvt_f32_f16_e32 v60, v87
	v_cvt_f32_f16_sdwa v61, v87 dst_sel:DWORD dst_unused:UNUSED_PAD src0_sel:WORD_1
	v_cvt_f32_f16_sdwa v59, v86 dst_sel:DWORD dst_unused:UNUSED_PAD src0_sel:WORD_1
	v_cvt_pk_f16_f32 v57, v56, v57
	v_cvt_pk_f16_f32 v56, v54, v55
	global_store_dwordx2 v[78:79], v[56:57], off offset:256
	v_pk_mul_f32 v[54:55], v[60:61], s[66:67] op_sel_hi:[1,0]
	v_pk_mul_f32 v[56:57], v[58:59], s[66:67] op_sel_hi:[1,0]
	v_pk_fma_f32 v[48:49], v[48:49], v[144:145], v[54:55]
	v_pk_fma_f32 v[46:47], v[46:47], v[142:143], v[56:57]
	v_cvt_pk_f16_f32 v49, v48, v49
	v_cvt_pk_f16_f32 v48, v46, v47
	global_store_dwordx2 v[78:79], v[48:49], off offset:288
	s_waitcnt vmcnt(15)
	v_cvt_f32_f16_e32 v46, v90
	v_cvt_f32_f16_e32 v48, v91
	v_cvt_f32_f16_sdwa v49, v91 dst_sel:DWORD dst_unused:UNUSED_PAD src0_sel:WORD_1
	v_cvt_f32_f16_sdwa v47, v90 dst_sel:DWORD dst_unused:UNUSED_PAD src0_sel:WORD_1
	v_lshl_add_u64 v[54:55], s[70:71], 0, v[88:89]
	v_lshl_add_u64 v[54:55], v[54:55], 0, v[156:157]
	v_pk_mul_f32 v[48:49], v[48:49], s[66:67] op_sel_hi:[1,0]
	v_pk_mul_f32 v[46:47], v[46:47], s[66:67] op_sel_hi:[1,0]
	v_pk_fma_f32 v[48:49], v[52:53], v[132:133], v[48:49]
	v_pk_fma_f32 v[46:47], v[50:51], v[130:131], v[46:47]
	s_waitcnt vmcnt(14)
	v_cvt_f32_f16_e32 v50, v92
	v_cvt_f32_f16_e32 v52, v93
	v_cvt_f32_f16_sdwa v53, v93 dst_sel:DWORD dst_unused:UNUSED_PAD src0_sel:WORD_1
	v_cvt_f32_f16_sdwa v51, v92 dst_sel:DWORD dst_unused:UNUSED_PAD src0_sel:WORD_1
	v_cvt_pk_f16_f32 v49, v48, v49
	v_cvt_pk_f16_f32 v48, v46, v47
	global_store_dwordx2 v[54:55], v[48:49], off
	v_pk_mul_f32 v[46:47], v[52:53], s[66:67] op_sel_hi:[1,0]
	v_pk_mul_f32 v[48:49], v[50:51], s[66:67] op_sel_hi:[1,0]
	v_pk_fma_f32 v[44:45], v[44:45], v[136:137], v[46:47]
	v_pk_fma_f32 v[42:43], v[42:43], v[134:135], v[48:49]
	s_waitcnt vmcnt(14)
	v_cvt_f32_f16_e32 v46, v94
	v_cvt_f32_f16_e32 v48, v95
	v_cvt_f32_f16_sdwa v49, v95 dst_sel:DWORD dst_unused:UNUSED_PAD src0_sel:WORD_1
	v_cvt_f32_f16_sdwa v47, v94 dst_sel:DWORD dst_unused:UNUSED_PAD src0_sel:WORD_1
	v_cvt_pk_f16_f32 v45, v44, v45
	v_cvt_pk_f16_f32 v44, v42, v43
	global_store_dwordx2 v[54:55], v[44:45], off offset:32
	v_pk_mul_f32 v[42:43], v[48:49], s[66:67] op_sel_hi:[1,0]
	v_pk_mul_f32 v[44:45], v[46:47], s[66:67] op_sel_hi:[1,0]
	v_pk_fma_f32 v[40:41], v[40:41], v[140:141], v[42:43]
	v_pk_fma_f32 v[38:39], v[38:39], v[138:139], v[44:45]
	s_waitcnt vmcnt(14)
	v_cvt_f32_f16_e32 v42, v96
	v_cvt_f32_f16_e32 v44, v97
	v_cvt_f32_f16_sdwa v45, v97 dst_sel:DWORD dst_unused:UNUSED_PAD src0_sel:WORD_1
	v_cvt_f32_f16_sdwa v43, v96 dst_sel:DWORD dst_unused:UNUSED_PAD src0_sel:WORD_1
	v_cvt_pk_f16_f32 v41, v40, v41
	v_cvt_pk_f16_f32 v40, v38, v39
	global_store_dwordx2 v[54:55], v[40:41], off offset:256
	v_pk_mul_f32 v[38:39], v[44:45], s[66:67] op_sel_hi:[1,0]
	v_pk_mul_f32 v[40:41], v[42:43], s[66:67] op_sel_hi:[1,0]
	v_pk_fma_f32 v[32:33], v[32:33], v[144:145], v[38:39]
	v_pk_fma_f32 v[30:31], v[30:31], v[142:143], v[40:41]
	v_cvt_pk_f16_f32 v33, v32, v33
	v_cvt_pk_f16_f32 v32, v30, v31
	global_store_dwordx2 v[54:55], v[32:33], off offset:288
	s_waitcnt vmcnt(15)
	v_cvt_f32_f16_e32 v30, v100
	v_cvt_f32_f16_e32 v32, v101
	v_cvt_f32_f16_sdwa v33, v101 dst_sel:DWORD dst_unused:UNUSED_PAD src0_sel:WORD_1
	v_cvt_f32_f16_sdwa v31, v100 dst_sel:DWORD dst_unused:UNUSED_PAD src0_sel:WORD_1
	v_lshl_add_u64 v[38:39], s[70:71], 0, v[98:99]
	v_lshl_add_u64 v[38:39], v[38:39], 0, v[156:157]
	v_pk_mul_f32 v[32:33], v[32:33], s[66:67] op_sel_hi:[1,0]
	v_pk_mul_f32 v[30:31], v[30:31], s[66:67] op_sel_hi:[1,0]
	v_pk_fma_f32 v[32:33], v[36:37], v[132:133], v[32:33]
	v_pk_fma_f32 v[30:31], v[34:35], v[130:131], v[30:31]
	s_waitcnt vmcnt(14)
	v_cvt_f32_f16_e32 v34, v102
	v_cvt_f32_f16_e32 v36, v103
	v_cvt_f32_f16_sdwa v37, v103 dst_sel:DWORD dst_unused:UNUSED_PAD src0_sel:WORD_1
	v_cvt_f32_f16_sdwa v35, v102 dst_sel:DWORD dst_unused:UNUSED_PAD src0_sel:WORD_1
	v_cvt_pk_f16_f32 v33, v32, v33
	v_cvt_pk_f16_f32 v32, v30, v31
	global_store_dwordx2 v[38:39], v[32:33], off
	v_pk_mul_f32 v[30:31], v[36:37], s[66:67] op_sel_hi:[1,0]
	v_pk_mul_f32 v[32:33], v[34:35], s[66:67] op_sel_hi:[1,0]
	v_pk_fma_f32 v[28:29], v[28:29], v[136:137], v[30:31]
	v_pk_fma_f32 v[26:27], v[26:27], v[134:135], v[32:33]
	s_waitcnt vmcnt(14)
	v_cvt_f32_f16_e32 v30, v104
	v_cvt_f32_f16_e32 v32, v105
	v_cvt_f32_f16_sdwa v33, v105 dst_sel:DWORD dst_unused:UNUSED_PAD src0_sel:WORD_1
	v_cvt_f32_f16_sdwa v31, v104 dst_sel:DWORD dst_unused:UNUSED_PAD src0_sel:WORD_1
	v_cvt_pk_f16_f32 v29, v28, v29
	v_cvt_pk_f16_f32 v28, v26, v27
	global_store_dwordx2 v[38:39], v[28:29], off offset:32
	v_pk_mul_f32 v[26:27], v[32:33], s[66:67] op_sel_hi:[1,0]
	v_pk_mul_f32 v[28:29], v[30:31], s[66:67] op_sel_hi:[1,0]
	v_pk_fma_f32 v[24:25], v[24:25], v[140:141], v[26:27]
	v_pk_fma_f32 v[22:23], v[22:23], v[138:139], v[28:29]
	s_waitcnt vmcnt(14)
	v_cvt_f32_f16_e32 v26, v76
	v_cvt_f32_f16_e32 v28, v77
	v_cvt_f32_f16_sdwa v29, v77 dst_sel:DWORD dst_unused:UNUSED_PAD src0_sel:WORD_1
	v_cvt_f32_f16_sdwa v27, v76 dst_sel:DWORD dst_unused:UNUSED_PAD src0_sel:WORD_1
	v_cvt_pk_f16_f32 v25, v24, v25
	v_cvt_pk_f16_f32 v24, v22, v23
	global_store_dwordx2 v[38:39], v[24:25], off offset:256
	v_pk_mul_f32 v[22:23], v[28:29], s[66:67] op_sel_hi:[1,0]
	v_pk_mul_f32 v[24:25], v[26:27], s[66:67] op_sel_hi:[1,0]
	v_pk_fma_f32 v[16:17], v[16:17], v[144:145], v[22:23]
	v_pk_fma_f32 v[14:15], v[14:15], v[142:143], v[24:25]
	v_cvt_pk_f16_f32 v17, v16, v17
	v_cvt_pk_f16_f32 v16, v14, v15
	global_store_dwordx2 v[38:39], v[16:17], off offset:288
	s_waitcnt vmcnt(15)
	v_cvt_f32_f16_e32 v14, v74
	v_cvt_f32_f16_e32 v16, v75
	v_cvt_f32_f16_sdwa v17, v75 dst_sel:DWORD dst_unused:UNUSED_PAD src0_sel:WORD_1
	v_cvt_f32_f16_sdwa v15, v74 dst_sel:DWORD dst_unused:UNUSED_PAD src0_sel:WORD_1
	v_lshl_add_u64 v[22:23], s[70:71], 0, v[72:73]
	v_lshl_add_u64 v[22:23], v[22:23], 0, v[156:157]
	v_pk_mul_f32 v[16:17], v[16:17], s[66:67] op_sel_hi:[1,0]
	v_pk_mul_f32 v[14:15], v[14:15], s[66:67] op_sel_hi:[1,0]
	v_pk_fma_f32 v[16:17], v[20:21], v[132:133], v[16:17]
	v_pk_fma_f32 v[14:15], v[18:19], v[130:131], v[14:15]
	s_waitcnt vmcnt(14)
	v_cvt_f32_f16_e32 v18, v70
	v_cvt_f32_f16_e32 v20, v71
	v_cvt_f32_f16_sdwa v21, v71 dst_sel:DWORD dst_unused:UNUSED_PAD src0_sel:WORD_1
	v_cvt_f32_f16_sdwa v19, v70 dst_sel:DWORD dst_unused:UNUSED_PAD src0_sel:WORD_1
	v_cvt_pk_f16_f32 v17, v16, v17
	v_cvt_pk_f16_f32 v16, v14, v15
	global_store_dwordx2 v[22:23], v[16:17], off
	v_pk_mul_f32 v[14:15], v[20:21], s[66:67] op_sel_hi:[1,0]
	v_pk_mul_f32 v[16:17], v[18:19], s[66:67] op_sel_hi:[1,0]
	v_pk_fma_f32 v[12:13], v[12:13], v[136:137], v[14:15]
	v_pk_fma_f32 v[10:11], v[10:11], v[134:135], v[16:17]
	s_waitcnt vmcnt(14)
	v_cvt_f32_f16_e32 v14, v68
	v_cvt_f32_f16_e32 v16, v69
	v_cvt_f32_f16_sdwa v17, v69 dst_sel:DWORD dst_unused:UNUSED_PAD src0_sel:WORD_1
	v_cvt_f32_f16_sdwa v15, v68 dst_sel:DWORD dst_unused:UNUSED_PAD src0_sel:WORD_1
	v_cvt_pk_f16_f32 v13, v12, v13
	v_cvt_pk_f16_f32 v12, v10, v11
	global_store_dwordx2 v[22:23], v[12:13], off offset:32
	v_pk_mul_f32 v[10:11], v[16:17], s[66:67] op_sel_hi:[1,0]
	v_pk_mul_f32 v[12:13], v[14:15], s[66:67] op_sel_hi:[1,0]
	v_pk_fma_f32 v[8:9], v[8:9], v[140:141], v[10:11]
	v_pk_fma_f32 v[6:7], v[6:7], v[138:139], v[12:13]
	s_waitcnt vmcnt(14)
	v_cvt_f32_f16_e32 v10, v66
	v_cvt_f32_f16_e32 v12, v67
	v_cvt_f32_f16_sdwa v13, v67 dst_sel:DWORD dst_unused:UNUSED_PAD src0_sel:WORD_1
	v_cvt_f32_f16_sdwa v11, v66 dst_sel:DWORD dst_unused:UNUSED_PAD src0_sel:WORD_1
	v_cvt_pk_f16_f32 v9, v8, v9
	v_cvt_pk_f16_f32 v8, v6, v7
	global_store_dwordx2 v[22:23], v[8:9], off offset:256
	v_pk_mul_f32 v[6:7], v[12:13], s[66:67] op_sel_hi:[1,0]
	v_pk_mul_f32 v[8:9], v[10:11], s[66:67] op_sel_hi:[1,0]
	v_pk_fma_f32 v[4:5], v[4:5], v[144:145], v[6:7]
	v_pk_fma_f32 v[2:3], v[2:3], v[142:143], v[8:9]
	v_cvt_pk_f16_f32 v5, v4, v5
	v_cvt_pk_f16_f32 v4, v2, v3
	global_store_dwordx2 v[22:23], v[4:5], off offset:288
	s_cbranch_vccnz .LBB0_1195
	s_andn2_b64 vcc, exec, s[0:1]
	s_cbranch_vccnz .LBB0_1194
	s_branch .LBB0_1194

.LBB0_1559:
	v_and_b32_e32 v17, 15, v16
	v_lshl_or_b32 v18, s5, 6, v17
	v_ashrrev_i32_e32 v20, 6, v16
	s_lshl_b32 s5, s5, 13
	v_lshl_add_u32 v22, v20, 10, s5
	s_lshl_b32 s5, s4, 5
	s_and_b32 s8, s5, 0x60
	s_add_i32 m0, s17, 0x18000
	v_lshl_add_u64 v[8:9], v[8:9], 0, s[2:3]
	s_lshr_b32 s5, s8, 3
	s_waitcnt vmcnt(2)
	s_barrier
	global_load_lds_dwordx4 v[8:9], off
	v_lshl_add_u64 v[6:7], v[6:7], 0, s[2:3]
	s_add_i32 m0, s17, 0x1a000
	s_add_i32 s46, s17, 0x8000
	s_add_i32 s47, s17, 0xa000
	global_load_lds_dwordx4 v[6:7], off
	v_lshl_add_u64 v[2:3], v[2:3], 0, s[2:3]
	s_mov_b32 m0, s46
	s_add_u32 s6, s20, 0x80080
	global_load_lds_dwordx4 v[2:3], off
	v_lshl_add_u64 v[2:3], v[4:5], 0, s[2:3]
	s_mov_b32 m0, s47
	s_addc_u32 s7, s21, 0
	global_load_lds_dwordx4 v[2:3], off
	s_add_i32 m0, s17, 0x1c000
	v_lshl_add_u64 v[2:3], s[6:7], 0, v[0:1]
	global_load_lds_dwordx4 v[2:3], off
	v_lshl_add_u64 v[2:3], s[6:7], 0, v[130:131]
	s_add_i32 m0, s17, 0x1e000
	v_ashrrev_i32_e32 v19, 1, v16
	global_load_lds_dwordx4 v[2:3], off
	v_and_b32_e32 v19, -8, v19
	v_or_b32_e32 v2, 16, v18
	v_add_u32_e32 v161, s8, v19
	v_ashrrev_i32_e32 v19, 31, v18
	v_ashrrev_i32_e32 v3, 31, v2
	v_lshlrev_b64 v[136:137], 7, v[18:19]
	v_lshlrev_b64 v[138:139], 7, v[2:3]
	v_or_b32_e32 v2, 32, v18
	s_mov_b64 s[6:7], 0x4000
	v_ashrrev_i32_e32 v3, 31, v2
	v_lshl_add_u64 v[144:145], v[136:137], 0, s[6:7]
	s_mov_b64 s[6:7], 0x4800
	v_lshlrev_b64 v[140:141], 7, v[2:3]
	v_or_b32_e32 v2, 48, v18
	v_lshl_add_u64 v[146:147], v[136:137], 0, s[6:7]
	s_mov_b64 s[6:7], 0x5000
	v_ashrrev_i32_e32 v3, 31, v2
	v_lshl_add_u64 v[148:149], v[136:137], 0, s[6:7]
	s_mov_b64 s[6:7], 0x5800
	v_lshlrev_b64 v[142:143], 7, v[2:3]
	v_lshl_add_u64 v[150:151], v[136:137], 0, s[6:7]
	v_and_b32_e32 v2, 56, v161
	v_readlane_b32 s6, v254, 48
	v_lshlrev_b32_e32 v2, 1, v2
	v_mov_b32_e32 v3, v1
	v_readlane_b32 s7, v254, 49
	v_and_b32_e32 v21, 48, v16
	v_lshlrev_b32_e32 v16, 2, v16
	v_lshl_add_u64 v[152:153], s[6:7], 0, v[2:3]
	v_lshlrev_b32_e32 v2, 15, v13
	v_and_b32_e32 v2, 0xffff0000, v2
	v_lshl_add_u32 v2, v14, 12, v2
	v_and_b32_e32 v3, 1, v13
	v_lshl_or_b32 v2, v3, 6, v2
	v_lshl_add_u32 v154, v15, 1, v2
	v_lshlrev_b32_e32 v2, 15, v10
	v_and_b32_e32 v2, 0xffff0000, v2
	v_lshl_or_b32 v17, v17, 6, v21
	v_and_b32_e32 v16, 32, v16
	s_waitcnt vmcnt(6)
	v_lshl_add_u32 v2, v11, 12, v2
	v_and_b32_e32 v3, 1, v10
	v_bitop3_b32 v21, v17, v22, v16 bitop3:0xde
	v_add_lshl_u32 v20, s5, v20, 10
	s_cmp_lt_u32 s4, 4
	v_lshl_or_b32 v2, v3, 6, v2
	v_bitop3_b32 v160, v17, v20, v16 bitop3:0xde
	s_cselect_b64 s[4:5], -1, 0
	s_ashr_i32 s48, s25, 31
	v_mov_b32_e32 v155, v1
	v_lshl_add_u32 v156, v12, 1, v2
	v_mov_b32_e32 v157, v1
	s_mov_b32 s49, 0
	v_add_u32_e32 v162, 0, v21
	s_branch .LBB0_1562

.Lh0_4:
	s_add_u32 s20, s18, 0xfff80080
	s_addc_u32 s21, s19, -1
	s_add_i32 s54, 0, 0x10000
	s_cmp_eq_u32 s53, 28
	s_cselect_b32 s23, s9, s21
	s_cselect_b32 s22, s15, s20
	v_add_u32_e32 v158, s54, v160
	s_cselect_b32 s21, s7, s52
	s_cselect_b32 s20, s50, s51
	s_add_i32 s56, 0, 0x14000
	ds_read_b128 v[164:167], v158
	ds_read_b128 v[168:171], v158 offset:1024
	ds_read_b128 v[172:175], v158 offset:2048
	ds_read_b128 v[176:179], v158 offset:3072
	v_add_u32_e32 v158, s56, v160
	ds_read_b128 v[180:183], v158
	ds_read_b128 v[184:187], v158 offset:1024
	ds_read_b128 v[188:191], v158 offset:2048
	ds_read_b128 v[192:195], v158 offset:3072
	v_lshl_add_u64 v[158:159], s[18:19], 0, v[154:155]
	s_add_i32 m0, s17, 0xc000
	ds_read_b128 v[196:199], v162
	ds_read_b128 v[200:203], v162 offset:1024
	ds_read_b128 v[204:207], v162 offset:2048
	ds_read_b128 v[220:223], v162 offset:3072
	ds_read_b128 v[224:227], v162 offset:4096
	ds_read_b128 v[228:231], v162 offset:5120
	ds_read_b128 v[232:235], v162 offset:6144
	ds_read_b128 v[236:239], v162 offset:7168
	global_load_lds_dwordx4 v[158:159], off
	v_lshl_add_u64 v[158:159], s[18:19], 0, v[156:157]
	s_add_i32 m0, s17, 0xe000
	s_nop 0
	global_load_lds_dwordx4 v[158:159], off
	s_waitcnt vmcnt(8)
	s_waitcnt lgkmcnt(0)
	s_barrier
	s_setprio 1
	s_waitcnt lgkmcnt(0)
	v_mfma_f32_16x16x32_bf16 v[122:125], v[164:167], v[196:199], v[122:125]
	v_mfma_f32_16x16x32_bf16 v[114:117], v[172:175], v[196:199], v[114:117]
	v_mfma_f32_16x16x32_bf16 v[106:109], v[164:167], v[204:207], v[106:109]
	v_mfma_f32_16x16x32_bf16 v[98:101], v[172:175], v[204:207], v[98:101]
	v_mfma_f32_16x16x32_bf16 v[90:93], v[164:167], v[224:227], v[90:93]
	v_mfma_f32_16x16x32_bf16 v[82:85], v[172:175], v[224:227], v[82:85]
	v_mfma_f32_16x16x32_bf16 v[74:77], v[164:167], v[232:235], v[74:77]
	v_mfma_f32_16x16x32_bf16 v[66:69], v[172:175], v[232:235], v[66:69]
	v_mfma_f32_16x16x32_bf16 v[122:125], v[168:171], v[200:203], v[122:125]
	v_mfma_f32_16x16x32_bf16 v[114:117], v[176:179], v[200:203], v[114:117]
	v_mfma_f32_16x16x32_bf16 v[106:109], v[168:171], v[220:223], v[106:109]
	v_mfma_f32_16x16x32_bf16 v[98:101], v[176:179], v[220:223], v[98:101]
	v_mfma_f32_16x16x32_bf16 v[90:93], v[168:171], v[228:231], v[90:93]
	v_mfma_f32_16x16x32_bf16 v[82:85], v[176:179], v[228:231], v[82:85]
	v_mfma_f32_16x16x32_bf16 v[74:77], v[168:171], v[236:239], v[74:77]
	v_mfma_f32_16x16x32_bf16 v[66:69], v[176:179], v[236:239], v[66:69]
	s_setprio 0
	s_setprio 1
	v_mfma_f32_16x16x32_bf16 v[126:129], v[180:183], v[196:199], v[126:129]
	v_mfma_f32_16x16x32_bf16 v[118:121], v[188:191], v[196:199], v[118:121]
	v_mfma_f32_16x16x32_bf16 v[110:113], v[180:183], v[204:207], v[110:113]
	v_mfma_f32_16x16x32_bf16 v[102:105], v[188:191], v[204:207], v[102:105]
	v_mfma_f32_16x16x32_bf16 v[94:97], v[180:183], v[224:227], v[94:97]
	v_mfma_f32_16x16x32_bf16 v[86:89], v[188:191], v[224:227], v[86:89]
	v_mfma_f32_16x16x32_bf16 v[78:81], v[180:183], v[232:235], v[78:81]
	v_mfma_f32_16x16x32_bf16 v[70:73], v[188:191], v[232:235], v[70:73]
	v_mfma_f32_16x16x32_bf16 v[126:129], v[184:187], v[200:203], v[126:129]
	v_mfma_f32_16x16x32_bf16 v[118:121], v[192:195], v[200:203], v[118:121]
	v_mfma_f32_16x16x32_bf16 v[110:113], v[184:187], v[220:223], v[110:113]
	v_mfma_f32_16x16x32_bf16 v[102:105], v[192:195], v[220:223], v[102:105]
	v_mfma_f32_16x16x32_bf16 v[94:97], v[184:187], v[228:231], v[94:97]
	v_mfma_f32_16x16x32_bf16 v[86:89], v[192:195], v[228:231], v[86:89]
	v_mfma_f32_16x16x32_bf16 v[78:81], v[184:187], v[236:239], v[78:81]
	v_mfma_f32_16x16x32_bf16 v[70:73], v[192:195], v[236:239], v[70:73]
	s_setprio 0
	s_add_i32 s54, s54, s41
	v_lshl_add_u64 v[158:159], s[20:21], 0, v[0:1]
	s_mov_b32 m0, s54
	ds_read_b128 v[196:199], v162 offset:16384
	ds_read_b128 v[200:203], v162 offset:17408
	ds_read_b128 v[204:207], v162 offset:18432
	ds_read_b128 v[220:223], v162 offset:19456
	ds_read_b128 v[224:227], v162 offset:20480
	ds_read_b128 v[228:231], v162 offset:21504
	ds_read_b128 v[232:235], v162 offset:22528
	ds_read_b128 v[236:239], v162 offset:23552
	global_load_lds_dwordx4 v[158:159], off
	s_add_i32 m0, s54, 0x2000
	s_add_u32 s54, s20, 0x80000
	v_lshl_add_u64 v[208:209], s[20:21], 0, v[130:131]
	s_addc_u32 s55, s21, 0
	s_add_i32 s56, s56, s41
	global_load_lds_dwordx4 v[208:209], off
	v_lshl_add_u64 v[216:217], s[54:55], 0, v[0:1]
	s_mov_b32 m0, s56
	v_lshl_add_u64 v[244:245], s[22:23], 0, v[132:133]
	global_load_lds_dwordx4 v[216:217], off
	v_lshl_add_u64 v[216:217], s[54:55], 0, v[130:131]
	s_add_i32 m0, s56, 0x2000
	s_nop 0
	global_load_lds_dwordx4 v[216:217], off
	v_lshl_add_u64 v[216:217], s[22:23], 0, v[134:135]
	s_mov_b32 m0, s17
	s_nop 0
	global_load_lds_dwordx4 v[216:217], off
	s_mov_b32 m0, s43
	s_nop 0
	global_load_lds_dwordx4 v[244:245], off
	s_waitcnt vmcnt(8)
	s_waitcnt lgkmcnt(0)
	s_barrier
	s_setprio 1
	s_waitcnt lgkmcnt(0)
	v_mfma_f32_16x16x32_bf16 v[58:61], v[164:167], v[196:199], v[58:61]
	v_mfma_f32_16x16x32_bf16 v[50:53], v[172:175], v[196:199], v[50:53]
	v_mfma_f32_16x16x32_bf16 v[42:45], v[164:167], v[204:207], v[42:45]
	v_mfma_f32_16x16x32_bf16 v[34:37], v[172:175], v[204:207], v[34:37]
	v_mfma_f32_16x16x32_bf16 v[26:29], v[164:167], v[224:227], v[26:29]
	v_mfma_f32_16x16x32_bf16 v[18:21], v[172:175], v[224:227], v[18:21]
	v_mfma_f32_16x16x32_bf16 v[10:13], v[164:167], v[232:235], v[10:13]
	v_mfma_f32_16x16x32_bf16 v[2:5], v[172:175], v[232:235], v[2:5]
	v_mfma_f32_16x16x32_bf16 v[58:61], v[168:171], v[200:203], v[58:61]
	v_mfma_f32_16x16x32_bf16 v[50:53], v[176:179], v[200:203], v[50:53]
	v_mfma_f32_16x16x32_bf16 v[42:45], v[168:171], v[220:223], v[42:45]
	v_mfma_f32_16x16x32_bf16 v[34:37], v[176:179], v[220:223], v[34:37]
	v_mfma_f32_16x16x32_bf16 v[26:29], v[168:171], v[228:231], v[26:29]
	v_mfma_f32_16x16x32_bf16 v[18:21], v[176:179], v[228:231], v[18:21]
	v_mfma_f32_16x16x32_bf16 v[10:13], v[168:171], v[236:239], v[10:13]
	v_mfma_f32_16x16x32_bf16 v[2:5], v[176:179], v[236:239], v[2:5]
	s_setprio 0
	s_setprio 1
	v_mfma_f32_16x16x32_bf16 v[62:65], v[180:183], v[196:199], v[62:65]
	v_mfma_f32_16x16x32_bf16 v[54:57], v[188:191], v[196:199], v[54:57]
	v_mfma_f32_16x16x32_bf16 v[46:49], v[180:183], v[204:207], v[46:49]
	v_mfma_f32_16x16x32_bf16 v[38:41], v[188:191], v[204:207], v[38:41]
	v_mfma_f32_16x16x32_bf16 v[30:33], v[180:183], v[224:227], v[30:33]
	v_mfma_f32_16x16x32_bf16 v[22:25], v[188:191], v[224:227], v[22:25]
	v_mfma_f32_16x16x32_bf16 v[14:17], v[180:183], v[232:235], v[14:17]
	v_mfma_f32_16x16x32_bf16 v[6:9], v[188:191], v[232:235], v[6:9]
	v_mfma_f32_16x16x32_bf16 v[62:65], v[184:187], v[200:203], v[62:65]
	v_mfma_f32_16x16x32_bf16 v[54:57], v[192:195], v[200:203], v[54:57]
	v_mfma_f32_16x16x32_bf16 v[46:49], v[184:187], v[220:223], v[46:49]
	v_mfma_f32_16x16x32_bf16 v[38:41], v[192:195], v[220:223], v[38:41]
	v_mfma_f32_16x16x32_bf16 v[30:33], v[184:187], v[228:231], v[30:33]
	v_mfma_f32_16x16x32_bf16 v[22:25], v[192:195], v[228:231], v[22:25]
	v_mfma_f32_16x16x32_bf16 v[14:17], v[184:187], v[236:239], v[14:17]
	v_mfma_f32_16x16x32_bf16 v[6:9], v[192:195], v[236:239], v[6:9]
	s_setprio 0
	s_add_i32 s54, 0, 0x18000
	v_add_u32_e32 v163, s54, v160
	s_add_i32 s55, 0, 0x1c000
	ds_read_b128 v[164:167], v163
	ds_read_b128 v[168:171], v163 offset:1024
	ds_read_b128 v[172:175], v163 offset:2048
	ds_read_b128 v[176:179], v163 offset:3072
	v_add_u32_e32 v163, s55, v160
	ds_read_b128 v[180:183], v163
	ds_read_b128 v[184:187], v163 offset:1024
	ds_read_b128 v[188:191], v163 offset:2048
	ds_read_b128 v[192:195], v163 offset:3072
	s_add_u32 s22, s22, 0x80000
	s_addc_u32 s23, s23, 0
	s_mov_b32 m0, s44
	v_lshl_add_u64 v[246:247], s[22:23], 0, v[134:135]
	ds_read_b128 v[196:199], v162 offset:32768
	ds_read_b128 v[200:203], v162 offset:33792
	ds_read_b128 v[204:207], v162 offset:34816
	ds_read_b128 v[220:223], v162 offset:35840
	ds_read_b128 v[224:227], v162 offset:36864
	ds_read_b128 v[228:231], v162 offset:37888
	ds_read_b128 v[232:235], v162 offset:38912
	ds_read_b128 v[236:239], v162 offset:39936
	global_load_lds_dwordx4 v[246:247], off
	v_lshl_add_u64 v[246:247], s[22:23], 0, v[132:133]
	s_mov_b32 m0, s45
	s_nop 0
	global_load_lds_dwordx4 v[246:247], off
	s_waitcnt vmcnt(8)
	s_waitcnt lgkmcnt(0)
	s_barrier
	s_setprio 1
	s_waitcnt lgkmcnt(0)
	v_mfma_f32_16x16x32_bf16 v[122:125], v[164:167], v[196:199], v[122:125]
	v_mfma_f32_16x16x32_bf16 v[114:117], v[172:175], v[196:199], v[114:117]
	v_mfma_f32_16x16x32_bf16 v[106:109], v[164:167], v[204:207], v[106:109]
	v_mfma_f32_16x16x32_bf16 v[98:101], v[172:175], v[204:207], v[98:101]
	v_mfma_f32_16x16x32_bf16 v[90:93], v[164:167], v[224:227], v[90:93]
	v_mfma_f32_16x16x32_bf16 v[82:85], v[172:175], v[224:227], v[82:85]
	v_mfma_f32_16x16x32_bf16 v[74:77], v[164:167], v[232:235], v[74:77]
	v_mfma_f32_16x16x32_bf16 v[66:69], v[172:175], v[232:235], v[66:69]
	v_mfma_f32_16x16x32_bf16 v[122:125], v[168:171], v[200:203], v[122:125]
	v_mfma_f32_16x16x32_bf16 v[114:117], v[176:179], v[200:203], v[114:117]
	v_mfma_f32_16x16x32_bf16 v[106:109], v[168:171], v[220:223], v[106:109]
	v_mfma_f32_16x16x32_bf16 v[98:101], v[176:179], v[220:223], v[98:101]
	v_mfma_f32_16x16x32_bf16 v[90:93], v[168:171], v[228:231], v[90:93]
	v_mfma_f32_16x16x32_bf16 v[82:85], v[176:179], v[228:231], v[82:85]
	v_mfma_f32_16x16x32_bf16 v[74:77], v[168:171], v[236:239], v[74:77]
	v_mfma_f32_16x16x32_bf16 v[66:69], v[176:179], v[236:239], v[66:69]
	s_setprio 0
	s_setprio 1
	v_mfma_f32_16x16x32_bf16 v[126:129], v[180:183], v[196:199], v[126:129]
	v_mfma_f32_16x16x32_bf16 v[118:121], v[188:191], v[196:199], v[118:121]
	v_mfma_f32_16x16x32_bf16 v[110:113], v[180:183], v[204:207], v[110:113]
	v_mfma_f32_16x16x32_bf16 v[102:105], v[188:191], v[204:207], v[102:105]
	v_mfma_f32_16x16x32_bf16 v[94:97], v[180:183], v[224:227], v[94:97]
	v_mfma_f32_16x16x32_bf16 v[86:89], v[188:191], v[224:227], v[86:89]
	v_mfma_f32_16x16x32_bf16 v[78:81], v[180:183], v[232:235], v[78:81]
	v_mfma_f32_16x16x32_bf16 v[70:73], v[188:191], v[232:235], v[70:73]
	v_mfma_f32_16x16x32_bf16 v[126:129], v[184:187], v[200:203], v[126:129]
	v_mfma_f32_16x16x32_bf16 v[118:121], v[192:195], v[200:203], v[118:121]
	v_mfma_f32_16x16x32_bf16 v[110:113], v[184:187], v[220:223], v[110:113]
	v_mfma_f32_16x16x32_bf16 v[102:105], v[192:195], v[220:223], v[102:105]
	v_mfma_f32_16x16x32_bf16 v[94:97], v[184:187], v[228:231], v[94:97]
	v_mfma_f32_16x16x32_bf16 v[86:89], v[192:195], v[228:231], v[86:89]
	v_mfma_f32_16x16x32_bf16 v[78:81], v[184:187], v[236:239], v[78:81]
	v_mfma_f32_16x16x32_bf16 v[70:73], v[192:195], v[236:239], v[70:73]
	s_setprio 0
	s_add_i32 s22, s54, s41
	v_lshl_add_u64 v[158:159], v[158:159], 0, s[2:3]
	s_mov_b32 m0, s22
	ds_read_b128 v[196:199], v162 offset:49152
	ds_read_b128 v[200:203], v162 offset:50176
	ds_read_b128 v[204:207], v162 offset:51200
	ds_read_b128 v[220:223], v162 offset:52224
	ds_read_b128 v[224:227], v162 offset:53248
	ds_read_b128 v[228:231], v162 offset:54272
	ds_read_b128 v[232:235], v162 offset:55296
	ds_read_b128 v[236:239], v162 offset:56320
	global_load_lds_dwordx4 v[158:159], off
	s_add_i32 m0, s22, 0x2000
	s_add_u32 s20, s20, 0x80080
	v_lshl_add_u64 v[158:159], v[208:209], 0, s[2:3]
	s_addc_u32 s21, s21, 0
	s_add_i32 s22, s55, s41
	global_load_lds_dwordx4 v[158:159], off
	v_lshl_add_u64 v[158:159], s[20:21], 0, v[0:1]
	s_mov_b32 m0, s22
	s_nop 0
	global_load_lds_dwordx4 v[158:159], off
	v_lshl_add_u64 v[158:159], s[20:21], 0, v[130:131]
	s_add_i32 m0, s22, 0x2000
	s_nop 0
	global_load_lds_dwordx4 v[158:159], off
	v_lshl_add_u64 v[158:159], v[216:217], 0, s[2:3]
	s_mov_b32 m0, s46
	s_nop 0
	global_load_lds_dwordx4 v[158:159], off
	v_lshl_add_u64 v[158:159], v[244:245], 0, s[2:3]
	s_mov_b32 m0, s47
	s_nop 0
	global_load_lds_dwordx4 v[158:159], off
	s_waitcnt vmcnt(8)
	s_waitcnt lgkmcnt(0)
	s_barrier
	s_setprio 1
	s_waitcnt lgkmcnt(0)
	v_mfma_f32_16x16x32_bf16 v[58:61], v[164:167], v[196:199], v[58:61]
	v_mfma_f32_16x16x32_bf16 v[50:53], v[172:175], v[196:199], v[50:53]
	v_mfma_f32_16x16x32_bf16 v[42:45], v[164:167], v[204:207], v[42:45]
	v_mfma_f32_16x16x32_bf16 v[34:37], v[172:175], v[204:207], v[34:37]
	v_mfma_f32_16x16x32_bf16 v[26:29], v[164:167], v[224:227], v[26:29]
	v_mfma_f32_16x16x32_bf16 v[18:21], v[172:175], v[224:227], v[18:21]
	v_mfma_f32_16x16x32_bf16 v[10:13], v[164:167], v[232:235], v[10:13]
	v_mfma_f32_16x16x32_bf16 v[2:5], v[172:175], v[232:235], v[2:5]
	v_mfma_f32_16x16x32_bf16 v[58:61], v[168:171], v[200:203], v[58:61]
	v_mfma_f32_16x16x32_bf16 v[50:53], v[176:179], v[200:203], v[50:53]
	v_mfma_f32_16x16x32_bf16 v[42:45], v[168:171], v[220:223], v[42:45]
	v_mfma_f32_16x16x32_bf16 v[34:37], v[176:179], v[220:223], v[34:37]
	v_mfma_f32_16x16x32_bf16 v[26:29], v[168:171], v[228:231], v[26:29]
	v_mfma_f32_16x16x32_bf16 v[18:21], v[176:179], v[228:231], v[18:21]
	v_mfma_f32_16x16x32_bf16 v[10:13], v[168:171], v[236:239], v[10:13]
	v_mfma_f32_16x16x32_bf16 v[2:5], v[176:179], v[236:239], v[2:5]
	s_setprio 0
	s_setprio 1
	v_mfma_f32_16x16x32_bf16 v[62:65], v[180:183], v[196:199], v[62:65]
	v_mfma_f32_16x16x32_bf16 v[54:57], v[188:191], v[196:199], v[54:57]
	v_mfma_f32_16x16x32_bf16 v[46:49], v[180:183], v[204:207], v[46:49]
	v_mfma_f32_16x16x32_bf16 v[38:41], v[188:191], v[204:207], v[38:41]
	v_mfma_f32_16x16x32_bf16 v[30:33], v[180:183], v[224:227], v[30:33]
	v_mfma_f32_16x16x32_bf16 v[22:25], v[188:191], v[224:227], v[22:25]
	v_mfma_f32_16x16x32_bf16 v[14:17], v[180:183], v[232:235], v[14:17]
	v_mfma_f32_16x16x32_bf16 v[6:9], v[188:191], v[232:235], v[6:9]
	v_mfma_f32_16x16x32_bf16 v[62:65], v[184:187], v[200:203], v[62:65]
	v_mfma_f32_16x16x32_bf16 v[54:57], v[192:195], v[200:203], v[54:57]
	v_mfma_f32_16x16x32_bf16 v[46:49], v[184:187], v[220:223], v[46:49]
	v_mfma_f32_16x16x32_bf16 v[38:41], v[192:195], v[220:223], v[38:41]
	v_mfma_f32_16x16x32_bf16 v[30:33], v[184:187], v[228:231], v[30:33]
	v_mfma_f32_16x16x32_bf16 v[22:25], v[192:195], v[228:231], v[22:25]
	v_mfma_f32_16x16x32_bf16 v[14:17], v[184:187], v[236:239], v[14:17]
	v_mfma_f32_16x16x32_bf16 v[6:9], v[192:195], v[236:239], v[6:9]
	s_setprio 0
	s_add_i32 s53, s53, 2
	s_add_u32 s18, s18, 0x100
	s_addc_u32 s19, s19, 0
	s_add_u32 s51, s51, 0x100
	s_addc_u32 s52, s52, 0
	s_cmp_gt_u32 s53, 29
	s_cbranch_scc0 .Lh0_4
	s_branch .Ldone_4
.Lh1_4:
	s_add_u32 s20, s18, 0xfff80080
	s_addc_u32 s21, s19, -1
	s_add_i32 s54, 0, 0x10000
	s_cmp_eq_u32 s53, 28
	s_cselect_b32 s23, s9, s21
	s_cselect_b32 s22, s15, s20
	v_add_u32_e32 v158, s54, v160
	s_cselect_b32 s21, s7, s52
	s_cselect_b32 s20, s50, s51
	s_add_i32 s56, 0, 0x14000
	ds_read_b128 v[164:167], v158
	ds_read_b128 v[168:171], v158 offset:1024
	ds_read_b128 v[172:175], v158 offset:2048
	ds_read_b128 v[176:179], v158 offset:3072
	v_add_u32_e32 v158, s56, v160
	ds_read_b128 v[180:183], v158
	ds_read_b128 v[184:187], v158 offset:1024
	ds_read_b128 v[188:191], v158 offset:2048
	ds_read_b128 v[192:195], v158 offset:3072
	v_lshl_add_u64 v[158:159], s[18:19], 0, v[154:155]
	s_add_i32 m0, s17, 0xc000
	ds_read_b128 v[196:199], v162
	ds_read_b128 v[200:203], v162 offset:1024
	ds_read_b128 v[204:207], v162 offset:2048
	ds_read_b128 v[220:223], v162 offset:3072
	ds_read_b128 v[224:227], v162 offset:4096
	ds_read_b128 v[228:231], v162 offset:5120
	ds_read_b128 v[232:235], v162 offset:6144
	ds_read_b128 v[236:239], v162 offset:7168
	global_load_lds_dwordx4 v[158:159], off
	v_lshl_add_u64 v[158:159], s[18:19], 0, v[156:157]
	s_add_i32 m0, s17, 0xe000
	s_nop 0
	global_load_lds_dwordx4 v[158:159], off
	s_waitcnt vmcnt(8)
	s_waitcnt lgkmcnt(0)
	s_setprio 1
	s_waitcnt lgkmcnt(0)
	v_mfma_f32_16x16x32_bf16 v[122:125], v[164:167], v[196:199], v[122:125]
	v_mfma_f32_16x16x32_bf16 v[114:117], v[172:175], v[196:199], v[114:117]
	v_mfma_f32_16x16x32_bf16 v[106:109], v[164:167], v[204:207], v[106:109]
	v_mfma_f32_16x16x32_bf16 v[98:101], v[172:175], v[204:207], v[98:101]
	v_mfma_f32_16x16x32_bf16 v[90:93], v[164:167], v[224:227], v[90:93]
	v_mfma_f32_16x16x32_bf16 v[82:85], v[172:175], v[224:227], v[82:85]
	v_mfma_f32_16x16x32_bf16 v[74:77], v[164:167], v[232:235], v[74:77]
	v_mfma_f32_16x16x32_bf16 v[66:69], v[172:175], v[232:235], v[66:69]
	v_mfma_f32_16x16x32_bf16 v[122:125], v[168:171], v[200:203], v[122:125]
	v_mfma_f32_16x16x32_bf16 v[114:117], v[176:179], v[200:203], v[114:117]
	v_mfma_f32_16x16x32_bf16 v[106:109], v[168:171], v[220:223], v[106:109]
	v_mfma_f32_16x16x32_bf16 v[98:101], v[176:179], v[220:223], v[98:101]
	v_mfma_f32_16x16x32_bf16 v[90:93], v[168:171], v[228:231], v[90:93]
	v_mfma_f32_16x16x32_bf16 v[82:85], v[176:179], v[228:231], v[82:85]
	v_mfma_f32_16x16x32_bf16 v[74:77], v[168:171], v[236:239], v[74:77]
	v_mfma_f32_16x16x32_bf16 v[66:69], v[176:179], v[236:239], v[66:69]
	s_setprio 0
	s_setprio 1
	v_mfma_f32_16x16x32_bf16 v[126:129], v[180:183], v[196:199], v[126:129]
	v_mfma_f32_16x16x32_bf16 v[118:121], v[188:191], v[196:199], v[118:121]
	v_mfma_f32_16x16x32_bf16 v[110:113], v[180:183], v[204:207], v[110:113]
	v_mfma_f32_16x16x32_bf16 v[102:105], v[188:191], v[204:207], v[102:105]
	v_mfma_f32_16x16x32_bf16 v[94:97], v[180:183], v[224:227], v[94:97]
	v_mfma_f32_16x16x32_bf16 v[86:89], v[188:191], v[224:227], v[86:89]
	v_mfma_f32_16x16x32_bf16 v[78:81], v[180:183], v[232:235], v[78:81]
	v_mfma_f32_16x16x32_bf16 v[70:73], v[188:191], v[232:235], v[70:73]
	v_mfma_f32_16x16x32_bf16 v[126:129], v[184:187], v[200:203], v[126:129]
	v_mfma_f32_16x16x32_bf16 v[118:121], v[192:195], v[200:203], v[118:121]
	v_mfma_f32_16x16x32_bf16 v[110:113], v[184:187], v[220:223], v[110:113]
	v_mfma_f32_16x16x32_bf16 v[102:105], v[192:195], v[220:223], v[102:105]
	v_mfma_f32_16x16x32_bf16 v[94:97], v[184:187], v[228:231], v[94:97]
	v_mfma_f32_16x16x32_bf16 v[86:89], v[192:195], v[228:231], v[86:89]
	v_mfma_f32_16x16x32_bf16 v[78:81], v[184:187], v[236:239], v[78:81]
	v_mfma_f32_16x16x32_bf16 v[70:73], v[192:195], v[236:239], v[70:73]
	s_setprio 0
	s_barrier
	s_add_i32 s54, s54, s41
	v_lshl_add_u64 v[158:159], s[20:21], 0, v[0:1]
	s_mov_b32 m0, s54
	ds_read_b128 v[196:199], v162 offset:16384
	ds_read_b128 v[200:203], v162 offset:17408
	ds_read_b128 v[204:207], v162 offset:18432
	ds_read_b128 v[220:223], v162 offset:19456
	ds_read_b128 v[224:227], v162 offset:20480
	ds_read_b128 v[228:231], v162 offset:21504
	ds_read_b128 v[232:235], v162 offset:22528
	ds_read_b128 v[236:239], v162 offset:23552
	global_load_lds_dwordx4 v[158:159], off
	s_add_i32 m0, s54, 0x2000
	s_add_u32 s54, s20, 0x80000
	v_lshl_add_u64 v[208:209], s[20:21], 0, v[130:131]
	s_addc_u32 s55, s21, 0
	s_add_i32 s56, s56, s41
	global_load_lds_dwordx4 v[208:209], off
	v_lshl_add_u64 v[216:217], s[54:55], 0, v[0:1]
	s_mov_b32 m0, s56
	v_lshl_add_u64 v[244:245], s[22:23], 0, v[132:133]
	global_load_lds_dwordx4 v[216:217], off
	v_lshl_add_u64 v[216:217], s[54:55], 0, v[130:131]
	s_add_i32 m0, s56, 0x2000
	s_nop 0
	global_load_lds_dwordx4 v[216:217], off
	v_lshl_add_u64 v[216:217], s[22:23], 0, v[134:135]
	s_mov_b32 m0, s17
	s_nop 0
	global_load_lds_dwordx4 v[216:217], off
	s_mov_b32 m0, s43
	s_nop 0
	global_load_lds_dwordx4 v[244:245], off
	s_waitcnt vmcnt(8)
	s_waitcnt lgkmcnt(0)
	s_setprio 1
	s_waitcnt lgkmcnt(0)
	v_mfma_f32_16x16x32_bf16 v[58:61], v[164:167], v[196:199], v[58:61]
	v_mfma_f32_16x16x32_bf16 v[50:53], v[172:175], v[196:199], v[50:53]
	v_mfma_f32_16x16x32_bf16 v[42:45], v[164:167], v[204:207], v[42:45]
	v_mfma_f32_16x16x32_bf16 v[34:37], v[172:175], v[204:207], v[34:37]
	v_mfma_f32_16x16x32_bf16 v[26:29], v[164:167], v[224:227], v[26:29]
	v_mfma_f32_16x16x32_bf16 v[18:21], v[172:175], v[224:227], v[18:21]
	v_mfma_f32_16x16x32_bf16 v[10:13], v[164:167], v[232:235], v[10:13]
	v_mfma_f32_16x16x32_bf16 v[2:5], v[172:175], v[232:235], v[2:5]
	v_mfma_f32_16x16x32_bf16 v[58:61], v[168:171], v[200:203], v[58:61]
	v_mfma_f32_16x16x32_bf16 v[50:53], v[176:179], v[200:203], v[50:53]
	v_mfma_f32_16x16x32_bf16 v[42:45], v[168:171], v[220:223], v[42:45]
	v_mfma_f32_16x16x32_bf16 v[34:37], v[176:179], v[220:223], v[34:37]
	v_mfma_f32_16x16x32_bf16 v[26:29], v[168:171], v[228:231], v[26:29]
	v_mfma_f32_16x16x32_bf16 v[18:21], v[176:179], v[228:231], v[18:21]
	v_mfma_f32_16x16x32_bf16 v[10:13], v[168:171], v[236:239], v[10:13]
	v_mfma_f32_16x16x32_bf16 v[2:5], v[176:179], v[236:239], v[2:5]
	s_setprio 0
	s_setprio 1
	v_mfma_f32_16x16x32_bf16 v[62:65], v[180:183], v[196:199], v[62:65]
	v_mfma_f32_16x16x32_bf16 v[54:57], v[188:191], v[196:199], v[54:57]
	v_mfma_f32_16x16x32_bf16 v[46:49], v[180:183], v[204:207], v[46:49]
	v_mfma_f32_16x16x32_bf16 v[38:41], v[188:191], v[204:207], v[38:41]
	v_mfma_f32_16x16x32_bf16 v[30:33], v[180:183], v[224:227], v[30:33]
	v_mfma_f32_16x16x32_bf16 v[22:25], v[188:191], v[224:227], v[22:25]
	v_mfma_f32_16x16x32_bf16 v[14:17], v[180:183], v[232:235], v[14:17]
	v_mfma_f32_16x16x32_bf16 v[6:9], v[188:191], v[232:235], v[6:9]
	v_mfma_f32_16x16x32_bf16 v[62:65], v[184:187], v[200:203], v[62:65]
	v_mfma_f32_16x16x32_bf16 v[54:57], v[192:195], v[200:203], v[54:57]
	v_mfma_f32_16x16x32_bf16 v[46:49], v[184:187], v[220:223], v[46:49]
	v_mfma_f32_16x16x32_bf16 v[38:41], v[192:195], v[220:223], v[38:41]
	v_mfma_f32_16x16x32_bf16 v[30:33], v[184:187], v[228:231], v[30:33]
	v_mfma_f32_16x16x32_bf16 v[22:25], v[192:195], v[228:231], v[22:25]
	v_mfma_f32_16x16x32_bf16 v[14:17], v[184:187], v[236:239], v[14:17]
	v_mfma_f32_16x16x32_bf16 v[6:9], v[192:195], v[236:239], v[6:9]
	s_setprio 0
	s_barrier
	s_add_i32 s54, 0, 0x18000
	v_add_u32_e32 v163, s54, v160
	s_add_i32 s55, 0, 0x1c000
	ds_read_b128 v[164:167], v163
	ds_read_b128 v[168:171], v163 offset:1024
	ds_read_b128 v[172:175], v163 offset:2048
	ds_read_b128 v[176:179], v163 offset:3072
	v_add_u32_e32 v163, s55, v160
	ds_read_b128 v[180:183], v163
	ds_read_b128 v[184:187], v163 offset:1024
	ds_read_b128 v[188:191], v163 offset:2048
	ds_read_b128 v[192:195], v163 offset:3072
	s_add_u32 s22, s22, 0x80000
	s_addc_u32 s23, s23, 0
	s_mov_b32 m0, s44
	v_lshl_add_u64 v[246:247], s[22:23], 0, v[134:135]
	ds_read_b128 v[196:199], v162 offset:32768
	ds_read_b128 v[200:203], v162 offset:33792
	ds_read_b128 v[204:207], v162 offset:34816
	ds_read_b128 v[220:223], v162 offset:35840
	ds_read_b128 v[224:227], v162 offset:36864
	ds_read_b128 v[228:231], v162 offset:37888
	ds_read_b128 v[232:235], v162 offset:38912
	ds_read_b128 v[236:239], v162 offset:39936
	global_load_lds_dwordx4 v[246:247], off
	v_lshl_add_u64 v[246:247], s[22:23], 0, v[132:133]
	s_mov_b32 m0, s45
	s_nop 0
	global_load_lds_dwordx4 v[246:247], off
	s_waitcnt vmcnt(8)
	s_waitcnt lgkmcnt(0)
	s_setprio 1
	s_waitcnt lgkmcnt(0)
	v_mfma_f32_16x16x32_bf16 v[122:125], v[164:167], v[196:199], v[122:125]
	v_mfma_f32_16x16x32_bf16 v[114:117], v[172:175], v[196:199], v[114:117]
	v_mfma_f32_16x16x32_bf16 v[106:109], v[164:167], v[204:207], v[106:109]
	v_mfma_f32_16x16x32_bf16 v[98:101], v[172:175], v[204:207], v[98:101]
	v_mfma_f32_16x16x32_bf16 v[90:93], v[164:167], v[224:227], v[90:93]
	v_mfma_f32_16x16x32_bf16 v[82:85], v[172:175], v[224:227], v[82:85]
	v_mfma_f32_16x16x32_bf16 v[74:77], v[164:167], v[232:235], v[74:77]
	v_mfma_f32_16x16x32_bf16 v[66:69], v[172:175], v[232:235], v[66:69]
	v_mfma_f32_16x16x32_bf16 v[122:125], v[168:171], v[200:203], v[122:125]
	v_mfma_f32_16x16x32_bf16 v[114:117], v[176:179], v[200:203], v[114:117]
	v_mfma_f32_16x16x32_bf16 v[106:109], v[168:171], v[220:223], v[106:109]
	v_mfma_f32_16x16x32_bf16 v[98:101], v[176:179], v[220:223], v[98:101]
	v_mfma_f32_16x16x32_bf16 v[90:93], v[168:171], v[228:231], v[90:93]
	v_mfma_f32_16x16x32_bf16 v[82:85], v[176:179], v[228:231], v[82:85]
	v_mfma_f32_16x16x32_bf16 v[74:77], v[168:171], v[236:239], v[74:77]
	v_mfma_f32_16x16x32_bf16 v[66:69], v[176:179], v[236:239], v[66:69]
	s_setprio 0
	s_setprio 1
	v_mfma_f32_16x16x32_bf16 v[126:129], v[180:183], v[196:199], v[126:129]
	v_mfma_f32_16x16x32_bf16 v[118:121], v[188:191], v[196:199], v[118:121]
	v_mfma_f32_16x16x32_bf16 v[110:113], v[180:183], v[204:207], v[110:113]
	v_mfma_f32_16x16x32_bf16 v[102:105], v[188:191], v[204:207], v[102:105]
	v_mfma_f32_16x16x32_bf16 v[94:97], v[180:183], v[224:227], v[94:97]
	v_mfma_f32_16x16x32_bf16 v[86:89], v[188:191], v[224:227], v[86:89]
	v_mfma_f32_16x16x32_bf16 v[78:81], v[180:183], v[232:235], v[78:81]
	v_mfma_f32_16x16x32_bf16 v[70:73], v[188:191], v[232:235], v[70:73]
	v_mfma_f32_16x16x32_bf16 v[126:129], v[184:187], v[200:203], v[126:129]
	v_mfma_f32_16x16x32_bf16 v[118:121], v[192:195], v[200:203], v[118:121]
	v_mfma_f32_16x16x32_bf16 v[110:113], v[184:187], v[220:223], v[110:113]
	v_mfma_f32_16x16x32_bf16 v[102:105], v[192:195], v[220:223], v[102:105]
	v_mfma_f32_16x16x32_bf16 v[94:97], v[184:187], v[228:231], v[94:97]
	v_mfma_f32_16x16x32_bf16 v[86:89], v[192:195], v[228:231], v[86:89]
	v_mfma_f32_16x16x32_bf16 v[78:81], v[184:187], v[236:239], v[78:81]
	v_mfma_f32_16x16x32_bf16 v[70:73], v[192:195], v[236:239], v[70:73]
	s_setprio 0
	s_barrier
	s_add_i32 s22, s54, s41
	v_lshl_add_u64 v[158:159], v[158:159], 0, s[2:3]
	s_mov_b32 m0, s22
	ds_read_b128 v[196:199], v162 offset:49152
	ds_read_b128 v[200:203], v162 offset:50176
	ds_read_b128 v[204:207], v162 offset:51200
	ds_read_b128 v[220:223], v162 offset:52224
	ds_read_b128 v[224:227], v162 offset:53248
	ds_read_b128 v[228:231], v162 offset:54272
	ds_read_b128 v[232:235], v162 offset:55296
	ds_read_b128 v[236:239], v162 offset:56320
	global_load_lds_dwordx4 v[158:159], off
	s_add_i32 m0, s22, 0x2000
	s_add_u32 s20, s20, 0x80080
	v_lshl_add_u64 v[158:159], v[208:209], 0, s[2:3]
	s_addc_u32 s21, s21, 0
	s_add_i32 s22, s55, s41
	global_load_lds_dwordx4 v[158:159], off
	v_lshl_add_u64 v[158:159], s[20:21], 0, v[0:1]
	s_mov_b32 m0, s22
	s_nop 0
	global_load_lds_dwordx4 v[158:159], off
	v_lshl_add_u64 v[158:159], s[20:21], 0, v[130:131]
	s_add_i32 m0, s22, 0x2000
	s_nop 0
	global_load_lds_dwordx4 v[158:159], off
	v_lshl_add_u64 v[158:159], v[216:217], 0, s[2:3]
	s_mov_b32 m0, s46
	s_nop 0
	global_load_lds_dwordx4 v[158:159], off
	v_lshl_add_u64 v[158:159], v[244:245], 0, s[2:3]
	s_mov_b32 m0, s47
	s_nop 0
	global_load_lds_dwordx4 v[158:159], off
	s_waitcnt vmcnt(8)
	s_waitcnt lgkmcnt(0)
	s_setprio 1
	s_waitcnt lgkmcnt(0)
	v_mfma_f32_16x16x32_bf16 v[58:61], v[164:167], v[196:199], v[58:61]
	v_mfma_f32_16x16x32_bf16 v[50:53], v[172:175], v[196:199], v[50:53]
	v_mfma_f32_16x16x32_bf16 v[42:45], v[164:167], v[204:207], v[42:45]
	v_mfma_f32_16x16x32_bf16 v[34:37], v[172:175], v[204:207], v[34:37]
	v_mfma_f32_16x16x32_bf16 v[26:29], v[164:167], v[224:227], v[26:29]
	v_mfma_f32_16x16x32_bf16 v[18:21], v[172:175], v[224:227], v[18:21]
	v_mfma_f32_16x16x32_bf16 v[10:13], v[164:167], v[232:235], v[10:13]
	v_mfma_f32_16x16x32_bf16 v[2:5], v[172:175], v[232:235], v[2:5]
	v_mfma_f32_16x16x32_bf16 v[58:61], v[168:171], v[200:203], v[58:61]
	v_mfma_f32_16x16x32_bf16 v[50:53], v[176:179], v[200:203], v[50:53]
	v_mfma_f32_16x16x32_bf16 v[42:45], v[168:171], v[220:223], v[42:45]
	v_mfma_f32_16x16x32_bf16 v[34:37], v[176:179], v[220:223], v[34:37]
	v_mfma_f32_16x16x32_bf16 v[26:29], v[168:171], v[228:231], v[26:29]
	v_mfma_f32_16x16x32_bf16 v[18:21], v[176:179], v[228:231], v[18:21]
	v_mfma_f32_16x16x32_bf16 v[10:13], v[168:171], v[236:239], v[10:13]
	v_mfma_f32_16x16x32_bf16 v[2:5], v[176:179], v[236:239], v[2:5]
	s_setprio 0
	s_setprio 1
	v_mfma_f32_16x16x32_bf16 v[62:65], v[180:183], v[196:199], v[62:65]
	v_mfma_f32_16x16x32_bf16 v[54:57], v[188:191], v[196:199], v[54:57]
	v_mfma_f32_16x16x32_bf16 v[46:49], v[180:183], v[204:207], v[46:49]
	v_mfma_f32_16x16x32_bf16 v[38:41], v[188:191], v[204:207], v[38:41]
	v_mfma_f32_16x16x32_bf16 v[30:33], v[180:183], v[224:227], v[30:33]
	v_mfma_f32_16x16x32_bf16 v[22:25], v[188:191], v[224:227], v[22:25]
	v_mfma_f32_16x16x32_bf16 v[14:17], v[180:183], v[232:235], v[14:17]
	v_mfma_f32_16x16x32_bf16 v[6:9], v[188:191], v[232:235], v[6:9]
	v_mfma_f32_16x16x32_bf16 v[62:65], v[184:187], v[200:203], v[62:65]
	v_mfma_f32_16x16x32_bf16 v[54:57], v[192:195], v[200:203], v[54:57]
	v_mfma_f32_16x16x32_bf16 v[46:49], v[184:187], v[220:223], v[46:49]
	v_mfma_f32_16x16x32_bf16 v[38:41], v[192:195], v[220:223], v[38:41]
	v_mfma_f32_16x16x32_bf16 v[30:33], v[184:187], v[228:231], v[30:33]
	v_mfma_f32_16x16x32_bf16 v[22:25], v[192:195], v[228:231], v[22:25]
	v_mfma_f32_16x16x32_bf16 v[14:17], v[184:187], v[236:239], v[14:17]
	v_mfma_f32_16x16x32_bf16 v[6:9], v[192:195], v[236:239], v[6:9]
	s_setprio 0
	s_barrier
	s_add_i32 s53, s53, 2
	s_add_u32 s18, s18, 0x100
	s_addc_u32 s19, s19, 0
	s_add_u32 s51, s51, 0x100
	s_addc_u32 s52, s52, 0
	s_cmp_gt_u32 s53, 29
	s_cbranch_scc0 .Lh1_4

.LBB0_1568:
	v_lshl_add_u32 v158, s16, 7, v161
	v_ashrrev_i32_e32 v158, 6, v158
	v_ashrrev_i32_e32 v159, 31, v158
	v_mov_b32_e32 v163, 0x58
	v_mad_i64_i32 v[158:159], s[14:15], s14, v163, v[158:159]
	v_exp_f32_e32 v163, v122
	v_pk_mul_f32 v[128:129], v[124:125], v[128:129]
	v_pk_mul_f32 v[120:121], v[116:117], v[120:121]
	v_pk_mul_f32 v[112:113], v[108:109], v[112:113]
	v_add_f32_e32 v163, 1.0, v163
	v_rcp_f32_e32 v166, v163
	v_exp_f32_e32 v163, v123
	v_pk_mul_f32 v[122:123], v[122:123], v[126:127]
	v_pk_mul_f32 v[104:105], v[100:101], v[104:105]
	v_pk_mul_f32 v[96:97], v[92:93], v[96:97]
	v_add_f32_e32 v163, 1.0, v163
	v_rcp_f32_e32 v167, v163
	v_pk_mul_f32 v[88:89], v[84:85], v[88:89]
	v_pk_mul_f32 v[80:81], v[76:77], v[80:81]
	v_pk_mul_f32 v[72:73], v[68:69], v[72:73]
	v_pk_mul_f32 v[122:123], v[166:167], v[122:123]
	v_pk_mul_f32 v[64:65], v[60:61], v[64:65]
	v_cvt_pk_bf16_f32 v122, v122, v123
	v_exp_f32_e32 v123, v124
	v_pk_mul_f32 v[56:57], v[52:53], v[56:57]
	v_pk_mul_f32 v[48:49], v[44:45], v[48:49]
	v_pk_mul_f32 v[40:41], v[36:37], v[40:41]
	v_add_f32_e32 v123, 1.0, v123
	v_rcp_f32_e32 v124, v123
	v_exp_f32_e32 v123, v125
	v_pk_mul_f32 v[32:33], v[28:29], v[32:33]
	v_pk_mul_f32 v[24:25], v[20:21], v[24:25]
	v_pk_mul_f32 v[16:17], v[12:13], v[16:17]
	v_add_f32_e32 v123, 1.0, v123
	v_rcp_f32_e32 v125, v123
	v_lshlrev_b64 v[158:159], 15, v[158:159]
	v_pk_mul_f32 v[8:9], v[4:5], v[8:9]
	v_lshl_add_u64 v[158:159], v[152:153], 0, v[158:159]
	v_pk_mul_f32 v[124:125], v[124:125], v[128:129]
	v_lshl_add_u64 v[164:165], v[158:159], 0, v[136:137]
	v_cvt_pk_bf16_f32 v123, v124, v125
	v_exp_f32_e32 v124, v114
	v_exp_f32_e32 v125, v115
	v_pk_mul_f32 v[114:115], v[114:115], v[118:119]
	s_mov_b64 s[14:15], -1
	v_add_f32_e32 v124, 1.0, v124
	v_add_f32_e32 v125, 1.0, v125
	v_rcp_f32_e32 v124, v124
	v_rcp_f32_e32 v125, v125
	s_andn2_b64 vcc, exec, s[34:35]
	v_pk_mul_f32 v[114:115], v[124:125], v[114:115]
	s_nop 0
	v_cvt_pk_bf16_f32 v124, v114, v115
	v_exp_f32_e32 v114, v116
	v_exp_f32_e32 v115, v117
	v_exp_f32_e32 v116, v106
	v_exp_f32_e32 v117, v107
	v_pk_mul_f32 v[106:107], v[106:107], v[110:111]
	v_add_f32_e32 v114, 1.0, v114
	v_add_f32_e32 v116, 1.0, v116
	v_add_f32_e32 v117, 1.0, v117
	v_rcp_f32_e32 v116, v116
	v_rcp_f32_e32 v117, v117
	v_add_f32_e32 v115, 1.0, v115
	v_rcp_f32_e32 v114, v114
	v_rcp_f32_e32 v115, v115
	v_pk_mul_f32 v[106:107], v[116:117], v[106:107]
	v_pk_mul_f32 v[114:115], v[114:115], v[120:121]
	v_cvt_pk_bf16_f32 v106, v106, v107
	v_exp_f32_e32 v107, v108
	v_cvt_pk_bf16_f32 v125, v114, v115
	v_lshl_add_u64 v[114:115], v[158:159], 0, v[138:139]
	global_store_dwordx4 v[164:165], v[122:125], off
	v_add_f32_e32 v107, 1.0, v107
	v_rcp_f32_e32 v108, v107
	v_exp_f32_e32 v107, v109
	s_nop 0
	v_add_f32_e32 v107, 1.0, v107
	v_rcp_f32_e32 v109, v107
	s_nop 0
	v_pk_mul_f32 v[108:109], v[108:109], v[112:113]
	s_nop 0
	v_cvt_pk_bf16_f32 v107, v108, v109
	v_exp_f32_e32 v108, v98
	v_exp_f32_e32 v109, v99
	v_pk_mul_f32 v[98:99], v[98:99], v[102:103]
	v_add_f32_e32 v108, 1.0, v108
	v_add_f32_e32 v109, 1.0, v109
	v_rcp_f32_e32 v108, v108
	v_rcp_f32_e32 v109, v109
	s_nop 0
	v_pk_mul_f32 v[98:99], v[108:109], v[98:99]
	s_nop 0
	v_cvt_pk_bf16_f32 v108, v98, v99
	v_exp_f32_e32 v98, v100
	v_exp_f32_e32 v99, v101
	v_exp_f32_e32 v100, v90
	v_exp_f32_e32 v101, v91
	v_pk_mul_f32 v[90:91], v[90:91], v[94:95]
	v_add_f32_e32 v98, 1.0, v98
	v_add_f32_e32 v100, 1.0, v100
	v_add_f32_e32 v101, 1.0, v101
	v_rcp_f32_e32 v100, v100
	v_rcp_f32_e32 v101, v101
	v_add_f32_e32 v99, 1.0, v99
	v_rcp_f32_e32 v98, v98
	v_rcp_f32_e32 v99, v99
	v_pk_mul_f32 v[90:91], v[100:101], v[90:91]
	v_pk_mul_f32 v[98:99], v[98:99], v[104:105]
	v_cvt_pk_bf16_f32 v90, v90, v91
	v_exp_f32_e32 v91, v92
	v_cvt_pk_bf16_f32 v109, v98, v99
	v_lshl_add_u64 v[98:99], v[158:159], 0, v[140:141]
	global_store_dwordx4 v[114:115], v[106:109], off
	v_add_f32_e32 v91, 1.0, v91
	v_rcp_f32_e32 v92, v91
	v_exp_f32_e32 v91, v93
	s_nop 0
	v_add_f32_e32 v91, 1.0, v91
	v_rcp_f32_e32 v93, v91
	s_nop 0
	v_pk_mul_f32 v[92:93], v[92:93], v[96:97]
	s_nop 0
	v_cvt_pk_bf16_f32 v91, v92, v93
	v_exp_f32_e32 v92, v82
	v_exp_f32_e32 v93, v83
	v_pk_mul_f32 v[82:83], v[82:83], v[86:87]
	v_add_f32_e32 v92, 1.0, v92
	v_add_f32_e32 v93, 1.0, v93
	v_rcp_f32_e32 v92, v92
	v_rcp_f32_e32 v93, v93
	s_nop 0
	v_pk_mul_f32 v[82:83], v[92:93], v[82:83]
	s_nop 0
	v_cvt_pk_bf16_f32 v92, v82, v83
	v_exp_f32_e32 v82, v84
	v_exp_f32_e32 v83, v85
	v_exp_f32_e32 v84, v74
	v_exp_f32_e32 v85, v75
	v_pk_mul_f32 v[74:75], v[74:75], v[78:79]
	v_add_f32_e32 v82, 1.0, v82
	v_add_f32_e32 v84, 1.0, v84
	v_add_f32_e32 v85, 1.0, v85
	v_rcp_f32_e32 v84, v84
	v_rcp_f32_e32 v85, v85
	v_add_f32_e32 v83, 1.0, v83
	v_rcp_f32_e32 v82, v82
	v_rcp_f32_e32 v83, v83
	v_pk_mul_f32 v[74:75], v[84:85], v[74:75]
	v_pk_mul_f32 v[82:83], v[82:83], v[88:89]
	v_cvt_pk_bf16_f32 v74, v74, v75
	v_exp_f32_e32 v75, v76
	v_cvt_pk_bf16_f32 v93, v82, v83
	v_lshl_add_u64 v[82:83], v[158:159], 0, v[142:143]
	global_store_dwordx4 v[98:99], v[90:93], off
	v_add_f32_e32 v75, 1.0, v75
	v_rcp_f32_e32 v76, v75
	v_exp_f32_e32 v75, v77
	s_nop 0
	v_add_f32_e32 v75, 1.0, v75
	v_rcp_f32_e32 v77, v75
	s_nop 0
	v_pk_mul_f32 v[76:77], v[76:77], v[80:81]
	s_nop 0
	v_cvt_pk_bf16_f32 v75, v76, v77
	v_exp_f32_e32 v76, v66
	v_exp_f32_e32 v77, v67
	v_pk_mul_f32 v[66:67], v[66:67], v[70:71]
	v_add_f32_e32 v76, 1.0, v76
	v_add_f32_e32 v77, 1.0, v77
	v_rcp_f32_e32 v76, v76
	v_rcp_f32_e32 v77, v77
	s_nop 0
	v_pk_mul_f32 v[66:67], v[76:77], v[66:67]
	s_nop 0
	v_cvt_pk_bf16_f32 v76, v66, v67
	v_exp_f32_e32 v66, v68
	v_exp_f32_e32 v67, v69
	v_exp_f32_e32 v68, v58
	v_exp_f32_e32 v69, v59
	v_pk_mul_f32 v[58:59], v[58:59], v[62:63]
	v_add_f32_e32 v66, 1.0, v66
	v_add_f32_e32 v68, 1.0, v68
	v_add_f32_e32 v69, 1.0, v69
	v_rcp_f32_e32 v68, v68
	v_rcp_f32_e32 v69, v69
	v_add_f32_e32 v67, 1.0, v67
	v_rcp_f32_e32 v66, v66
	v_rcp_f32_e32 v67, v67
	v_pk_mul_f32 v[58:59], v[68:69], v[58:59]
	v_pk_mul_f32 v[66:67], v[66:67], v[72:73]
	v_cvt_pk_bf16_f32 v58, v58, v59
	v_exp_f32_e32 v59, v60
	v_cvt_pk_bf16_f32 v77, v66, v67
	v_lshl_add_u64 v[66:67], v[158:159], 0, v[144:145]
	global_store_dwordx4 v[82:83], v[74:77], off
	v_add_f32_e32 v59, 1.0, v59
	v_rcp_f32_e32 v60, v59
	v_exp_f32_e32 v59, v61
	s_nop 0
	v_add_f32_e32 v59, 1.0, v59
	v_rcp_f32_e32 v61, v59
	s_nop 0
	v_pk_mul_f32 v[60:61], v[60:61], v[64:65]
	s_nop 0
	v_cvt_pk_bf16_f32 v59, v60, v61
	v_exp_f32_e32 v60, v50
	v_exp_f32_e32 v61, v51
	v_pk_mul_f32 v[50:51], v[50:51], v[54:55]
	v_add_f32_e32 v60, 1.0, v60
	v_add_f32_e32 v61, 1.0, v61
	v_rcp_f32_e32 v60, v60
	v_rcp_f32_e32 v61, v61
	s_nop 0
	v_pk_mul_f32 v[50:51], v[60:61], v[50:51]
	s_nop 0
	v_cvt_pk_bf16_f32 v60, v50, v51
	v_exp_f32_e32 v50, v52
	v_exp_f32_e32 v51, v53
	v_exp_f32_e32 v52, v42
	v_exp_f32_e32 v53, v43
	v_pk_mul_f32 v[42:43], v[42:43], v[46:47]
	v_add_f32_e32 v50, 1.0, v50
	v_add_f32_e32 v52, 1.0, v52
	v_add_f32_e32 v53, 1.0, v53
	v_rcp_f32_e32 v52, v52
	v_rcp_f32_e32 v53, v53
	v_add_f32_e32 v51, 1.0, v51
	v_rcp_f32_e32 v50, v50
	v_rcp_f32_e32 v51, v51
	v_pk_mul_f32 v[42:43], v[52:53], v[42:43]
	v_pk_mul_f32 v[50:51], v[50:51], v[56:57]
	v_cvt_pk_bf16_f32 v42, v42, v43
	v_exp_f32_e32 v43, v44
	v_cvt_pk_bf16_f32 v61, v50, v51
	v_lshl_add_u64 v[50:51], v[158:159], 0, v[146:147]
	global_store_dwordx4 v[66:67], v[58:61], off
	v_add_f32_e32 v43, 1.0, v43
	v_rcp_f32_e32 v44, v43
	v_exp_f32_e32 v43, v45
	s_nop 0
	v_add_f32_e32 v43, 1.0, v43
	v_rcp_f32_e32 v45, v43
	s_nop 0
	v_pk_mul_f32 v[44:45], v[44:45], v[48:49]
	s_nop 0
	v_cvt_pk_bf16_f32 v43, v44, v45
	v_exp_f32_e32 v44, v34
	v_exp_f32_e32 v45, v35
	v_pk_mul_f32 v[34:35], v[34:35], v[38:39]
	v_add_f32_e32 v44, 1.0, v44
	v_add_f32_e32 v45, 1.0, v45
	v_rcp_f32_e32 v44, v44
	v_rcp_f32_e32 v45, v45
	s_nop 0
	v_pk_mul_f32 v[34:35], v[44:45], v[34:35]
	s_nop 0
	v_cvt_pk_bf16_f32 v44, v34, v35
	v_exp_f32_e32 v34, v36
	v_exp_f32_e32 v35, v37
	v_exp_f32_e32 v36, v26
	v_exp_f32_e32 v37, v27
	v_pk_mul_f32 v[26:27], v[26:27], v[30:31]
	v_add_f32_e32 v34, 1.0, v34
	v_add_f32_e32 v36, 1.0, v36
	v_add_f32_e32 v37, 1.0, v37
	v_rcp_f32_e32 v36, v36
	v_rcp_f32_e32 v37, v37
	v_add_f32_e32 v35, 1.0, v35
	v_rcp_f32_e32 v34, v34
	v_rcp_f32_e32 v35, v35
	v_pk_mul_f32 v[26:27], v[36:37], v[26:27]
	v_pk_mul_f32 v[34:35], v[34:35], v[40:41]
	v_cvt_pk_bf16_f32 v26, v26, v27
	v_exp_f32_e32 v27, v28
	v_cvt_pk_bf16_f32 v45, v34, v35
	v_lshl_add_u64 v[34:35], v[158:159], 0, v[148:149]
	global_store_dwordx4 v[50:51], v[42:45], off
	v_add_f32_e32 v27, 1.0, v27
	v_rcp_f32_e32 v28, v27
	v_exp_f32_e32 v27, v29
	s_nop 0
	v_add_f32_e32 v27, 1.0, v27
	v_rcp_f32_e32 v29, v27
	s_nop 0
	v_pk_mul_f32 v[28:29], v[28:29], v[32:33]
	s_nop 0
	v_cvt_pk_bf16_f32 v27, v28, v29
	v_exp_f32_e32 v28, v18
	v_exp_f32_e32 v29, v19
	v_pk_mul_f32 v[18:19], v[18:19], v[22:23]
	v_add_f32_e32 v28, 1.0, v28
	v_add_f32_e32 v29, 1.0, v29
	v_rcp_f32_e32 v28, v28
	v_rcp_f32_e32 v29, v29
	s_nop 0
	v_pk_mul_f32 v[18:19], v[28:29], v[18:19]
	s_nop 0
	v_cvt_pk_bf16_f32 v28, v18, v19
	v_exp_f32_e32 v18, v20
	v_exp_f32_e32 v19, v21
	v_exp_f32_e32 v20, v10
	v_exp_f32_e32 v21, v11
	v_pk_mul_f32 v[10:11], v[10:11], v[14:15]
	v_add_f32_e32 v18, 1.0, v18
	v_add_f32_e32 v20, 1.0, v20
	v_add_f32_e32 v21, 1.0, v21
	v_rcp_f32_e32 v20, v20
	v_rcp_f32_e32 v21, v21
	v_add_f32_e32 v19, 1.0, v19
	v_rcp_f32_e32 v18, v18
	v_rcp_f32_e32 v19, v19
	v_pk_mul_f32 v[10:11], v[20:21], v[10:11]
	v_pk_mul_f32 v[18:19], v[18:19], v[24:25]
	v_cvt_pk_bf16_f32 v10, v10, v11
	v_exp_f32_e32 v11, v12
	v_cvt_pk_bf16_f32 v29, v18, v19
	v_lshl_add_u64 v[18:19], v[158:159], 0, v[150:151]
	global_store_dwordx4 v[34:35], v[26:29], off
	v_add_f32_e32 v11, 1.0, v11
	v_rcp_f32_e32 v12, v11
	v_exp_f32_e32 v11, v13
	s_nop 0
	v_add_f32_e32 v11, 1.0, v11
	v_rcp_f32_e32 v13, v11
	s_nop 0
	v_pk_mul_f32 v[12:13], v[12:13], v[16:17]
	s_nop 0
	v_cvt_pk_bf16_f32 v11, v12, v13
	v_exp_f32_e32 v12, v2
	v_exp_f32_e32 v13, v3
	v_pk_mul_f32 v[2:3], v[2:3], v[6:7]
	v_add_f32_e32 v12, 1.0, v12
	v_add_f32_e32 v13, 1.0, v13
	v_rcp_f32_e32 v12, v12
	v_rcp_f32_e32 v13, v13
	s_nop 0
	v_pk_mul_f32 v[2:3], v[12:13], v[2:3]
	s_nop 0
	v_cvt_pk_bf16_f32 v12, v2, v3
	v_exp_f32_e32 v2, v4
	v_exp_f32_e32 v3, v5
	v_add_f32_e32 v2, 1.0, v2
	v_add_f32_e32 v3, 1.0, v3
	v_rcp_f32_e32 v2, v2
	v_rcp_f32_e32 v3, v3
	s_nop 0
	v_pk_mul_f32 v[2:3], v[2:3], v[8:9]
	s_nop 0
	v_cvt_pk_bf16_f32 v13, v2, v3
	global_store_dwordx4 v[18:19], v[10:13], off
	s_cbranch_vccnz .LBB0_1561
	s_andn2_b64 vcc, exec, s[0:1]
	s_cbranch_vccnz .LBB0_1560
	s_branch .LBB0_1560

.LBB0_1830:
	v_readlane_b32 s8, v255, 33
	v_readlane_b32 s34, v255, 37
	v_readlane_b32 s9, v255, 34
	s_add_u32 s87, s8, 0xa000
	v_readlane_b32 s35, v255, 38
	s_addc_u32 s89, s9, 0
	s_lshl_b64 s[0:1], s[34:35], 13
	v_readlane_b32 s16, v253, 6
	v_readlane_b32 s17, v253, 7
	s_add_u32 s94, s16, s0
	v_readlane_b32 s18, v253, 8
	v_readlane_b32 s20, v253, 10
	s_addc_u32 s95, s17, s1
	v_readlane_b32 s19, v253, 9
	v_readlane_b32 s21, v253, 11
	s_add_u32 s20, s18, s0
	s_addc_u32 s21, s19, s1
	v_readlane_b32 s0, v255, 29
	v_readlane_b32 s1, v255, 30
	s_or_b64 s[4:5], s[84:85], s[0:1]
	s_xor_b64 s[0:1], s[4:5], -1
	s_add_u32 s8, s8, 0x3c000
	s_addc_u32 s9, s9, 0
	v_readlane_b32 s25, v253, 15
	s_and_b64 s[4:5], s[4:5], exec
	s_cselect_b32 s25, 0, s9
	s_cselect_b32 s72, 0, s8
	s_lshl_b32 s68, s34, 13
	s_lshl_b64 s[4:5], s[68:69], 2
	v_readlane_b32 s8, v254, 44
	s_add_u32 s4, s8, s4
	v_readlane_b32 s8, v254, 45
	s_addc_u32 s5, s8, s5
	s_add_u32 s68, s4, 0x4000
	s_addc_u32 s73, s5, 0
	s_and_b32 s8, s6, 3
	s_add_i32 m0, s47, 0x18000
	v_lshl_add_u64 v[2:3], v[2:3], 0, s[2:3]
	s_lshl_b32 s48, s7, 6
	s_lshl_b32 s49, s8, 5
	s_waitcnt vmcnt(2)
	s_barrier
	global_load_lds_dwordx4 v[2:3], off
	s_add_i32 m0, s47, 0x1a000
	s_add_u32 s4, s12, 0x8000
	v_mov_b32_e32 v221, v1
	v_lshl_add_u64 v[2:3], v[4:5], 0, s[2:3]
	s_addc_u32 s5, s13, 0
	s_add_i32 s50, s47, 0x8000
	v_mov_b32_e32 v225, v1
	global_load_lds_dwordx4 v[2:3], off
	v_lshl_add_u64 v[2:3], s[4:5], 0, v[220:221]
	s_mov_b32 m0, s50
	s_add_i32 s51, s47, 0xa000
	global_load_lds_dwordx4 v[2:3], off
	v_lshl_add_u64 v[2:3], s[4:5], 0, v[224:225]
	s_add_u32 s4, s14, 0x164080
	s_mov_b32 m0, s51
	s_addc_u32 s5, s15, 0
	global_load_lds_dwordx4 v[2:3], off
	s_add_i32 m0, s47, 0x1c000
	v_lshl_add_u64 v[2:3], s[4:5], 0, v[222:223]
	global_load_lds_dwordx4 v[2:3], off
	v_lshl_add_u64 v[2:3], s[4:5], 0, v[226:227]
	s_add_i32 m0, s47, 0x1e000
	s_cmp_lt_u32 s6, 4
	global_load_lds_dwordx4 v[2:3], off
	v_lshlrev_b32_e32 v2, 10, v0
	v_and_b32_e32 v2, 0xfffff800, v2
	s_cselect_b64 s[44:45], -1, 0
	s_lshl_b32 s9, s7, 11
	s_lshl_b32 s52, s6, 5
	v_lshl_add_u32 v2, v6, 7, v2
	v_and_b32_e32 v0, 1, v0
	s_cmp_eq_u32 s6, 0
	v_lshl_or_b32 v0, v0, 6, v2
	s_cselect_b64 s[4:5], -1, 0
	s_lshl_b32 s6, s8, 3
	v_lshl_add_u32 v228, v7, 1, v0
	v_lshlrev_b32_e32 v0, 10, v8
	v_ashrrev_i32_e32 v251, 4, v11
	v_and_b32_e32 v243, 15, v11
	v_and_b32_e32 v13, 48, v11
	v_and_b32_e32 v12, 0xfffffc00, v12
	v_lshlrev_b32_e32 v11, 2, v11
	s_add_i32 s6, s6, 0
	v_and_b32_e32 v0, 0xfffff800, v0
	v_readlane_b32 s26, v253, 16
	v_readlane_b32 s27, v253, 17
	v_readlane_b32 s28, v253, 18
	v_readlane_b32 s29, v253, 19
	v_readlane_b32 s30, v253, 20
	v_readlane_b32 s31, v253, 21
	v_lshl_add_u32 v14, s7, 13, v12
	v_lshl_or_b32 v13, v243, 6, v13
	v_and_b32_e32 v11, 32, v11
	s_waitcnt vmcnt(6)
	s_add_i32 s55, s6, s9
	s_lshl_b32 s6, s7, 9
	v_lshl_add_u32 v0, v9, 7, v0
	v_and_b32_e32 v2, 1, v8
	v_readlane_b32 s24, v253, 14
	v_bitop3_b32 v14, v13, v14, v11 bitop3:0xde
	v_lshl_add_u32 v12, s8, 12, v12
	s_add_i32 s56, s6, 0
	v_lshl_or_b32 v0, v2, 6, v0
	v_readlane_b32 s26, v253, 22
	v_readlane_b32 s28, v255, 11
	v_readlane_b32 s30, v255, 13
	s_mov_b32 s24, 0
	v_bitop3_b32 v246, v13, v12, v11 bitop3:0xde
	s_ashr_i32 s53, s63, 31
	s_ashr_i32 s54, s78, 31
	s_add_i32 s55, s55, 0x20400
	s_add_i32 s56, s56, 0x22400
	v_mov_b32_e32 v229, v1
	v_lshl_add_u32 v230, v10, 1, v0
	v_mov_b32_e32 v231, v1
	v_add_u32_e32 v247, 0, v14
	v_readlane_b32 s27, v253, 23
	v_readlane_b32 s29, v255, 12
	v_readlane_b32 s31, v255, 14
	v_readlane_b32 s22, v253, 12
	v_readlane_b32 s23, v253, 13
	s_branch .LBB0_1833

.LBB0_1844:
	s_and_b64 vcc, exec, s[44:45]
	s_cbranch_vccz .Lh1_5
.Lh0_5:
	s_add_u32 s14, s12, 0x4000
	s_addc_u32 s15, s13, 0
	s_cmpk_eq_i32 s37, 0x54
	s_cselect_b32 s18, s6, s14
	s_cselect_b32 s19, s7, s15
	s_cselect_b32 s16, s8, s11
	s_cselect_b32 s17, s9, s36
	s_add_u32 s14, s18, 0x8000
	s_addc_u32 s15, s19, 0
	s_add_i32 s38, 0, 0x10000
	v_add_u32_e32 v0, s38, v246
	s_add_i32 s40, 0, 0x14000
	ds_read_b128 v[130:133], v0
	ds_read_b128 v[134:137], v0 offset:1024
	ds_read_b128 v[138:141], v0 offset:2048
	ds_read_b128 v[142:145], v0 offset:3072
	v_add_u32_e32 v0, s40, v246
	ds_read_b128 v[146:149], v0
	ds_read_b128 v[150:153], v0 offset:1024
	ds_read_b128 v[154:157], v0 offset:2048
	ds_read_b128 v[158:161], v0 offset:3072
	v_lshl_add_u64 v[194:195], s[12:13], 0, v[228:229]
	s_add_i32 m0, s47, 0xc000
	ds_read_b128 v[162:165], v247
	ds_read_b128 v[166:169], v247 offset:1024
	ds_read_b128 v[170:173], v247 offset:2048
	ds_read_b128 v[174:177], v247 offset:3072
	ds_read_b128 v[178:181], v247 offset:4096
	ds_read_b128 v[182:185], v247 offset:5120
	ds_read_b128 v[186:189], v247 offset:6144
	ds_read_b128 v[190:193], v247 offset:7168
	global_load_lds_dwordx4 v[194:195], off
	v_lshl_add_u64 v[194:195], s[12:13], 0, v[230:231]
	s_add_i32 m0, s47, 0xe000
	s_nop 0
	global_load_lds_dwordx4 v[194:195], off
	s_waitcnt vmcnt(8)
	s_waitcnt lgkmcnt(0)
	s_barrier
	s_setprio 1
	s_waitcnt lgkmcnt(0)
	v_mfma_f32_16x16x32_bf16 v[126:129], v[130:133], v[162:165], v[126:129]
	v_mfma_f32_16x16x32_bf16 v[122:125], v[138:141], v[162:165], v[122:125]
	v_mfma_f32_16x16x32_bf16 v[114:117], v[130:133], v[170:173], v[114:117]
	v_mfma_f32_16x16x32_bf16 v[106:109], v[138:141], v[170:173], v[106:109]
	v_mfma_f32_16x16x32_bf16 v[94:97], v[130:133], v[178:181], v[94:97]
	v_mfma_f32_16x16x32_bf16 v[90:93], v[138:141], v[178:181], v[90:93]
	v_mfma_f32_16x16x32_bf16 v[86:89], v[130:133], v[186:189], v[86:89]
	v_mfma_f32_16x16x32_bf16 v[82:85], v[138:141], v[186:189], v[82:85]
	v_mfma_f32_16x16x32_bf16 v[126:129], v[134:137], v[166:169], v[126:129]
	v_mfma_f32_16x16x32_bf16 v[122:125], v[142:145], v[166:169], v[122:125]
	v_mfma_f32_16x16x32_bf16 v[114:117], v[134:137], v[174:177], v[114:117]
	v_mfma_f32_16x16x32_bf16 v[106:109], v[142:145], v[174:177], v[106:109]
	v_mfma_f32_16x16x32_bf16 v[94:97], v[134:137], v[182:185], v[94:97]
	v_mfma_f32_16x16x32_bf16 v[90:93], v[142:145], v[182:185], v[90:93]
	v_mfma_f32_16x16x32_bf16 v[86:89], v[134:137], v[190:193], v[86:89]
	v_mfma_f32_16x16x32_bf16 v[82:85], v[142:145], v[190:193], v[82:85]
	s_setprio 0
	s_setprio 1
	v_mfma_f32_16x16x32_bf16 v[118:121], v[146:149], v[162:165], v[118:121]
	v_mfma_f32_16x16x32_bf16 v[110:113], v[154:157], v[162:165], v[110:113]
	v_mfma_f32_16x16x32_bf16 v[102:105], v[146:149], v[170:173], v[102:105]
	v_mfma_f32_16x16x32_bf16 v[98:101], v[154:157], v[170:173], v[98:101]
	v_mfma_f32_16x16x32_bf16 v[78:81], v[146:149], v[178:181], v[78:81]
	v_mfma_f32_16x16x32_bf16 v[74:77], v[154:157], v[178:181], v[74:77]
	v_mfma_f32_16x16x32_bf16 v[70:73], v[146:149], v[186:189], v[70:73]
	v_mfma_f32_16x16x32_bf16 v[66:69], v[154:157], v[186:189], v[66:69]
	v_mfma_f32_16x16x32_bf16 v[118:121], v[150:153], v[166:169], v[118:121]
	v_mfma_f32_16x16x32_bf16 v[110:113], v[158:161], v[166:169], v[110:113]
	v_mfma_f32_16x16x32_bf16 v[102:105], v[150:153], v[174:177], v[102:105]
	v_mfma_f32_16x16x32_bf16 v[98:101], v[158:161], v[174:177], v[98:101]
	v_mfma_f32_16x16x32_bf16 v[78:81], v[150:153], v[182:185], v[78:81]
	v_mfma_f32_16x16x32_bf16 v[74:77], v[158:161], v[182:185], v[74:77]
	v_mfma_f32_16x16x32_bf16 v[70:73], v[150:153], v[190:193], v[70:73]
	v_mfma_f32_16x16x32_bf16 v[66:69], v[158:161], v[190:193], v[66:69]
	s_setprio 0
	s_add_i32 s38, s38, s46
	v_lshl_add_u64 v[194:195], s[16:17], 0, v[222:223]
	s_mov_b32 m0, s38
	ds_read_b128 v[162:165], v247 offset:16384
	ds_read_b128 v[166:169], v247 offset:17408
	ds_read_b128 v[170:173], v247 offset:18432
	ds_read_b128 v[174:177], v247 offset:19456
	ds_read_b128 v[178:181], v247 offset:20480
	ds_read_b128 v[182:185], v247 offset:21504
	ds_read_b128 v[186:189], v247 offset:22528
	ds_read_b128 v[190:193], v247 offset:23552
	global_load_lds_dwordx4 v[194:195], off
	s_add_i32 m0, s38, 0x2000
	s_add_u32 s38, s16, 0x164000
	v_lshl_add_u64 v[196:197], s[16:17], 0, v[226:227]
	s_addc_u32 s39, s17, 0
	s_add_i32 s40, s40, s46
	global_load_lds_dwordx4 v[196:197], off
	v_lshl_add_u64 v[198:199], s[38:39], 0, v[222:223]
	s_mov_b32 m0, s40
	s_nop 0
	global_load_lds_dwordx4 v[198:199], off
	v_lshl_add_u64 v[198:199], s[38:39], 0, v[226:227]
	s_add_i32 m0, s40, 0x2000
	s_nop 0
	global_load_lds_dwordx4 v[198:199], off
	v_lshl_add_u64 v[198:199], s[18:19], 0, v[220:221]
	s_mov_b32 m0, s47
	s_nop 0
	global_load_lds_dwordx4 v[198:199], off
	v_lshl_add_u64 v[198:199], s[18:19], 0, v[224:225]
	s_mov_b32 m0, s74
	s_nop 0
	global_load_lds_dwordx4 v[198:199], off
	s_waitcnt vmcnt(8)
	s_waitcnt lgkmcnt(0)
	s_barrier
	s_setprio 1
	s_waitcnt lgkmcnt(0)
	v_mfma_f32_16x16x32_bf16 v[62:65], v[130:133], v[162:165], v[62:65]
	v_mfma_f32_16x16x32_bf16 v[58:61], v[138:141], v[162:165], v[58:61]
	v_mfma_f32_16x16x32_bf16 v[54:57], v[130:133], v[170:173], v[54:57]
	v_mfma_f32_16x16x32_bf16 v[50:53], v[138:141], v[170:173], v[50:53]
	v_mfma_f32_16x16x32_bf16 v[30:33], v[130:133], v[178:181], v[30:33]
	v_mfma_f32_16x16x32_bf16 v[26:29], v[138:141], v[178:181], v[26:29]
	v_mfma_f32_16x16x32_bf16 v[22:25], v[130:133], v[186:189], v[22:25]
	v_mfma_f32_16x16x32_bf16 v[18:21], v[138:141], v[186:189], v[18:21]
	v_mfma_f32_16x16x32_bf16 v[62:65], v[134:137], v[166:169], v[62:65]
	v_mfma_f32_16x16x32_bf16 v[58:61], v[142:145], v[166:169], v[58:61]
	v_mfma_f32_16x16x32_bf16 v[54:57], v[134:137], v[174:177], v[54:57]
	v_mfma_f32_16x16x32_bf16 v[50:53], v[142:145], v[174:177], v[50:53]
	v_mfma_f32_16x16x32_bf16 v[30:33], v[134:137], v[182:185], v[30:33]
	v_mfma_f32_16x16x32_bf16 v[26:29], v[142:145], v[182:185], v[26:29]
	v_mfma_f32_16x16x32_bf16 v[22:25], v[134:137], v[190:193], v[22:25]
	v_mfma_f32_16x16x32_bf16 v[18:21], v[142:145], v[190:193], v[18:21]
	s_setprio 0
	s_setprio 1
	v_mfma_f32_16x16x32_bf16 v[46:49], v[146:149], v[162:165], v[46:49]
	v_mfma_f32_16x16x32_bf16 v[42:45], v[154:157], v[162:165], v[42:45]
	v_mfma_f32_16x16x32_bf16 v[38:41], v[146:149], v[170:173], v[38:41]
	v_mfma_f32_16x16x32_bf16 v[34:37], v[154:157], v[170:173], v[34:37]
	v_mfma_f32_16x16x32_bf16 v[14:17], v[146:149], v[178:181], v[14:17]
	v_mfma_f32_16x16x32_bf16 v[10:13], v[154:157], v[178:181], v[10:13]
	v_mfma_f32_16x16x32_bf16 v[6:9], v[146:149], v[186:189], v[6:9]
	v_mfma_f32_16x16x32_bf16 v[2:5], v[154:157], v[186:189], v[2:5]
	v_mfma_f32_16x16x32_bf16 v[46:49], v[150:153], v[166:169], v[46:49]
	v_mfma_f32_16x16x32_bf16 v[42:45], v[158:161], v[166:169], v[42:45]
	v_mfma_f32_16x16x32_bf16 v[38:41], v[150:153], v[174:177], v[38:41]
	v_mfma_f32_16x16x32_bf16 v[34:37], v[158:161], v[174:177], v[34:37]
	v_mfma_f32_16x16x32_bf16 v[14:17], v[150:153], v[182:185], v[14:17]
	v_mfma_f32_16x16x32_bf16 v[10:13], v[158:161], v[182:185], v[10:13]
	v_mfma_f32_16x16x32_bf16 v[6:9], v[150:153], v[190:193], v[6:9]
	v_mfma_f32_16x16x32_bf16 v[2:5], v[158:161], v[190:193], v[2:5]
	s_setprio 0
	s_add_i32 s38, 0, 0x18000
	v_add_u32_e32 v0, s38, v246
	s_add_i32 s39, 0, 0x1c000
	ds_read_b128 v[130:133], v0
	ds_read_b128 v[134:137], v0 offset:1024
	ds_read_b128 v[138:141], v0 offset:2048
	ds_read_b128 v[142:145], v0 offset:3072
	v_add_u32_e32 v0, s39, v246
	ds_read_b128 v[146:149], v0
	ds_read_b128 v[150:153], v0 offset:1024
	ds_read_b128 v[154:157], v0 offset:2048
	ds_read_b128 v[158:161], v0 offset:3072
	s_add_u32 s18, s18, 0x4000
	s_addc_u32 s19, s19, 0
	s_mov_b32 m0, s75
	v_lshl_add_u64 v[198:199], s[18:19], 0, v[220:221]
	ds_read_b128 v[162:165], v247 offset:32768
	ds_read_b128 v[166:169], v247 offset:33792
	ds_read_b128 v[170:173], v247 offset:34816
	ds_read_b128 v[174:177], v247 offset:35840
	ds_read_b128 v[178:181], v247 offset:36864
	ds_read_b128 v[182:185], v247 offset:37888
	ds_read_b128 v[186:189], v247 offset:38912
	ds_read_b128 v[190:193], v247 offset:39936
	global_load_lds_dwordx4 v[198:199], off
	v_lshl_add_u64 v[198:199], s[18:19], 0, v[224:225]
	s_mov_b32 m0, s86
	s_nop 0
	global_load_lds_dwordx4 v[198:199], off
	s_waitcnt vmcnt(8)
	s_waitcnt lgkmcnt(0)
	s_barrier
	s_setprio 1
	s_waitcnt lgkmcnt(0)
	v_mfma_f32_16x16x32_bf16 v[126:129], v[130:133], v[162:165], v[126:129]
	v_mfma_f32_16x16x32_bf16 v[122:125], v[138:141], v[162:165], v[122:125]
	v_mfma_f32_16x16x32_bf16 v[114:117], v[130:133], v[170:173], v[114:117]
	v_mfma_f32_16x16x32_bf16 v[106:109], v[138:141], v[170:173], v[106:109]
	v_mfma_f32_16x16x32_bf16 v[94:97], v[130:133], v[178:181], v[94:97]
	v_mfma_f32_16x16x32_bf16 v[90:93], v[138:141], v[178:181], v[90:93]
	v_mfma_f32_16x16x32_bf16 v[86:89], v[130:133], v[186:189], v[86:89]
	v_mfma_f32_16x16x32_bf16 v[82:85], v[138:141], v[186:189], v[82:85]
	v_mfma_f32_16x16x32_bf16 v[126:129], v[134:137], v[166:169], v[126:129]
	v_mfma_f32_16x16x32_bf16 v[122:125], v[142:145], v[166:169], v[122:125]
	v_mfma_f32_16x16x32_bf16 v[114:117], v[134:137], v[174:177], v[114:117]
	v_mfma_f32_16x16x32_bf16 v[106:109], v[142:145], v[174:177], v[106:109]
	v_mfma_f32_16x16x32_bf16 v[94:97], v[134:137], v[182:185], v[94:97]
	v_mfma_f32_16x16x32_bf16 v[90:93], v[142:145], v[182:185], v[90:93]
	v_mfma_f32_16x16x32_bf16 v[86:89], v[134:137], v[190:193], v[86:89]
	v_mfma_f32_16x16x32_bf16 v[82:85], v[142:145], v[190:193], v[82:85]
	s_setprio 0
	s_setprio 1
	v_mfma_f32_16x16x32_bf16 v[118:121], v[146:149], v[162:165], v[118:121]
	v_mfma_f32_16x16x32_bf16 v[110:113], v[154:157], v[162:165], v[110:113]
	v_mfma_f32_16x16x32_bf16 v[102:105], v[146:149], v[170:173], v[102:105]
	v_mfma_f32_16x16x32_bf16 v[98:101], v[154:157], v[170:173], v[98:101]
	v_mfma_f32_16x16x32_bf16 v[78:81], v[146:149], v[178:181], v[78:81]
	v_mfma_f32_16x16x32_bf16 v[74:77], v[154:157], v[178:181], v[74:77]
	v_mfma_f32_16x16x32_bf16 v[70:73], v[146:149], v[186:189], v[70:73]
	v_mfma_f32_16x16x32_bf16 v[66:69], v[154:157], v[186:189], v[66:69]
	v_mfma_f32_16x16x32_bf16 v[118:121], v[150:153], v[166:169], v[118:121]
	v_mfma_f32_16x16x32_bf16 v[110:113], v[158:161], v[166:169], v[110:113]
	v_mfma_f32_16x16x32_bf16 v[102:105], v[150:153], v[174:177], v[102:105]
	v_mfma_f32_16x16x32_bf16 v[98:101], v[158:161], v[174:177], v[98:101]
	v_mfma_f32_16x16x32_bf16 v[78:81], v[150:153], v[182:185], v[78:81]
	v_mfma_f32_16x16x32_bf16 v[74:77], v[158:161], v[182:185], v[74:77]
	v_mfma_f32_16x16x32_bf16 v[70:73], v[150:153], v[190:193], v[70:73]
	v_mfma_f32_16x16x32_bf16 v[66:69], v[158:161], v[190:193], v[66:69]
	s_setprio 0
	s_add_i32 s18, s38, s46
	v_lshl_add_u64 v[194:195], v[194:195], 0, s[2:3]
	s_mov_b32 m0, s18
	ds_read_b128 v[162:165], v247 offset:49152
	ds_read_b128 v[166:169], v247 offset:50176
	ds_read_b128 v[170:173], v247 offset:51200
	ds_read_b128 v[174:177], v247 offset:52224
	ds_read_b128 v[178:181], v247 offset:53248
	ds_read_b128 v[182:185], v247 offset:54272
	ds_read_b128 v[186:189], v247 offset:55296
	ds_read_b128 v[190:193], v247 offset:56320
	global_load_lds_dwordx4 v[194:195], off
	s_add_i32 m0, s18, 0x2000
	s_add_u32 s16, s16, 0x164080
	v_lshl_add_u64 v[194:195], v[196:197], 0, s[2:3]
	s_addc_u32 s17, s17, 0
	s_add_i32 s18, s39, s46
	global_load_lds_dwordx4 v[194:195], off
	v_lshl_add_u64 v[194:195], s[16:17], 0, v[222:223]
	s_mov_b32 m0, s18
	s_nop 0
	global_load_lds_dwordx4 v[194:195], off
	v_lshl_add_u64 v[194:195], s[16:17], 0, v[226:227]
	s_add_i32 m0, s18, 0x2000
	s_nop 0
	global_load_lds_dwordx4 v[194:195], off
	v_lshl_add_u64 v[194:195], s[14:15], 0, v[220:221]
	s_mov_b32 m0, s50
	s_nop 0
	global_load_lds_dwordx4 v[194:195], off
	v_lshl_add_u64 v[194:195], s[14:15], 0, v[224:225]
	s_mov_b32 m0, s51
	s_nop 0
	global_load_lds_dwordx4 v[194:195], off
	s_waitcnt vmcnt(8)
	s_waitcnt lgkmcnt(0)
	s_barrier
	s_setprio 1
	s_waitcnt lgkmcnt(0)
	v_mfma_f32_16x16x32_bf16 v[62:65], v[130:133], v[162:165], v[62:65]
	v_mfma_f32_16x16x32_bf16 v[58:61], v[138:141], v[162:165], v[58:61]
	v_mfma_f32_16x16x32_bf16 v[54:57], v[130:133], v[170:173], v[54:57]
	v_mfma_f32_16x16x32_bf16 v[50:53], v[138:141], v[170:173], v[50:53]
	v_mfma_f32_16x16x32_bf16 v[30:33], v[130:133], v[178:181], v[30:33]
	v_mfma_f32_16x16x32_bf16 v[26:29], v[138:141], v[178:181], v[26:29]
	v_mfma_f32_16x16x32_bf16 v[22:25], v[130:133], v[186:189], v[22:25]
	v_mfma_f32_16x16x32_bf16 v[18:21], v[138:141], v[186:189], v[18:21]
	v_mfma_f32_16x16x32_bf16 v[62:65], v[134:137], v[166:169], v[62:65]
	v_mfma_f32_16x16x32_bf16 v[58:61], v[142:145], v[166:169], v[58:61]
	v_mfma_f32_16x16x32_bf16 v[54:57], v[134:137], v[174:177], v[54:57]
	v_mfma_f32_16x16x32_bf16 v[50:53], v[142:145], v[174:177], v[50:53]
	v_mfma_f32_16x16x32_bf16 v[30:33], v[134:137], v[182:185], v[30:33]
	v_mfma_f32_16x16x32_bf16 v[26:29], v[142:145], v[182:185], v[26:29]
	v_mfma_f32_16x16x32_bf16 v[22:25], v[134:137], v[190:193], v[22:25]
	v_mfma_f32_16x16x32_bf16 v[18:21], v[142:145], v[190:193], v[18:21]
	s_setprio 0
	s_setprio 1
	v_mfma_f32_16x16x32_bf16 v[46:49], v[146:149], v[162:165], v[46:49]
	v_mfma_f32_16x16x32_bf16 v[42:45], v[154:157], v[162:165], v[42:45]
	v_mfma_f32_16x16x32_bf16 v[38:41], v[146:149], v[170:173], v[38:41]
	v_mfma_f32_16x16x32_bf16 v[34:37], v[154:157], v[170:173], v[34:37]
	v_mfma_f32_16x16x32_bf16 v[14:17], v[146:149], v[178:181], v[14:17]
	v_mfma_f32_16x16x32_bf16 v[10:13], v[154:157], v[178:181], v[10:13]
	v_mfma_f32_16x16x32_bf16 v[6:9], v[146:149], v[186:189], v[6:9]
	v_mfma_f32_16x16x32_bf16 v[2:5], v[154:157], v[186:189], v[2:5]
	v_mfma_f32_16x16x32_bf16 v[46:49], v[150:153], v[166:169], v[46:49]
	v_mfma_f32_16x16x32_bf16 v[42:45], v[158:161], v[166:169], v[42:45]
	v_mfma_f32_16x16x32_bf16 v[38:41], v[150:153], v[174:177], v[38:41]
	v_mfma_f32_16x16x32_bf16 v[34:37], v[158:161], v[174:177], v[34:37]
	v_mfma_f32_16x16x32_bf16 v[14:17], v[150:153], v[182:185], v[14:17]
	v_mfma_f32_16x16x32_bf16 v[10:13], v[158:161], v[182:185], v[10:13]
	v_mfma_f32_16x16x32_bf16 v[6:9], v[150:153], v[190:193], v[6:9]
	v_mfma_f32_16x16x32_bf16 v[2:5], v[158:161], v[190:193], v[2:5]
	s_setprio 0
	s_add_i32 s37, s37, 2
	s_add_u32 s11, s11, 0x100
	s_addc_u32 s36, s36, 0
	s_add_u32 s12, s12, 0x10000
	s_addc_u32 s13, s13, 0
	s_cmpk_gt_u32 s37, 0x55
	s_cbranch_scc0 .Lh0_5
	s_branch .Ldone_5
.Lh1_5:
	s_add_u32 s14, s12, 0x4000
	s_addc_u32 s15, s13, 0
	s_cmpk_eq_i32 s37, 0x54
	s_cselect_b32 s18, s6, s14
	s_cselect_b32 s19, s7, s15
	s_cselect_b32 s16, s8, s11
	s_cselect_b32 s17, s9, s36
	s_add_u32 s14, s18, 0x8000
	s_addc_u32 s15, s19, 0
	s_add_i32 s38, 0, 0x10000
	v_add_u32_e32 v0, s38, v246
	s_add_i32 s40, 0, 0x14000
	ds_read_b128 v[130:133], v0
	ds_read_b128 v[134:137], v0 offset:1024
	ds_read_b128 v[138:141], v0 offset:2048
	ds_read_b128 v[142:145], v0 offset:3072
	v_add_u32_e32 v0, s40, v246
	ds_read_b128 v[146:149], v0
	ds_read_b128 v[150:153], v0 offset:1024
	ds_read_b128 v[154:157], v0 offset:2048
	ds_read_b128 v[158:161], v0 offset:3072
	v_lshl_add_u64 v[194:195], s[12:13], 0, v[228:229]
	s_add_i32 m0, s47, 0xc000
	ds_read_b128 v[162:165], v247
	ds_read_b128 v[166:169], v247 offset:1024
	ds_read_b128 v[170:173], v247 offset:2048
	ds_read_b128 v[174:177], v247 offset:3072
	ds_read_b128 v[178:181], v247 offset:4096
	ds_read_b128 v[182:185], v247 offset:5120
	ds_read_b128 v[186:189], v247 offset:6144
	ds_read_b128 v[190:193], v247 offset:7168
	global_load_lds_dwordx4 v[194:195], off
	v_lshl_add_u64 v[194:195], s[12:13], 0, v[230:231]
	s_add_i32 m0, s47, 0xe000
	s_nop 0
	global_load_lds_dwordx4 v[194:195], off
	s_waitcnt vmcnt(8)
	s_waitcnt lgkmcnt(0)
	s_setprio 1
	s_waitcnt lgkmcnt(0)
	v_mfma_f32_16x16x32_bf16 v[126:129], v[130:133], v[162:165], v[126:129]
	v_mfma_f32_16x16x32_bf16 v[122:125], v[138:141], v[162:165], v[122:125]
	v_mfma_f32_16x16x32_bf16 v[114:117], v[130:133], v[170:173], v[114:117]
	v_mfma_f32_16x16x32_bf16 v[106:109], v[138:141], v[170:173], v[106:109]
	v_mfma_f32_16x16x32_bf16 v[94:97], v[130:133], v[178:181], v[94:97]
	v_mfma_f32_16x16x32_bf16 v[90:93], v[138:141], v[178:181], v[90:93]
	v_mfma_f32_16x16x32_bf16 v[86:89], v[130:133], v[186:189], v[86:89]
	v_mfma_f32_16x16x32_bf16 v[82:85], v[138:141], v[186:189], v[82:85]
	v_mfma_f32_16x16x32_bf16 v[126:129], v[134:137], v[166:169], v[126:129]
	v_mfma_f32_16x16x32_bf16 v[122:125], v[142:145], v[166:169], v[122:125]
	v_mfma_f32_16x16x32_bf16 v[114:117], v[134:137], v[174:177], v[114:117]
	v_mfma_f32_16x16x32_bf16 v[106:109], v[142:145], v[174:177], v[106:109]
	v_mfma_f32_16x16x32_bf16 v[94:97], v[134:137], v[182:185], v[94:97]
	v_mfma_f32_16x16x32_bf16 v[90:93], v[142:145], v[182:185], v[90:93]
	v_mfma_f32_16x16x32_bf16 v[86:89], v[134:137], v[190:193], v[86:89]
	v_mfma_f32_16x16x32_bf16 v[82:85], v[142:145], v[190:193], v[82:85]
	s_setprio 0
	s_setprio 1
	v_mfma_f32_16x16x32_bf16 v[118:121], v[146:149], v[162:165], v[118:121]
	v_mfma_f32_16x16x32_bf16 v[110:113], v[154:157], v[162:165], v[110:113]
	v_mfma_f32_16x16x32_bf16 v[102:105], v[146:149], v[170:173], v[102:105]
	v_mfma_f32_16x16x32_bf16 v[98:101], v[154:157], v[170:173], v[98:101]
	v_mfma_f32_16x16x32_bf16 v[78:81], v[146:149], v[178:181], v[78:81]
	v_mfma_f32_16x16x32_bf16 v[74:77], v[154:157], v[178:181], v[74:77]
	v_mfma_f32_16x16x32_bf16 v[70:73], v[146:149], v[186:189], v[70:73]
	v_mfma_f32_16x16x32_bf16 v[66:69], v[154:157], v[186:189], v[66:69]
	v_mfma_f32_16x16x32_bf16 v[118:121], v[150:153], v[166:169], v[118:121]
	v_mfma_f32_16x16x32_bf16 v[110:113], v[158:161], v[166:169], v[110:113]
	v_mfma_f32_16x16x32_bf16 v[102:105], v[150:153], v[174:177], v[102:105]
	v_mfma_f32_16x16x32_bf16 v[98:101], v[158:161], v[174:177], v[98:101]
	v_mfma_f32_16x16x32_bf16 v[78:81], v[150:153], v[182:185], v[78:81]
	v_mfma_f32_16x16x32_bf16 v[74:77], v[158:161], v[182:185], v[74:77]
	v_mfma_f32_16x16x32_bf16 v[70:73], v[150:153], v[190:193], v[70:73]
	v_mfma_f32_16x16x32_bf16 v[66:69], v[158:161], v[190:193], v[66:69]
	s_setprio 0
	s_barrier
	s_add_i32 s38, s38, s46
	v_lshl_add_u64 v[194:195], s[16:17], 0, v[222:223]
	s_mov_b32 m0, s38
	ds_read_b128 v[162:165], v247 offset:16384
	ds_read_b128 v[166:169], v247 offset:17408
	ds_read_b128 v[170:173], v247 offset:18432
	ds_read_b128 v[174:177], v247 offset:19456
	ds_read_b128 v[178:181], v247 offset:20480
	ds_read_b128 v[182:185], v247 offset:21504
	ds_read_b128 v[186:189], v247 offset:22528
	ds_read_b128 v[190:193], v247 offset:23552
	global_load_lds_dwordx4 v[194:195], off
	s_add_i32 m0, s38, 0x2000
	s_add_u32 s38, s16, 0x164000
	v_lshl_add_u64 v[196:197], s[16:17], 0, v[226:227]
	s_addc_u32 s39, s17, 0
	s_add_i32 s40, s40, s46
	global_load_lds_dwordx4 v[196:197], off
	v_lshl_add_u64 v[198:199], s[38:39], 0, v[222:223]
	s_mov_b32 m0, s40
	s_nop 0
	global_load_lds_dwordx4 v[198:199], off
	v_lshl_add_u64 v[198:199], s[38:39], 0, v[226:227]
	s_add_i32 m0, s40, 0x2000
	s_nop 0
	global_load_lds_dwordx4 v[198:199], off
	v_lshl_add_u64 v[198:199], s[18:19], 0, v[220:221]
	s_mov_b32 m0, s47
	s_nop 0
	global_load_lds_dwordx4 v[198:199], off
	v_lshl_add_u64 v[198:199], s[18:19], 0, v[224:225]
	s_mov_b32 m0, s74
	s_nop 0
	global_load_lds_dwordx4 v[198:199], off
	s_waitcnt vmcnt(8)
	s_waitcnt lgkmcnt(0)
	s_setprio 1
	s_waitcnt lgkmcnt(0)
	v_mfma_f32_16x16x32_bf16 v[62:65], v[130:133], v[162:165], v[62:65]
	v_mfma_f32_16x16x32_bf16 v[58:61], v[138:141], v[162:165], v[58:61]
	v_mfma_f32_16x16x32_bf16 v[54:57], v[130:133], v[170:173], v[54:57]
	v_mfma_f32_16x16x32_bf16 v[50:53], v[138:141], v[170:173], v[50:53]
	v_mfma_f32_16x16x32_bf16 v[30:33], v[130:133], v[178:181], v[30:33]
	v_mfma_f32_16x16x32_bf16 v[26:29], v[138:141], v[178:181], v[26:29]
	v_mfma_f32_16x16x32_bf16 v[22:25], v[130:133], v[186:189], v[22:25]
	v_mfma_f32_16x16x32_bf16 v[18:21], v[138:141], v[186:189], v[18:21]
	v_mfma_f32_16x16x32_bf16 v[62:65], v[134:137], v[166:169], v[62:65]
	v_mfma_f32_16x16x32_bf16 v[58:61], v[142:145], v[166:169], v[58:61]
	v_mfma_f32_16x16x32_bf16 v[54:57], v[134:137], v[174:177], v[54:57]
	v_mfma_f32_16x16x32_bf16 v[50:53], v[142:145], v[174:177], v[50:53]
	v_mfma_f32_16x16x32_bf16 v[30:33], v[134:137], v[182:185], v[30:33]
	v_mfma_f32_16x16x32_bf16 v[26:29], v[142:145], v[182:185], v[26:29]
	v_mfma_f32_16x16x32_bf16 v[22:25], v[134:137], v[190:193], v[22:25]
	v_mfma_f32_16x16x32_bf16 v[18:21], v[142:145], v[190:193], v[18:21]
	s_setprio 0
	s_setprio 1
	v_mfma_f32_16x16x32_bf16 v[46:49], v[146:149], v[162:165], v[46:49]
	v_mfma_f32_16x16x32_bf16 v[42:45], v[154:157], v[162:165], v[42:45]
	v_mfma_f32_16x16x32_bf16 v[38:41], v[146:149], v[170:173], v[38:41]
	v_mfma_f32_16x16x32_bf16 v[34:37], v[154:157], v[170:173], v[34:37]
	v_mfma_f32_16x16x32_bf16 v[14:17], v[146:149], v[178:181], v[14:17]
	v_mfma_f32_16x16x32_bf16 v[10:13], v[154:157], v[178:181], v[10:13]
	v_mfma_f32_16x16x32_bf16 v[6:9], v[146:149], v[186:189], v[6:9]
	v_mfma_f32_16x16x32_bf16 v[2:5], v[154:157], v[186:189], v[2:5]
	v_mfma_f32_16x16x32_bf16 v[46:49], v[150:153], v[166:169], v[46:49]
	v_mfma_f32_16x16x32_bf16 v[42:45], v[158:161], v[166:169], v[42:45]
	v_mfma_f32_16x16x32_bf16 v[38:41], v[150:153], v[174:177], v[38:41]
	v_mfma_f32_16x16x32_bf16 v[34:37], v[158:161], v[174:177], v[34:37]
	v_mfma_f32_16x16x32_bf16 v[14:17], v[150:153], v[182:185], v[14:17]
	v_mfma_f32_16x16x32_bf16 v[10:13], v[158:161], v[182:185], v[10:13]
	v_mfma_f32_16x16x32_bf16 v[6:9], v[150:153], v[190:193], v[6:9]
	v_mfma_f32_16x16x32_bf16 v[2:5], v[158:161], v[190:193], v[2:5]
	s_setprio 0
	s_barrier
	s_add_i32 s38, 0, 0x18000
	v_add_u32_e32 v0, s38, v246
	s_add_i32 s39, 0, 0x1c000
	ds_read_b128 v[130:133], v0
	ds_read_b128 v[134:137], v0 offset:1024
	ds_read_b128 v[138:141], v0 offset:2048
	ds_read_b128 v[142:145], v0 offset:3072
	v_add_u32_e32 v0, s39, v246
	ds_read_b128 v[146:149], v0
	ds_read_b128 v[150:153], v0 offset:1024
	ds_read_b128 v[154:157], v0 offset:2048
	ds_read_b128 v[158:161], v0 offset:3072
	s_add_u32 s18, s18, 0x4000
	s_addc_u32 s19, s19, 0
	s_mov_b32 m0, s75
	v_lshl_add_u64 v[198:199], s[18:19], 0, v[220:221]
	ds_read_b128 v[162:165], v247 offset:32768
	ds_read_b128 v[166:169], v247 offset:33792
	ds_read_b128 v[170:173], v247 offset:34816
	ds_read_b128 v[174:177], v247 offset:35840
	ds_read_b128 v[178:181], v247 offset:36864
	ds_read_b128 v[182:185], v247 offset:37888
	ds_read_b128 v[186:189], v247 offset:38912
	ds_read_b128 v[190:193], v247 offset:39936
	global_load_lds_dwordx4 v[198:199], off
	v_lshl_add_u64 v[198:199], s[18:19], 0, v[224:225]
	s_mov_b32 m0, s86
	s_nop 0
	global_load_lds_dwordx4 v[198:199], off
	s_waitcnt vmcnt(8)
	s_waitcnt lgkmcnt(0)
	s_setprio 1
	s_waitcnt lgkmcnt(0)
	v_mfma_f32_16x16x32_bf16 v[126:129], v[130:133], v[162:165], v[126:129]
	v_mfma_f32_16x16x32_bf16 v[122:125], v[138:141], v[162:165], v[122:125]
	v_mfma_f32_16x16x32_bf16 v[114:117], v[130:133], v[170:173], v[114:117]
	v_mfma_f32_16x16x32_bf16 v[106:109], v[138:141], v[170:173], v[106:109]
	v_mfma_f32_16x16x32_bf16 v[94:97], v[130:133], v[178:181], v[94:97]
	v_mfma_f32_16x16x32_bf16 v[90:93], v[138:141], v[178:181], v[90:93]
	v_mfma_f32_16x16x32_bf16 v[86:89], v[130:133], v[186:189], v[86:89]
	v_mfma_f32_16x16x32_bf16 v[82:85], v[138:141], v[186:189], v[82:85]
	v_mfma_f32_16x16x32_bf16 v[126:129], v[134:137], v[166:169], v[126:129]
	v_mfma_f32_16x16x32_bf16 v[122:125], v[142:145], v[166:169], v[122:125]
	v_mfma_f32_16x16x32_bf16 v[114:117], v[134:137], v[174:177], v[114:117]
	v_mfma_f32_16x16x32_bf16 v[106:109], v[142:145], v[174:177], v[106:109]
	v_mfma_f32_16x16x32_bf16 v[94:97], v[134:137], v[182:185], v[94:97]
	v_mfma_f32_16x16x32_bf16 v[90:93], v[142:145], v[182:185], v[90:93]
	v_mfma_f32_16x16x32_bf16 v[86:89], v[134:137], v[190:193], v[86:89]
	v_mfma_f32_16x16x32_bf16 v[82:85], v[142:145], v[190:193], v[82:85]
	s_setprio 0
	s_setprio 1
	v_mfma_f32_16x16x32_bf16 v[118:121], v[146:149], v[162:165], v[118:121]
	v_mfma_f32_16x16x32_bf16 v[110:113], v[154:157], v[162:165], v[110:113]
	v_mfma_f32_16x16x32_bf16 v[102:105], v[146:149], v[170:173], v[102:105]
	v_mfma_f32_16x16x32_bf16 v[98:101], v[154:157], v[170:173], v[98:101]
	v_mfma_f32_16x16x32_bf16 v[78:81], v[146:149], v[178:181], v[78:81]
	v_mfma_f32_16x16x32_bf16 v[74:77], v[154:157], v[178:181], v[74:77]
	v_mfma_f32_16x16x32_bf16 v[70:73], v[146:149], v[186:189], v[70:73]
	v_mfma_f32_16x16x32_bf16 v[66:69], v[154:157], v[186:189], v[66:69]
	v_mfma_f32_16x16x32_bf16 v[118:121], v[150:153], v[166:169], v[118:121]
	v_mfma_f32_16x16x32_bf16 v[110:113], v[158:161], v[166:169], v[110:113]
	v_mfma_f32_16x16x32_bf16 v[102:105], v[150:153], v[174:177], v[102:105]
	v_mfma_f32_16x16x32_bf16 v[98:101], v[158:161], v[174:177], v[98:101]
	v_mfma_f32_16x16x32_bf16 v[78:81], v[150:153], v[182:185], v[78:81]
	v_mfma_f32_16x16x32_bf16 v[74:77], v[158:161], v[182:185], v[74:77]
	v_mfma_f32_16x16x32_bf16 v[70:73], v[150:153], v[190:193], v[70:73]
	v_mfma_f32_16x16x32_bf16 v[66:69], v[158:161], v[190:193], v[66:69]
	s_setprio 0
	s_barrier
	s_add_i32 s18, s38, s46
	v_lshl_add_u64 v[194:195], v[194:195], 0, s[2:3]
	s_mov_b32 m0, s18
	ds_read_b128 v[162:165], v247 offset:49152
	ds_read_b128 v[166:169], v247 offset:50176
	ds_read_b128 v[170:173], v247 offset:51200
	ds_read_b128 v[174:177], v247 offset:52224
	ds_read_b128 v[178:181], v247 offset:53248
	ds_read_b128 v[182:185], v247 offset:54272
	ds_read_b128 v[186:189], v247 offset:55296
	ds_read_b128 v[190:193], v247 offset:56320
	global_load_lds_dwordx4 v[194:195], off
	s_add_i32 m0, s18, 0x2000
	s_add_u32 s16, s16, 0x164080
	v_lshl_add_u64 v[194:195], v[196:197], 0, s[2:3]
	s_addc_u32 s17, s17, 0
	s_add_i32 s18, s39, s46
	global_load_lds_dwordx4 v[194:195], off
	v_lshl_add_u64 v[194:195], s[16:17], 0, v[222:223]
	s_mov_b32 m0, s18
	s_nop 0
	global_load_lds_dwordx4 v[194:195], off
	v_lshl_add_u64 v[194:195], s[16:17], 0, v[226:227]
	s_add_i32 m0, s18, 0x2000
	s_nop 0
	global_load_lds_dwordx4 v[194:195], off
	v_lshl_add_u64 v[194:195], s[14:15], 0, v[220:221]
	s_mov_b32 m0, s50
	s_nop 0
	global_load_lds_dwordx4 v[194:195], off
	v_lshl_add_u64 v[194:195], s[14:15], 0, v[224:225]
	s_mov_b32 m0, s51
	s_nop 0
	global_load_lds_dwordx4 v[194:195], off
	s_waitcnt vmcnt(8)
	s_waitcnt lgkmcnt(0)
	s_setprio 1
	s_waitcnt lgkmcnt(0)
	v_mfma_f32_16x16x32_bf16 v[62:65], v[130:133], v[162:165], v[62:65]
	v_mfma_f32_16x16x32_bf16 v[58:61], v[138:141], v[162:165], v[58:61]
	v_mfma_f32_16x16x32_bf16 v[54:57], v[130:133], v[170:173], v[54:57]
	v_mfma_f32_16x16x32_bf16 v[50:53], v[138:141], v[170:173], v[50:53]
	v_mfma_f32_16x16x32_bf16 v[30:33], v[130:133], v[178:181], v[30:33]
	v_mfma_f32_16x16x32_bf16 v[26:29], v[138:141], v[178:181], v[26:29]
	v_mfma_f32_16x16x32_bf16 v[22:25], v[130:133], v[186:189], v[22:25]
	v_mfma_f32_16x16x32_bf16 v[18:21], v[138:141], v[186:189], v[18:21]
	v_mfma_f32_16x16x32_bf16 v[62:65], v[134:137], v[166:169], v[62:65]
	v_mfma_f32_16x16x32_bf16 v[58:61], v[142:145], v[166:169], v[58:61]
	v_mfma_f32_16x16x32_bf16 v[54:57], v[134:137], v[174:177], v[54:57]
	v_mfma_f32_16x16x32_bf16 v[50:53], v[142:145], v[174:177], v[50:53]
	v_mfma_f32_16x16x32_bf16 v[30:33], v[134:137], v[182:185], v[30:33]
	v_mfma_f32_16x16x32_bf16 v[26:29], v[142:145], v[182:185], v[26:29]
	v_mfma_f32_16x16x32_bf16 v[22:25], v[134:137], v[190:193], v[22:25]
	v_mfma_f32_16x16x32_bf16 v[18:21], v[142:145], v[190:193], v[18:21]
	s_setprio 0
	s_setprio 1
	v_mfma_f32_16x16x32_bf16 v[46:49], v[146:149], v[162:165], v[46:49]
	v_mfma_f32_16x16x32_bf16 v[42:45], v[154:157], v[162:165], v[42:45]
	v_mfma_f32_16x16x32_bf16 v[38:41], v[146:149], v[170:173], v[38:41]
	v_mfma_f32_16x16x32_bf16 v[34:37], v[154:157], v[170:173], v[34:37]
	v_mfma_f32_16x16x32_bf16 v[14:17], v[146:149], v[178:181], v[14:17]
	v_mfma_f32_16x16x32_bf16 v[10:13], v[154:157], v[178:181], v[10:13]
	v_mfma_f32_16x16x32_bf16 v[6:9], v[146:149], v[186:189], v[6:9]
	v_mfma_f32_16x16x32_bf16 v[2:5], v[154:157], v[186:189], v[2:5]
	v_mfma_f32_16x16x32_bf16 v[46:49], v[150:153], v[166:169], v[46:49]
	v_mfma_f32_16x16x32_bf16 v[42:45], v[158:161], v[166:169], v[42:45]
	v_mfma_f32_16x16x32_bf16 v[38:41], v[150:153], v[174:177], v[38:41]
	v_mfma_f32_16x16x32_bf16 v[34:37], v[158:161], v[174:177], v[34:37]
	v_mfma_f32_16x16x32_bf16 v[14:17], v[150:153], v[182:185], v[14:17]
	v_mfma_f32_16x16x32_bf16 v[10:13], v[158:161], v[182:185], v[10:13]
	v_mfma_f32_16x16x32_bf16 v[6:9], v[150:153], v[190:193], v[6:9]
	v_mfma_f32_16x16x32_bf16 v[2:5], v[158:161], v[190:193], v[2:5]
	s_setprio 0
	s_barrier
	s_add_i32 s37, s37, 2
	s_add_u32 s11, s11, 0x100
	s_addc_u32 s36, s36, 0
	s_add_u32 s12, s12, 0x10000
	s_addc_u32 s13, s13, 0
	s_cmpk_gt_u32 s37, 0x55
	s_cbranch_scc0 .Lh1_5

.LBB0_2000:
	s_andn2_b64 vcc, exec, s[92:93]
	s_cbranch_vccnz .LBB0_1831
	s_branch .LBB0_1831

.LBB0_2007:
	v_and_b32_e32 v13, 15, v12
	v_lshl_or_b32 v14, s7, 6, v13
	v_ashrrev_i32_e32 v16, 6, v12
	s_lshl_b32 s7, s7, 13
	v_lshl_add_u32 v18, v16, 10, s7
	s_lshl_b32 s7, s6, 5
	s_and_b32 s10, s7, 0x60
	s_add_i32 m0, s38, 0x18000
	v_lshl_add_u64 v[2:3], v[2:3], 0, s[2:3]
	s_lshr_b32 s7, s10, 3
	s_waitcnt vmcnt(2)
	s_barrier
	global_load_lds_dwordx4 v[2:3], off
	s_add_i32 m0, s38, 0x1a000
	s_add_u32 s8, s14, 0x8000
	v_mov_b32_e32 v135, v1
	v_lshl_add_u64 v[2:3], v[4:5], 0, s[2:3]
	s_addc_u32 s9, s15, 0
	s_add_i32 s42, s38, 0x8000
	v_mov_b32_e32 v133, v1
	global_load_lds_dwordx4 v[2:3], off
	v_lshl_add_u64 v[2:3], s[8:9], 0, v[134:135]
	s_mov_b32 m0, s42
	s_add_i32 s43, s38, 0xa000
	global_load_lds_dwordx4 v[2:3], off
	v_lshl_add_u64 v[2:3], s[8:9], 0, v[132:133]
	s_add_u32 s8, s12, 0x164080
	s_mov_b32 m0, s43
	s_addc_u32 s9, s13, 0
	global_load_lds_dwordx4 v[2:3], off
	s_add_i32 m0, s38, 0x1c000
	v_lshl_add_u64 v[2:3], s[8:9], 0, v[0:1]
	global_load_lds_dwordx4 v[2:3], off
	v_lshl_add_u64 v[2:3], s[8:9], 0, v[130:131]
	s_add_i32 m0, s38, 0x1e000
	v_ashrrev_i32_e32 v15, 1, v12
	global_load_lds_dwordx4 v[2:3], off
	v_lshlrev_b32_e32 v2, 10, v9
	v_and_b32_e32 v2, 0xfffff800, v2
	v_lshl_add_u32 v2, v10, 7, v2
	v_and_b32_e32 v3, 1, v9
	v_lshl_or_b32 v2, v3, 6, v2
	v_lshl_add_u32 v136, v11, 1, v2
	v_lshlrev_b32_e32 v2, 10, v6
	v_and_b32_e32 v17, 48, v12
	v_lshlrev_b32_e32 v12, 2, v12
	v_and_b32_e32 v2, 0xfffff800, v2
	v_lshl_or_b32 v13, v13, 6, v17
	v_and_b32_e32 v12, 32, v12
	s_waitcnt vmcnt(6)
	v_lshl_add_u32 v2, v7, 7, v2
	v_and_b32_e32 v3, 1, v6
	v_and_b32_e32 v15, -8, v15
	v_bitop3_b32 v17, v13, v18, v12 bitop3:0xde
	v_add_lshl_u32 v16, s7, v16, 10
	s_cmp_lt_u32 s6, 4
	v_lshl_or_b32 v2, v3, 6, v2
	v_bitop3_b32 v140, v13, v16, v12 bitop3:0xde
	s_cselect_b64 s[6:7], -1, 0
	v_add_u32_e32 v141, s10, v15
	s_ashr_i32 s45, s22, 31
	v_add_u32_e32 v142, 0xffffc000, v14
	v_mov_b32_e32 v137, v1
	v_lshl_add_u32 v138, v8, 1, v2
	v_mov_b32_e32 v139, v1
	s_mov_b32 s46, 0
	v_add_u32_e32 v143, 0, v17
	s_branch .LBB0_2010

.Lh0_6:
	s_add_u32 s14, s12, 0x4000
	s_addc_u32 s15, s13, 0
	s_cmp_eq_u32 s50, 18
	s_cselect_b32 s18, s8, s14
	s_cselect_b32 s19, s9, s15
	s_cselect_b32 s16, s10, s36
	s_cselect_b32 s17, s11, s37
	s_add_u32 s14, s18, 0x8000
	s_addc_u32 s15, s19, 0
	s_add_i32 s51, 0, 0x10000
	s_add_i32 s54, 0, 0x14000
	v_add_u32_e32 v156, s51, v140
	v_add_u32_e32 v172, s54, v140
	ds_read_b128 v[144:147], v156
	ds_read_b128 v[148:151], v156 offset:1024
	ds_read_b128 v[152:155], v156 offset:2048
	ds_read_b128 v[156:159], v156 offset:3072
	ds_read_b128 v[160:163], v172
	ds_read_b128 v[164:167], v172 offset:1024
	ds_read_b128 v[168:171], v172 offset:2048
	ds_read_b128 v[172:175], v172 offset:3072
	v_lshl_add_u64 v[208:209], s[12:13], 0, v[136:137]
	s_add_i32 m0, s38, 0xc000
	ds_read_b128 v[176:179], v143
	ds_read_b128 v[180:183], v143 offset:1024
	ds_read_b128 v[184:187], v143 offset:2048
	ds_read_b128 v[188:191], v143 offset:3072
	ds_read_b128 v[192:195], v143 offset:4096
	ds_read_b128 v[196:199], v143 offset:5120
	ds_read_b128 v[200:203], v143 offset:6144
	ds_read_b128 v[204:207], v143 offset:7168
	global_load_lds_dwordx4 v[208:209], off
	v_lshl_add_u64 v[208:209], s[12:13], 0, v[138:139]
	s_add_i32 m0, s38, 0xe000
	s_nop 0
	global_load_lds_dwordx4 v[208:209], off
	s_waitcnt vmcnt(8)
	s_waitcnt lgkmcnt(0)
	s_barrier
	s_setprio 1
	s_waitcnt lgkmcnt(0)
	v_mfma_f32_16x16x32_bf16 v[126:129], v[144:147], v[176:179], v[126:129]
	v_mfma_f32_16x16x32_bf16 v[122:125], v[152:155], v[176:179], v[122:125]
	v_mfma_f32_16x16x32_bf16 v[118:121], v[144:147], v[184:187], v[118:121]
	v_mfma_f32_16x16x32_bf16 v[114:117], v[152:155], v[184:187], v[114:117]
	v_mfma_f32_16x16x32_bf16 v[102:105], v[144:147], v[192:195], v[102:105]
	v_mfma_f32_16x16x32_bf16 v[98:101], v[152:155], v[192:195], v[98:101]
	v_mfma_f32_16x16x32_bf16 v[86:89], v[144:147], v[200:203], v[86:89]
	v_mfma_f32_16x16x32_bf16 v[82:85], v[152:155], v[200:203], v[82:85]
	v_mfma_f32_16x16x32_bf16 v[126:129], v[148:151], v[180:183], v[126:129]
	v_mfma_f32_16x16x32_bf16 v[122:125], v[156:159], v[180:183], v[122:125]
	v_mfma_f32_16x16x32_bf16 v[118:121], v[148:151], v[188:191], v[118:121]
	v_mfma_f32_16x16x32_bf16 v[114:117], v[156:159], v[188:191], v[114:117]
	v_mfma_f32_16x16x32_bf16 v[102:105], v[148:151], v[196:199], v[102:105]
	v_mfma_f32_16x16x32_bf16 v[98:101], v[156:159], v[196:199], v[98:101]
	v_mfma_f32_16x16x32_bf16 v[86:89], v[148:151], v[204:207], v[86:89]
	v_mfma_f32_16x16x32_bf16 v[82:85], v[156:159], v[204:207], v[82:85]
	s_setprio 0
	s_setprio 1
	v_mfma_f32_16x16x32_bf16 v[110:113], v[160:163], v[176:179], v[110:113]
	v_mfma_f32_16x16x32_bf16 v[106:109], v[168:171], v[176:179], v[106:109]
	v_mfma_f32_16x16x32_bf16 v[94:97], v[160:163], v[184:187], v[94:97]
	v_mfma_f32_16x16x32_bf16 v[90:93], v[168:171], v[184:187], v[90:93]
	v_mfma_f32_16x16x32_bf16 v[78:81], v[160:163], v[192:195], v[78:81]
	v_mfma_f32_16x16x32_bf16 v[74:77], v[168:171], v[192:195], v[74:77]
	v_mfma_f32_16x16x32_bf16 v[70:73], v[160:163], v[200:203], v[70:73]
	v_mfma_f32_16x16x32_bf16 v[66:69], v[168:171], v[200:203], v[66:69]
	v_mfma_f32_16x16x32_bf16 v[110:113], v[164:167], v[180:183], v[110:113]
	v_mfma_f32_16x16x32_bf16 v[106:109], v[172:175], v[180:183], v[106:109]
	v_mfma_f32_16x16x32_bf16 v[94:97], v[164:167], v[188:191], v[94:97]
	v_mfma_f32_16x16x32_bf16 v[90:93], v[172:175], v[188:191], v[90:93]
	v_mfma_f32_16x16x32_bf16 v[78:81], v[164:167], v[196:199], v[78:81]
	v_mfma_f32_16x16x32_bf16 v[74:77], v[172:175], v[196:199], v[74:77]
	v_mfma_f32_16x16x32_bf16 v[70:73], v[164:167], v[204:207], v[70:73]
	v_mfma_f32_16x16x32_bf16 v[66:69], v[172:175], v[204:207], v[66:69]
	s_setprio 0
	s_add_i32 s51, s51, s24
	v_lshl_add_u64 v[208:209], s[16:17], 0, v[0:1]
	s_mov_b32 m0, s51
	ds_read_b128 v[176:179], v143 offset:16384
	ds_read_b128 v[180:183], v143 offset:17408
	ds_read_b128 v[184:187], v143 offset:18432
	ds_read_b128 v[188:191], v143 offset:19456
	ds_read_b128 v[192:195], v143 offset:20480
	ds_read_b128 v[196:199], v143 offset:21504
	ds_read_b128 v[200:203], v143 offset:22528
	ds_read_b128 v[204:207], v143 offset:23552
	global_load_lds_dwordx4 v[208:209], off
	s_add_i32 m0, s51, 0x2000
	s_add_u32 s52, s16, 0x164000
	v_lshl_add_u64 v[216:217], s[16:17], 0, v[130:131]
	s_addc_u32 s53, s17, 0
	s_add_i32 s51, s54, s24
	global_load_lds_dwordx4 v[216:217], off
	v_lshl_add_u64 v[220:221], s[52:53], 0, v[0:1]
	s_mov_b32 m0, s51
	s_nop 0
	global_load_lds_dwordx4 v[220:221], off
	v_lshl_add_u64 v[220:221], s[52:53], 0, v[130:131]
	s_add_i32 m0, s51, 0x2000
	s_nop 0
	global_load_lds_dwordx4 v[220:221], off
	v_lshl_add_u64 v[220:221], s[18:19], 0, v[134:135]
	s_mov_b32 m0, s38
	s_nop 0
	global_load_lds_dwordx4 v[220:221], off
	v_lshl_add_u64 v[220:221], s[18:19], 0, v[132:133]
	s_mov_b32 m0, s39
	s_nop 0
	global_load_lds_dwordx4 v[220:221], off
	s_waitcnt vmcnt(8)
	s_waitcnt lgkmcnt(0)
	s_barrier
	s_setprio 1
	s_waitcnt lgkmcnt(0)
	v_mfma_f32_16x16x32_bf16 v[62:65], v[144:147], v[176:179], v[62:65]
	v_mfma_f32_16x16x32_bf16 v[58:61], v[152:155], v[176:179], v[58:61]
	v_mfma_f32_16x16x32_bf16 v[54:57], v[144:147], v[184:187], v[54:57]
	v_mfma_f32_16x16x32_bf16 v[50:53], v[152:155], v[184:187], v[50:53]
	v_mfma_f32_16x16x32_bf16 v[38:41], v[144:147], v[192:195], v[38:41]
	v_mfma_f32_16x16x32_bf16 v[34:37], v[152:155], v[192:195], v[34:37]
	v_mfma_f32_16x16x32_bf16 v[22:25], v[144:147], v[200:203], v[22:25]
	v_mfma_f32_16x16x32_bf16 v[18:21], v[152:155], v[200:203], v[18:21]
	v_mfma_f32_16x16x32_bf16 v[62:65], v[148:151], v[180:183], v[62:65]
	v_mfma_f32_16x16x32_bf16 v[58:61], v[156:159], v[180:183], v[58:61]
	v_mfma_f32_16x16x32_bf16 v[54:57], v[148:151], v[188:191], v[54:57]
	v_mfma_f32_16x16x32_bf16 v[50:53], v[156:159], v[188:191], v[50:53]
	v_mfma_f32_16x16x32_bf16 v[38:41], v[148:151], v[196:199], v[38:41]
	v_mfma_f32_16x16x32_bf16 v[34:37], v[156:159], v[196:199], v[34:37]
	v_mfma_f32_16x16x32_bf16 v[22:25], v[148:151], v[204:207], v[22:25]
	v_mfma_f32_16x16x32_bf16 v[18:21], v[156:159], v[204:207], v[18:21]
	s_setprio 0
	s_setprio 1
	v_mfma_f32_16x16x32_bf16 v[46:49], v[160:163], v[176:179], v[46:49]
	v_mfma_f32_16x16x32_bf16 v[42:45], v[168:171], v[176:179], v[42:45]
	v_mfma_f32_16x16x32_bf16 v[30:33], v[160:163], v[184:187], v[30:33]
	v_mfma_f32_16x16x32_bf16 v[26:29], v[168:171], v[184:187], v[26:29]
	v_mfma_f32_16x16x32_bf16 v[14:17], v[160:163], v[192:195], v[14:17]
	v_mfma_f32_16x16x32_bf16 v[10:13], v[168:171], v[192:195], v[10:13]
	v_mfma_f32_16x16x32_bf16 v[6:9], v[160:163], v[200:203], v[6:9]
	v_mfma_f32_16x16x32_bf16 v[2:5], v[168:171], v[200:203], v[2:5]
	v_mfma_f32_16x16x32_bf16 v[46:49], v[164:167], v[180:183], v[46:49]
	v_mfma_f32_16x16x32_bf16 v[42:45], v[172:175], v[180:183], v[42:45]
	v_mfma_f32_16x16x32_bf16 v[30:33], v[164:167], v[188:191], v[30:33]
	v_mfma_f32_16x16x32_bf16 v[26:29], v[172:175], v[188:191], v[26:29]
	v_mfma_f32_16x16x32_bf16 v[14:17], v[164:167], v[196:199], v[14:17]
	v_mfma_f32_16x16x32_bf16 v[10:13], v[172:175], v[196:199], v[10:13]
	v_mfma_f32_16x16x32_bf16 v[6:9], v[164:167], v[204:207], v[6:9]
	v_mfma_f32_16x16x32_bf16 v[2:5], v[172:175], v[204:207], v[2:5]
	s_setprio 0
	s_add_i32 s51, 0, 0x18000
	s_add_i32 s52, 0, 0x1c000
	v_add_u32_e32 v156, s51, v140
	v_add_u32_e32 v172, s52, v140
	ds_read_b128 v[144:147], v156
	ds_read_b128 v[148:151], v156 offset:1024
	ds_read_b128 v[152:155], v156 offset:2048
	ds_read_b128 v[156:159], v156 offset:3072
	ds_read_b128 v[160:163], v172
	ds_read_b128 v[164:167], v172 offset:1024
	ds_read_b128 v[168:171], v172 offset:2048
	ds_read_b128 v[172:175], v172 offset:3072
	s_add_u32 s18, s18, 0x4000
	s_addc_u32 s19, s19, 0
	s_mov_b32 m0, s40
	v_lshl_add_u64 v[220:221], s[18:19], 0, v[134:135]
	ds_read_b128 v[176:179], v143 offset:32768
	ds_read_b128 v[180:183], v143 offset:33792
	ds_read_b128 v[184:187], v143 offset:34816
	ds_read_b128 v[188:191], v143 offset:35840
	ds_read_b128 v[192:195], v143 offset:36864
	ds_read_b128 v[196:199], v143 offset:37888
	ds_read_b128 v[200:203], v143 offset:38912
	ds_read_b128 v[204:207], v143 offset:39936
	global_load_lds_dwordx4 v[220:221], off
	v_lshl_add_u64 v[220:221], s[18:19], 0, v[132:133]
	s_mov_b32 m0, s41
	s_nop 0
	global_load_lds_dwordx4 v[220:221], off
	s_waitcnt vmcnt(8)
	s_waitcnt lgkmcnt(0)
	s_barrier
	s_setprio 1
	s_waitcnt lgkmcnt(0)
	v_mfma_f32_16x16x32_bf16 v[126:129], v[144:147], v[176:179], v[126:129]
	v_mfma_f32_16x16x32_bf16 v[122:125], v[152:155], v[176:179], v[122:125]
	v_mfma_f32_16x16x32_bf16 v[118:121], v[144:147], v[184:187], v[118:121]
	v_mfma_f32_16x16x32_bf16 v[114:117], v[152:155], v[184:187], v[114:117]
	v_mfma_f32_16x16x32_bf16 v[102:105], v[144:147], v[192:195], v[102:105]
	v_mfma_f32_16x16x32_bf16 v[98:101], v[152:155], v[192:195], v[98:101]
	v_mfma_f32_16x16x32_bf16 v[86:89], v[144:147], v[200:203], v[86:89]
	v_mfma_f32_16x16x32_bf16 v[82:85], v[152:155], v[200:203], v[82:85]
	v_mfma_f32_16x16x32_bf16 v[126:129], v[148:151], v[180:183], v[126:129]
	v_mfma_f32_16x16x32_bf16 v[122:125], v[156:159], v[180:183], v[122:125]
	v_mfma_f32_16x16x32_bf16 v[118:121], v[148:151], v[188:191], v[118:121]
	v_mfma_f32_16x16x32_bf16 v[114:117], v[156:159], v[188:191], v[114:117]
	v_mfma_f32_16x16x32_bf16 v[102:105], v[148:151], v[196:199], v[102:105]
	v_mfma_f32_16x16x32_bf16 v[98:101], v[156:159], v[196:199], v[98:101]
	v_mfma_f32_16x16x32_bf16 v[86:89], v[148:151], v[204:207], v[86:89]
	v_mfma_f32_16x16x32_bf16 v[82:85], v[156:159], v[204:207], v[82:85]
	s_setprio 0
	s_setprio 1
	v_mfma_f32_16x16x32_bf16 v[110:113], v[160:163], v[176:179], v[110:113]
	v_mfma_f32_16x16x32_bf16 v[106:109], v[168:171], v[176:179], v[106:109]
	v_mfma_f32_16x16x32_bf16 v[94:97], v[160:163], v[184:187], v[94:97]
	v_mfma_f32_16x16x32_bf16 v[90:93], v[168:171], v[184:187], v[90:93]
	v_mfma_f32_16x16x32_bf16 v[78:81], v[160:163], v[192:195], v[78:81]
	v_mfma_f32_16x16x32_bf16 v[74:77], v[168:171], v[192:195], v[74:77]
	v_mfma_f32_16x16x32_bf16 v[70:73], v[160:163], v[200:203], v[70:73]
	v_mfma_f32_16x16x32_bf16 v[66:69], v[168:171], v[200:203], v[66:69]
	v_mfma_f32_16x16x32_bf16 v[110:113], v[164:167], v[180:183], v[110:113]
	v_mfma_f32_16x16x32_bf16 v[106:109], v[172:175], v[180:183], v[106:109]
	v_mfma_f32_16x16x32_bf16 v[94:97], v[164:167], v[188:191], v[94:97]
	v_mfma_f32_16x16x32_bf16 v[90:93], v[172:175], v[188:191], v[90:93]
	v_mfma_f32_16x16x32_bf16 v[78:81], v[164:167], v[196:199], v[78:81]
	v_mfma_f32_16x16x32_bf16 v[74:77], v[172:175], v[196:199], v[74:77]
	v_mfma_f32_16x16x32_bf16 v[70:73], v[164:167], v[204:207], v[70:73]
	v_mfma_f32_16x16x32_bf16 v[66:69], v[172:175], v[204:207], v[66:69]
	s_setprio 0
	s_add_i32 s18, s51, s24
	v_lshl_add_u64 v[208:209], v[208:209], 0, s[2:3]
	s_mov_b32 m0, s18
	ds_read_b128 v[176:179], v143 offset:49152
	ds_read_b128 v[180:183], v143 offset:50176
	ds_read_b128 v[184:187], v143 offset:51200
	ds_read_b128 v[188:191], v143 offset:52224
	ds_read_b128 v[192:195], v143 offset:53248
	ds_read_b128 v[196:199], v143 offset:54272
	ds_read_b128 v[200:203], v143 offset:55296
	ds_read_b128 v[204:207], v143 offset:56320
	global_load_lds_dwordx4 v[208:209], off
	s_add_i32 m0, s18, 0x2000
	s_add_u32 s16, s16, 0x164080
	v_lshl_add_u64 v[208:209], v[216:217], 0, s[2:3]
	s_addc_u32 s17, s17, 0
	s_add_i32 s18, s52, s24
	global_load_lds_dwordx4 v[208:209], off
	v_lshl_add_u64 v[208:209], s[16:17], 0, v[0:1]
	s_mov_b32 m0, s18
	s_nop 0
	global_load_lds_dwordx4 v[208:209], off
	v_lshl_add_u64 v[208:209], s[16:17], 0, v[130:131]
	s_add_i32 m0, s18, 0x2000
	s_nop 0
	global_load_lds_dwordx4 v[208:209], off
	v_lshl_add_u64 v[208:209], s[14:15], 0, v[134:135]
	s_mov_b32 m0, s42
	s_nop 0
	global_load_lds_dwordx4 v[208:209], off
	v_lshl_add_u64 v[208:209], s[14:15], 0, v[132:133]
	s_mov_b32 m0, s43
	s_nop 0
	global_load_lds_dwordx4 v[208:209], off
	s_waitcnt vmcnt(8)
	s_waitcnt lgkmcnt(0)
	s_barrier
	s_setprio 1
	s_waitcnt lgkmcnt(0)
	v_mfma_f32_16x16x32_bf16 v[62:65], v[144:147], v[176:179], v[62:65]
	v_mfma_f32_16x16x32_bf16 v[58:61], v[152:155], v[176:179], v[58:61]
	v_mfma_f32_16x16x32_bf16 v[54:57], v[144:147], v[184:187], v[54:57]
	v_mfma_f32_16x16x32_bf16 v[50:53], v[152:155], v[184:187], v[50:53]
	v_mfma_f32_16x16x32_bf16 v[38:41], v[144:147], v[192:195], v[38:41]
	v_mfma_f32_16x16x32_bf16 v[34:37], v[152:155], v[192:195], v[34:37]
	v_mfma_f32_16x16x32_bf16 v[22:25], v[144:147], v[200:203], v[22:25]
	v_mfma_f32_16x16x32_bf16 v[18:21], v[152:155], v[200:203], v[18:21]
	v_mfma_f32_16x16x32_bf16 v[62:65], v[148:151], v[180:183], v[62:65]
	v_mfma_f32_16x16x32_bf16 v[58:61], v[156:159], v[180:183], v[58:61]
	v_mfma_f32_16x16x32_bf16 v[54:57], v[148:151], v[188:191], v[54:57]
	v_mfma_f32_16x16x32_bf16 v[50:53], v[156:159], v[188:191], v[50:53]
	v_mfma_f32_16x16x32_bf16 v[38:41], v[148:151], v[196:199], v[38:41]
	v_mfma_f32_16x16x32_bf16 v[34:37], v[156:159], v[196:199], v[34:37]
	v_mfma_f32_16x16x32_bf16 v[22:25], v[148:151], v[204:207], v[22:25]
	v_mfma_f32_16x16x32_bf16 v[18:21], v[156:159], v[204:207], v[18:21]
	s_setprio 0
	s_setprio 1
	v_mfma_f32_16x16x32_bf16 v[46:49], v[160:163], v[176:179], v[46:49]
	v_mfma_f32_16x16x32_bf16 v[42:45], v[168:171], v[176:179], v[42:45]
	v_mfma_f32_16x16x32_bf16 v[30:33], v[160:163], v[184:187], v[30:33]
	v_mfma_f32_16x16x32_bf16 v[26:29], v[168:171], v[184:187], v[26:29]
	v_mfma_f32_16x16x32_bf16 v[14:17], v[160:163], v[192:195], v[14:17]
	v_mfma_f32_16x16x32_bf16 v[10:13], v[168:171], v[192:195], v[10:13]
	v_mfma_f32_16x16x32_bf16 v[6:9], v[160:163], v[200:203], v[6:9]
	v_mfma_f32_16x16x32_bf16 v[2:5], v[168:171], v[200:203], v[2:5]
	v_mfma_f32_16x16x32_bf16 v[46:49], v[164:167], v[180:183], v[46:49]
	v_mfma_f32_16x16x32_bf16 v[42:45], v[172:175], v[180:183], v[42:45]
	v_mfma_f32_16x16x32_bf16 v[30:33], v[164:167], v[188:191], v[30:33]
	v_mfma_f32_16x16x32_bf16 v[26:29], v[172:175], v[188:191], v[26:29]
	v_mfma_f32_16x16x32_bf16 v[14:17], v[164:167], v[196:199], v[14:17]
	v_mfma_f32_16x16x32_bf16 v[10:13], v[172:175], v[196:199], v[10:13]
	v_mfma_f32_16x16x32_bf16 v[6:9], v[164:167], v[204:207], v[6:9]
	v_mfma_f32_16x16x32_bf16 v[2:5], v[172:175], v[204:207], v[2:5]
	s_setprio 0
	s_add_i32 s50, s50, 2
	s_add_u32 s36, s36, 0x100
	s_addc_u32 s37, s37, 0
	s_add_u32 s12, s12, 0x10000
	s_addc_u32 s13, s13, 0
	s_cmp_gt_u32 s50, 19
	s_cbranch_scc0 .Lh0_6
	s_branch .Ldone_6
.Lh1_6:
	s_add_u32 s14, s12, 0x4000
	s_addc_u32 s15, s13, 0
	s_cmp_eq_u32 s50, 18
	s_cselect_b32 s18, s8, s14
	s_cselect_b32 s19, s9, s15
	s_cselect_b32 s16, s10, s36
	s_cselect_b32 s17, s11, s37
	s_add_u32 s14, s18, 0x8000
	s_addc_u32 s15, s19, 0
	s_add_i32 s51, 0, 0x10000
	s_add_i32 s54, 0, 0x14000
	v_add_u32_e32 v156, s51, v140
	v_add_u32_e32 v172, s54, v140
	ds_read_b128 v[144:147], v156
	ds_read_b128 v[148:151], v156 offset:1024
	ds_read_b128 v[152:155], v156 offset:2048
	ds_read_b128 v[156:159], v156 offset:3072
	ds_read_b128 v[160:163], v172
	ds_read_b128 v[164:167], v172 offset:1024
	ds_read_b128 v[168:171], v172 offset:2048
	ds_read_b128 v[172:175], v172 offset:3072
	v_lshl_add_u64 v[208:209], s[12:13], 0, v[136:137]
	s_add_i32 m0, s38, 0xc000
	ds_read_b128 v[176:179], v143
	ds_read_b128 v[180:183], v143 offset:1024
	ds_read_b128 v[184:187], v143 offset:2048
	ds_read_b128 v[188:191], v143 offset:3072
	ds_read_b128 v[192:195], v143 offset:4096
	ds_read_b128 v[196:199], v143 offset:5120
	ds_read_b128 v[200:203], v143 offset:6144
	ds_read_b128 v[204:207], v143 offset:7168
	global_load_lds_dwordx4 v[208:209], off
	v_lshl_add_u64 v[208:209], s[12:13], 0, v[138:139]
	s_add_i32 m0, s38, 0xe000
	s_nop 0
	global_load_lds_dwordx4 v[208:209], off
	s_waitcnt vmcnt(8)
	s_waitcnt lgkmcnt(0)
	s_setprio 1
	s_waitcnt lgkmcnt(0)
	v_mfma_f32_16x16x32_bf16 v[126:129], v[144:147], v[176:179], v[126:129]
	v_mfma_f32_16x16x32_bf16 v[122:125], v[152:155], v[176:179], v[122:125]
	v_mfma_f32_16x16x32_bf16 v[118:121], v[144:147], v[184:187], v[118:121]
	v_mfma_f32_16x16x32_bf16 v[114:117], v[152:155], v[184:187], v[114:117]
	v_mfma_f32_16x16x32_bf16 v[102:105], v[144:147], v[192:195], v[102:105]
	v_mfma_f32_16x16x32_bf16 v[98:101], v[152:155], v[192:195], v[98:101]
	v_mfma_f32_16x16x32_bf16 v[86:89], v[144:147], v[200:203], v[86:89]
	v_mfma_f32_16x16x32_bf16 v[82:85], v[152:155], v[200:203], v[82:85]
	v_mfma_f32_16x16x32_bf16 v[126:129], v[148:151], v[180:183], v[126:129]
	v_mfma_f32_16x16x32_bf16 v[122:125], v[156:159], v[180:183], v[122:125]
	v_mfma_f32_16x16x32_bf16 v[118:121], v[148:151], v[188:191], v[118:121]
	v_mfma_f32_16x16x32_bf16 v[114:117], v[156:159], v[188:191], v[114:117]
	v_mfma_f32_16x16x32_bf16 v[102:105], v[148:151], v[196:199], v[102:105]
	v_mfma_f32_16x16x32_bf16 v[98:101], v[156:159], v[196:199], v[98:101]
	v_mfma_f32_16x16x32_bf16 v[86:89], v[148:151], v[204:207], v[86:89]
	v_mfma_f32_16x16x32_bf16 v[82:85], v[156:159], v[204:207], v[82:85]
	s_setprio 0
	s_setprio 1
	v_mfma_f32_16x16x32_bf16 v[110:113], v[160:163], v[176:179], v[110:113]
	v_mfma_f32_16x16x32_bf16 v[106:109], v[168:171], v[176:179], v[106:109]
	v_mfma_f32_16x16x32_bf16 v[94:97], v[160:163], v[184:187], v[94:97]
	v_mfma_f32_16x16x32_bf16 v[90:93], v[168:171], v[184:187], v[90:93]
	v_mfma_f32_16x16x32_bf16 v[78:81], v[160:163], v[192:195], v[78:81]
	v_mfma_f32_16x16x32_bf16 v[74:77], v[168:171], v[192:195], v[74:77]
	v_mfma_f32_16x16x32_bf16 v[70:73], v[160:163], v[200:203], v[70:73]
	v_mfma_f32_16x16x32_bf16 v[66:69], v[168:171], v[200:203], v[66:69]
	v_mfma_f32_16x16x32_bf16 v[110:113], v[164:167], v[180:183], v[110:113]
	v_mfma_f32_16x16x32_bf16 v[106:109], v[172:175], v[180:183], v[106:109]
	v_mfma_f32_16x16x32_bf16 v[94:97], v[164:167], v[188:191], v[94:97]
	v_mfma_f32_16x16x32_bf16 v[90:93], v[172:175], v[188:191], v[90:93]
	v_mfma_f32_16x16x32_bf16 v[78:81], v[164:167], v[196:199], v[78:81]
	v_mfma_f32_16x16x32_bf16 v[74:77], v[172:175], v[196:199], v[74:77]
	v_mfma_f32_16x16x32_bf16 v[70:73], v[164:167], v[204:207], v[70:73]
	v_mfma_f32_16x16x32_bf16 v[66:69], v[172:175], v[204:207], v[66:69]
	s_setprio 0
	s_barrier
	s_add_i32 s51, s51, s24
	v_lshl_add_u64 v[208:209], s[16:17], 0, v[0:1]
	s_mov_b32 m0, s51
	ds_read_b128 v[176:179], v143 offset:16384
	ds_read_b128 v[180:183], v143 offset:17408
	ds_read_b128 v[184:187], v143 offset:18432
	ds_read_b128 v[188:191], v143 offset:19456
	ds_read_b128 v[192:195], v143 offset:20480
	ds_read_b128 v[196:199], v143 offset:21504
	ds_read_b128 v[200:203], v143 offset:22528
	ds_read_b128 v[204:207], v143 offset:23552
	global_load_lds_dwordx4 v[208:209], off
	s_add_i32 m0, s51, 0x2000
	s_add_u32 s52, s16, 0x164000
	v_lshl_add_u64 v[216:217], s[16:17], 0, v[130:131]
	s_addc_u32 s53, s17, 0
	s_add_i32 s51, s54, s24
	global_load_lds_dwordx4 v[216:217], off
	v_lshl_add_u64 v[220:221], s[52:53], 0, v[0:1]
	s_mov_b32 m0, s51
	s_nop 0
	global_load_lds_dwordx4 v[220:221], off
	v_lshl_add_u64 v[220:221], s[52:53], 0, v[130:131]
	s_add_i32 m0, s51, 0x2000
	s_nop 0
	global_load_lds_dwordx4 v[220:221], off
	v_lshl_add_u64 v[220:221], s[18:19], 0, v[134:135]
	s_mov_b32 m0, s38
	s_nop 0
	global_load_lds_dwordx4 v[220:221], off
	v_lshl_add_u64 v[220:221], s[18:19], 0, v[132:133]
	s_mov_b32 m0, s39
	s_nop 0
	global_load_lds_dwordx4 v[220:221], off
	s_waitcnt vmcnt(8)
	s_waitcnt lgkmcnt(0)
	s_setprio 1
	s_waitcnt lgkmcnt(0)
	v_mfma_f32_16x16x32_bf16 v[62:65], v[144:147], v[176:179], v[62:65]
	v_mfma_f32_16x16x32_bf16 v[58:61], v[152:155], v[176:179], v[58:61]
	v_mfma_f32_16x16x32_bf16 v[54:57], v[144:147], v[184:187], v[54:57]
	v_mfma_f32_16x16x32_bf16 v[50:53], v[152:155], v[184:187], v[50:53]
	v_mfma_f32_16x16x32_bf16 v[38:41], v[144:147], v[192:195], v[38:41]
	v_mfma_f32_16x16x32_bf16 v[34:37], v[152:155], v[192:195], v[34:37]
	v_mfma_f32_16x16x32_bf16 v[22:25], v[144:147], v[200:203], v[22:25]
	v_mfma_f32_16x16x32_bf16 v[18:21], v[152:155], v[200:203], v[18:21]
	v_mfma_f32_16x16x32_bf16 v[62:65], v[148:151], v[180:183], v[62:65]
	v_mfma_f32_16x16x32_bf16 v[58:61], v[156:159], v[180:183], v[58:61]
	v_mfma_f32_16x16x32_bf16 v[54:57], v[148:151], v[188:191], v[54:57]
	v_mfma_f32_16x16x32_bf16 v[50:53], v[156:159], v[188:191], v[50:53]
	v_mfma_f32_16x16x32_bf16 v[38:41], v[148:151], v[196:199], v[38:41]
	v_mfma_f32_16x16x32_bf16 v[34:37], v[156:159], v[196:199], v[34:37]
	v_mfma_f32_16x16x32_bf16 v[22:25], v[148:151], v[204:207], v[22:25]
	v_mfma_f32_16x16x32_bf16 v[18:21], v[156:159], v[204:207], v[18:21]
	s_setprio 0
	s_setprio 1
	v_mfma_f32_16x16x32_bf16 v[46:49], v[160:163], v[176:179], v[46:49]
	v_mfma_f32_16x16x32_bf16 v[42:45], v[168:171], v[176:179], v[42:45]
	v_mfma_f32_16x16x32_bf16 v[30:33], v[160:163], v[184:187], v[30:33]
	v_mfma_f32_16x16x32_bf16 v[26:29], v[168:171], v[184:187], v[26:29]
	v_mfma_f32_16x16x32_bf16 v[14:17], v[160:163], v[192:195], v[14:17]
	v_mfma_f32_16x16x32_bf16 v[10:13], v[168:171], v[192:195], v[10:13]
	v_mfma_f32_16x16x32_bf16 v[6:9], v[160:163], v[200:203], v[6:9]
	v_mfma_f32_16x16x32_bf16 v[2:5], v[168:171], v[200:203], v[2:5]
	v_mfma_f32_16x16x32_bf16 v[46:49], v[164:167], v[180:183], v[46:49]
	v_mfma_f32_16x16x32_bf16 v[42:45], v[172:175], v[180:183], v[42:45]
	v_mfma_f32_16x16x32_bf16 v[30:33], v[164:167], v[188:191], v[30:33]
	v_mfma_f32_16x16x32_bf16 v[26:29], v[172:175], v[188:191], v[26:29]
	v_mfma_f32_16x16x32_bf16 v[14:17], v[164:167], v[196:199], v[14:17]
	v_mfma_f32_16x16x32_bf16 v[10:13], v[172:175], v[196:199], v[10:13]
	v_mfma_f32_16x16x32_bf16 v[6:9], v[164:167], v[204:207], v[6:9]
	v_mfma_f32_16x16x32_bf16 v[2:5], v[172:175], v[204:207], v[2:5]
	s_setprio 0
	s_barrier
	s_add_i32 s51, 0, 0x18000
	s_add_i32 s52, 0, 0x1c000
	v_add_u32_e32 v156, s51, v140
	v_add_u32_e32 v172, s52, v140
	ds_read_b128 v[144:147], v156
	ds_read_b128 v[148:151], v156 offset:1024
	ds_read_b128 v[152:155], v156 offset:2048
	ds_read_b128 v[156:159], v156 offset:3072
	ds_read_b128 v[160:163], v172
	ds_read_b128 v[164:167], v172 offset:1024
	ds_read_b128 v[168:171], v172 offset:2048
	ds_read_b128 v[172:175], v172 offset:3072
	s_add_u32 s18, s18, 0x4000
	s_addc_u32 s19, s19, 0
	s_mov_b32 m0, s40
	v_lshl_add_u64 v[220:221], s[18:19], 0, v[134:135]
	ds_read_b128 v[176:179], v143 offset:32768
	ds_read_b128 v[180:183], v143 offset:33792
	ds_read_b128 v[184:187], v143 offset:34816
	ds_read_b128 v[188:191], v143 offset:35840
	ds_read_b128 v[192:195], v143 offset:36864
	ds_read_b128 v[196:199], v143 offset:37888
	ds_read_b128 v[200:203], v143 offset:38912
	ds_read_b128 v[204:207], v143 offset:39936
	global_load_lds_dwordx4 v[220:221], off
	v_lshl_add_u64 v[220:221], s[18:19], 0, v[132:133]
	s_mov_b32 m0, s41
	s_nop 0
	global_load_lds_dwordx4 v[220:221], off
	s_waitcnt vmcnt(8)
	s_waitcnt lgkmcnt(0)
	s_setprio 1
	s_waitcnt lgkmcnt(0)
	v_mfma_f32_16x16x32_bf16 v[126:129], v[144:147], v[176:179], v[126:129]
	v_mfma_f32_16x16x32_bf16 v[122:125], v[152:155], v[176:179], v[122:125]
	v_mfma_f32_16x16x32_bf16 v[118:121], v[144:147], v[184:187], v[118:121]
	v_mfma_f32_16x16x32_bf16 v[114:117], v[152:155], v[184:187], v[114:117]
	v_mfma_f32_16x16x32_bf16 v[102:105], v[144:147], v[192:195], v[102:105]
	v_mfma_f32_16x16x32_bf16 v[98:101], v[152:155], v[192:195], v[98:101]
	v_mfma_f32_16x16x32_bf16 v[86:89], v[144:147], v[200:203], v[86:89]
	v_mfma_f32_16x16x32_bf16 v[82:85], v[152:155], v[200:203], v[82:85]
	v_mfma_f32_16x16x32_bf16 v[126:129], v[148:151], v[180:183], v[126:129]
	v_mfma_f32_16x16x32_bf16 v[122:125], v[156:159], v[180:183], v[122:125]
	v_mfma_f32_16x16x32_bf16 v[118:121], v[148:151], v[188:191], v[118:121]
	v_mfma_f32_16x16x32_bf16 v[114:117], v[156:159], v[188:191], v[114:117]
	v_mfma_f32_16x16x32_bf16 v[102:105], v[148:151], v[196:199], v[102:105]
	v_mfma_f32_16x16x32_bf16 v[98:101], v[156:159], v[196:199], v[98:101]
	v_mfma_f32_16x16x32_bf16 v[86:89], v[148:151], v[204:207], v[86:89]
	v_mfma_f32_16x16x32_bf16 v[82:85], v[156:159], v[204:207], v[82:85]
	s_setprio 0
	s_setprio 1
	v_mfma_f32_16x16x32_bf16 v[110:113], v[160:163], v[176:179], v[110:113]
	v_mfma_f32_16x16x32_bf16 v[106:109], v[168:171], v[176:179], v[106:109]
	v_mfma_f32_16x16x32_bf16 v[94:97], v[160:163], v[184:187], v[94:97]
	v_mfma_f32_16x16x32_bf16 v[90:93], v[168:171], v[184:187], v[90:93]
	v_mfma_f32_16x16x32_bf16 v[78:81], v[160:163], v[192:195], v[78:81]
	v_mfma_f32_16x16x32_bf16 v[74:77], v[168:171], v[192:195], v[74:77]
	v_mfma_f32_16x16x32_bf16 v[70:73], v[160:163], v[200:203], v[70:73]
	v_mfma_f32_16x16x32_bf16 v[66:69], v[168:171], v[200:203], v[66:69]
	v_mfma_f32_16x16x32_bf16 v[110:113], v[164:167], v[180:183], v[110:113]
	v_mfma_f32_16x16x32_bf16 v[106:109], v[172:175], v[180:183], v[106:109]
	v_mfma_f32_16x16x32_bf16 v[94:97], v[164:167], v[188:191], v[94:97]
	v_mfma_f32_16x16x32_bf16 v[90:93], v[172:175], v[188:191], v[90:93]
	v_mfma_f32_16x16x32_bf16 v[78:81], v[164:167], v[196:199], v[78:81]
	v_mfma_f32_16x16x32_bf16 v[74:77], v[172:175], v[196:199], v[74:77]
	v_mfma_f32_16x16x32_bf16 v[70:73], v[164:167], v[204:207], v[70:73]
	v_mfma_f32_16x16x32_bf16 v[66:69], v[172:175], v[204:207], v[66:69]
	s_setprio 0
	s_barrier
	s_add_i32 s18, s51, s24
	v_lshl_add_u64 v[208:209], v[208:209], 0, s[2:3]
	s_mov_b32 m0, s18
	ds_read_b128 v[176:179], v143 offset:49152
	ds_read_b128 v[180:183], v143 offset:50176
	ds_read_b128 v[184:187], v143 offset:51200
	ds_read_b128 v[188:191], v143 offset:52224
	ds_read_b128 v[192:195], v143 offset:53248
	ds_read_b128 v[196:199], v143 offset:54272
	ds_read_b128 v[200:203], v143 offset:55296
	ds_read_b128 v[204:207], v143 offset:56320
	global_load_lds_dwordx4 v[208:209], off
	s_add_i32 m0, s18, 0x2000
	s_add_u32 s16, s16, 0x164080
	v_lshl_add_u64 v[208:209], v[216:217], 0, s[2:3]
	s_addc_u32 s17, s17, 0
	s_add_i32 s18, s52, s24
	global_load_lds_dwordx4 v[208:209], off
	v_lshl_add_u64 v[208:209], s[16:17], 0, v[0:1]
	s_mov_b32 m0, s18
	s_nop 0
	global_load_lds_dwordx4 v[208:209], off
	v_lshl_add_u64 v[208:209], s[16:17], 0, v[130:131]
	s_add_i32 m0, s18, 0x2000
	s_nop 0
	global_load_lds_dwordx4 v[208:209], off
	v_lshl_add_u64 v[208:209], s[14:15], 0, v[134:135]
	s_mov_b32 m0, s42
	s_nop 0
	global_load_lds_dwordx4 v[208:209], off
	v_lshl_add_u64 v[208:209], s[14:15], 0, v[132:133]
	s_mov_b32 m0, s43
	s_nop 0
	global_load_lds_dwordx4 v[208:209], off
	s_waitcnt vmcnt(8)
	s_waitcnt lgkmcnt(0)
	s_setprio 1
	s_waitcnt lgkmcnt(0)
	v_mfma_f32_16x16x32_bf16 v[62:65], v[144:147], v[176:179], v[62:65]
	v_mfma_f32_16x16x32_bf16 v[58:61], v[152:155], v[176:179], v[58:61]
	v_mfma_f32_16x16x32_bf16 v[54:57], v[144:147], v[184:187], v[54:57]
	v_mfma_f32_16x16x32_bf16 v[50:53], v[152:155], v[184:187], v[50:53]
	v_mfma_f32_16x16x32_bf16 v[38:41], v[144:147], v[192:195], v[38:41]
	v_mfma_f32_16x16x32_bf16 v[34:37], v[152:155], v[192:195], v[34:37]
	v_mfma_f32_16x16x32_bf16 v[22:25], v[144:147], v[200:203], v[22:25]
	v_mfma_f32_16x16x32_bf16 v[18:21], v[152:155], v[200:203], v[18:21]
	v_mfma_f32_16x16x32_bf16 v[62:65], v[148:151], v[180:183], v[62:65]
	v_mfma_f32_16x16x32_bf16 v[58:61], v[156:159], v[180:183], v[58:61]
	v_mfma_f32_16x16x32_bf16 v[54:57], v[148:151], v[188:191], v[54:57]
	v_mfma_f32_16x16x32_bf16 v[50:53], v[156:159], v[188:191], v[50:53]
	v_mfma_f32_16x16x32_bf16 v[38:41], v[148:151], v[196:199], v[38:41]
	v_mfma_f32_16x16x32_bf16 v[34:37], v[156:159], v[196:199], v[34:37]
	v_mfma_f32_16x16x32_bf16 v[22:25], v[148:151], v[204:207], v[22:25]
	v_mfma_f32_16x16x32_bf16 v[18:21], v[156:159], v[204:207], v[18:21]
	s_setprio 0
	s_setprio 1
	v_mfma_f32_16x16x32_bf16 v[46:49], v[160:163], v[176:179], v[46:49]
	v_mfma_f32_16x16x32_bf16 v[42:45], v[168:171], v[176:179], v[42:45]
	v_mfma_f32_16x16x32_bf16 v[30:33], v[160:163], v[184:187], v[30:33]
	v_mfma_f32_16x16x32_bf16 v[26:29], v[168:171], v[184:187], v[26:29]
	v_mfma_f32_16x16x32_bf16 v[14:17], v[160:163], v[192:195], v[14:17]
	v_mfma_f32_16x16x32_bf16 v[10:13], v[168:171], v[192:195], v[10:13]
	v_mfma_f32_16x16x32_bf16 v[6:9], v[160:163], v[200:203], v[6:9]
	v_mfma_f32_16x16x32_bf16 v[2:5], v[168:171], v[200:203], v[2:5]
	v_mfma_f32_16x16x32_bf16 v[46:49], v[164:167], v[180:183], v[46:49]
	v_mfma_f32_16x16x32_bf16 v[42:45], v[172:175], v[180:183], v[42:45]
	v_mfma_f32_16x16x32_bf16 v[30:33], v[164:167], v[188:191], v[30:33]
	v_mfma_f32_16x16x32_bf16 v[26:29], v[172:175], v[188:191], v[26:29]
	v_mfma_f32_16x16x32_bf16 v[14:17], v[164:167], v[196:199], v[14:17]
	v_mfma_f32_16x16x32_bf16 v[10:13], v[172:175], v[196:199], v[10:13]
	v_mfma_f32_16x16x32_bf16 v[6:9], v[164:167], v[204:207], v[6:9]
	v_mfma_f32_16x16x32_bf16 v[2:5], v[172:175], v[204:207], v[2:5]
	s_setprio 0
	s_barrier
	s_add_i32 s50, s50, 2
	s_add_u32 s36, s36, 0x100
	s_addc_u32 s37, s37, 0
	s_add_u32 s12, s12, 0x10000
	s_addc_u32 s13, s13, 0
	s_cmp_gt_u32 s50, 19
	s_cbranch_scc0 .Lh1_6

.LBB0_2020:
	v_lshl_add_u32 v144, s5, 8, v141
	s_ashr_i32 s5, s4, 31
	s_lshl_b64 s[4:5], s[4:5], 22
	v_readlane_b32 s12, v254, 40
	s_add_u32 s4, s12, s4
	v_readlane_b32 s12, v254, 41
	v_lshl_add_u32 v146, s44, 8, v142
	s_addc_u32 s5, s12, s5
	v_ashrrev_i32_e32 v145, 31, v144
	v_ashrrev_i32_e32 v147, 31, v146
	v_lshl_add_u64 v[144:145], v[144:145], 1, s[4:5]
	v_lshlrev_b64 v[148:149], 12, v[146:147]
	v_lshl_add_u64 v[148:149], v[144:145], 0, v[148:149]
	v_cvt_pk_f16_f32 v109, v108, v109
	v_cvt_pk_f16_f32 v108, v106, v107
	v_cvt_pk_f16_f32 v107, v112, v113
	v_cvt_pk_f16_f32 v106, v110, v111
	global_store_dwordx4 v[148:149], v[106:109], off offset:256
	v_cvt_pk_f16_f32 v93, v92, v93
	v_cvt_pk_f16_f32 v92, v90, v91
	v_or_b32_e32 v106, 16, v146
	v_ashrrev_i32_e32 v107, 31, v106
	v_lshlrev_b64 v[106:107], 12, v[106:107]
	v_lshl_add_u64 v[110:111], v[144:145], 0, v[106:107]
	v_cvt_pk_f16_f32 v91, v96, v97
	v_cvt_pk_f16_f32 v90, v94, v95
	global_store_dwordx4 v[110:111], v[90:93], off offset:256
	v_cvt_pk_f16_f32 v77, v76, v77
	v_cvt_pk_f16_f32 v76, v74, v75
	v_or_b32_e32 v90, 32, v146
	v_ashrrev_i32_e32 v91, 31, v90
	v_lshlrev_b64 v[90:91], 12, v[90:91]
	v_lshl_add_u64 v[94:95], v[144:145], 0, v[90:91]
	v_cvt_pk_f16_f32 v75, v80, v81
	v_cvt_pk_f16_f32 v74, v78, v79
	global_store_dwordx4 v[94:95], v[74:77], off offset:256
	v_cvt_pk_f16_f32 v69, v68, v69
	v_cvt_pk_f16_f32 v68, v66, v67
	v_or_b32_e32 v74, 48, v146
	v_ashrrev_i32_e32 v75, 31, v74
	v_lshlrev_b64 v[74:75], 12, v[74:75]
	v_lshl_add_u64 v[78:79], v[144:145], 0, v[74:75]
	v_cvt_pk_f16_f32 v67, v72, v73
	v_cvt_pk_f16_f32 v66, v70, v71
	s_mov_b64 s[4:5], 0x80000
	global_store_dwordx4 v[78:79], v[66:69], off offset:256
	v_cvt_pk_f16_f32 v61, v60, v61
	v_cvt_pk_f16_f32 v60, v58, v59
	v_lshl_add_u64 v[66:67], v[148:149], 0, s[4:5]
	v_cvt_pk_f16_f32 v58, v62, v63
	v_add_co_u32_e32 v62, vcc, s79, v148
	s_mov_b64 s[4:5], 0x90000
	s_nop 0
	v_addc_co_u32_e32 v63, vcc, 0, v149, vcc
	v_cvt_pk_f16_f32 v45, v44, v45
	v_cvt_pk_f16_f32 v44, v42, v43
	v_cvt_pk_f16_f32 v42, v46, v47
	v_lshl_add_u64 v[46:47], v[148:149], 0, s[4:5]
	s_mov_b32 s4, 0x90000
	v_cvt_pk_f16_f32 v43, v48, v49
	v_add_co_u32_e32 v48, vcc, s4, v148
	s_mov_b64 s[4:5], 0xa0000
	s_nop 0
	v_addc_co_u32_e32 v49, vcc, 0, v149, vcc
	v_cvt_pk_f16_f32 v29, v28, v29
	v_cvt_pk_f16_f32 v28, v26, v27
	v_cvt_pk_f16_f32 v26, v30, v31
	v_lshl_add_u64 v[30:31], v[148:149], 0, s[4:5]
	s_mov_b32 s4, 0xa0000
	v_cvt_pk_f16_f32 v27, v32, v33
	v_add_co_u32_e32 v32, vcc, s4, v148
	s_mov_b64 s[4:5], 0xb0000
	s_nop 0
	v_addc_co_u32_e32 v33, vcc, 0, v149, vcc
	v_cvt_pk_f16_f32 v13, v12, v13
	v_cvt_pk_f16_f32 v12, v10, v11
	v_cvt_pk_f16_f32 v10, v14, v15
	v_lshl_add_u64 v[14:15], v[148:149], 0, s[4:5]
	s_mov_b32 s4, 0xb0000
	v_cvt_pk_f16_f32 v11, v16, v17
	v_add_co_u32_e32 v16, vcc, s4, v148
	v_cvt_pk_f16_f32 v125, v124, v125
	s_nop 0
	v_addc_co_u32_e32 v17, vcc, 0, v149, vcc
	v_cvt_pk_f16_f32 v124, v122, v123
	v_cvt_pk_f16_f32 v123, v128, v129
	v_cvt_pk_f16_f32 v122, v126, v127
	v_cvt_pk_f16_f32 v109, v116, v117
	v_cvt_pk_f16_f32 v108, v114, v115
	v_cvt_pk_f16_f32 v107, v120, v121
	v_cvt_pk_f16_f32 v106, v118, v119
	v_cvt_pk_f16_f32 v93, v100, v101
	v_cvt_pk_f16_f32 v92, v98, v99
	v_cvt_pk_f16_f32 v91, v104, v105
	v_cvt_pk_f16_f32 v90, v102, v103
	v_cvt_pk_f16_f32 v77, v84, v85
	v_cvt_pk_f16_f32 v76, v82, v83
	v_cvt_pk_f16_f32 v75, v88, v89
	v_cvt_pk_f16_f32 v74, v86, v87
	v_cvt_pk_f16_f32 v59, v64, v65
	global_store_dwordx4 v[66:67], v[42:45], off offset:256
	global_store_dwordx4 v[46:47], v[26:29], off offset:256
	global_store_dwordx4 v[30:31], v[10:13], off offset:256
	v_cvt_pk_f16_f32 v45, v52, v53
	v_cvt_pk_f16_f32 v44, v50, v51
	v_cvt_pk_f16_f32 v43, v56, v57
	v_cvt_pk_f16_f32 v42, v54, v55
	v_cvt_pk_f16_f32 v29, v36, v37
	v_cvt_pk_f16_f32 v28, v34, v35
	v_cvt_pk_f16_f32 v27, v40, v41
	v_cvt_pk_f16_f32 v26, v38, v39
	v_cvt_pk_f16_f32 v13, v20, v21
	v_cvt_pk_f16_f32 v12, v18, v19
	v_cvt_pk_f16_f32 v11, v24, v25
	v_cvt_pk_f16_f32 v10, v22, v23
	v_cvt_pk_f16_f32 v5, v4, v5
	v_cvt_pk_f16_f32 v4, v2, v3
	v_cvt_pk_f16_f32 v3, v8, v9
	v_cvt_pk_f16_f32 v2, v6, v7
	s_and_b64 vcc, exec, s[34:35]
	s_mov_b64 s[4:5], -1
	global_store_dwordx4 v[148:149], v[122:125], off
	global_store_dwordx4 v[110:111], v[106:109], off
	global_store_dwordx4 v[94:95], v[90:93], off
	global_store_dwordx4 v[78:79], v[74:77], off
	global_store_dwordx4 v[62:63], v[58:61], off
	global_store_dwordx4 v[48:49], v[42:45], off
	global_store_dwordx4 v[32:33], v[26:29], off
	global_store_dwordx4 v[16:17], v[10:13], off
	global_store_dwordx4 v[14:15], v[2:5], off offset:256
	s_cbranch_vccnz .LBB0_2009
	s_andn2_b64 vcc, exec, s[0:1]
	s_cbranch_vccnz .LBB0_2008
	s_branch .LBB0_2008
